# plus: removed the 156 compiler-duplicated s_waitcnt lgkmcnt(0) that follow s_setprio 1 directly behind an identical drain (GEMM phases)
# speedup vs baseline: 1.0086x; 1.0029x over previous
; #define STAGEA(P, br, kt) do { const char* _g = uptr(A + (size_t)(br) * lda + (size_t)(kt) * BK); \
;     _Pragma("unroll") for (int _i = 0; _i < 2; ++_i) { \
;       __builtin_amdgcn_global_load_lds((const unsigned*)(_g + offA[_i]), (unsigned*)((char*)(P) + tidx * 16 + _i * 8192), 16, 0, 0); } } while (0)
; #define STAGEB(P, br, kt) do { const char* _g = uptr(Bt + (size_t)(br) * ldb + (size_t)(kt) * BK); \
;     _Pragma("unroll") for (int _i = 0; _i < 2; ++_i) { \
;       __builtin_amdgcn_global_load_lds((const unsigned*)(_g + offB[_i]), (unsigned*)((char*)(P) + tidx * 16 + _i * 8192), 16, 0, 0); } } while (0)
; #define LDA(dst, b, h) _Pragma("unroll") for (int m = 0; m < 4; ++m) _Pragma("unroll") for (int k = 0; k < 2; ++k) \
;     dst[m][k] = *reinterpret_cast<const bf16x8*>((char*)SA(b, h) + aoff + m * 2048 + k * 1024)
; #define LDB(dst, b, h) _Pragma("unroll") for (int n = 0; n < 2; ++n) _Pragma("unroll") for (int k = 0; k < 2; ++k) \
;     dst[n][k] = *reinterpret_cast<const bf16x8*>((char*)SB(b, h) + boff + n * (SWAP ? 256 : 2048) + k * 1024)
; #define WAIT_V(n) asm volatile("s_waitcnt vmcnt(" #n ")" ::: "memory")
; #define WAIT_L(n) asm volatile("s_waitcnt lgkmcnt(" #n ")" ::: "memory")
; #define BAR __builtin_amdgcn_s_barrier()
; #define SCHED __builtin_amdgcn_sched_barrier(0)
; template <int EPI>
; DI void gemm_phase(const u16* __restrict__ A, int lda, const u16* __restrict__ Bt, int ldb,
;                    int M, int N, int K, const Epi& e, unsigned char* shmraw, int wv, int slot) {
;     ...
;       LDB(B0, 0, 0); SCHED; LDA(At, 0, 0); STAGEA(SA(1, 1), brow + HALF, t + 1);
;       WAIT_L(8); BAR; WAIT_L(0); MMA(0, 0, At, B0); BAR; SCHED;
;       LDB(B1, 0, 1); STAGEB(SB(0, 0), bcol, t + 2);
;       BAR; WAIT_L(0); MMA(0, 1, At, B1); BAR;
;       LDA(At, 0, 1); STAGEA(SA(0, 0), brow, t + 2);
;       BAR; WAIT_L(0); MMA(1, 0, At, B0); BAR; SCHED;
;       STAGEB(SB(0, 1), bcol + HALF, t + 2);
;       WAIT_V(6); BAR; MMA(1, 1, At, B1); BAR;
.LBB0_242:
	ds_read_b128 v[162:165], v157
	ds_read_b128 v[166:169], v157 offset:256
	ds_read_b128 v[170:173], v157 offset:1024
	ds_read_b128 v[174:177], v157 offset:1280
	s_add_u32 s45, s42, s14
	s_addc_u32 s47, s43, s15
	s_add_u32 s46, s45, 0x80
	s_addc_u32 s47, s47, 0
	v_readfirstlane_b32 s45, v155
	v_lshl_add_u64 v[134:135], s[46:47], 0, v[132:133]
	s_mov_b32 m0, s45
	v_readfirstlane_b32 s45, v156
	ds_read_b128 v[178:181], v154
	ds_read_b128 v[182:185], v154 offset:1024
	ds_read_b128 v[186:189], v154 offset:2048
	ds_read_b128 v[190:193], v154 offset:3072
	ds_read_b128 v[194:197], v154 offset:4096
	ds_read_b128 v[198:201], v154 offset:5120
	ds_read_b128 v[202:205], v154 offset:6144
	ds_read_b128 v[206:209], v154 offset:7168
	global_load_lds_dwordx4 v[134:135], off
	v_lshl_add_u64 v[134:135], s[46:47], 0, v[130:131]
	s_mov_b32 m0, s45
	s_nop 0
	global_load_lds_dwordx4 v[134:135], off
	s_waitcnt lgkmcnt(8)
	s_barrier
	s_waitcnt lgkmcnt(0)
	s_setprio 1
	v_mfma_f32_16x16x32_bf16 v[124:127], v[162:165], v[178:181], v[124:127]
	v_mfma_f32_16x16x32_bf16 v[120:123], v[166:169], v[178:181], v[120:123]
	v_mfma_f32_16x16x32_bf16 v[116:119], v[162:165], v[186:189], v[116:119]
	v_mfma_f32_16x16x32_bf16 v[112:115], v[166:169], v[186:189], v[112:115]
	v_mfma_f32_16x16x32_bf16 v[108:111], v[162:165], v[194:197], v[108:111]
	v_mfma_f32_16x16x32_bf16 v[104:107], v[166:169], v[194:197], v[104:107]
	v_mfma_f32_16x16x32_bf16 v[100:103], v[162:165], v[202:205], v[100:103]
	v_mfma_f32_16x16x32_bf16 v[96:99], v[166:169], v[202:205], v[96:99]
	v_mfma_f32_16x16x32_bf16 v[124:127], v[170:173], v[182:185], v[124:127]
	v_mfma_f32_16x16x32_bf16 v[120:123], v[174:177], v[182:185], v[120:123]
	v_mfma_f32_16x16x32_bf16 v[116:119], v[170:173], v[190:193], v[116:119]
	v_mfma_f32_16x16x32_bf16 v[112:115], v[174:177], v[190:193], v[112:115]
	v_mfma_f32_16x16x32_bf16 v[108:111], v[170:173], v[198:201], v[108:111]
	v_mfma_f32_16x16x32_bf16 v[104:107], v[174:177], v[198:201], v[104:107]
	v_mfma_f32_16x16x32_bf16 v[100:103], v[170:173], v[206:209], v[100:103]
	v_mfma_f32_16x16x32_bf16 v[96:99], v[174:177], v[206:209], v[96:99]
	s_setprio 0
	s_barrier
	s_add_u32 s45, s31, s14
	s_addc_u32 s48, s36, s15
	s_add_u32 s46, s45, 0x100
	s_addc_u32 s47, s48, 0
	v_readfirstlane_b32 s49, v139
	v_lshl_add_u64 v[134:135], s[46:47], 0, v[132:133]
	s_mov_b32 m0, s49
	ds_read_b128 v[210:213], v158
	ds_read_b128 v[214:217], v158 offset:256
	ds_read_b128 v[218:221], v158 offset:1024
	ds_read_b128 v[222:225], v158 offset:1280
	global_load_lds_dwordx4 v[134:135], off
	v_lshl_add_u64 v[134:135], s[46:47], 0, v[130:131]
	v_readfirstlane_b32 s46, v140
	s_mov_b32 m0, s46
	s_nop 0
	global_load_lds_dwordx4 v[134:135], off
	s_barrier
	s_waitcnt lgkmcnt(0)
	s_setprio 1
	v_mfma_f32_16x16x32_bf16 v[52:55], v[210:213], v[178:181], v[52:55]
	v_mfma_f32_16x16x32_bf16 v[40:43], v[214:217], v[178:181], v[40:43]
	v_mfma_f32_16x16x32_bf16 v[36:39], v[210:213], v[186:189], v[36:39]
	v_mfma_f32_16x16x32_bf16 v[32:35], v[214:217], v[186:189], v[32:35]
	v_mfma_f32_16x16x32_bf16 v[28:31], v[210:213], v[194:197], v[28:31]
	v_mfma_f32_16x16x32_bf16 v[24:27], v[214:217], v[194:197], v[24:27]
	v_mfma_f32_16x16x32_bf16 v[20:23], v[210:213], v[202:205], v[20:23]
	v_mfma_f32_16x16x32_bf16 v[16:19], v[214:217], v[202:205], v[16:19]
	v_mfma_f32_16x16x32_bf16 v[52:55], v[218:221], v[182:185], v[52:55]
	v_mfma_f32_16x16x32_bf16 v[40:43], v[222:225], v[182:185], v[40:43]
	v_mfma_f32_16x16x32_bf16 v[36:39], v[218:221], v[190:193], v[36:39]
	v_mfma_f32_16x16x32_bf16 v[32:35], v[222:225], v[190:193], v[32:35]
	v_mfma_f32_16x16x32_bf16 v[28:31], v[218:221], v[198:201], v[28:31]
	v_mfma_f32_16x16x32_bf16 v[24:27], v[222:225], v[198:201], v[24:27]
	v_mfma_f32_16x16x32_bf16 v[20:23], v[218:221], v[206:209], v[20:23]
	v_mfma_f32_16x16x32_bf16 v[16:19], v[222:225], v[206:209], v[16:19]
	s_setprio 0
	s_add_u32 s49, s13, s14
	s_addc_u32 s50, s37, s15
	s_add_u32 s46, s49, 0x100
	s_addc_u32 s47, s50, 0
	v_readfirstlane_b32 s51, v141
	v_lshl_add_u64 v[134:135], s[46:47], 0, v[132:133]
	s_mov_b32 m0, s51
	s_barrier
	ds_read_b128 v[178:181], v154 offset:16384
	ds_read_b128 v[182:185], v154 offset:17408
	ds_read_b128 v[186:189], v154 offset:18432
	ds_read_b128 v[190:193], v154 offset:19456
	ds_read_b128 v[194:197], v154 offset:20480
	ds_read_b128 v[198:201], v154 offset:21504
	ds_read_b128 v[202:205], v154 offset:22528
	ds_read_b128 v[206:209], v154 offset:23552
	global_load_lds_dwordx4 v[134:135], off
	v_lshl_add_u64 v[134:135], s[46:47], 0, v[130:131]
	v_readfirstlane_b32 s46, v142
	s_mov_b32 m0, s46
	s_nop 0
	global_load_lds_dwordx4 v[134:135], off
	s_barrier
	s_waitcnt lgkmcnt(0)
	s_setprio 1
	v_mfma_f32_16x16x32_bf16 v[12:15], v[162:165], v[178:181], v[12:15]
	v_mfma_f32_16x16x32_bf16 v[8:11], v[166:169], v[178:181], v[8:11]
	v_mfma_f32_16x16x32_bf16 v[4:7], v[162:165], v[186:189], v[4:7]
	v_mfma_f32_16x16x32_bf16 v[0:3], v[166:169], v[186:189], v[0:3]
	v_mfma_f32_16x16x32_bf16 v[44:47], v[162:165], v[194:197], v[44:47]
	v_mfma_f32_16x16x32_bf16 v[48:51], v[166:169], v[194:197], v[48:51]
	v_mfma_f32_16x16x32_bf16 v[56:59], v[162:165], v[202:205], v[56:59]
	v_mfma_f32_16x16x32_bf16 v[64:67], v[166:169], v[202:205], v[64:67]
	v_mfma_f32_16x16x32_bf16 v[12:15], v[170:173], v[182:185], v[12:15]
	v_mfma_f32_16x16x32_bf16 v[8:11], v[174:177], v[182:185], v[8:11]
	v_mfma_f32_16x16x32_bf16 v[4:7], v[170:173], v[190:193], v[4:7]
	v_mfma_f32_16x16x32_bf16 v[0:3], v[174:177], v[190:193], v[0:3]
	v_mfma_f32_16x16x32_bf16 v[44:47], v[170:173], v[198:201], v[44:47]
	v_mfma_f32_16x16x32_bf16 v[48:51], v[174:177], v[198:201], v[48:51]
	v_mfma_f32_16x16x32_bf16 v[56:59], v[170:173], v[206:209], v[56:59]
	v_mfma_f32_16x16x32_bf16 v[64:67], v[174:177], v[206:209], v[64:67]
	s_setprio 0
	s_barrier
; #define STAGEA(P, br, kt) do { const char* _g = uptr(A + (size_t)(br) * lda + (size_t)(kt) * BK); \
;     _Pragma("unroll") for (int _i = 0; _i < 2; ++_i) { \
;       __builtin_amdgcn_global_load_lds((const unsigned*)(_g + offA[_i]), (unsigned*)((char*)(P) + tidx * 16 + _i * 8192), 16, 0, 0); } } while (0)
; #define STAGEB(P, br, kt) do { const char* _g = uptr(Bt + (size_t)(br) * ldb + (size_t)(kt) * BK); \
;     _Pragma("unroll") for (int _i = 0; _i < 2; ++_i) { \
;       __builtin_amdgcn_global_load_lds((const unsigned*)(_g + offB[_i]), (unsigned*)((char*)(P) + tidx * 16 + _i * 8192), 16, 0, 0); } } while (0)
; #define LDA(dst, b, h) _Pragma("unroll") for (int m = 0; m < 4; ++m) _Pragma("unroll") for (int k = 0; k < 2; ++k) \
;     dst[m][k] = *reinterpret_cast<const bf16x8*>((char*)SA(b, h) + aoff + m * 2048 + k * 1024)
; #define LDB(dst, b, h) _Pragma("unroll") for (int n = 0; n < 2; ++n) _Pragma("unroll") for (int k = 0; k < 2; ++k) \
;     dst[n][k] = *reinterpret_cast<const bf16x8*>((char*)SB(b, h) + boff + n * (SWAP ? 256 : 2048) + k * 1024)
; #define WAIT_V(n) asm volatile("s_waitcnt vmcnt(" #n ")" ::: "memory")
; #define WAIT_L(n) asm volatile("s_waitcnt lgkmcnt(" #n ")" ::: "memory")
; #define BAR __builtin_amdgcn_s_barrier()
; #define SCHED __builtin_amdgcn_sched_barrier(0)
; template <int EPI>
; DI void gemm_phase(const u16* __restrict__ A, int lda, const u16* __restrict__ Bt, int ldb,
;                    int M, int N, int K, const Epi& e, unsigned char* shmraw, int wv, int slot) {
;     ...
;       STAGEB(SB(0, 1), bcol + HALF, t + 2);
;       WAIT_V(6); BAR; MMA(1, 1, At, B1); BAR;
;       LDB(B0, 1, 0); SCHED; LDA(At, 1, 0); STAGEA(SA(0, 1), brow + HALF, t + 2);
;       WAIT_L(8); BAR; WAIT_L(0); MMA(0, 0, At, B0); BAR; SCHED;
;       LDB(B1, 1, 1); STAGEB(SB(1, 0), bcol, t + 3);
;       BAR; WAIT_L(0); MMA(0, 1, At, B1); BAR;
	s_add_u32 s51, s38, s14
	s_addc_u32 s54, s39, s15
	s_add_u32 s46, s51, 0x100
	s_addc_u32 s47, s54, 0
	v_readfirstlane_b32 s55, v143
	v_lshl_add_u64 v[134:135], s[46:47], 0, v[132:133]
	s_mov_b32 m0, s55
	s_nop 0
	global_load_lds_dwordx4 v[134:135], off
	v_lshl_add_u64 v[134:135], s[46:47], 0, v[130:131]
	v_readfirstlane_b32 s46, v144
	s_mov_b32 m0, s46
	s_nop 0
	global_load_lds_dwordx4 v[134:135], off
	s_waitcnt vmcnt(6)
	s_barrier
	s_setprio 1
	v_mfma_f32_16x16x32_bf16 v[60:63], v[210:213], v[178:181], v[60:63]
	v_mfma_f32_16x16x32_bf16 v[68:71], v[214:217], v[178:181], v[68:71]
	v_mfma_f32_16x16x32_bf16 v[72:75], v[210:213], v[186:189], v[72:75]
	v_mfma_f32_16x16x32_bf16 v[76:79], v[214:217], v[186:189], v[76:79]
	v_mfma_f32_16x16x32_bf16 v[80:83], v[210:213], v[194:197], v[80:83]
	v_mfma_f32_16x16x32_bf16 v[84:87], v[214:217], v[194:197], v[84:87]
	v_mfma_f32_16x16x32_bf16 v[88:91], v[210:213], v[202:205], v[88:91]
	v_mfma_f32_16x16x32_bf16 v[92:95], v[214:217], v[202:205], v[92:95]
	v_mfma_f32_16x16x32_bf16 v[60:63], v[218:221], v[182:185], v[60:63]
	v_mfma_f32_16x16x32_bf16 v[68:71], v[222:225], v[182:185], v[68:71]
	v_mfma_f32_16x16x32_bf16 v[72:75], v[218:221], v[190:193], v[72:75]
	v_mfma_f32_16x16x32_bf16 v[76:79], v[222:225], v[190:193], v[76:79]
	v_mfma_f32_16x16x32_bf16 v[80:83], v[218:221], v[198:201], v[80:83]
	v_mfma_f32_16x16x32_bf16 v[84:87], v[222:225], v[198:201], v[84:87]
	v_mfma_f32_16x16x32_bf16 v[88:91], v[218:221], v[206:209], v[88:91]
	v_mfma_f32_16x16x32_bf16 v[92:95], v[222:225], v[206:209], v[92:95]
	s_setprio 0
	s_barrier
	ds_read_b128 v[162:165], v159
	ds_read_b128 v[166:169], v159 offset:256
	ds_read_b128 v[170:173], v159 offset:1024
	ds_read_b128 v[174:177], v159 offset:1280
	s_add_u32 s46, s40, s14
	s_addc_u32 s47, s41, s15
	v_readfirstlane_b32 s55, v145
	v_lshl_add_u64 v[134:135], s[46:47], 0, v[132:133]
	s_mov_b32 m0, s55
	ds_read_b128 v[178:181], v154 offset:32768
	ds_read_b128 v[182:185], v154 offset:33792
	ds_read_b128 v[186:189], v154 offset:34816
	ds_read_b128 v[190:193], v154 offset:35840
	ds_read_b128 v[194:197], v154 offset:36864
	ds_read_b128 v[198:201], v154 offset:37888
	ds_read_b128 v[202:205], v154 offset:38912
	ds_read_b128 v[206:209], v154 offset:39936
	global_load_lds_dwordx4 v[134:135], off
	v_lshl_add_u64 v[134:135], s[46:47], 0, v[130:131]
	v_readfirstlane_b32 s46, v146
	s_mov_b32 m0, s46
	s_nop 0
	global_load_lds_dwordx4 v[134:135], off
	s_waitcnt lgkmcnt(8)
	s_barrier
	s_waitcnt lgkmcnt(0)
	s_setprio 1
	v_mfma_f32_16x16x32_bf16 v[124:127], v[162:165], v[178:181], v[124:127]
	v_mfma_f32_16x16x32_bf16 v[120:123], v[166:169], v[178:181], v[120:123]
	v_mfma_f32_16x16x32_bf16 v[116:119], v[162:165], v[186:189], v[116:119]
	v_mfma_f32_16x16x32_bf16 v[112:115], v[166:169], v[186:189], v[112:115]
	v_mfma_f32_16x16x32_bf16 v[108:111], v[162:165], v[194:197], v[108:111]
	v_mfma_f32_16x16x32_bf16 v[104:107], v[166:169], v[194:197], v[104:107]
	v_mfma_f32_16x16x32_bf16 v[100:103], v[162:165], v[202:205], v[100:103]
	v_mfma_f32_16x16x32_bf16 v[96:99], v[166:169], v[202:205], v[96:99]
	v_mfma_f32_16x16x32_bf16 v[124:127], v[170:173], v[182:185], v[124:127]
	v_mfma_f32_16x16x32_bf16 v[120:123], v[174:177], v[182:185], v[120:123]
	v_mfma_f32_16x16x32_bf16 v[116:119], v[170:173], v[190:193], v[116:119]
	v_mfma_f32_16x16x32_bf16 v[112:115], v[174:177], v[190:193], v[112:115]
	v_mfma_f32_16x16x32_bf16 v[108:111], v[170:173], v[198:201], v[108:111]
	v_mfma_f32_16x16x32_bf16 v[104:107], v[174:177], v[198:201], v[104:107]
	v_mfma_f32_16x16x32_bf16 v[100:103], v[170:173], v[206:209], v[100:103]
	v_mfma_f32_16x16x32_bf16 v[96:99], v[174:177], v[206:209], v[96:99]
	s_setprio 0
	s_barrier
	s_add_u32 s46, s45, 0x180
	s_addc_u32 s47, s48, 0
	v_readfirstlane_b32 s45, v147
	v_lshl_add_u64 v[134:135], s[46:47], 0, v[132:133]
	s_mov_b32 m0, s45
	v_readfirstlane_b32 s45, v148
	ds_read_b128 v[210:213], v160
	ds_read_b128 v[214:217], v160 offset:256
	ds_read_b128 v[218:221], v160 offset:1024
	ds_read_b128 v[222:225], v160 offset:1280
	global_load_lds_dwordx4 v[134:135], off
	v_lshl_add_u64 v[134:135], s[46:47], 0, v[130:131]
	s_mov_b32 m0, s45
	s_nop 0
	global_load_lds_dwordx4 v[134:135], off
	s_barrier
	s_waitcnt lgkmcnt(0)
	s_setprio 1
	v_mfma_f32_16x16x32_bf16 v[52:55], v[210:213], v[178:181], v[52:55]
	v_mfma_f32_16x16x32_bf16 v[40:43], v[214:217], v[178:181], v[40:43]
	v_mfma_f32_16x16x32_bf16 v[36:39], v[210:213], v[186:189], v[36:39]
	v_mfma_f32_16x16x32_bf16 v[32:35], v[214:217], v[186:189], v[32:35]
	v_mfma_f32_16x16x32_bf16 v[28:31], v[210:213], v[194:197], v[28:31]
	v_mfma_f32_16x16x32_bf16 v[24:27], v[214:217], v[194:197], v[24:27]
	v_mfma_f32_16x16x32_bf16 v[20:23], v[210:213], v[202:205], v[20:23]
	v_mfma_f32_16x16x32_bf16 v[16:19], v[214:217], v[202:205], v[16:19]
	v_mfma_f32_16x16x32_bf16 v[52:55], v[218:221], v[182:185], v[52:55]
	v_mfma_f32_16x16x32_bf16 v[40:43], v[222:225], v[182:185], v[40:43]
	v_mfma_f32_16x16x32_bf16 v[36:39], v[218:221], v[190:193], v[36:39]
	v_mfma_f32_16x16x32_bf16 v[32:35], v[222:225], v[190:193], v[32:35]
	v_mfma_f32_16x16x32_bf16 v[28:31], v[218:221], v[198:201], v[28:31]
	v_mfma_f32_16x16x32_bf16 v[24:27], v[222:225], v[198:201], v[24:27]
	v_mfma_f32_16x16x32_bf16 v[20:23], v[218:221], v[206:209], v[20:23]
	v_mfma_f32_16x16x32_bf16 v[16:19], v[222:225], v[206:209], v[16:19]
	s_setprio 0
	s_add_u32 s46, s49, 0x180
	s_addc_u32 s47, s50, 0
	v_readfirstlane_b32 s45, v149
	v_lshl_add_u64 v[134:135], s[46:47], 0, v[132:133]
	s_mov_b32 m0, s45
	v_readfirstlane_b32 s45, v150
	s_barrier
; #define STAGEA(P, br, kt) do { const char* _g = uptr(A + (size_t)(br) * lda + (size_t)(kt) * BK); \
;     _Pragma("unroll") for (int _i = 0; _i < 2; ++_i) { \
;       __builtin_amdgcn_global_load_lds((const unsigned*)(_g + offA[_i]), (unsigned*)((char*)(P) + tidx * 16 + _i * 8192), 16, 0, 0); } } while (0)
; #define STAGEB(P, br, kt) do { const char* _g = uptr(Bt + (size_t)(br) * ldb + (size_t)(kt) * BK); \
;     _Pragma("unroll") for (int _i = 0; _i < 2; ++_i) { \
;       __builtin_amdgcn_global_load_lds((const unsigned*)(_g + offB[_i]), (unsigned*)((char*)(P) + tidx * 16 + _i * 8192), 16, 0, 0); } } while (0)
; #define LDA(dst, b, h) _Pragma("unroll") for (int m = 0; m < 4; ++m) _Pragma("unroll") for (int k = 0; k < 2; ++k) \
;     dst[m][k] = *reinterpret_cast<const bf16x8*>((char*)SA(b, h) + aoff + m * 2048 + k * 1024)
; #define LDB(dst, b, h) _Pragma("unroll") for (int n = 0; n < 2; ++n) _Pragma("unroll") for (int k = 0; k < 2; ++k) \
;     dst[n][k] = *reinterpret_cast<const bf16x8*>((char*)SB(b, h) + boff + n * (SWAP ? 256 : 2048) + k * 1024)
; #define WAIT_V(n) asm volatile("s_waitcnt vmcnt(" #n ")" ::: "memory")
; #define WAIT_L(n) asm volatile("s_waitcnt lgkmcnt(" #n ")" ::: "memory")
; #define BAR __builtin_amdgcn_s_barrier()
; #define SCHED __builtin_amdgcn_sched_barrier(0)
; template <int EPI>
; DI void gemm_phase(const u16* __restrict__ A, int lda, const u16* __restrict__ Bt, int ldb,
;                    int M, int N, int K, const Epi& e, unsigned char* shmraw, int wv, int slot) {
;     ...
;       LDA(At, 1, 1); STAGEA(SA(1, 0), brow, t + 3);
;       BAR; WAIT_L(0); MMA(1, 0, At, B0); BAR; SCHED;
;       STAGEB(SB(1, 1), bcol + HALF, t + 3);
;       WAIT_V(6); BAR; MMA(1, 1, At, B1); BAR;
;     }
;     { LDB(B0, 0, 0); LDA(At, 0, 0); STAGEA(SA(1, 1), brow + HALF, nt - 1);
;       BAR; WAIT_L(0); MMA(0, 0, At, B0); BAR;
;       LDB(B1, 0, 1); BAR; WAIT_L(0); MMA(0, 1, At, B1); BAR;
	ds_read_b128 v[178:181], v154 offset:49152
	ds_read_b128 v[182:185], v154 offset:50176
	ds_read_b128 v[186:189], v154 offset:51200
	ds_read_b128 v[190:193], v154 offset:52224
	ds_read_b128 v[194:197], v154 offset:53248
	ds_read_b128 v[198:201], v154 offset:54272
	ds_read_b128 v[202:205], v154 offset:55296
	ds_read_b128 v[206:209], v154 offset:56320
	global_load_lds_dwordx4 v[134:135], off
	v_lshl_add_u64 v[134:135], s[46:47], 0, v[130:131]
	s_mov_b32 m0, s45
	s_nop 0
	global_load_lds_dwordx4 v[134:135], off
	s_barrier
	s_waitcnt lgkmcnt(0)
	s_setprio 1
	v_mfma_f32_16x16x32_bf16 v[12:15], v[162:165], v[178:181], v[12:15]
	v_mfma_f32_16x16x32_bf16 v[8:11], v[166:169], v[178:181], v[8:11]
	v_mfma_f32_16x16x32_bf16 v[4:7], v[162:165], v[186:189], v[4:7]
	v_mfma_f32_16x16x32_bf16 v[0:3], v[166:169], v[186:189], v[0:3]
	v_mfma_f32_16x16x32_bf16 v[44:47], v[162:165], v[194:197], v[44:47]
	v_mfma_f32_16x16x32_bf16 v[48:51], v[166:169], v[194:197], v[48:51]
	v_mfma_f32_16x16x32_bf16 v[56:59], v[162:165], v[202:205], v[56:59]
	v_mfma_f32_16x16x32_bf16 v[64:67], v[166:169], v[202:205], v[64:67]
	v_mfma_f32_16x16x32_bf16 v[12:15], v[170:173], v[182:185], v[12:15]
	v_mfma_f32_16x16x32_bf16 v[8:11], v[174:177], v[182:185], v[8:11]
	v_mfma_f32_16x16x32_bf16 v[4:7], v[170:173], v[190:193], v[4:7]
	v_mfma_f32_16x16x32_bf16 v[0:3], v[174:177], v[190:193], v[0:3]
	v_mfma_f32_16x16x32_bf16 v[44:47], v[170:173], v[198:201], v[44:47]
	v_mfma_f32_16x16x32_bf16 v[48:51], v[174:177], v[198:201], v[48:51]
	v_mfma_f32_16x16x32_bf16 v[56:59], v[170:173], v[206:209], v[56:59]
	v_mfma_f32_16x16x32_bf16 v[64:67], v[174:177], v[206:209], v[64:67]
	s_setprio 0
	s_barrier
	s_add_u32 s46, s51, 0x180
	s_addc_u32 s47, s54, 0
	v_readfirstlane_b32 s45, v151
	v_lshl_add_u64 v[134:135], s[46:47], 0, v[132:133]
	s_mov_b32 m0, s45
	v_readfirstlane_b32 s45, v152
	global_load_lds_dwordx4 v[134:135], off
	v_lshl_add_u64 v[134:135], s[46:47], 0, v[130:131]
	s_mov_b32 m0, s45
	s_nop 0
	global_load_lds_dwordx4 v[134:135], off
	s_waitcnt vmcnt(6)
	s_barrier
	s_setprio 1
	v_mfma_f32_16x16x32_bf16 v[60:63], v[210:213], v[178:181], v[60:63]
	v_mfma_f32_16x16x32_bf16 v[68:71], v[214:217], v[178:181], v[68:71]
	v_mfma_f32_16x16x32_bf16 v[72:75], v[210:213], v[186:189], v[72:75]
	v_mfma_f32_16x16x32_bf16 v[76:79], v[214:217], v[186:189], v[76:79]
	v_mfma_f32_16x16x32_bf16 v[80:83], v[210:213], v[194:197], v[80:83]
	v_mfma_f32_16x16x32_bf16 v[84:87], v[214:217], v[194:197], v[84:87]
	v_mfma_f32_16x16x32_bf16 v[88:91], v[210:213], v[202:205], v[88:91]
	v_mfma_f32_16x16x32_bf16 v[92:95], v[214:217], v[202:205], v[92:95]
	v_mfma_f32_16x16x32_bf16 v[60:63], v[218:221], v[182:185], v[60:63]
	v_mfma_f32_16x16x32_bf16 v[68:71], v[222:225], v[182:185], v[68:71]
	v_mfma_f32_16x16x32_bf16 v[72:75], v[218:221], v[190:193], v[72:75]
	v_mfma_f32_16x16x32_bf16 v[76:79], v[222:225], v[190:193], v[76:79]
	v_mfma_f32_16x16x32_bf16 v[80:83], v[218:221], v[198:201], v[80:83]
	v_mfma_f32_16x16x32_bf16 v[84:87], v[222:225], v[198:201], v[84:87]
	v_mfma_f32_16x16x32_bf16 v[88:91], v[218:221], v[206:209], v[88:91]
	v_mfma_f32_16x16x32_bf16 v[92:95], v[222:225], v[206:209], v[92:95]
	s_setprio 0
	s_add_i32 s44, s44, 2
	s_add_u32 s14, s14, 0x100
	s_addc_u32 s15, s15, 0
	s_cmp_lt_u32 s44, 12
	s_barrier
	s_cbranch_scc1 .LBB0_242
	v_add_u32_e32 v128, 16, v153
	s_add_u32 s14, s29, 0x780
	v_add_u32_e32 v134, 0x10000, v128
	s_addc_u32 s15, s30, 0
	v_readfirstlane_b32 s13, v155
	ds_read_b128 v[162:165], v134
	ds_read_b128 v[166:169], v134 offset:256
	ds_read_b128 v[170:173], v134 offset:1024
	ds_read_b128 v[174:177], v134 offset:1280
	ds_read_b128 v[178:181], v154
	ds_read_b128 v[182:185], v154 offset:1024
	ds_read_b128 v[186:189], v154 offset:2048
	ds_read_b128 v[190:193], v154 offset:3072
	ds_read_b128 v[194:197], v154 offset:4096
	ds_read_b128 v[198:201], v154 offset:5120
	ds_read_b128 v[202:205], v154 offset:6144
	ds_read_b128 v[206:209], v154 offset:7168
	v_lshl_add_u64 v[134:135], s[14:15], 0, v[132:133]
	s_mov_b32 m0, s13
	v_readfirstlane_b32 s13, v156
	global_load_lds_dwordx4 v[134:135], off
	v_lshl_add_u64 v[134:135], s[14:15], 0, v[130:131]
	s_mov_b32 m0, s13
	s_nop 0
	global_load_lds_dwordx4 v[134:135], off
	s_barrier
	s_waitcnt lgkmcnt(0)
	s_setprio 1
	v_mfma_f32_16x16x32_bf16 v[124:127], v[162:165], v[178:181], v[124:127]
	v_mfma_f32_16x16x32_bf16 v[120:123], v[166:169], v[178:181], v[120:123]
	v_mfma_f32_16x16x32_bf16 v[116:119], v[162:165], v[186:189], v[116:119]
	v_mfma_f32_16x16x32_bf16 v[112:115], v[166:169], v[186:189], v[112:115]
	v_mfma_f32_16x16x32_bf16 v[100:103], v[162:165], v[202:205], v[100:103]
	v_mfma_f32_16x16x32_bf16 v[96:99], v[166:169], v[202:205], v[96:99]
	v_mfma_f32_16x16x32_bf16 v[124:127], v[170:173], v[182:185], v[124:127]
	v_mfma_f32_16x16x32_bf16 v[120:123], v[174:177], v[182:185], v[120:123]
	v_mfma_f32_16x16x32_bf16 v[116:119], v[170:173], v[190:193], v[116:119]
	v_mfma_f32_16x16x32_bf16 v[112:115], v[174:177], v[190:193], v[112:115]
	v_mfma_f32_16x16x32_bf16 v[108:111], v[162:165], v[194:197], v[108:111]
	v_mfma_f32_16x16x32_bf16 v[104:107], v[166:169], v[194:197], v[104:107]
	v_mfma_f32_16x16x32_bf16 v[100:103], v[170:173], v[206:209], v[100:103]
	v_mfma_f32_16x16x32_bf16 v[96:99], v[174:177], v[206:209], v[96:99]
	v_mfma_f32_16x16x32_bf16 v[210:213], v[170:173], v[198:201], v[108:111]
	v_mfma_f32_16x16x32_bf16 v[214:217], v[174:177], v[198:201], v[104:107]
	s_setprio 0
	v_add_u32_e32 v134, 0x14000, v128
	s_barrier
	s_nop 0
	ds_read_b128 v[104:107], v134
	ds_read_b128 v[108:111], v134 offset:256
	ds_read_b128 v[218:221], v134 offset:1024
	ds_read_b128 v[222:225], v134 offset:1280
	s_barrier
; #define LDA(dst, b, h) _Pragma("unroll") for (int m = 0; m < 4; ++m) _Pragma("unroll") for (int k = 0; k < 2; ++k) \
;     dst[m][k] = *reinterpret_cast<const bf16x8*>((char*)SA(b, h) + aoff + m * 2048 + k * 1024)
; #define LDB(dst, b, h) _Pragma("unroll") for (int n = 0; n < 2; ++n) _Pragma("unroll") for (int k = 0; k < 2; ++k) \
;     dst[n][k] = *reinterpret_cast<const bf16x8*>((char*)SB(b, h) + boff + n * (SWAP ? 256 : 2048) + k * 1024)
; #define WAIT_V(n) asm volatile("s_waitcnt vmcnt(" #n ")" ::: "memory")
; #define WAIT_L(n) asm volatile("s_waitcnt lgkmcnt(" #n ")" ::: "memory")
; #define BAR __builtin_amdgcn_s_barrier()
; template <int EPI>
; DI void gemm_phase(const u16* __restrict__ A, int lda, const u16* __restrict__ Bt, int ldb,
;                    int M, int N, int K, const Epi& e, unsigned char* shmraw, int wv, int slot) {
;     ...
;       LDB(B1, 0, 1); BAR; WAIT_L(0); MMA(0, 1, At, B1); BAR;
;       LDA(At, 0, 1); WAIT_V(4); BAR; WAIT_L(0); MMA(1, 0, At, B0); MMA(1, 1, At, B1); BAR; }
;     { LDB(B0, 1, 0); LDA(At, 1, 0); WAIT_V(2); BAR; WAIT_L(0); MMA(0, 0, At, B0); BAR;
	s_waitcnt lgkmcnt(0)
	s_setprio 1
	v_mfma_f32_16x16x32_bf16 v[40:43], v[108:111], v[178:181], v[40:43]
	v_mfma_f32_16x16x32_bf16 v[36:39], v[104:107], v[186:189], v[36:39]
	v_mfma_f32_16x16x32_bf16 v[32:35], v[108:111], v[186:189], v[32:35]
	v_mfma_f32_16x16x32_bf16 v[20:23], v[104:107], v[202:205], v[20:23]
	v_mfma_f32_16x16x32_bf16 v[16:19], v[108:111], v[202:205], v[16:19]
	v_mfma_f32_16x16x32_bf16 v[52:55], v[104:107], v[178:181], v[52:55]
	v_mfma_f32_16x16x32_bf16 v[40:43], v[222:225], v[182:185], v[40:43]
	v_mfma_f32_16x16x32_bf16 v[36:39], v[218:221], v[190:193], v[36:39]
	v_mfma_f32_16x16x32_bf16 v[32:35], v[222:225], v[190:193], v[32:35]
	v_mfma_f32_16x16x32_bf16 v[28:31], v[104:107], v[194:197], v[28:31]
	v_mfma_f32_16x16x32_bf16 v[24:27], v[108:111], v[194:197], v[24:27]
	v_mfma_f32_16x16x32_bf16 v[20:23], v[218:221], v[206:209], v[20:23]
	v_mfma_f32_16x16x32_bf16 v[16:19], v[222:225], v[206:209], v[16:19]
	v_mfma_f32_16x16x32_bf16 v[226:229], v[218:221], v[182:185], v[52:55]
	v_mfma_f32_16x16x32_bf16 v[178:181], v[218:221], v[198:201], v[28:31]
	v_mfma_f32_16x16x32_bf16 v[182:185], v[222:225], v[198:201], v[24:27]
	s_setprio 0
	s_barrier
	s_nop 0
	ds_read_b128 v[24:27], v154 offset:16384
	ds_read_b128 v[28:31], v154 offset:17408
	ds_read_b128 v[52:55], v154 offset:18432
	ds_read_b128 v[186:189], v154 offset:19456
	ds_read_b128 v[190:193], v154 offset:20480
	ds_read_b128 v[194:197], v154 offset:21504
	ds_read_b128 v[198:201], v154 offset:22528
	ds_read_b128 v[202:205], v154 offset:23552
	s_waitcnt vmcnt(4)
	s_barrier
	s_waitcnt lgkmcnt(0)
	s_setprio 1
	v_mfma_f32_16x16x32_bf16 v[44:47], v[162:165], v[190:193], v[44:47]
	v_mfma_f32_16x16x32_bf16 v[206:209], v[170:173], v[194:197], v[44:47]
	v_mfma_f32_16x16x32_bf16 v[44:47], v[166:169], v[190:193], v[48:51]
	v_mfma_f32_16x16x32_bf16 v[12:15], v[162:165], v[24:27], v[12:15]
	v_mfma_f32_16x16x32_bf16 v[8:11], v[166:169], v[24:27], v[8:11]
	v_mfma_f32_16x16x32_bf16 v[4:7], v[162:165], v[52:55], v[4:7]
	v_mfma_f32_16x16x32_bf16 v[0:3], v[166:169], v[52:55], v[0:3]
	v_mfma_f32_16x16x32_bf16 v[230:233], v[174:177], v[194:197], v[44:47]
	v_mfma_f32_16x16x32_bf16 v[44:47], v[162:165], v[198:201], v[56:59]
	v_mfma_f32_16x16x32_bf16 v[12:15], v[170:173], v[28:31], v[12:15]
	v_mfma_f32_16x16x32_bf16 v[8:11], v[174:177], v[28:31], v[8:11]
	v_mfma_f32_16x16x32_bf16 v[4:7], v[170:173], v[186:189], v[4:7]
	v_mfma_f32_16x16x32_bf16 v[0:3], v[174:177], v[186:189], v[0:3]
	v_mfma_f32_16x16x32_bf16 v[56:59], v[170:173], v[202:205], v[44:47]
	v_mfma_f32_16x16x32_bf16 v[44:47], v[166:169], v[198:201], v[64:67]
	v_mfma_f32_16x16x32_bf16 v[162:165], v[174:177], v[202:205], v[44:47]
	s_setprio 0
	s_setprio 1
	v_mfma_f32_16x16x32_bf16 v[44:47], v[104:107], v[24:27], v[60:63]
	v_mfma_f32_16x16x32_bf16 v[24:27], v[108:111], v[24:27], v[68:71]
	v_mfma_f32_16x16x32_bf16 v[166:169], v[222:225], v[28:31], v[24:27]
	v_mfma_f32_16x16x32_bf16 v[24:27], v[104:107], v[52:55], v[72:75]
	v_mfma_f32_16x16x32_bf16 v[170:173], v[218:221], v[186:189], v[24:27]
	v_mfma_f32_16x16x32_bf16 v[24:27], v[108:111], v[52:55], v[76:79]
	v_mfma_f32_16x16x32_bf16 v[174:177], v[222:225], v[186:189], v[24:27]
	v_mfma_f32_16x16x32_bf16 v[24:27], v[104:107], v[190:193], v[80:83]
	v_mfma_f32_16x16x32_bf16 v[186:189], v[218:221], v[194:197], v[24:27]
	v_mfma_f32_16x16x32_bf16 v[24:27], v[108:111], v[190:193], v[84:87]
	v_mfma_f32_16x16x32_bf16 v[190:193], v[222:225], v[194:197], v[24:27]
	v_mfma_f32_16x16x32_bf16 v[24:27], v[104:107], v[198:201], v[88:91]
	v_mfma_f32_16x16x32_bf16 v[60:63], v[218:221], v[28:31], v[44:47]
	v_mfma_f32_16x16x32_bf16 v[194:197], v[218:221], v[202:205], v[24:27]
	v_mfma_f32_16x16x32_bf16 v[24:27], v[108:111], v[198:201], v[92:95]
	v_mfma_f32_16x16x32_bf16 v[198:201], v[222:225], v[202:205], v[24:27]
	s_setprio 0
	s_nop 5
	v_add_u32_e32 v24, 0x18000, v128
	s_barrier
	ds_read_b128 v[88:91], v24
	ds_read_b128 v[92:95], v24 offset:256
	ds_read_b128 v[202:205], v24 offset:1024
	ds_read_b128 v[218:221], v24 offset:1280
	ds_read_b128 v[44:47], v154 offset:32768
	ds_read_b128 v[64:67], v154 offset:33792
	ds_read_b128 v[68:71], v154 offset:34816
	ds_read_b128 v[72:75], v154 offset:35840
	ds_read_b128 v[76:79], v154 offset:36864
	ds_read_b128 v[222:225], v154 offset:37888
	ds_read_b128 v[234:237], v154 offset:38912
	ds_read_b128 v[238:241], v154 offset:39936
	s_waitcnt vmcnt(2)
	s_barrier
; #define LDA(dst, b, h) _Pragma("unroll") for (int m = 0; m < 4; ++m) _Pragma("unroll") for (int k = 0; k < 2; ++k) \
;     dst[m][k] = *reinterpret_cast<const bf16x8*>((char*)SA(b, h) + aoff + m * 2048 + k * 1024)
; #define LDB(dst, b, h) _Pragma("unroll") for (int n = 0; n < 2; ++n) _Pragma("unroll") for (int k = 0; k < 2; ++k) \
;     dst[n][k] = *reinterpret_cast<const bf16x8*>((char*)SB(b, h) + boff + n * (SWAP ? 256 : 2048) + k * 1024)
; #define WAIT_V(n) asm volatile("s_waitcnt vmcnt(" #n ")" ::: "memory")
; #define WAIT_L(n) asm volatile("s_waitcnt lgkmcnt(" #n ")" ::: "memory")
; #define BAR __builtin_amdgcn_s_barrier()
; template <int EPI>
; DI void gemm_phase(const u16* __restrict__ A, int lda, const u16* __restrict__ Bt, int ldb,
;                    int M, int N, int K, const Epi& e, unsigned char* shmraw, int wv, int slot) {
;     ...
;     { LDB(B0, 1, 0); LDA(At, 1, 0); WAIT_V(2); BAR; WAIT_L(0); MMA(0, 0, At, B0); BAR;
;       LDB(B1, 1, 1); WAIT_V(0); BAR; WAIT_L(0); MMA(0, 1, At, B1); BAR;
;       LDA(At, 1, 1); BAR; WAIT_L(0); MMA(1, 0, At, B0); MMA(1, 1, At, B1); BAR; }
;     if (wr == 0) BAR;
	s_waitcnt lgkmcnt(0)
	s_setprio 1
	v_mfma_f32_16x16x32_bf16 v[24:27], v[88:91], v[44:47], v[124:127]
	v_mfma_f32_16x16x32_bf16 v[104:107], v[202:205], v[64:67], v[24:27]
	v_mfma_f32_16x16x32_bf16 v[24:27], v[92:95], v[44:47], v[120:123]
	v_mfma_f32_16x16x32_bf16 v[108:111], v[218:221], v[64:67], v[24:27]
	v_mfma_f32_16x16x32_bf16 v[24:27], v[88:91], v[68:71], v[116:119]
	v_mfma_f32_16x16x32_bf16 v[80:83], v[202:205], v[72:75], v[24:27]
	v_mfma_f32_16x16x32_bf16 v[24:27], v[92:95], v[68:71], v[112:115]
	v_mfma_f32_16x16x32_bf16 v[84:87], v[218:221], v[72:75], v[24:27]
	v_mfma_f32_16x16x32_bf16 v[24:27], v[88:91], v[76:79], v[210:213]
	v_mfma_f32_16x16x32_bf16 v[48:51], v[202:205], v[222:225], v[24:27]
	v_mfma_f32_16x16x32_bf16 v[24:27], v[92:95], v[76:79], v[214:217]
	v_mfma_f32_16x16x32_bf16 v[52:55], v[218:221], v[222:225], v[24:27]
	v_mfma_f32_16x16x32_bf16 v[24:27], v[88:91], v[234:237], v[100:103]
	v_mfma_f32_16x16x32_bf16 v[28:31], v[92:95], v[234:237], v[96:99]
	v_mfma_f32_16x16x32_bf16 v[24:27], v[202:205], v[238:241], v[24:27]
	v_mfma_f32_16x16x32_bf16 v[28:31], v[218:221], v[238:241], v[28:31]
	s_setprio 0
	v_add_u32_e32 v96, 0x1c000, v128
	s_barrier
	ds_read_b128 v[210:213], v96
	ds_read_b128 v[214:217], v96 offset:256
	ds_read_b128 v[242:245], v96 offset:1024
	ds_read_b128 v[246:249], v96 offset:1280
	s_waitcnt vmcnt(0)
	s_barrier
	s_waitcnt lgkmcnt(0)
	s_setprio 1
	v_mfma_f32_16x16x32_bf16 v[32:35], v[214:217], v[68:71], v[32:35]
	v_mfma_f32_16x16x32_bf16 v[96:99], v[210:213], v[44:47], v[226:229]
	v_mfma_f32_16x16x32_bf16 v[116:119], v[246:249], v[72:75], v[32:35]
	v_mfma_f32_16x16x32_bf16 v[32:35], v[210:213], v[76:79], v[178:181]
	v_mfma_f32_16x16x32_bf16 v[120:123], v[242:245], v[64:67], v[96:99]
	v_mfma_f32_16x16x32_bf16 v[40:43], v[214:217], v[44:47], v[40:43]
	v_mfma_f32_16x16x32_bf16 v[36:39], v[210:213], v[68:71], v[36:39]
	v_mfma_f32_16x16x32_bf16 v[96:99], v[242:245], v[222:225], v[32:35]
	v_mfma_f32_16x16x32_bf16 v[32:35], v[214:217], v[76:79], v[182:185]
	v_mfma_f32_16x16x32_bf16 v[20:23], v[210:213], v[234:237], v[20:23]
	v_mfma_f32_16x16x32_bf16 v[16:19], v[214:217], v[234:237], v[16:19]
	v_mfma_f32_16x16x32_bf16 v[124:127], v[246:249], v[64:67], v[40:43]
	v_mfma_f32_16x16x32_bf16 v[112:115], v[242:245], v[72:75], v[36:39]
	v_mfma_f32_16x16x32_bf16 v[100:103], v[246:249], v[222:225], v[32:35]
	v_mfma_f32_16x16x32_bf16 v[72:75], v[242:245], v[238:241], v[20:23]
	v_mfma_f32_16x16x32_bf16 v[76:79], v[246:249], v[238:241], v[16:19]
	s_setprio 0
	s_barrier
	ds_read_b128 v[32:35], v154 offset:49152
	ds_read_b128 v[36:39], v154 offset:50176
	ds_read_b128 v[178:181], v154 offset:51200
	ds_read_b128 v[182:185], v154 offset:52224
	ds_read_b128 v[222:225], v154 offset:53248
	ds_read_b128 v[226:229], v154 offset:54272
	ds_read_b128 v[234:237], v154 offset:55296
	ds_read_b128 v[238:241], v154 offset:56320
	s_barrier
	s_waitcnt lgkmcnt(0)
	s_setprio 1
	v_mfma_f32_16x16x32_bf16 v[0:3], v[92:95], v[178:181], v[0:3]
	v_mfma_f32_16x16x32_bf16 v[44:47], v[218:221], v[182:185], v[0:3]
	v_mfma_f32_16x16x32_bf16 v[0:3], v[88:91], v[222:225], v[206:209]
	v_mfma_f32_16x16x32_bf16 v[4:7], v[88:91], v[178:181], v[4:7]
	v_mfma_f32_16x16x32_bf16 v[16:19], v[202:205], v[226:229], v[0:3]
	v_mfma_f32_16x16x32_bf16 v[0:3], v[92:95], v[222:225], v[230:233]
	v_mfma_f32_16x16x32_bf16 v[12:15], v[88:91], v[32:35], v[12:15]
	v_mfma_f32_16x16x32_bf16 v[8:11], v[92:95], v[32:35], v[8:11]
	v_mfma_f32_16x16x32_bf16 v[40:43], v[202:205], v[182:185], v[4:7]
	v_mfma_f32_16x16x32_bf16 v[20:23], v[218:221], v[226:229], v[0:3]
	v_mfma_f32_16x16x32_bf16 v[0:3], v[88:91], v[234:237], v[56:59]
	v_mfma_f32_16x16x32_bf16 v[4:7], v[92:95], v[234:237], v[162:165]
	v_mfma_f32_16x16x32_bf16 v[64:67], v[202:205], v[36:39], v[12:15]
	v_mfma_f32_16x16x32_bf16 v[68:71], v[218:221], v[36:39], v[8:11]
	v_mfma_f32_16x16x32_bf16 v[0:3], v[202:205], v[238:241], v[0:3]
	v_mfma_f32_16x16x32_bf16 v[4:7], v[218:221], v[238:241], v[4:7]
	s_setprio 0
	s_setprio 1
	v_mfma_f32_16x16x32_bf16 v[8:11], v[210:213], v[32:35], v[60:63]
	v_mfma_f32_16x16x32_bf16 v[88:91], v[242:245], v[36:39], v[8:11]
	v_mfma_f32_16x16x32_bf16 v[8:11], v[214:217], v[32:35], v[166:169]
	v_mfma_f32_16x16x32_bf16 v[92:95], v[246:249], v[36:39], v[8:11]
	v_mfma_f32_16x16x32_bf16 v[8:11], v[210:213], v[178:181], v[170:173]
	v_mfma_f32_16x16x32_bf16 v[56:59], v[242:245], v[182:185], v[8:11]
	v_mfma_f32_16x16x32_bf16 v[8:11], v[214:217], v[178:181], v[174:177]
	v_mfma_f32_16x16x32_bf16 v[60:63], v[246:249], v[182:185], v[8:11]
	v_mfma_f32_16x16x32_bf16 v[8:11], v[210:213], v[222:225], v[186:189]
	v_mfma_f32_16x16x32_bf16 v[32:35], v[242:245], v[226:229], v[8:11]
	v_mfma_f32_16x16x32_bf16 v[8:11], v[214:217], v[222:225], v[190:193]
	v_mfma_f32_16x16x32_bf16 v[36:39], v[246:249], v[226:229], v[8:11]
	v_mfma_f32_16x16x32_bf16 v[8:11], v[210:213], v[234:237], v[194:197]
	v_mfma_f32_16x16x32_bf16 v[12:15], v[214:217], v[234:237], v[198:201]
	v_mfma_f32_16x16x32_bf16 v[8:11], v[242:245], v[238:241], v[8:11]
	v_mfma_f32_16x16x32_bf16 v[12:15], v[246:249], v[238:241], v[12:15]
	s_setprio 0
	s_barrier
	s_and_saveexec_b64 s[14:15], s[4:5]
	s_cbranch_execz .LBB0_245
	s_barrier

; #define STAGEA(P, br, kt) do { const char* _g = uptr(A + (size_t)(br) * lda + (size_t)(kt) * BK); \
;     _Pragma("unroll") for (int _i = 0; _i < 2; ++_i) { \
;       __builtin_amdgcn_global_load_lds((const unsigned*)(_g + offA[_i]), (unsigned*)((char*)(P) + tidx * 16 + _i * 8192), 16, 0, 0); } } while (0)
; #define STAGEB(P, br, kt) do { const char* _g = uptr(Bt + (size_t)(br) * ldb + (size_t)(kt) * BK); \
;     _Pragma("unroll") for (int _i = 0; _i < 2; ++_i) { \
;       __builtin_amdgcn_global_load_lds((const unsigned*)(_g + offB[_i]), (unsigned*)((char*)(P) + tidx * 16 + _i * 8192), 16, 0, 0); } } while (0)
; #define LDA(dst, b, h) _Pragma("unroll") for (int m = 0; m < 4; ++m) _Pragma("unroll") for (int k = 0; k < 2; ++k) \
;     dst[m][k] = *reinterpret_cast<const bf16x8*>((char*)SA(b, h) + aoff + m * 2048 + k * 1024)
; #define LDB(dst, b, h) _Pragma("unroll") for (int n = 0; n < 2; ++n) _Pragma("unroll") for (int k = 0; k < 2; ++k) \
;     dst[n][k] = *reinterpret_cast<const bf16x8*>((char*)SB(b, h) + boff + n * (SWAP ? 256 : 2048) + k * 1024)
; #define WAIT_V(n) asm volatile("s_waitcnt vmcnt(" #n ")" ::: "memory")
; #define WAIT_L(n) asm volatile("s_waitcnt lgkmcnt(" #n ")" ::: "memory")
; #define BAR __builtin_amdgcn_s_barrier()
; #define SCHED __builtin_amdgcn_sched_barrier(0)
; template <int EPI>
; DI void gemm_phase(const u16* __restrict__ A, int lda, const u16* __restrict__ Bt, int ldb,
;                    int M, int N, int K, const Epi& e, unsigned char* shmraw, int wv, int slot) {
;     ...
;       LDB(B0, 0, 0); SCHED; LDA(At, 0, 0); STAGEA(SA(1, 1), brow + HALF, t + 1);
;       WAIT_L(8); BAR; WAIT_L(0); MMA(0, 0, At, B0); BAR; SCHED;
;       LDB(B1, 0, 1); STAGEB(SB(0, 0), bcol, t + 2);
;       BAR; WAIT_L(0); MMA(0, 1, At, B1); BAR;
;       LDA(At, 0, 1); STAGEA(SA(0, 0), brow, t + 2);
;       BAR; WAIT_L(0); MMA(1, 0, At, B0); BAR; SCHED;
;       STAGEB(SB(0, 1), bcol + HALF, t + 2);
;       WAIT_V(6); BAR; MMA(1, 1, At, B1); BAR;
.LBB0_333:
	ds_read_b128 v[130:133], v172
	ds_read_b128 v[134:137], v172 offset:256
	ds_read_b128 v[138:141], v172 offset:1024
	ds_read_b128 v[142:145], v172 offset:1280
	s_add_u32 s37, s40, s22
	s_addc_u32 s42, s41, s23
	s_add_u32 s68, s37, 0x80
	s_addc_u32 s69, s42, 0
	v_readfirstlane_b32 s37, v170
	v_lshl_add_u64 v[204:205], s[68:69], 0, v[0:1]
	s_mov_b32 m0, s37
	v_readfirstlane_b32 s37, v171
	ds_read_b128 v[148:151], v169
	ds_read_b128 v[176:179], v169 offset:1024
	ds_read_b128 v[180:183], v169 offset:2048
	ds_read_b128 v[184:187], v169 offset:3072
	ds_read_b128 v[188:191], v169 offset:4096
	ds_read_b128 v[192:195], v169 offset:5120
	ds_read_b128 v[196:199], v169 offset:6144
	ds_read_b128 v[200:203], v169 offset:7168
	global_load_lds_dwordx4 v[204:205], off
	v_lshl_add_u64 v[204:205], s[68:69], 0, v[146:147]
	s_mov_b32 m0, s37
	s_nop 0
	global_load_lds_dwordx4 v[204:205], off
	s_waitcnt lgkmcnt(8)
	s_barrier
	s_waitcnt lgkmcnt(0)
	s_setprio 1
	v_mfma_f32_16x16x32_bf16 v[126:129], v[130:133], v[148:151], v[126:129]
	v_mfma_f32_16x16x32_bf16 v[122:125], v[134:137], v[148:151], v[122:125]
	v_mfma_f32_16x16x32_bf16 v[118:121], v[130:133], v[180:183], v[118:121]
	v_mfma_f32_16x16x32_bf16 v[114:117], v[134:137], v[180:183], v[114:117]
	v_mfma_f32_16x16x32_bf16 v[110:113], v[130:133], v[188:191], v[110:113]
	v_mfma_f32_16x16x32_bf16 v[106:109], v[134:137], v[188:191], v[106:109]
	v_mfma_f32_16x16x32_bf16 v[102:105], v[130:133], v[196:199], v[102:105]
	v_mfma_f32_16x16x32_bf16 v[98:101], v[134:137], v[196:199], v[98:101]
	v_mfma_f32_16x16x32_bf16 v[126:129], v[138:141], v[176:179], v[126:129]
	v_mfma_f32_16x16x32_bf16 v[122:125], v[142:145], v[176:179], v[122:125]
	v_mfma_f32_16x16x32_bf16 v[118:121], v[138:141], v[184:187], v[118:121]
	v_mfma_f32_16x16x32_bf16 v[114:117], v[142:145], v[184:187], v[114:117]
	v_mfma_f32_16x16x32_bf16 v[110:113], v[138:141], v[192:195], v[110:113]
	v_mfma_f32_16x16x32_bf16 v[106:109], v[142:145], v[192:195], v[106:109]
	v_mfma_f32_16x16x32_bf16 v[102:105], v[138:141], v[200:203], v[102:105]
	v_mfma_f32_16x16x32_bf16 v[98:101], v[142:145], v[200:203], v[98:101]
	s_setprio 0
	s_barrier
	s_add_u32 s37, s9, s22
	s_addc_u32 s42, s31, s23
	s_add_u32 s68, s37, 0x100
	s_addc_u32 s69, s42, 0
	v_readfirstlane_b32 s48, v155
	v_lshl_add_u64 v[220:221], s[68:69], 0, v[0:1]
	s_mov_b32 m0, s48
	v_readfirstlane_b32 s48, v156
	ds_read_b128 v[204:207], v173
	ds_read_b128 v[208:211], v173 offset:256
	ds_read_b128 v[212:215], v173 offset:1024
	ds_read_b128 v[216:219], v173 offset:1280
	global_load_lds_dwordx4 v[220:221], off
	v_lshl_add_u64 v[220:221], s[68:69], 0, v[146:147]
	s_mov_b32 m0, s48
	s_nop 0
	global_load_lds_dwordx4 v[220:221], off
	s_barrier
	s_waitcnt lgkmcnt(0)
	s_setprio 1
	v_mfma_f32_16x16x32_bf16 v[94:97], v[204:207], v[148:151], v[94:97]
	v_mfma_f32_16x16x32_bf16 v[78:81], v[208:211], v[148:151], v[78:81]
	v_mfma_f32_16x16x32_bf16 v[62:65], v[204:207], v[180:183], v[62:65]
	v_mfma_f32_16x16x32_bf16 v[50:53], v[208:211], v[180:183], v[50:53]
	v_mfma_f32_16x16x32_bf16 v[46:49], v[204:207], v[188:191], v[46:49]
	v_mfma_f32_16x16x32_bf16 v[42:45], v[208:211], v[188:191], v[42:45]
	v_mfma_f32_16x16x32_bf16 v[38:41], v[204:207], v[196:199], v[38:41]
	v_mfma_f32_16x16x32_bf16 v[34:37], v[208:211], v[196:199], v[34:37]
	v_mfma_f32_16x16x32_bf16 v[94:97], v[212:215], v[176:179], v[94:97]
	v_mfma_f32_16x16x32_bf16 v[78:81], v[216:219], v[176:179], v[78:81]
	v_mfma_f32_16x16x32_bf16 v[62:65], v[212:215], v[184:187], v[62:65]
	v_mfma_f32_16x16x32_bf16 v[50:53], v[216:219], v[184:187], v[50:53]
	v_mfma_f32_16x16x32_bf16 v[46:49], v[212:215], v[192:195], v[46:49]
	v_mfma_f32_16x16x32_bf16 v[42:45], v[216:219], v[192:195], v[42:45]
	v_mfma_f32_16x16x32_bf16 v[38:41], v[212:215], v[200:203], v[38:41]
	v_mfma_f32_16x16x32_bf16 v[34:37], v[216:219], v[200:203], v[34:37]
	s_setprio 0
	s_add_u32 s48, s19, s22
	s_addc_u32 s54, s35, s23
	s_add_u32 s68, s48, 0x100
	s_addc_u32 s69, s54, 0
	v_readfirstlane_b32 s55, v157
	v_lshl_add_u64 v[220:221], s[68:69], 0, v[0:1]
	s_mov_b32 m0, s55
	v_readfirstlane_b32 s55, v158
	s_barrier
	ds_read_b128 v[148:151], v169 offset:16384
	ds_read_b128 v[176:179], v169 offset:17408
	ds_read_b128 v[180:183], v169 offset:18432
	ds_read_b128 v[184:187], v169 offset:19456
	ds_read_b128 v[188:191], v169 offset:20480
	ds_read_b128 v[192:195], v169 offset:21504
	ds_read_b128 v[196:199], v169 offset:22528
	ds_read_b128 v[200:203], v169 offset:23552
	global_load_lds_dwordx4 v[220:221], off
	v_lshl_add_u64 v[220:221], s[68:69], 0, v[146:147]
	s_mov_b32 m0, s55
	s_nop 0
	global_load_lds_dwordx4 v[220:221], off
	s_barrier
	s_waitcnt lgkmcnt(0)
	s_setprio 1
	v_mfma_f32_16x16x32_bf16 v[30:33], v[130:133], v[148:151], v[30:33]
	v_mfma_f32_16x16x32_bf16 v[26:29], v[134:137], v[148:151], v[26:29]
	v_mfma_f32_16x16x32_bf16 v[22:25], v[130:133], v[180:183], v[22:25]
	v_mfma_f32_16x16x32_bf16 v[18:21], v[134:137], v[180:183], v[18:21]
	v_mfma_f32_16x16x32_bf16 v[14:17], v[130:133], v[188:191], v[14:17]
	v_mfma_f32_16x16x32_bf16 v[10:13], v[134:137], v[188:191], v[10:13]
	v_mfma_f32_16x16x32_bf16 v[6:9], v[130:133], v[196:199], v[6:9]
	v_mfma_f32_16x16x32_bf16 v[2:5], v[134:137], v[196:199], v[2:5]
	v_mfma_f32_16x16x32_bf16 v[30:33], v[138:141], v[176:179], v[30:33]
	v_mfma_f32_16x16x32_bf16 v[26:29], v[142:145], v[176:179], v[26:29]
	v_mfma_f32_16x16x32_bf16 v[22:25], v[138:141], v[184:187], v[22:25]
	v_mfma_f32_16x16x32_bf16 v[18:21], v[142:145], v[184:187], v[18:21]
	v_mfma_f32_16x16x32_bf16 v[14:17], v[138:141], v[192:195], v[14:17]
	v_mfma_f32_16x16x32_bf16 v[10:13], v[142:145], v[192:195], v[10:13]
	v_mfma_f32_16x16x32_bf16 v[6:9], v[138:141], v[200:203], v[6:9]
	v_mfma_f32_16x16x32_bf16 v[2:5], v[142:145], v[200:203], v[2:5]
	s_setprio 0
	s_barrier
; #define STAGEA(P, br, kt) do { const char* _g = uptr(A + (size_t)(br) * lda + (size_t)(kt) * BK); \
;     _Pragma("unroll") for (int _i = 0; _i < 2; ++_i) { \
;       __builtin_amdgcn_global_load_lds((const unsigned*)(_g + offA[_i]), (unsigned*)((char*)(P) + tidx * 16 + _i * 8192), 16, 0, 0); } } while (0)
; #define STAGEB(P, br, kt) do { const char* _g = uptr(Bt + (size_t)(br) * ldb + (size_t)(kt) * BK); \
;     _Pragma("unroll") for (int _i = 0; _i < 2; ++_i) { \
;       __builtin_amdgcn_global_load_lds((const unsigned*)(_g + offB[_i]), (unsigned*)((char*)(P) + tidx * 16 + _i * 8192), 16, 0, 0); } } while (0)
; #define LDA(dst, b, h) _Pragma("unroll") for (int m = 0; m < 4; ++m) _Pragma("unroll") for (int k = 0; k < 2; ++k) \
;     dst[m][k] = *reinterpret_cast<const bf16x8*>((char*)SA(b, h) + aoff + m * 2048 + k * 1024)
; #define LDB(dst, b, h) _Pragma("unroll") for (int n = 0; n < 2; ++n) _Pragma("unroll") for (int k = 0; k < 2; ++k) \
;     dst[n][k] = *reinterpret_cast<const bf16x8*>((char*)SB(b, h) + boff + n * (SWAP ? 256 : 2048) + k * 1024)
; #define WAIT_V(n) asm volatile("s_waitcnt vmcnt(" #n ")" ::: "memory")
; #define WAIT_L(n) asm volatile("s_waitcnt lgkmcnt(" #n ")" ::: "memory")
; #define BAR __builtin_amdgcn_s_barrier()
; #define SCHED __builtin_amdgcn_sched_barrier(0)
; template <int EPI>
; DI void gemm_phase(const u16* __restrict__ A, int lda, const u16* __restrict__ Bt, int ldb,
;                    int M, int N, int K, const Epi& e, unsigned char* shmraw, int wv, int slot) {
;     ...
;       STAGEB(SB(0, 1), bcol + HALF, t + 2);
;       WAIT_V(6); BAR; MMA(1, 1, At, B1); BAR;
;       LDB(B0, 1, 0); SCHED; LDA(At, 1, 0); STAGEA(SA(0, 1), brow + HALF, t + 2);
;       WAIT_L(8); BAR; WAIT_L(0); MMA(0, 0, At, B0); BAR; SCHED;
;       LDB(B1, 1, 1); STAGEB(SB(1, 0), bcol, t + 3);
;       BAR; WAIT_L(0); MMA(0, 1, At, B1); BAR;
	s_add_u32 s55, s1, s22
	s_addc_u32 s70, s36, s23
	s_add_u32 s68, s55, 0x100
	s_addc_u32 s69, s70, 0
	v_readfirstlane_b32 s71, v159
	v_lshl_add_u64 v[130:131], s[68:69], 0, v[0:1]
	s_mov_b32 m0, s71
	s_nop 0
	global_load_lds_dwordx4 v[130:131], off
	v_lshl_add_u64 v[130:131], s[68:69], 0, v[146:147]
	v_readfirstlane_b32 s68, v160
	s_mov_b32 m0, s68
	s_nop 0
	global_load_lds_dwordx4 v[130:131], off
	s_waitcnt vmcnt(6)
	s_barrier
	s_setprio 1
	v_mfma_f32_16x16x32_bf16 v[54:57], v[204:207], v[148:151], v[54:57]
	v_mfma_f32_16x16x32_bf16 v[58:61], v[208:211], v[148:151], v[58:61]
	v_mfma_f32_16x16x32_bf16 v[66:69], v[204:207], v[180:183], v[66:69]
	v_mfma_f32_16x16x32_bf16 v[70:73], v[208:211], v[180:183], v[70:73]
	v_mfma_f32_16x16x32_bf16 v[74:77], v[204:207], v[188:191], v[74:77]
	v_mfma_f32_16x16x32_bf16 v[82:85], v[208:211], v[188:191], v[82:85]
	v_mfma_f32_16x16x32_bf16 v[86:89], v[204:207], v[196:199], v[86:89]
	v_mfma_f32_16x16x32_bf16 v[90:93], v[208:211], v[196:199], v[90:93]
	v_mfma_f32_16x16x32_bf16 v[54:57], v[212:215], v[176:179], v[54:57]
	v_mfma_f32_16x16x32_bf16 v[58:61], v[216:219], v[176:179], v[58:61]
	v_mfma_f32_16x16x32_bf16 v[66:69], v[212:215], v[184:187], v[66:69]
	v_mfma_f32_16x16x32_bf16 v[70:73], v[216:219], v[184:187], v[70:73]
	v_mfma_f32_16x16x32_bf16 v[74:77], v[212:215], v[192:195], v[74:77]
	v_mfma_f32_16x16x32_bf16 v[82:85], v[216:219], v[192:195], v[82:85]
	v_mfma_f32_16x16x32_bf16 v[86:89], v[212:215], v[200:203], v[86:89]
	v_mfma_f32_16x16x32_bf16 v[90:93], v[216:219], v[200:203], v[90:93]
	s_setprio 0
	s_barrier
	ds_read_b128 v[130:133], v174
	ds_read_b128 v[134:137], v174 offset:256
	ds_read_b128 v[138:141], v174 offset:1024
	ds_read_b128 v[142:145], v174 offset:1280
	s_add_u32 s68, s38, s22
	s_addc_u32 s69, s39, s23
	v_readfirstlane_b32 s71, v161
	v_lshl_add_u64 v[204:205], s[68:69], 0, v[0:1]
	s_mov_b32 m0, s71
	ds_read_b128 v[148:151], v169 offset:32768
	ds_read_b128 v[176:179], v169 offset:33792
	ds_read_b128 v[180:183], v169 offset:34816
	ds_read_b128 v[184:187], v169 offset:35840
	ds_read_b128 v[188:191], v169 offset:36864
	ds_read_b128 v[192:195], v169 offset:37888
	ds_read_b128 v[196:199], v169 offset:38912
	ds_read_b128 v[200:203], v169 offset:39936
	global_load_lds_dwordx4 v[204:205], off
	v_lshl_add_u64 v[204:205], s[68:69], 0, v[146:147]
	v_readfirstlane_b32 s68, v162
	s_mov_b32 m0, s68
	s_nop 0
	global_load_lds_dwordx4 v[204:205], off
	s_waitcnt lgkmcnt(8)
	s_barrier
	s_waitcnt lgkmcnt(0)
	s_setprio 1
	v_mfma_f32_16x16x32_bf16 v[126:129], v[130:133], v[148:151], v[126:129]
	v_mfma_f32_16x16x32_bf16 v[122:125], v[134:137], v[148:151], v[122:125]
	v_mfma_f32_16x16x32_bf16 v[118:121], v[130:133], v[180:183], v[118:121]
	v_mfma_f32_16x16x32_bf16 v[114:117], v[134:137], v[180:183], v[114:117]
	v_mfma_f32_16x16x32_bf16 v[110:113], v[130:133], v[188:191], v[110:113]
	v_mfma_f32_16x16x32_bf16 v[106:109], v[134:137], v[188:191], v[106:109]
	v_mfma_f32_16x16x32_bf16 v[102:105], v[130:133], v[196:199], v[102:105]
	v_mfma_f32_16x16x32_bf16 v[98:101], v[134:137], v[196:199], v[98:101]
	v_mfma_f32_16x16x32_bf16 v[126:129], v[138:141], v[176:179], v[126:129]
	v_mfma_f32_16x16x32_bf16 v[122:125], v[142:145], v[176:179], v[122:125]
	v_mfma_f32_16x16x32_bf16 v[118:121], v[138:141], v[184:187], v[118:121]
	v_mfma_f32_16x16x32_bf16 v[114:117], v[142:145], v[184:187], v[114:117]
	v_mfma_f32_16x16x32_bf16 v[110:113], v[138:141], v[192:195], v[110:113]
	v_mfma_f32_16x16x32_bf16 v[106:109], v[142:145], v[192:195], v[106:109]
	v_mfma_f32_16x16x32_bf16 v[102:105], v[138:141], v[200:203], v[102:105]
	v_mfma_f32_16x16x32_bf16 v[98:101], v[142:145], v[200:203], v[98:101]
	s_setprio 0
	s_barrier
	s_add_u32 s68, s37, 0x180
	s_addc_u32 s69, s42, 0
	v_readfirstlane_b32 s37, v163
	v_lshl_add_u64 v[220:221], s[68:69], 0, v[0:1]
	s_mov_b32 m0, s37
	v_readfirstlane_b32 s37, v164
	ds_read_b128 v[204:207], v175
	ds_read_b128 v[208:211], v175 offset:256
	ds_read_b128 v[212:215], v175 offset:1024
	ds_read_b128 v[216:219], v175 offset:1280
	global_load_lds_dwordx4 v[220:221], off
	v_lshl_add_u64 v[220:221], s[68:69], 0, v[146:147]
	s_mov_b32 m0, s37
	s_nop 0
	global_load_lds_dwordx4 v[220:221], off
	s_barrier
	s_waitcnt lgkmcnt(0)
	s_setprio 1
	v_mfma_f32_16x16x32_bf16 v[94:97], v[204:207], v[148:151], v[94:97]
	v_mfma_f32_16x16x32_bf16 v[78:81], v[208:211], v[148:151], v[78:81]
	v_mfma_f32_16x16x32_bf16 v[62:65], v[204:207], v[180:183], v[62:65]
	v_mfma_f32_16x16x32_bf16 v[50:53], v[208:211], v[180:183], v[50:53]
	v_mfma_f32_16x16x32_bf16 v[46:49], v[204:207], v[188:191], v[46:49]
	v_mfma_f32_16x16x32_bf16 v[42:45], v[208:211], v[188:191], v[42:45]
	v_mfma_f32_16x16x32_bf16 v[38:41], v[204:207], v[196:199], v[38:41]
	v_mfma_f32_16x16x32_bf16 v[34:37], v[208:211], v[196:199], v[34:37]
	v_mfma_f32_16x16x32_bf16 v[94:97], v[212:215], v[176:179], v[94:97]
	v_mfma_f32_16x16x32_bf16 v[78:81], v[216:219], v[176:179], v[78:81]
	v_mfma_f32_16x16x32_bf16 v[62:65], v[212:215], v[184:187], v[62:65]
	v_mfma_f32_16x16x32_bf16 v[50:53], v[216:219], v[184:187], v[50:53]
	v_mfma_f32_16x16x32_bf16 v[46:49], v[212:215], v[192:195], v[46:49]
	v_mfma_f32_16x16x32_bf16 v[42:45], v[216:219], v[192:195], v[42:45]
	v_mfma_f32_16x16x32_bf16 v[38:41], v[212:215], v[200:203], v[38:41]
	v_mfma_f32_16x16x32_bf16 v[34:37], v[216:219], v[200:203], v[34:37]
	s_setprio 0
	s_add_u32 s68, s48, 0x180
	s_addc_u32 s69, s54, 0
	v_readfirstlane_b32 s37, v165
	v_lshl_add_u64 v[220:221], s[68:69], 0, v[0:1]
	s_mov_b32 m0, s37
	v_readfirstlane_b32 s37, v166
	s_barrier
; #define STAGEA(P, br, kt) do { const char* _g = uptr(A + (size_t)(br) * lda + (size_t)(kt) * BK); \
;     _Pragma("unroll") for (int _i = 0; _i < 2; ++_i) { \
;       __builtin_amdgcn_global_load_lds((const unsigned*)(_g + offA[_i]), (unsigned*)((char*)(P) + tidx * 16 + _i * 8192), 16, 0, 0); } } while (0)
; #define STAGEB(P, br, kt) do { const char* _g = uptr(Bt + (size_t)(br) * ldb + (size_t)(kt) * BK); \
;     _Pragma("unroll") for (int _i = 0; _i < 2; ++_i) { \
;       __builtin_amdgcn_global_load_lds((const unsigned*)(_g + offB[_i]), (unsigned*)((char*)(P) + tidx * 16 + _i * 8192), 16, 0, 0); } } while (0)
; #define LDA(dst, b, h) _Pragma("unroll") for (int m = 0; m < 4; ++m) _Pragma("unroll") for (int k = 0; k < 2; ++k) \
;     dst[m][k] = *reinterpret_cast<const bf16x8*>((char*)SA(b, h) + aoff + m * 2048 + k * 1024)
; #define LDB(dst, b, h) _Pragma("unroll") for (int n = 0; n < 2; ++n) _Pragma("unroll") for (int k = 0; k < 2; ++k) \
;     dst[n][k] = *reinterpret_cast<const bf16x8*>((char*)SB(b, h) + boff + n * (SWAP ? 256 : 2048) + k * 1024)
; #define WAIT_V(n) asm volatile("s_waitcnt vmcnt(" #n ")" ::: "memory")
; #define WAIT_L(n) asm volatile("s_waitcnt lgkmcnt(" #n ")" ::: "memory")
; #define BAR __builtin_amdgcn_s_barrier()
; #define SCHED __builtin_amdgcn_sched_barrier(0)
; template <int EPI>
; DI void gemm_phase(const u16* __restrict__ A, int lda, const u16* __restrict__ Bt, int ldb,
;                    int M, int N, int K, const Epi& e, unsigned char* shmraw, int wv, int slot) {
;     ...
;       LDA(At, 1, 1); STAGEA(SA(1, 0), brow, t + 3);
;       BAR; WAIT_L(0); MMA(1, 0, At, B0); BAR; SCHED;
;       STAGEB(SB(1, 1), bcol + HALF, t + 3);
;       WAIT_V(6); BAR; MMA(1, 1, At, B1); BAR;
;     }
;     { LDB(B0, 0, 0); LDA(At, 0, 0); STAGEA(SA(1, 1), brow + HALF, nt - 1);
;       BAR; WAIT_L(0); MMA(0, 0, At, B0); BAR;
;       LDB(B1, 0, 1); BAR; WAIT_L(0); MMA(0, 1, At, B1); BAR;
	ds_read_b128 v[148:151], v169 offset:49152
	ds_read_b128 v[176:179], v169 offset:50176
	ds_read_b128 v[180:183], v169 offset:51200
	ds_read_b128 v[184:187], v169 offset:52224
	ds_read_b128 v[188:191], v169 offset:53248
	ds_read_b128 v[192:195], v169 offset:54272
	ds_read_b128 v[196:199], v169 offset:55296
	ds_read_b128 v[200:203], v169 offset:56320
	global_load_lds_dwordx4 v[220:221], off
	v_lshl_add_u64 v[220:221], s[68:69], 0, v[146:147]
	s_mov_b32 m0, s37
	s_nop 0
	global_load_lds_dwordx4 v[220:221], off
	s_barrier
	s_waitcnt lgkmcnt(0)
	s_setprio 1
	v_mfma_f32_16x16x32_bf16 v[30:33], v[130:133], v[148:151], v[30:33]
	v_mfma_f32_16x16x32_bf16 v[26:29], v[134:137], v[148:151], v[26:29]
	v_mfma_f32_16x16x32_bf16 v[22:25], v[130:133], v[180:183], v[22:25]
	v_mfma_f32_16x16x32_bf16 v[18:21], v[134:137], v[180:183], v[18:21]
	v_mfma_f32_16x16x32_bf16 v[14:17], v[130:133], v[188:191], v[14:17]
	v_mfma_f32_16x16x32_bf16 v[10:13], v[134:137], v[188:191], v[10:13]
	v_mfma_f32_16x16x32_bf16 v[6:9], v[130:133], v[196:199], v[6:9]
	v_mfma_f32_16x16x32_bf16 v[2:5], v[134:137], v[196:199], v[2:5]
	v_mfma_f32_16x16x32_bf16 v[30:33], v[138:141], v[176:179], v[30:33]
	v_mfma_f32_16x16x32_bf16 v[26:29], v[142:145], v[176:179], v[26:29]
	v_mfma_f32_16x16x32_bf16 v[22:25], v[138:141], v[184:187], v[22:25]
	v_mfma_f32_16x16x32_bf16 v[18:21], v[142:145], v[184:187], v[18:21]
	v_mfma_f32_16x16x32_bf16 v[14:17], v[138:141], v[192:195], v[14:17]
	v_mfma_f32_16x16x32_bf16 v[10:13], v[142:145], v[192:195], v[10:13]
	v_mfma_f32_16x16x32_bf16 v[6:9], v[138:141], v[200:203], v[6:9]
	v_mfma_f32_16x16x32_bf16 v[2:5], v[142:145], v[200:203], v[2:5]
	s_setprio 0
	s_barrier
	s_add_u32 s68, s55, 0x180
	s_addc_u32 s69, s70, 0
	v_readfirstlane_b32 s37, v167
	v_lshl_add_u64 v[130:131], s[68:69], 0, v[0:1]
	s_mov_b32 m0, s37
	v_readfirstlane_b32 s37, v168
	global_load_lds_dwordx4 v[130:131], off
	v_lshl_add_u64 v[130:131], s[68:69], 0, v[146:147]
	s_mov_b32 m0, s37
	s_nop 0
	global_load_lds_dwordx4 v[130:131], off
	s_waitcnt vmcnt(6)
	s_barrier
	s_setprio 1
	v_mfma_f32_16x16x32_bf16 v[54:57], v[204:207], v[148:151], v[54:57]
	v_mfma_f32_16x16x32_bf16 v[58:61], v[208:211], v[148:151], v[58:61]
	v_mfma_f32_16x16x32_bf16 v[66:69], v[204:207], v[180:183], v[66:69]
	v_mfma_f32_16x16x32_bf16 v[70:73], v[208:211], v[180:183], v[70:73]
	v_mfma_f32_16x16x32_bf16 v[74:77], v[204:207], v[188:191], v[74:77]
	v_mfma_f32_16x16x32_bf16 v[82:85], v[208:211], v[188:191], v[82:85]
	v_mfma_f32_16x16x32_bf16 v[86:89], v[204:207], v[196:199], v[86:89]
	v_mfma_f32_16x16x32_bf16 v[90:93], v[208:211], v[196:199], v[90:93]
	v_mfma_f32_16x16x32_bf16 v[54:57], v[212:215], v[176:179], v[54:57]
	v_mfma_f32_16x16x32_bf16 v[58:61], v[216:219], v[176:179], v[58:61]
	v_mfma_f32_16x16x32_bf16 v[66:69], v[212:215], v[184:187], v[66:69]
	v_mfma_f32_16x16x32_bf16 v[70:73], v[216:219], v[184:187], v[70:73]
	v_mfma_f32_16x16x32_bf16 v[74:77], v[212:215], v[192:195], v[74:77]
	v_mfma_f32_16x16x32_bf16 v[82:85], v[216:219], v[192:195], v[82:85]
	v_mfma_f32_16x16x32_bf16 v[86:89], v[212:215], v[200:203], v[86:89]
	v_mfma_f32_16x16x32_bf16 v[90:93], v[216:219], v[200:203], v[90:93]
	s_setprio 0
	s_add_i32 s43, s43, 2
	s_add_u32 s22, s22, 0x100
	s_addc_u32 s23, s23, 0
	s_cmp_lt_u32 s43, 12
	s_barrier
	s_cbranch_scc1 .LBB0_333
	s_add_u32 s22, s29, 0x780
	v_add_u32_e32 v152, 16, v153
	s_addc_u32 s23, s30, 0
	v_readfirstlane_b32 s1, v170
	v_add_u32_e32 v142, 0x10000, v152
	v_lshl_add_u64 v[204:205], s[22:23], 0, v[0:1]
	s_mov_b32 m0, s1
	v_readfirstlane_b32 s1, v171
	ds_read_b128 v[130:133], v142
	ds_read_b128 v[134:137], v142 offset:256
	ds_read_b128 v[138:141], v142 offset:1024
	ds_read_b128 v[142:145], v142 offset:1280
	ds_read_b128 v[148:151], v169
	ds_read_b128 v[176:179], v169 offset:1024
	ds_read_b128 v[180:183], v169 offset:2048
	ds_read_b128 v[184:187], v169 offset:3072
	ds_read_b128 v[188:191], v169 offset:4096
	ds_read_b128 v[192:195], v169 offset:5120
	ds_read_b128 v[196:199], v169 offset:6144
	ds_read_b128 v[200:203], v169 offset:7168
	global_load_lds_dwordx4 v[204:205], off
	v_lshl_add_u64 v[204:205], s[22:23], 0, v[146:147]
	s_mov_b32 m0, s1
	s_nop 0
	global_load_lds_dwordx4 v[204:205], off
	s_barrier
	s_waitcnt lgkmcnt(0)
	s_setprio 1
	v_mfma_f32_16x16x32_bf16 v[126:129], v[130:133], v[148:151], v[126:129]
	v_mfma_f32_16x16x32_bf16 v[122:125], v[134:137], v[148:151], v[122:125]
	v_mfma_f32_16x16x32_bf16 v[118:121], v[130:133], v[180:183], v[118:121]
	v_mfma_f32_16x16x32_bf16 v[110:113], v[130:133], v[188:191], v[110:113]
	v_mfma_f32_16x16x32_bf16 v[106:109], v[134:137], v[188:191], v[106:109]
	v_mfma_f32_16x16x32_bf16 v[98:101], v[134:137], v[196:199], v[98:101]
	v_mfma_f32_16x16x32_bf16 v[126:129], v[138:141], v[176:179], v[126:129]
	v_mfma_f32_16x16x32_bf16 v[122:125], v[142:145], v[176:179], v[122:125]
	v_mfma_f32_16x16x32_bf16 v[118:121], v[138:141], v[184:187], v[118:121]
	v_mfma_f32_16x16x32_bf16 v[114:117], v[134:137], v[180:183], v[114:117]
	v_mfma_f32_16x16x32_bf16 v[110:113], v[138:141], v[192:195], v[110:113]
	v_mfma_f32_16x16x32_bf16 v[106:109], v[142:145], v[192:195], v[106:109]
	v_mfma_f32_16x16x32_bf16 v[102:105], v[130:133], v[196:199], v[102:105]
	v_mfma_f32_16x16x32_bf16 v[98:101], v[142:145], v[200:203], v[98:101]
	v_mfma_f32_16x16x32_bf16 v[204:207], v[142:145], v[184:187], v[114:117]
	v_mfma_f32_16x16x32_bf16 v[208:211], v[138:141], v[200:203], v[102:105]
	s_setprio 0
	v_add_u32_e32 v154, 0x14000, v152
	s_barrier
	s_nop 1
	ds_read_b128 v[102:105], v154
	ds_read_b128 v[114:117], v154 offset:256
	ds_read_b128 v[212:215], v154 offset:1024
	ds_read_b128 v[216:219], v154 offset:1280
	s_barrier
; #define LDA(dst, b, h) _Pragma("unroll") for (int m = 0; m < 4; ++m) _Pragma("unroll") for (int k = 0; k < 2; ++k) \
;     dst[m][k] = *reinterpret_cast<const bf16x8*>((char*)SA(b, h) + aoff + m * 2048 + k * 1024)
; #define LDB(dst, b, h) _Pragma("unroll") for (int n = 0; n < 2; ++n) _Pragma("unroll") for (int k = 0; k < 2; ++k) \
;     dst[n][k] = *reinterpret_cast<const bf16x8*>((char*)SB(b, h) + boff + n * (SWAP ? 256 : 2048) + k * 1024)
; #define WAIT_V(n) asm volatile("s_waitcnt vmcnt(" #n ")" ::: "memory")
; #define WAIT_L(n) asm volatile("s_waitcnt lgkmcnt(" #n ")" ::: "memory")
; #define BAR __builtin_amdgcn_s_barrier()
; template <int EPI>
; DI void gemm_phase(const u16* __restrict__ A, int lda, const u16* __restrict__ Bt, int ldb,
;                    int M, int N, int K, const Epi& e, unsigned char* shmraw, int wv, int slot) {
;     ...
;       LDB(B1, 0, 1); BAR; WAIT_L(0); MMA(0, 1, At, B1); BAR;
;       LDA(At, 0, 1); WAIT_V(4); BAR; WAIT_L(0); MMA(1, 0, At, B0); MMA(1, 1, At, B1); BAR; }
;     { LDB(B0, 1, 0); LDA(At, 1, 0); WAIT_V(2); BAR; WAIT_L(0); MMA(0, 0, At, B0); BAR;
	s_waitcnt lgkmcnt(0)
	s_setprio 1
	v_mfma_f32_16x16x32_bf16 v[94:97], v[102:105], v[148:151], v[94:97]
	v_mfma_f32_16x16x32_bf16 v[78:81], v[114:117], v[148:151], v[78:81]
	v_mfma_f32_16x16x32_bf16 v[62:65], v[102:105], v[180:183], v[62:65]
	v_mfma_f32_16x16x32_bf16 v[50:53], v[114:117], v[180:183], v[50:53]
	v_mfma_f32_16x16x32_bf16 v[94:97], v[212:215], v[176:179], v[94:97]
	v_mfma_f32_16x16x32_bf16 v[78:81], v[216:219], v[176:179], v[78:81]
	v_mfma_f32_16x16x32_bf16 v[62:65], v[212:215], v[184:187], v[62:65]
	v_mfma_f32_16x16x32_bf16 v[50:53], v[216:219], v[184:187], v[50:53]
	v_mfma_f32_16x16x32_bf16 v[46:49], v[102:105], v[188:191], v[46:49]
	v_mfma_f32_16x16x32_bf16 v[42:45], v[114:117], v[188:191], v[42:45]
	v_mfma_f32_16x16x32_bf16 v[38:41], v[102:105], v[196:199], v[38:41]
	v_mfma_f32_16x16x32_bf16 v[34:37], v[114:117], v[196:199], v[34:37]
	v_mfma_f32_16x16x32_bf16 v[46:49], v[212:215], v[192:195], v[46:49]
	v_mfma_f32_16x16x32_bf16 v[42:45], v[216:219], v[192:195], v[42:45]
	v_mfma_f32_16x16x32_bf16 v[38:41], v[212:215], v[200:203], v[38:41]
	v_mfma_f32_16x16x32_bf16 v[34:37], v[216:219], v[200:203], v[34:37]
	s_setprio 0
	s_barrier
	ds_read_b128 v[148:151], v169 offset:16384
	ds_read_b128 v[176:179], v169 offset:17408
	ds_read_b128 v[180:183], v169 offset:18432
	ds_read_b128 v[184:187], v169 offset:19456
	ds_read_b128 v[188:191], v169 offset:20480
	ds_read_b128 v[192:195], v169 offset:21504
	ds_read_b128 v[196:199], v169 offset:22528
	ds_read_b128 v[200:203], v169 offset:23552
	s_waitcnt vmcnt(4)
	s_barrier
	s_waitcnt lgkmcnt(0)
	s_setprio 1
	v_mfma_f32_16x16x32_bf16 v[30:33], v[130:133], v[148:151], v[30:33]
	v_mfma_f32_16x16x32_bf16 v[26:29], v[134:137], v[148:151], v[26:29]
	v_mfma_f32_16x16x32_bf16 v[22:25], v[130:133], v[180:183], v[22:25]
	v_mfma_f32_16x16x32_bf16 v[18:21], v[134:137], v[180:183], v[18:21]
	v_mfma_f32_16x16x32_bf16 v[14:17], v[130:133], v[188:191], v[14:17]
	v_mfma_f32_16x16x32_bf16 v[10:13], v[134:137], v[188:191], v[10:13]
	v_mfma_f32_16x16x32_bf16 v[6:9], v[130:133], v[196:199], v[6:9]
	v_mfma_f32_16x16x32_bf16 v[2:5], v[134:137], v[196:199], v[2:5]
	v_mfma_f32_16x16x32_bf16 v[30:33], v[138:141], v[176:179], v[30:33]
	v_mfma_f32_16x16x32_bf16 v[26:29], v[142:145], v[176:179], v[26:29]
	v_mfma_f32_16x16x32_bf16 v[22:25], v[138:141], v[184:187], v[22:25]
	v_mfma_f32_16x16x32_bf16 v[18:21], v[142:145], v[184:187], v[18:21]
	v_mfma_f32_16x16x32_bf16 v[14:17], v[138:141], v[192:195], v[14:17]
	v_mfma_f32_16x16x32_bf16 v[10:13], v[142:145], v[192:195], v[10:13]
	v_mfma_f32_16x16x32_bf16 v[6:9], v[138:141], v[200:203], v[6:9]
	v_mfma_f32_16x16x32_bf16 v[2:5], v[142:145], v[200:203], v[2:5]
	s_setprio 0
	s_setprio 1
	v_mfma_f32_16x16x32_bf16 v[58:61], v[114:117], v[148:151], v[58:61]
	v_mfma_f32_16x16x32_bf16 v[54:57], v[102:105], v[148:151], v[54:57]
	v_mfma_f32_16x16x32_bf16 v[148:151], v[216:219], v[176:179], v[58:61]
	v_mfma_f32_16x16x32_bf16 v[58:61], v[102:105], v[180:183], v[66:69]
	v_mfma_f32_16x16x32_bf16 v[54:57], v[212:215], v[176:179], v[54:57]
	v_mfma_f32_16x16x32_bf16 v[176:179], v[212:215], v[184:187], v[58:61]
	v_mfma_f32_16x16x32_bf16 v[58:61], v[114:117], v[180:183], v[70:73]
	v_mfma_f32_16x16x32_bf16 v[180:183], v[216:219], v[184:187], v[58:61]
	v_mfma_f32_16x16x32_bf16 v[58:61], v[102:105], v[188:191], v[74:77]
	v_mfma_f32_16x16x32_bf16 v[184:187], v[212:215], v[192:195], v[58:61]
	v_mfma_f32_16x16x32_bf16 v[58:61], v[114:117], v[188:191], v[82:85]
	v_mfma_f32_16x16x32_bf16 v[188:191], v[216:219], v[192:195], v[58:61]
	v_mfma_f32_16x16x32_bf16 v[58:61], v[102:105], v[196:199], v[86:89]
	v_mfma_f32_16x16x32_bf16 v[192:195], v[212:215], v[200:203], v[58:61]
	v_mfma_f32_16x16x32_bf16 v[58:61], v[114:117], v[196:199], v[90:93]
	v_mfma_f32_16x16x32_bf16 v[196:199], v[216:219], v[200:203], v[58:61]
	s_setprio 0
	s_nop 5
	v_add_u32_e32 v58, 0x18000, v152
	s_barrier
	ds_read_b128 v[66:69], v58
	ds_read_b128 v[70:73], v58 offset:256
	ds_read_b128 v[200:203], v58 offset:1024
	ds_read_b128 v[212:215], v58 offset:1280
	ds_read_b128 v[58:61], v169 offset:32768
	ds_read_b128 v[74:77], v169 offset:33792
	ds_read_b128 v[86:89], v169 offset:34816
	ds_read_b128 v[216:219], v169 offset:35840
	ds_read_b128 v[220:223], v169 offset:36864
	ds_read_b128 v[224:227], v169 offset:37888
	ds_read_b128 v[228:231], v169 offset:38912
	ds_read_b128 v[232:235], v169 offset:39936
	s_waitcnt vmcnt(2)
	s_barrier
; #define LDA(dst, b, h) _Pragma("unroll") for (int m = 0; m < 4; ++m) _Pragma("unroll") for (int k = 0; k < 2; ++k) \
;     dst[m][k] = *reinterpret_cast<const bf16x8*>((char*)SA(b, h) + aoff + m * 2048 + k * 1024)
; #define LDB(dst, b, h) _Pragma("unroll") for (int n = 0; n < 2; ++n) _Pragma("unroll") for (int k = 0; k < 2; ++k) \
;     dst[n][k] = *reinterpret_cast<const bf16x8*>((char*)SB(b, h) + boff + n * (SWAP ? 256 : 2048) + k * 1024)
; #define WAIT_V(n) asm volatile("s_waitcnt vmcnt(" #n ")" ::: "memory")
; #define WAIT_L(n) asm volatile("s_waitcnt lgkmcnt(" #n ")" ::: "memory")
; #define BAR __builtin_amdgcn_s_barrier()
; template <int EPI>
; DI void gemm_phase(const u16* __restrict__ A, int lda, const u16* __restrict__ Bt, int ldb,
;                    int M, int N, int K, const Epi& e, unsigned char* shmraw, int wv, int slot) {
;     ...
;     { LDB(B0, 1, 0); LDA(At, 1, 0); WAIT_V(2); BAR; WAIT_L(0); MMA(0, 0, At, B0); BAR;
;       LDB(B1, 1, 1); WAIT_V(0); BAR; WAIT_L(0); MMA(0, 1, At, B1); BAR;
;       LDA(At, 1, 1); BAR; WAIT_L(0); MMA(1, 0, At, B0); MMA(1, 1, At, B1); BAR; }
;     if (wr == 0) BAR;
	s_waitcnt lgkmcnt(0)
	s_setprio 1
	v_mfma_f32_16x16x32_bf16 v[82:85], v[66:69], v[58:61], v[126:129]
	v_mfma_f32_16x16x32_bf16 v[138:141], v[200:203], v[74:77], v[82:85]
	v_mfma_f32_16x16x32_bf16 v[82:85], v[70:73], v[58:61], v[122:125]
	v_mfma_f32_16x16x32_bf16 v[142:145], v[212:215], v[74:77], v[82:85]
	v_mfma_f32_16x16x32_bf16 v[82:85], v[66:69], v[86:89], v[118:121]
	v_mfma_f32_16x16x32_bf16 v[114:117], v[200:203], v[216:219], v[82:85]
	v_mfma_f32_16x16x32_bf16 v[82:85], v[70:73], v[86:89], v[204:207]
	v_mfma_f32_16x16x32_bf16 v[122:125], v[212:215], v[216:219], v[82:85]
	v_mfma_f32_16x16x32_bf16 v[82:85], v[66:69], v[220:223], v[110:113]
	v_mfma_f32_16x16x32_bf16 v[102:105], v[200:203], v[224:227], v[82:85]
	v_mfma_f32_16x16x32_bf16 v[82:85], v[70:73], v[220:223], v[106:109]
	v_mfma_f32_16x16x32_bf16 v[110:113], v[212:215], v[224:227], v[82:85]
	v_mfma_f32_16x16x32_bf16 v[82:85], v[66:69], v[228:231], v[208:211]
	v_mfma_f32_16x16x32_bf16 v[90:93], v[70:73], v[228:231], v[98:101]
	v_mfma_f32_16x16x32_bf16 v[82:85], v[200:203], v[232:235], v[82:85]
	v_mfma_f32_16x16x32_bf16 v[90:93], v[212:215], v[232:235], v[90:93]
	s_setprio 0
	v_add_u32_e32 v98, 0x1c000, v152
	s_barrier
	ds_read_b128 v[204:207], v98
	ds_read_b128 v[208:211], v98 offset:256
	ds_read_b128 v[236:239], v98 offset:1024
	ds_read_b128 v[240:243], v98 offset:1280
	s_waitcnt vmcnt(0)
	s_barrier
	s_waitcnt lgkmcnt(0)
	s_setprio 1
	v_mfma_f32_16x16x32_bf16 v[94:97], v[204:207], v[58:61], v[94:97]
	v_mfma_f32_16x16x32_bf16 v[58:61], v[208:211], v[58:61], v[78:81]
	v_mfma_f32_16x16x32_bf16 v[134:137], v[240:243], v[74:77], v[58:61]
	v_mfma_f32_16x16x32_bf16 v[58:61], v[204:207], v[86:89], v[62:65]
	v_mfma_f32_16x16x32_bf16 v[50:53], v[208:211], v[86:89], v[50:53]
	v_mfma_f32_16x16x32_bf16 v[46:49], v[204:207], v[220:223], v[46:49]
	v_mfma_f32_16x16x32_bf16 v[42:45], v[208:211], v[220:223], v[42:45]
	v_mfma_f32_16x16x32_bf16 v[38:41], v[204:207], v[228:231], v[38:41]
	v_mfma_f32_16x16x32_bf16 v[34:37], v[208:211], v[228:231], v[34:37]
	v_mfma_f32_16x16x32_bf16 v[130:133], v[236:239], v[74:77], v[94:97]
	v_mfma_f32_16x16x32_bf16 v[118:121], v[236:239], v[216:219], v[58:61]
	v_mfma_f32_16x16x32_bf16 v[126:129], v[240:243], v[216:219], v[50:53]
	v_mfma_f32_16x16x32_bf16 v[98:101], v[236:239], v[224:227], v[46:49]
	v_mfma_f32_16x16x32_bf16 v[106:109], v[240:243], v[224:227], v[42:45]
	v_mfma_f32_16x16x32_bf16 v[86:89], v[236:239], v[232:235], v[38:41]
	v_mfma_f32_16x16x32_bf16 v[94:97], v[240:243], v[232:235], v[34:37]
	s_setprio 0
	s_barrier
	s_nop 0
	ds_read_b128 v[34:37], v169 offset:49152
	ds_read_b128 v[38:41], v169 offset:50176
	ds_read_b128 v[42:45], v169 offset:51200
	ds_read_b128 v[46:49], v169 offset:52224
	ds_read_b128 v[216:219], v169 offset:53248
	ds_read_b128 v[220:223], v169 offset:54272
	ds_read_b128 v[224:227], v169 offset:55296
	ds_read_b128 v[228:231], v169 offset:56320
	s_barrier
	s_waitcnt lgkmcnt(0)
	s_setprio 1
	v_mfma_f32_16x16x32_bf16 v[30:33], v[66:69], v[34:37], v[30:33]
	v_mfma_f32_16x16x32_bf16 v[26:29], v[70:73], v[34:37], v[26:29]
	v_mfma_f32_16x16x32_bf16 v[22:25], v[66:69], v[42:45], v[22:25]
	v_mfma_f32_16x16x32_bf16 v[18:21], v[70:73], v[42:45], v[18:21]
	v_mfma_f32_16x16x32_bf16 v[14:17], v[66:69], v[216:219], v[14:17]
	v_mfma_f32_16x16x32_bf16 v[10:13], v[70:73], v[216:219], v[10:13]
	v_mfma_f32_16x16x32_bf16 v[6:9], v[66:69], v[224:227], v[6:9]
	v_mfma_f32_16x16x32_bf16 v[2:5], v[70:73], v[224:227], v[2:5]
	v_mfma_f32_16x16x32_bf16 v[74:77], v[200:203], v[38:41], v[30:33]
	v_mfma_f32_16x16x32_bf16 v[78:81], v[212:215], v[38:41], v[26:29]
	v_mfma_f32_16x16x32_bf16 v[58:61], v[200:203], v[46:49], v[22:25]
	v_mfma_f32_16x16x32_bf16 v[62:65], v[212:215], v[46:49], v[18:21]
	v_mfma_f32_16x16x32_bf16 v[26:29], v[200:203], v[220:223], v[14:17]
	v_mfma_f32_16x16x32_bf16 v[30:33], v[212:215], v[220:223], v[10:13]
	v_mfma_f32_16x16x32_bf16 v[10:13], v[200:203], v[228:231], v[6:9]
	v_mfma_f32_16x16x32_bf16 v[14:17], v[212:215], v[228:231], v[2:5]
	s_setprio 0
	s_setprio 1
	v_mfma_f32_16x16x32_bf16 v[2:5], v[204:207], v[34:37], v[54:57]
	v_mfma_f32_16x16x32_bf16 v[66:69], v[236:239], v[38:41], v[2:5]
	v_mfma_f32_16x16x32_bf16 v[2:5], v[208:211], v[34:37], v[148:151]
	v_mfma_f32_16x16x32_bf16 v[70:73], v[240:243], v[38:41], v[2:5]
	v_mfma_f32_16x16x32_bf16 v[2:5], v[204:207], v[42:45], v[176:179]
	v_mfma_f32_16x16x32_bf16 v[50:53], v[236:239], v[46:49], v[2:5]
	v_mfma_f32_16x16x32_bf16 v[2:5], v[208:211], v[42:45], v[180:183]
	v_mfma_f32_16x16x32_bf16 v[54:57], v[240:243], v[46:49], v[2:5]
	v_mfma_f32_16x16x32_bf16 v[2:5], v[204:207], v[216:219], v[184:187]
	v_mfma_f32_16x16x32_bf16 v[18:21], v[236:239], v[220:223], v[2:5]
	v_mfma_f32_16x16x32_bf16 v[2:5], v[208:211], v[216:219], v[188:191]
	v_mfma_f32_16x16x32_bf16 v[22:25], v[240:243], v[220:223], v[2:5]
	v_mfma_f32_16x16x32_bf16 v[2:5], v[204:207], v[224:227], v[192:195]
	v_mfma_f32_16x16x32_bf16 v[6:9], v[208:211], v[224:227], v[196:199]
	v_mfma_f32_16x16x32_bf16 v[2:5], v[236:239], v[228:231], v[2:5]
	v_mfma_f32_16x16x32_bf16 v[6:9], v[240:243], v[228:231], v[6:9]
	s_setprio 0
	s_barrier
	s_and_saveexec_b64 s[22:23], s[6:7]
	s_cbranch_execz .LBB0_336
	s_barrier

; #define STAGEA(P, br, kt) do { const char* _g = uptr(A + (size_t)(br) * lda + (size_t)(kt) * BK); \
;     _Pragma("unroll") for (int _i = 0; _i < 2; ++_i) { \
;       __builtin_amdgcn_global_load_lds((const unsigned*)(_g + offA[_i]), (unsigned*)((char*)(P) + tidx * 16 + _i * 8192), 16, 0, 0); } } while (0)
; #define STAGEB(P, br, kt) do { const char* _g = uptr(Bt + (size_t)(br) * ldb + (size_t)(kt) * BK); \
;     _Pragma("unroll") for (int _i = 0; _i < 2; ++_i) { \
;       __builtin_amdgcn_global_load_lds((const unsigned*)(_g + offB[_i]), (unsigned*)((char*)(P) + tidx * 16 + _i * 8192), 16, 0, 0); } } while (0)
; #define LDA(dst, b, h) _Pragma("unroll") for (int m = 0; m < 4; ++m) _Pragma("unroll") for (int k = 0; k < 2; ++k) \
;     dst[m][k] = *reinterpret_cast<const bf16x8*>((char*)SA(b, h) + aoff + m * 2048 + k * 1024)
; #define LDB(dst, b, h) _Pragma("unroll") for (int n = 0; n < 2; ++n) _Pragma("unroll") for (int k = 0; k < 2; ++k) \
;     dst[n][k] = *reinterpret_cast<const bf16x8*>((char*)SB(b, h) + boff + n * (SWAP ? 256 : 2048) + k * 1024)
; #define WAIT_V(n) asm volatile("s_waitcnt vmcnt(" #n ")" ::: "memory")
; #define WAIT_L(n) asm volatile("s_waitcnt lgkmcnt(" #n ")" ::: "memory")
; #define BAR __builtin_amdgcn_s_barrier()
; #define SCHED __builtin_amdgcn_sched_barrier(0)
; template <int EPI>
; DI void gemm_phase(const u16* __restrict__ A, int lda, const u16* __restrict__ Bt, int ldb,
;                    int M, int N, int K, const Epi& e, unsigned char* shmraw, int wv, int slot) {
;     ...
;       LDB(B0, 0, 0); SCHED; LDA(At, 0, 0); STAGEA(SA(1, 1), brow + HALF, t + 1);
;       WAIT_L(8); BAR; WAIT_L(0); MMA(0, 0, At, B0); BAR; SCHED;
;       LDB(B1, 0, 1); STAGEB(SB(0, 0), bcol, t + 2);
;       BAR; WAIT_L(0); MMA(0, 1, At, B1); BAR;
;       LDA(At, 0, 1); STAGEA(SA(0, 0), brow, t + 2);
;       BAR; WAIT_L(0); MMA(1, 0, At, B0); BAR; SCHED;
;       STAGEB(SB(0, 1), bcol + HALF, t + 2);
;       WAIT_V(6); BAR; MMA(1, 1, At, B1); BAR;
.LBB0_432:
	v_add_u32_e32 v0, s33, v168
	ds_read_b128 v[132:135], v0
	ds_read_b128 v[136:139], v0 offset:256
	ds_read_b128 v[140:143], v0 offset:1024
	ds_read_b128 v[150:153], v0 offset:1280
	s_add_u32 s37, s41, vcc_lo
	s_addc_u32 s42, s1, vcc_hi
	s_add_u32 s90, s37, 0x80
	v_add_u32_e32 v0, 0xc000, v171
	s_addc_u32 s91, s42, 0
	v_readfirstlane_b32 s37, v0
	v_lshl_add_u64 v[130:131], s[90:91], 0, v[148:149]
	s_mov_b32 m0, s37
	ds_read_b128 v[154:157], v196
	ds_read_b128 v[158:161], v196 offset:1024
	ds_read_b128 v[162:165], v196 offset:2048
	ds_read_b128 v[180:183], v196 offset:3072
	ds_read_b128 v[184:187], v196 offset:4096
	ds_read_b128 v[188:191], v196 offset:5120
	ds_read_b128 v[198:201], v196 offset:6144
	ds_read_b128 v[202:205], v196 offset:7168
	global_load_lds_dwordx4 v[130:131], off
	v_add_u32_e32 v130, 0xe000, v171
	v_lshl_add_u64 v[144:145], s[90:91], 0, v[146:147]
	v_readfirstlane_b32 s37, v130
	s_mov_b32 m0, s37
	s_nop 0
	global_load_lds_dwordx4 v[144:145], off
	s_waitcnt lgkmcnt(8)
	s_barrier
	s_waitcnt lgkmcnt(0)
	s_setprio 1
	v_mfma_f32_16x16x32_bf16 v[126:129], v[132:135], v[154:157], v[126:129]
	v_mfma_f32_16x16x32_bf16 v[122:125], v[136:139], v[154:157], v[122:125]
	v_mfma_f32_16x16x32_bf16 v[118:121], v[132:135], v[162:165], v[118:121]
	v_mfma_f32_16x16x32_bf16 v[114:117], v[136:139], v[162:165], v[114:117]
	v_mfma_f32_16x16x32_bf16 v[110:113], v[132:135], v[184:187], v[110:113]
	v_mfma_f32_16x16x32_bf16 v[106:109], v[136:139], v[184:187], v[106:109]
	v_mfma_f32_16x16x32_bf16 v[102:105], v[132:135], v[198:201], v[102:105]
	v_mfma_f32_16x16x32_bf16 v[98:101], v[136:139], v[198:201], v[98:101]
	v_mfma_f32_16x16x32_bf16 v[126:129], v[140:143], v[158:161], v[126:129]
	v_mfma_f32_16x16x32_bf16 v[122:125], v[150:153], v[158:161], v[122:125]
	v_mfma_f32_16x16x32_bf16 v[118:121], v[140:143], v[180:183], v[118:121]
	v_mfma_f32_16x16x32_bf16 v[114:117], v[150:153], v[180:183], v[114:117]
	v_mfma_f32_16x16x32_bf16 v[110:113], v[140:143], v[188:191], v[110:113]
	v_mfma_f32_16x16x32_bf16 v[106:109], v[150:153], v[188:191], v[106:109]
	v_mfma_f32_16x16x32_bf16 v[102:105], v[140:143], v[202:205], v[102:105]
	v_mfma_f32_16x16x32_bf16 v[98:101], v[150:153], v[202:205], v[98:101]
	s_setprio 0
	s_barrier
	s_add_u32 s37, s27, vcc_lo
	s_addc_u32 s42, s73, vcc_hi
	s_add_u32 s90, s37, 0x100
	s_addc_u32 s91, s42, 0
	v_readfirstlane_b32 s54, v169
	v_add_u32_e32 v131, s84, v168
	v_lshl_add_u64 v[144:145], s[90:91], 0, v[148:149]
	s_mov_b32 m0, s54
	v_readfirstlane_b32 s54, v170
	ds_read_b128 v[206:209], v131
	ds_read_b128 v[210:213], v131 offset:256
	ds_read_b128 v[214:217], v131 offset:1024
	ds_read_b128 v[218:221], v131 offset:1280
	global_load_lds_dwordx4 v[144:145], off
	v_lshl_add_u64 v[144:145], s[90:91], 0, v[146:147]
	s_mov_b32 m0, s54
	s_nop 0
	global_load_lds_dwordx4 v[144:145], off
	s_barrier
	s_waitcnt lgkmcnt(0)
	s_setprio 1
	v_mfma_f32_16x16x32_bf16 v[94:97], v[206:209], v[154:157], v[94:97]
	v_mfma_f32_16x16x32_bf16 v[78:81], v[210:213], v[154:157], v[78:81]
	v_mfma_f32_16x16x32_bf16 v[62:65], v[206:209], v[162:165], v[62:65]
	v_mfma_f32_16x16x32_bf16 v[50:53], v[210:213], v[162:165], v[50:53]
	v_mfma_f32_16x16x32_bf16 v[46:49], v[206:209], v[184:187], v[46:49]
	v_mfma_f32_16x16x32_bf16 v[42:45], v[210:213], v[184:187], v[42:45]
	v_mfma_f32_16x16x32_bf16 v[38:41], v[206:209], v[198:201], v[38:41]
	v_mfma_f32_16x16x32_bf16 v[34:37], v[210:213], v[198:201], v[34:37]
	v_mfma_f32_16x16x32_bf16 v[94:97], v[214:217], v[158:161], v[94:97]
	v_mfma_f32_16x16x32_bf16 v[78:81], v[218:221], v[158:161], v[78:81]
	v_mfma_f32_16x16x32_bf16 v[62:65], v[214:217], v[180:183], v[62:65]
	v_mfma_f32_16x16x32_bf16 v[50:53], v[218:221], v[180:183], v[50:53]
	v_mfma_f32_16x16x32_bf16 v[46:49], v[214:217], v[188:191], v[46:49]
	v_mfma_f32_16x16x32_bf16 v[42:45], v[218:221], v[188:191], v[42:45]
	v_mfma_f32_16x16x32_bf16 v[38:41], v[214:217], v[202:205], v[38:41]
	v_mfma_f32_16x16x32_bf16 v[34:37], v[218:221], v[202:205], v[34:37]
	s_setprio 0
	s_add_u32 s54, s29, vcc_lo
	s_addc_u32 s55, s74, vcc_hi
	s_add_u32 s90, s54, 0x100
	s_addc_u32 s91, s55, 0
	v_readfirstlane_b32 s75, v171
	v_lshl_add_u64 v[144:145], s[90:91], 0, v[148:149]
	s_mov_b32 m0, s75
	v_readfirstlane_b32 s75, v172
	s_barrier
	ds_read_b128 v[154:157], v196 offset:16384
	ds_read_b128 v[158:161], v196 offset:17408
	ds_read_b128 v[162:165], v196 offset:18432
	ds_read_b128 v[180:183], v196 offset:19456
	ds_read_b128 v[184:187], v196 offset:20480
	ds_read_b128 v[188:191], v196 offset:21504
	ds_read_b128 v[198:201], v196 offset:22528
	ds_read_b128 v[202:205], v196 offset:23552
	global_load_lds_dwordx4 v[144:145], off
	v_lshl_add_u64 v[144:145], s[90:91], 0, v[146:147]
	s_mov_b32 m0, s75
	s_nop 0
	global_load_lds_dwordx4 v[144:145], off
	s_barrier
	s_waitcnt lgkmcnt(0)
	s_setprio 1
	v_mfma_f32_16x16x32_bf16 v[30:33], v[132:135], v[154:157], v[30:33]
	v_mfma_f32_16x16x32_bf16 v[26:29], v[136:139], v[154:157], v[26:29]
	v_mfma_f32_16x16x32_bf16 v[22:25], v[132:135], v[162:165], v[22:25]
	v_mfma_f32_16x16x32_bf16 v[18:21], v[136:139], v[162:165], v[18:21]
	v_mfma_f32_16x16x32_bf16 v[14:17], v[132:135], v[184:187], v[14:17]
	v_mfma_f32_16x16x32_bf16 v[10:13], v[136:139], v[184:187], v[10:13]
	v_mfma_f32_16x16x32_bf16 v[6:9], v[132:135], v[198:201], v[6:9]
	v_mfma_f32_16x16x32_bf16 v[2:5], v[136:139], v[198:201], v[2:5]
	v_mfma_f32_16x16x32_bf16 v[30:33], v[140:143], v[158:161], v[30:33]
	v_mfma_f32_16x16x32_bf16 v[26:29], v[150:153], v[158:161], v[26:29]
	v_mfma_f32_16x16x32_bf16 v[22:25], v[140:143], v[180:183], v[22:25]
	v_mfma_f32_16x16x32_bf16 v[18:21], v[150:153], v[180:183], v[18:21]
	v_mfma_f32_16x16x32_bf16 v[14:17], v[140:143], v[188:191], v[14:17]
	v_mfma_f32_16x16x32_bf16 v[10:13], v[150:153], v[188:191], v[10:13]
	v_mfma_f32_16x16x32_bf16 v[6:9], v[140:143], v[202:205], v[6:9]
	v_mfma_f32_16x16x32_bf16 v[2:5], v[150:153], v[202:205], v[2:5]
	s_setprio 0
	s_barrier
; #define STAGEA(P, br, kt) do { const char* _g = uptr(A + (size_t)(br) * lda + (size_t)(kt) * BK); \
;     _Pragma("unroll") for (int _i = 0; _i < 2; ++_i) { \
;       __builtin_amdgcn_global_load_lds((const unsigned*)(_g + offA[_i]), (unsigned*)((char*)(P) + tidx * 16 + _i * 8192), 16, 0, 0); } } while (0)
; #define STAGEB(P, br, kt) do { const char* _g = uptr(Bt + (size_t)(br) * ldb + (size_t)(kt) * BK); \
;     _Pragma("unroll") for (int _i = 0; _i < 2; ++_i) { \
;       __builtin_amdgcn_global_load_lds((const unsigned*)(_g + offB[_i]), (unsigned*)((char*)(P) + tidx * 16 + _i * 8192), 16, 0, 0); } } while (0)
; #define LDA(dst, b, h) _Pragma("unroll") for (int m = 0; m < 4; ++m) _Pragma("unroll") for (int k = 0; k < 2; ++k) \
;     dst[m][k] = *reinterpret_cast<const bf16x8*>((char*)SA(b, h) + aoff + m * 2048 + k * 1024)
; #define LDB(dst, b, h) _Pragma("unroll") for (int n = 0; n < 2; ++n) _Pragma("unroll") for (int k = 0; k < 2; ++k) \
;     dst[n][k] = *reinterpret_cast<const bf16x8*>((char*)SB(b, h) + boff + n * (SWAP ? 256 : 2048) + k * 1024)
; #define WAIT_V(n) asm volatile("s_waitcnt vmcnt(" #n ")" ::: "memory")
; #define WAIT_L(n) asm volatile("s_waitcnt lgkmcnt(" #n ")" ::: "memory")
; #define BAR __builtin_amdgcn_s_barrier()
; #define SCHED __builtin_amdgcn_sched_barrier(0)
; template <int EPI>
; DI void gemm_phase(const u16* __restrict__ A, int lda, const u16* __restrict__ Bt, int ldb,
;                    int M, int N, int K, const Epi& e, unsigned char* shmraw, int wv, int slot) {
;     ...
;       STAGEB(SB(0, 1), bcol + HALF, t + 2);
;       WAIT_V(6); BAR; MMA(1, 1, At, B1); BAR;
;       LDB(B0, 1, 0); SCHED; LDA(At, 1, 0); STAGEA(SA(0, 1), brow + HALF, t + 2);
;       WAIT_L(8); BAR; WAIT_L(0); MMA(0, 0, At, B0); BAR; SCHED;
;       LDB(B1, 1, 1); STAGEB(SB(1, 0), bcol, t + 3);
;       BAR; WAIT_L(0); MMA(0, 1, At, B1); BAR;
	s_add_u32 s75, s35, vcc_lo
	s_addc_u32 s76, s38, vcc_hi
	s_add_u32 s90, s75, 0x100
	s_addc_u32 s91, s76, 0
	v_readfirstlane_b32 s89, v173
	v_lshl_add_u64 v[132:133], s[90:91], 0, v[148:149]
	s_mov_b32 m0, s89
	v_readfirstlane_b32 s89, v174
	global_load_lds_dwordx4 v[132:133], off
	v_lshl_add_u64 v[132:133], s[90:91], 0, v[146:147]
	s_mov_b32 m0, s89
	s_nop 0
	global_load_lds_dwordx4 v[132:133], off
	s_waitcnt vmcnt(6)
	s_barrier
	s_setprio 1
	v_mfma_f32_16x16x32_bf16 v[54:57], v[206:209], v[154:157], v[54:57]
	v_mfma_f32_16x16x32_bf16 v[58:61], v[210:213], v[154:157], v[58:61]
	v_mfma_f32_16x16x32_bf16 v[66:69], v[206:209], v[162:165], v[66:69]
	v_mfma_f32_16x16x32_bf16 v[70:73], v[210:213], v[162:165], v[70:73]
	v_mfma_f32_16x16x32_bf16 v[74:77], v[206:209], v[184:187], v[74:77]
	v_mfma_f32_16x16x32_bf16 v[82:85], v[210:213], v[184:187], v[82:85]
	v_mfma_f32_16x16x32_bf16 v[86:89], v[206:209], v[198:201], v[86:89]
	v_mfma_f32_16x16x32_bf16 v[90:93], v[210:213], v[198:201], v[90:93]
	v_mfma_f32_16x16x32_bf16 v[54:57], v[214:217], v[158:161], v[54:57]
	v_mfma_f32_16x16x32_bf16 v[58:61], v[218:221], v[158:161], v[58:61]
	v_mfma_f32_16x16x32_bf16 v[66:69], v[214:217], v[180:183], v[66:69]
	v_mfma_f32_16x16x32_bf16 v[70:73], v[218:221], v[180:183], v[70:73]
	v_mfma_f32_16x16x32_bf16 v[74:77], v[214:217], v[188:191], v[74:77]
	v_mfma_f32_16x16x32_bf16 v[82:85], v[218:221], v[188:191], v[82:85]
	v_mfma_f32_16x16x32_bf16 v[86:89], v[214:217], v[202:205], v[86:89]
	v_mfma_f32_16x16x32_bf16 v[90:93], v[218:221], v[202:205], v[90:93]
	s_setprio 0
	v_add_u32_e32 v131, s85, v168
	s_barrier
	ds_read_b128 v[132:135], v131
	ds_read_b128 v[136:139], v131 offset:256
	ds_read_b128 v[140:143], v131 offset:1024
	ds_read_b128 v[150:153], v131 offset:1280
	s_add_u32 s90, s39, vcc_lo
	s_addc_u32 s91, s40, vcc_hi
	v_readfirstlane_b32 s89, v175
	v_lshl_add_u64 v[144:145], s[90:91], 0, v[148:149]
	s_mov_b32 m0, s89
	v_readfirstlane_b32 s89, v176
	ds_read_b128 v[154:157], v196 offset:32768
	ds_read_b128 v[158:161], v196 offset:33792
	ds_read_b128 v[162:165], v196 offset:34816
	ds_read_b128 v[180:183], v196 offset:35840
	ds_read_b128 v[184:187], v196 offset:36864
	ds_read_b128 v[188:191], v196 offset:37888
	ds_read_b128 v[198:201], v196 offset:38912
	ds_read_b128 v[202:205], v196 offset:39936
	global_load_lds_dwordx4 v[144:145], off
	v_lshl_add_u64 v[144:145], s[90:91], 0, v[146:147]
	s_mov_b32 m0, s89
	s_nop 0
	global_load_lds_dwordx4 v[144:145], off
	s_waitcnt lgkmcnt(8)
	s_barrier
	s_waitcnt lgkmcnt(0)
	s_setprio 1
	v_mfma_f32_16x16x32_bf16 v[126:129], v[132:135], v[154:157], v[126:129]
	v_mfma_f32_16x16x32_bf16 v[122:125], v[136:139], v[154:157], v[122:125]
	v_mfma_f32_16x16x32_bf16 v[118:121], v[132:135], v[162:165], v[118:121]
	v_mfma_f32_16x16x32_bf16 v[114:117], v[136:139], v[162:165], v[114:117]
	v_mfma_f32_16x16x32_bf16 v[110:113], v[132:135], v[184:187], v[110:113]
	v_mfma_f32_16x16x32_bf16 v[106:109], v[136:139], v[184:187], v[106:109]
	v_mfma_f32_16x16x32_bf16 v[102:105], v[132:135], v[198:201], v[102:105]
	v_mfma_f32_16x16x32_bf16 v[98:101], v[136:139], v[198:201], v[98:101]
	v_mfma_f32_16x16x32_bf16 v[126:129], v[140:143], v[158:161], v[126:129]
	v_mfma_f32_16x16x32_bf16 v[122:125], v[150:153], v[158:161], v[122:125]
	v_mfma_f32_16x16x32_bf16 v[118:121], v[140:143], v[180:183], v[118:121]
	v_mfma_f32_16x16x32_bf16 v[114:117], v[150:153], v[180:183], v[114:117]
	v_mfma_f32_16x16x32_bf16 v[110:113], v[140:143], v[188:191], v[110:113]
	v_mfma_f32_16x16x32_bf16 v[106:109], v[150:153], v[188:191], v[106:109]
	v_mfma_f32_16x16x32_bf16 v[102:105], v[140:143], v[202:205], v[102:105]
	v_mfma_f32_16x16x32_bf16 v[98:101], v[150:153], v[202:205], v[98:101]
	s_setprio 0
	s_barrier
	s_add_u32 s90, s37, 0x180
	s_addc_u32 s91, s42, 0
	v_readfirstlane_b32 s37, v177
	v_add_u32_e32 v131, s86, v168
	v_lshl_add_u64 v[144:145], s[90:91], 0, v[148:149]
	s_mov_b32 m0, s37
	v_readfirstlane_b32 s37, v178
	ds_read_b128 v[206:209], v131
	ds_read_b128 v[210:213], v131 offset:256
	ds_read_b128 v[214:217], v131 offset:1024
	ds_read_b128 v[218:221], v131 offset:1280
	global_load_lds_dwordx4 v[144:145], off
	v_lshl_add_u64 v[144:145], s[90:91], 0, v[146:147]
	s_mov_b32 m0, s37
	s_nop 0
	global_load_lds_dwordx4 v[144:145], off
	s_barrier
	s_waitcnt lgkmcnt(0)
	s_setprio 1
	v_mfma_f32_16x16x32_bf16 v[94:97], v[206:209], v[154:157], v[94:97]
	v_mfma_f32_16x16x32_bf16 v[78:81], v[210:213], v[154:157], v[78:81]
	v_mfma_f32_16x16x32_bf16 v[62:65], v[206:209], v[162:165], v[62:65]
	v_mfma_f32_16x16x32_bf16 v[50:53], v[210:213], v[162:165], v[50:53]
	v_mfma_f32_16x16x32_bf16 v[46:49], v[206:209], v[184:187], v[46:49]
	v_mfma_f32_16x16x32_bf16 v[42:45], v[210:213], v[184:187], v[42:45]
	v_mfma_f32_16x16x32_bf16 v[38:41], v[206:209], v[198:201], v[38:41]
	v_mfma_f32_16x16x32_bf16 v[34:37], v[210:213], v[198:201], v[34:37]
	v_mfma_f32_16x16x32_bf16 v[94:97], v[214:217], v[158:161], v[94:97]
	v_mfma_f32_16x16x32_bf16 v[78:81], v[218:221], v[158:161], v[78:81]
	v_mfma_f32_16x16x32_bf16 v[62:65], v[214:217], v[180:183], v[62:65]
	v_mfma_f32_16x16x32_bf16 v[50:53], v[218:221], v[180:183], v[50:53]
	v_mfma_f32_16x16x32_bf16 v[46:49], v[214:217], v[188:191], v[46:49]
	v_mfma_f32_16x16x32_bf16 v[42:45], v[218:221], v[188:191], v[42:45]
	v_mfma_f32_16x16x32_bf16 v[38:41], v[214:217], v[202:205], v[38:41]
	v_mfma_f32_16x16x32_bf16 v[34:37], v[218:221], v[202:205], v[34:37]
	s_setprio 0
	s_add_u32 s90, s54, 0x180
	s_addc_u32 s91, s55, 0
	v_readfirstlane_b32 s37, v179
	v_lshl_add_u64 v[144:145], s[90:91], 0, v[148:149]
	s_mov_b32 m0, s37
	v_readfirstlane_b32 s37, v193
	s_barrier
; #define STAGEA(P, br, kt) do { const char* _g = uptr(A + (size_t)(br) * lda + (size_t)(kt) * BK); \
;     _Pragma("unroll") for (int _i = 0; _i < 2; ++_i) { \
;       __builtin_amdgcn_global_load_lds((const unsigned*)(_g + offA[_i]), (unsigned*)((char*)(P) + tidx * 16 + _i * 8192), 16, 0, 0); } } while (0)
; #define STAGEB(P, br, kt) do { const char* _g = uptr(Bt + (size_t)(br) * ldb + (size_t)(kt) * BK); \
;     _Pragma("unroll") for (int _i = 0; _i < 2; ++_i) { \
;       __builtin_amdgcn_global_load_lds((const unsigned*)(_g + offB[_i]), (unsigned*)((char*)(P) + tidx * 16 + _i * 8192), 16, 0, 0); } } while (0)
; #define LDA(dst, b, h) _Pragma("unroll") for (int m = 0; m < 4; ++m) _Pragma("unroll") for (int k = 0; k < 2; ++k) \
;     dst[m][k] = *reinterpret_cast<const bf16x8*>((char*)SA(b, h) + aoff + m * 2048 + k * 1024)
; #define LDB(dst, b, h) _Pragma("unroll") for (int n = 0; n < 2; ++n) _Pragma("unroll") for (int k = 0; k < 2; ++k) \
;     dst[n][k] = *reinterpret_cast<const bf16x8*>((char*)SB(b, h) + boff + n * (SWAP ? 256 : 2048) + k * 1024)
; #define WAIT_V(n) asm volatile("s_waitcnt vmcnt(" #n ")" ::: "memory")
; #define WAIT_L(n) asm volatile("s_waitcnt lgkmcnt(" #n ")" ::: "memory")
; #define BAR __builtin_amdgcn_s_barrier()
; #define SCHED __builtin_amdgcn_sched_barrier(0)
; template <int EPI>
; DI void gemm_phase(const u16* __restrict__ A, int lda, const u16* __restrict__ Bt, int ldb,
;                    int M, int N, int K, const Epi& e, unsigned char* shmraw, int wv, int slot) {
;     ...
;       LDA(At, 1, 1); STAGEA(SA(1, 0), brow, t + 3);
;       BAR; WAIT_L(0); MMA(1, 0, At, B0); BAR; SCHED;
;       STAGEB(SB(1, 1), bcol + HALF, t + 3);
;       WAIT_V(6); BAR; MMA(1, 1, At, B1); BAR;
;     }
;     { LDB(B0, 0, 0); LDA(At, 0, 0); STAGEA(SA(1, 1), brow + HALF, nt - 1);
;       BAR; WAIT_L(0); MMA(0, 0, At, B0); BAR;
;       LDB(B1, 0, 1); BAR; WAIT_L(0); MMA(0, 1, At, B1); BAR;
	ds_read_b128 v[154:157], v196 offset:49152
	ds_read_b128 v[158:161], v196 offset:50176
	ds_read_b128 v[162:165], v196 offset:51200
	ds_read_b128 v[180:183], v196 offset:52224
	ds_read_b128 v[184:187], v196 offset:53248
	ds_read_b128 v[188:191], v196 offset:54272
	ds_read_b128 v[198:201], v196 offset:55296
	ds_read_b128 v[202:205], v196 offset:56320
	global_load_lds_dwordx4 v[144:145], off
	v_lshl_add_u64 v[144:145], s[90:91], 0, v[146:147]
	s_mov_b32 m0, s37
	s_nop 0
	global_load_lds_dwordx4 v[144:145], off
	s_barrier
	s_waitcnt lgkmcnt(0)
	s_setprio 1
	v_mfma_f32_16x16x32_bf16 v[30:33], v[132:135], v[154:157], v[30:33]
	v_mfma_f32_16x16x32_bf16 v[26:29], v[136:139], v[154:157], v[26:29]
	v_mfma_f32_16x16x32_bf16 v[22:25], v[132:135], v[162:165], v[22:25]
	v_mfma_f32_16x16x32_bf16 v[18:21], v[136:139], v[162:165], v[18:21]
	v_mfma_f32_16x16x32_bf16 v[14:17], v[132:135], v[184:187], v[14:17]
	v_mfma_f32_16x16x32_bf16 v[10:13], v[136:139], v[184:187], v[10:13]
	v_mfma_f32_16x16x32_bf16 v[6:9], v[132:135], v[198:201], v[6:9]
	v_mfma_f32_16x16x32_bf16 v[2:5], v[136:139], v[198:201], v[2:5]
	v_mfma_f32_16x16x32_bf16 v[30:33], v[140:143], v[158:161], v[30:33]
	v_mfma_f32_16x16x32_bf16 v[26:29], v[150:153], v[158:161], v[26:29]
	v_mfma_f32_16x16x32_bf16 v[22:25], v[140:143], v[180:183], v[22:25]
	v_mfma_f32_16x16x32_bf16 v[18:21], v[150:153], v[180:183], v[18:21]
	v_mfma_f32_16x16x32_bf16 v[14:17], v[140:143], v[188:191], v[14:17]
	v_mfma_f32_16x16x32_bf16 v[10:13], v[150:153], v[188:191], v[10:13]
	v_mfma_f32_16x16x32_bf16 v[6:9], v[140:143], v[202:205], v[6:9]
	v_mfma_f32_16x16x32_bf16 v[2:5], v[150:153], v[202:205], v[2:5]
	s_setprio 0
	s_barrier
	s_add_u32 s90, s75, 0x180
	s_addc_u32 s91, s76, 0
	v_readfirstlane_b32 s37, v194
	v_lshl_add_u64 v[132:133], s[90:91], 0, v[148:149]
	s_mov_b32 m0, s37
	v_readfirstlane_b32 s37, v195
	global_load_lds_dwordx4 v[132:133], off
	v_lshl_add_u64 v[132:133], s[90:91], 0, v[146:147]
	s_mov_b32 m0, s37
	s_nop 0
	global_load_lds_dwordx4 v[132:133], off
	s_waitcnt vmcnt(6)
	s_barrier
	s_setprio 1
	v_mfma_f32_16x16x32_bf16 v[54:57], v[206:209], v[154:157], v[54:57]
	v_mfma_f32_16x16x32_bf16 v[58:61], v[210:213], v[154:157], v[58:61]
	v_mfma_f32_16x16x32_bf16 v[66:69], v[206:209], v[162:165], v[66:69]
	v_mfma_f32_16x16x32_bf16 v[70:73], v[210:213], v[162:165], v[70:73]
	v_mfma_f32_16x16x32_bf16 v[74:77], v[206:209], v[184:187], v[74:77]
	v_mfma_f32_16x16x32_bf16 v[82:85], v[210:213], v[184:187], v[82:85]
	v_mfma_f32_16x16x32_bf16 v[86:89], v[206:209], v[198:201], v[86:89]
	v_mfma_f32_16x16x32_bf16 v[90:93], v[210:213], v[198:201], v[90:93]
	v_mfma_f32_16x16x32_bf16 v[54:57], v[214:217], v[158:161], v[54:57]
	v_mfma_f32_16x16x32_bf16 v[58:61], v[218:221], v[158:161], v[58:61]
	v_mfma_f32_16x16x32_bf16 v[66:69], v[214:217], v[180:183], v[66:69]
	v_mfma_f32_16x16x32_bf16 v[70:73], v[218:221], v[180:183], v[70:73]
	v_mfma_f32_16x16x32_bf16 v[74:77], v[214:217], v[188:191], v[74:77]
	v_mfma_f32_16x16x32_bf16 v[82:85], v[218:221], v[188:191], v[82:85]
	v_mfma_f32_16x16x32_bf16 v[86:89], v[214:217], v[202:205], v[86:89]
	v_mfma_f32_16x16x32_bf16 v[90:93], v[218:221], v[202:205], v[90:93]
	s_setprio 0
	s_add_i32 s36, s36, 2
	s_add_u32 vcc_lo, vcc_lo, 0x100
	s_addc_u32 vcc_hi, vcc_hi, 0
	s_cmp_lt_u32 s36, 12
	s_barrier
	s_cbranch_scc1 .LBB0_432
	s_add_u32 s38, s9, 0x780
	v_add_u32_e32 v166, 16, v168
	s_addc_u32 s39, s13, 0
	v_readfirstlane_b32 s1, v0
	v_add_u32_e32 v131, 0x10000, v166
	v_lshl_add_u64 v[144:145], s[38:39], 0, v[148:149]
	s_mov_b32 m0, s1
	v_readfirstlane_b32 s1, v130
	ds_read_b128 v[132:135], v131
	ds_read_b128 v[136:139], v131 offset:256
	ds_read_b128 v[140:143], v131 offset:1024
	ds_read_b128 v[150:153], v131 offset:1280
	ds_read_b128 v[154:157], v196
	ds_read_b128 v[158:161], v196 offset:1024
	ds_read_b128 v[162:165], v196 offset:2048
	ds_read_b128 v[180:183], v196 offset:3072
	ds_read_b128 v[184:187], v196 offset:4096
	ds_read_b128 v[188:191], v196 offset:5120
	ds_read_b128 v[198:201], v196 offset:6144
	ds_read_b128 v[202:205], v196 offset:7168
	global_load_lds_dwordx4 v[144:145], off
	v_lshl_add_u64 v[144:145], s[38:39], 0, v[146:147]
	s_mov_b32 m0, s1
	s_nop 0
	global_load_lds_dwordx4 v[144:145], off
	s_barrier
	s_waitcnt lgkmcnt(0)
	s_setprio 1
	v_mfma_f32_16x16x32_bf16 v[126:129], v[132:135], v[154:157], v[126:129]
	v_mfma_f32_16x16x32_bf16 v[118:121], v[132:135], v[162:165], v[118:121]
	v_mfma_f32_16x16x32_bf16 v[114:117], v[136:139], v[162:165], v[114:117]
	v_mfma_f32_16x16x32_bf16 v[106:109], v[136:139], v[184:187], v[106:109]
	v_mfma_f32_16x16x32_bf16 v[98:101], v[136:139], v[198:201], v[98:101]
	v_mfma_f32_16x16x32_bf16 v[126:129], v[140:143], v[158:161], v[126:129]
	v_mfma_f32_16x16x32_bf16 v[122:125], v[136:139], v[154:157], v[122:125]
	v_mfma_f32_16x16x32_bf16 v[118:121], v[140:143], v[180:183], v[118:121]
	v_mfma_f32_16x16x32_bf16 v[114:117], v[150:153], v[180:183], v[114:117]
	v_mfma_f32_16x16x32_bf16 v[110:113], v[132:135], v[184:187], v[110:113]
	v_mfma_f32_16x16x32_bf16 v[106:109], v[150:153], v[188:191], v[106:109]
	v_mfma_f32_16x16x32_bf16 v[102:105], v[132:135], v[198:201], v[102:105]
	v_mfma_f32_16x16x32_bf16 v[98:101], v[150:153], v[202:205], v[98:101]
	v_mfma_f32_16x16x32_bf16 v[206:209], v[150:153], v[158:161], v[122:125]
	v_mfma_f32_16x16x32_bf16 v[210:213], v[140:143], v[188:191], v[110:113]
	v_mfma_f32_16x16x32_bf16 v[214:217], v[140:143], v[202:205], v[102:105]
	s_setprio 0
	v_add_u32_e32 v0, 0x14000, v166
	s_barrier
	s_nop 0
	ds_read_b128 v[102:105], v0
	ds_read_b128 v[110:113], v0 offset:256
	ds_read_b128 v[122:125], v0 offset:1024
	ds_read_b128 v[218:221], v0 offset:1280
	s_barrier
; #define LDA(dst, b, h) _Pragma("unroll") for (int m = 0; m < 4; ++m) _Pragma("unroll") for (int k = 0; k < 2; ++k) \
;     dst[m][k] = *reinterpret_cast<const bf16x8*>((char*)SA(b, h) + aoff + m * 2048 + k * 1024)
; #define LDB(dst, b, h) _Pragma("unroll") for (int n = 0; n < 2; ++n) _Pragma("unroll") for (int k = 0; k < 2; ++k) \
;     dst[n][k] = *reinterpret_cast<const bf16x8*>((char*)SB(b, h) + boff + n * (SWAP ? 256 : 2048) + k * 1024)
; #define WAIT_V(n) asm volatile("s_waitcnt vmcnt(" #n ")" ::: "memory")
; #define WAIT_L(n) asm volatile("s_waitcnt lgkmcnt(" #n ")" ::: "memory")
; #define BAR __builtin_amdgcn_s_barrier()
; template <int EPI>
; DI void gemm_phase(const u16* __restrict__ A, int lda, const u16* __restrict__ Bt, int ldb,
;                    int M, int N, int K, const Epi& e, unsigned char* shmraw, int wv, int slot) {
;     ...
;       LDB(B1, 0, 1); BAR; WAIT_L(0); MMA(0, 1, At, B1); BAR;
;       LDA(At, 0, 1); WAIT_V(4); BAR; WAIT_L(0); MMA(1, 0, At, B0); MMA(1, 1, At, B1); BAR; }
;     { LDB(B0, 1, 0); LDA(At, 1, 0); WAIT_V(2); BAR; WAIT_L(0); MMA(0, 0, At, B0); BAR;
	s_waitcnt lgkmcnt(0)
	s_setprio 1
	v_mfma_f32_16x16x32_bf16 v[62:65], v[102:105], v[162:165], v[62:65]
	v_mfma_f32_16x16x32_bf16 v[50:53], v[110:113], v[162:165], v[50:53]
	v_mfma_f32_16x16x32_bf16 v[46:49], v[102:105], v[184:187], v[46:49]
	v_mfma_f32_16x16x32_bf16 v[42:45], v[110:113], v[184:187], v[42:45]
	v_mfma_f32_16x16x32_bf16 v[38:41], v[102:105], v[198:201], v[38:41]
	v_mfma_f32_16x16x32_bf16 v[34:37], v[110:113], v[198:201], v[34:37]
	v_mfma_f32_16x16x32_bf16 v[94:97], v[102:105], v[154:157], v[94:97]
	v_mfma_f32_16x16x32_bf16 v[78:81], v[110:113], v[154:157], v[78:81]
	v_mfma_f32_16x16x32_bf16 v[62:65], v[122:125], v[180:183], v[62:65]
	v_mfma_f32_16x16x32_bf16 v[50:53], v[218:221], v[180:183], v[50:53]
	v_mfma_f32_16x16x32_bf16 v[46:49], v[122:125], v[188:191], v[46:49]
	v_mfma_f32_16x16x32_bf16 v[42:45], v[218:221], v[188:191], v[42:45]
	v_mfma_f32_16x16x32_bf16 v[38:41], v[122:125], v[202:205], v[38:41]
	v_mfma_f32_16x16x32_bf16 v[34:37], v[218:221], v[202:205], v[34:37]
	v_mfma_f32_16x16x32_bf16 v[222:225], v[122:125], v[158:161], v[94:97]
	v_mfma_f32_16x16x32_bf16 v[154:157], v[218:221], v[158:161], v[78:81]
	s_setprio 0
	s_barrier
	s_nop 0
	ds_read_b128 v[78:81], v196 offset:16384
	ds_read_b128 v[94:97], v196 offset:17408
	ds_read_b128 v[158:161], v196 offset:18432
	ds_read_b128 v[162:165], v196 offset:19456
	ds_read_b128 v[180:183], v196 offset:20480
	ds_read_b128 v[184:187], v196 offset:21504
	ds_read_b128 v[188:191], v196 offset:22528
	ds_read_b128 v[198:201], v196 offset:23552
	s_waitcnt vmcnt(4)
	s_barrier
	s_waitcnt lgkmcnt(0)
	s_setprio 1
	v_mfma_f32_16x16x32_bf16 v[30:33], v[132:135], v[78:81], v[30:33]
	v_mfma_f32_16x16x32_bf16 v[26:29], v[136:139], v[78:81], v[26:29]
	v_mfma_f32_16x16x32_bf16 v[22:25], v[132:135], v[158:161], v[22:25]
	v_mfma_f32_16x16x32_bf16 v[18:21], v[136:139], v[158:161], v[18:21]
	v_mfma_f32_16x16x32_bf16 v[14:17], v[132:135], v[180:183], v[14:17]
	v_mfma_f32_16x16x32_bf16 v[10:13], v[136:139], v[180:183], v[10:13]
	v_mfma_f32_16x16x32_bf16 v[6:9], v[132:135], v[188:191], v[6:9]
	v_mfma_f32_16x16x32_bf16 v[2:5], v[136:139], v[188:191], v[2:5]
	v_mfma_f32_16x16x32_bf16 v[30:33], v[140:143], v[94:97], v[30:33]
	v_mfma_f32_16x16x32_bf16 v[26:29], v[150:153], v[94:97], v[26:29]
	v_mfma_f32_16x16x32_bf16 v[22:25], v[140:143], v[162:165], v[22:25]
	v_mfma_f32_16x16x32_bf16 v[18:21], v[150:153], v[162:165], v[18:21]
	v_mfma_f32_16x16x32_bf16 v[14:17], v[140:143], v[184:187], v[14:17]
	v_mfma_f32_16x16x32_bf16 v[10:13], v[150:153], v[184:187], v[10:13]
	v_mfma_f32_16x16x32_bf16 v[6:9], v[140:143], v[198:201], v[6:9]
	v_mfma_f32_16x16x32_bf16 v[2:5], v[150:153], v[198:201], v[2:5]
	s_setprio 0
	s_setprio 1
	v_mfma_f32_16x16x32_bf16 v[58:61], v[110:113], v[78:81], v[58:61]
	v_mfma_f32_16x16x32_bf16 v[130:133], v[218:221], v[94:97], v[58:61]
	v_mfma_f32_16x16x32_bf16 v[58:61], v[102:105], v[158:161], v[66:69]
	v_mfma_f32_16x16x32_bf16 v[134:137], v[122:125], v[162:165], v[58:61]
	v_mfma_f32_16x16x32_bf16 v[58:61], v[110:113], v[158:161], v[70:73]
	v_mfma_f32_16x16x32_bf16 v[138:141], v[218:221], v[162:165], v[58:61]
	v_mfma_f32_16x16x32_bf16 v[58:61], v[102:105], v[180:183], v[74:77]
	v_mfma_f32_16x16x32_bf16 v[142:145], v[122:125], v[184:187], v[58:61]
	v_mfma_f32_16x16x32_bf16 v[58:61], v[110:113], v[180:183], v[82:85]
	v_mfma_f32_16x16x32_bf16 v[54:57], v[102:105], v[78:81], v[54:57]
	v_mfma_f32_16x16x32_bf16 v[150:153], v[218:221], v[184:187], v[58:61]
	v_mfma_f32_16x16x32_bf16 v[58:61], v[102:105], v[188:191], v[86:89]
	v_mfma_f32_16x16x32_bf16 v[54:57], v[122:125], v[94:97], v[54:57]
	v_mfma_f32_16x16x32_bf16 v[158:161], v[122:125], v[198:201], v[58:61]
	v_mfma_f32_16x16x32_bf16 v[58:61], v[110:113], v[188:191], v[90:93]
	v_mfma_f32_16x16x32_bf16 v[162:165], v[218:221], v[198:201], v[58:61]
	s_setprio 0
	v_add_u32_e32 v0, 0x18000, v166
	s_barrier
	ds_read_b128 v[180:183], v0
	ds_read_b128 v[184:187], v0 offset:256
	ds_read_b128 v[188:191], v0 offset:1024
	ds_read_b128 v[198:201], v0 offset:1280
	ds_read_b128 v[58:61], v196 offset:32768
	ds_read_b128 v[66:69], v196 offset:33792
	ds_read_b128 v[74:77], v196 offset:34816
	ds_read_b128 v[82:85], v196 offset:35840
	ds_read_b128 v[86:89], v196 offset:36864
	ds_read_b128 v[202:205], v196 offset:37888
	ds_read_b128 v[218:221], v196 offset:38912
	ds_read_b128 v[226:229], v196 offset:39936
	s_waitcnt vmcnt(2)
	s_barrier
; #define LDA(dst, b, h) _Pragma("unroll") for (int m = 0; m < 4; ++m) _Pragma("unroll") for (int k = 0; k < 2; ++k) \
;     dst[m][k] = *reinterpret_cast<const bf16x8*>((char*)SA(b, h) + aoff + m * 2048 + k * 1024)
; #define LDB(dst, b, h) _Pragma("unroll") for (int n = 0; n < 2; ++n) _Pragma("unroll") for (int k = 0; k < 2; ++k) \
;     dst[n][k] = *reinterpret_cast<const bf16x8*>((char*)SB(b, h) + boff + n * (SWAP ? 256 : 2048) + k * 1024)
; #define WAIT_V(n) asm volatile("s_waitcnt vmcnt(" #n ")" ::: "memory")
; #define WAIT_L(n) asm volatile("s_waitcnt lgkmcnt(" #n ")" ::: "memory")
; #define BAR __builtin_amdgcn_s_barrier()
; template <int EPI>
; DI void gemm_phase(const u16* __restrict__ A, int lda, const u16* __restrict__ Bt, int ldb,
;                    int M, int N, int K, const Epi& e, unsigned char* shmraw, int wv, int slot) {
;     ...
;     { LDB(B0, 1, 0); LDA(At, 1, 0); WAIT_V(2); BAR; WAIT_L(0); MMA(0, 0, At, B0); BAR;
;       LDB(B1, 1, 1); WAIT_V(0); BAR; WAIT_L(0); MMA(0, 1, At, B1); BAR;
;       LDA(At, 1, 1); BAR; WAIT_L(0); MMA(1, 0, At, B0); MMA(1, 1, At, B1); BAR; }
;     if (wr == 0) BAR;
	s_waitcnt lgkmcnt(0)
	s_setprio 1
	v_mfma_f32_16x16x32_bf16 v[70:73], v[180:183], v[58:61], v[126:129]
	v_mfma_f32_16x16x32_bf16 v[122:125], v[188:191], v[66:69], v[70:73]
	v_mfma_f32_16x16x32_bf16 v[70:73], v[184:187], v[58:61], v[206:209]
	v_mfma_f32_16x16x32_bf16 v[126:129], v[198:201], v[66:69], v[70:73]
	v_mfma_f32_16x16x32_bf16 v[70:73], v[180:183], v[74:77], v[118:121]
	v_mfma_f32_16x16x32_bf16 v[102:105], v[188:191], v[82:85], v[70:73]
	v_mfma_f32_16x16x32_bf16 v[70:73], v[184:187], v[74:77], v[114:117]
	v_mfma_f32_16x16x32_bf16 v[110:113], v[198:201], v[82:85], v[70:73]
	v_mfma_f32_16x16x32_bf16 v[70:73], v[180:183], v[86:89], v[210:213]
	v_mfma_f32_16x16x32_bf16 v[90:93], v[188:191], v[202:205], v[70:73]
	v_mfma_f32_16x16x32_bf16 v[70:73], v[184:187], v[86:89], v[106:109]
	v_mfma_f32_16x16x32_bf16 v[94:97], v[198:201], v[202:205], v[70:73]
	v_mfma_f32_16x16x32_bf16 v[70:73], v[180:183], v[218:221], v[214:217]
	v_mfma_f32_16x16x32_bf16 v[78:81], v[184:187], v[218:221], v[98:101]
	v_mfma_f32_16x16x32_bf16 v[70:73], v[188:191], v[226:229], v[70:73]
	v_mfma_f32_16x16x32_bf16 v[78:81], v[198:201], v[226:229], v[78:81]
	s_setprio 0
	v_add_u32_e32 v0, 0x1c000, v166
	s_barrier
	ds_read_b128 v[206:209], v0
	ds_read_b128 v[210:213], v0 offset:256
	ds_read_b128 v[214:217], v0 offset:1024
	ds_read_b128 v[230:233], v0 offset:1280
	s_waitcnt vmcnt(0)
	s_barrier
	s_waitcnt lgkmcnt(0)
	s_setprio 1
	v_mfma_f32_16x16x32_bf16 v[98:101], v[206:209], v[58:61], v[222:225]
	v_mfma_f32_16x16x32_bf16 v[58:61], v[210:213], v[58:61], v[154:157]
	v_mfma_f32_16x16x32_bf16 v[118:121], v[230:233], v[66:69], v[58:61]
	v_mfma_f32_16x16x32_bf16 v[58:61], v[206:209], v[74:77], v[62:65]
	v_mfma_f32_16x16x32_bf16 v[50:53], v[210:213], v[74:77], v[50:53]
	v_mfma_f32_16x16x32_bf16 v[46:49], v[206:209], v[86:89], v[46:49]
	v_mfma_f32_16x16x32_bf16 v[42:45], v[210:213], v[86:89], v[42:45]
	v_mfma_f32_16x16x32_bf16 v[38:41], v[206:209], v[218:221], v[38:41]
	v_mfma_f32_16x16x32_bf16 v[34:37], v[210:213], v[218:221], v[34:37]
	v_mfma_f32_16x16x32_bf16 v[114:117], v[214:217], v[66:69], v[98:101]
	v_mfma_f32_16x16x32_bf16 v[98:101], v[214:217], v[82:85], v[58:61]
	v_mfma_f32_16x16x32_bf16 v[106:109], v[230:233], v[82:85], v[50:53]
	v_mfma_f32_16x16x32_bf16 v[82:85], v[214:217], v[202:205], v[46:49]
	v_mfma_f32_16x16x32_bf16 v[86:89], v[230:233], v[202:205], v[42:45]
	v_mfma_f32_16x16x32_bf16 v[66:69], v[214:217], v[226:229], v[38:41]
	v_mfma_f32_16x16x32_bf16 v[74:77], v[230:233], v[226:229], v[34:37]
	s_setprio 0
	s_barrier
	s_nop 0
	ds_read_b128 v[34:37], v196 offset:49152
	ds_read_b128 v[38:41], v196 offset:50176
	ds_read_b128 v[154:157], v196 offset:51200
	ds_read_b128 v[202:205], v196 offset:52224
	ds_read_b128 v[218:221], v196 offset:53248
	ds_read_b128 v[222:225], v196 offset:54272
	ds_read_b128 v[226:229], v196 offset:55296
	ds_read_b128 v[234:237], v196 offset:56320
	s_barrier
	s_waitcnt lgkmcnt(0)
	s_setprio 1
	v_mfma_f32_16x16x32_bf16 v[30:33], v[180:183], v[34:37], v[30:33]
	v_mfma_f32_16x16x32_bf16 v[26:29], v[184:187], v[34:37], v[26:29]
	v_mfma_f32_16x16x32_bf16 v[22:25], v[180:183], v[154:157], v[22:25]
	v_mfma_f32_16x16x32_bf16 v[18:21], v[184:187], v[154:157], v[18:21]
	v_mfma_f32_16x16x32_bf16 v[14:17], v[180:183], v[218:221], v[14:17]
	v_mfma_f32_16x16x32_bf16 v[10:13], v[184:187], v[218:221], v[10:13]
	v_mfma_f32_16x16x32_bf16 v[6:9], v[180:183], v[226:229], v[6:9]
	v_mfma_f32_16x16x32_bf16 v[2:5], v[184:187], v[226:229], v[2:5]
	v_mfma_f32_16x16x32_bf16 v[58:61], v[188:191], v[38:41], v[30:33]
	v_mfma_f32_16x16x32_bf16 v[62:65], v[198:201], v[38:41], v[26:29]
	v_mfma_f32_16x16x32_bf16 v[42:45], v[188:191], v[202:205], v[22:25]
	v_mfma_f32_16x16x32_bf16 v[46:49], v[198:201], v[202:205], v[18:21]
	v_mfma_f32_16x16x32_bf16 v[26:29], v[188:191], v[222:225], v[14:17]
	v_mfma_f32_16x16x32_bf16 v[30:33], v[198:201], v[222:225], v[10:13]
	v_mfma_f32_16x16x32_bf16 v[10:13], v[188:191], v[234:237], v[6:9]
	v_mfma_f32_16x16x32_bf16 v[14:17], v[198:201], v[234:237], v[2:5]
	s_setprio 0
	s_setprio 1
	v_mfma_f32_16x16x32_bf16 v[2:5], v[206:209], v[34:37], v[54:57]
	v_mfma_f32_16x16x32_bf16 v[50:53], v[214:217], v[38:41], v[2:5]
	v_mfma_f32_16x16x32_bf16 v[2:5], v[210:213], v[34:37], v[130:133]
	v_mfma_f32_16x16x32_bf16 v[54:57], v[230:233], v[38:41], v[2:5]
	v_mfma_f32_16x16x32_bf16 v[2:5], v[206:209], v[154:157], v[134:137]
	v_mfma_f32_16x16x32_bf16 v[34:37], v[214:217], v[202:205], v[2:5]
	v_mfma_f32_16x16x32_bf16 v[2:5], v[210:213], v[154:157], v[138:141]
	v_mfma_f32_16x16x32_bf16 v[38:41], v[230:233], v[202:205], v[2:5]
	v_mfma_f32_16x16x32_bf16 v[2:5], v[206:209], v[218:221], v[142:145]
	v_mfma_f32_16x16x32_bf16 v[18:21], v[214:217], v[222:225], v[2:5]
	v_mfma_f32_16x16x32_bf16 v[2:5], v[210:213], v[218:221], v[150:153]
	v_mfma_f32_16x16x32_bf16 v[22:25], v[230:233], v[222:225], v[2:5]
	v_mfma_f32_16x16x32_bf16 v[2:5], v[206:209], v[226:229], v[158:161]
	v_mfma_f32_16x16x32_bf16 v[6:9], v[210:213], v[226:229], v[162:165]
	v_mfma_f32_16x16x32_bf16 v[2:5], v[214:217], v[234:237], v[2:5]
	v_mfma_f32_16x16x32_bf16 v[6:9], v[230:233], v[234:237], v[6:9]
	s_setprio 0
	s_barrier
	s_and_saveexec_b64 vcc, s[6:7]
	s_cbranch_execz .LBB0_435
	s_barrier

; #define STAGEA(P, br, kt) do { const char* _g = uptr(A + (size_t)(br) * lda + (size_t)(kt) * BK); \
;     _Pragma("unroll") for (int _i = 0; _i < 2; ++_i) { \
;       __builtin_amdgcn_global_load_lds((const unsigned*)(_g + offA[_i]), (unsigned*)((char*)(P) + tidx * 16 + _i * 8192), 16, 0, 0); } } while (0)
; #define STAGEB(P, br, kt) do { const char* _g = uptr(Bt + (size_t)(br) * ldb + (size_t)(kt) * BK); \
;     _Pragma("unroll") for (int _i = 0; _i < 2; ++_i) { \
;       __builtin_amdgcn_global_load_lds((const unsigned*)(_g + offB[_i]), (unsigned*)((char*)(P) + tidx * 16 + _i * 8192), 16, 0, 0); } } while (0)
; #define LDA(dst, b, h) _Pragma("unroll") for (int m = 0; m < 4; ++m) _Pragma("unroll") for (int k = 0; k < 2; ++k) \
;     dst[m][k] = *reinterpret_cast<const bf16x8*>((char*)SA(b, h) + aoff + m * 2048 + k * 1024)
; #define LDB(dst, b, h) _Pragma("unroll") for (int n = 0; n < 2; ++n) _Pragma("unroll") for (int k = 0; k < 2; ++k) \
;     dst[n][k] = *reinterpret_cast<const bf16x8*>((char*)SB(b, h) + boff + n * (SWAP ? 256 : 2048) + k * 1024)
; #define WAIT_V(n) asm volatile("s_waitcnt vmcnt(" #n ")" ::: "memory")
; #define WAIT_L(n) asm volatile("s_waitcnt lgkmcnt(" #n ")" ::: "memory")
; #define BAR __builtin_amdgcn_s_barrier()
; #define SCHED __builtin_amdgcn_sched_barrier(0)
; template <int EPI>
; DI void gemm_phase(const u16* __restrict__ A, int lda, const u16* __restrict__ Bt, int ldb,
;                    int M, int N, int K, const Epi& e, unsigned char* shmraw, int wv, int slot) {
;     ...
;       LDB(B0, 0, 0); SCHED; LDA(At, 0, 0); STAGEA(SA(1, 1), brow + HALF, t + 1);
;       WAIT_L(8); BAR; WAIT_L(0); MMA(0, 0, At, B0); BAR; SCHED;
;       LDB(B1, 0, 1); STAGEB(SB(0, 0), bcol, t + 2);
;       BAR; WAIT_L(0); MMA(0, 1, At, B1); BAR;
;       LDA(At, 0, 1); STAGEA(SA(0, 0), brow, t + 2);
;       BAR; WAIT_L(0); MMA(1, 0, At, B0); BAR; SCHED;
;       STAGEB(SB(0, 1), bcol + HALF, t + 2);
;       WAIT_V(6); BAR; MMA(1, 1, At, B1); BAR;
.LBB0_650:
	s_waitcnt lgkmcnt(0)
	v_add_u32_e32 v0, s33, v193
	ds_read_b128 v[132:135], v0
	ds_read_b128 v[136:139], v0 offset:256
	ds_read_b128 v[140:143], v0 offset:1024
	ds_read_b128 v[144:147], v0 offset:1280
	s_add_u32 s36, vcc_lo, s26
	s_addc_u32 s37, s74, s27
	s_add_u32 s90, s36, 0x80
	v_add_u32_e32 v0, 0xc000, v196
	s_addc_u32 s91, s37, 0
	v_readfirstlane_b32 s42, v0
	v_lshl_add_u64 v[130:131], s[90:91], 0, v[152:153]
	s_mov_b32 m0, s42
	ds_read_b128 v[154:157], v208
	ds_read_b128 v[158:161], v208 offset:1024
	ds_read_b128 v[162:165], v208 offset:2048
	ds_read_b128 v[166:169], v208 offset:3072
	ds_read_b128 v[170:173], v208 offset:4096
	ds_read_b128 v[174:177], v208 offset:5120
	ds_read_b128 v[178:181], v208 offset:6144
	ds_read_b128 v[182:185], v208 offset:7168
	global_load_lds_dwordx4 v[130:131], off
	v_add_u32_e32 v130, 0xe000, v196
	v_lshl_add_u64 v[148:149], s[90:91], 0, v[150:151]
	v_readfirstlane_b32 s42, v130
	s_mov_b32 m0, s42
	s_nop 0
	global_load_lds_dwordx4 v[148:149], off
	s_waitcnt lgkmcnt(8)
	s_barrier
	s_waitcnt lgkmcnt(0)
	s_setprio 1
	v_mfma_f32_16x16x32_bf16 v[126:129], v[132:135], v[154:157], v[126:129]
	v_mfma_f32_16x16x32_bf16 v[122:125], v[136:139], v[154:157], v[122:125]
	v_mfma_f32_16x16x32_bf16 v[118:121], v[132:135], v[162:165], v[118:121]
	v_mfma_f32_16x16x32_bf16 v[114:117], v[136:139], v[162:165], v[114:117]
	v_mfma_f32_16x16x32_bf16 v[110:113], v[132:135], v[170:173], v[110:113]
	v_mfma_f32_16x16x32_bf16 v[106:109], v[136:139], v[170:173], v[106:109]
	v_mfma_f32_16x16x32_bf16 v[102:105], v[132:135], v[178:181], v[102:105]
	v_mfma_f32_16x16x32_bf16 v[98:101], v[136:139], v[178:181], v[98:101]
	v_mfma_f32_16x16x32_bf16 v[126:129], v[140:143], v[158:161], v[126:129]
	v_mfma_f32_16x16x32_bf16 v[122:125], v[144:147], v[158:161], v[122:125]
	v_mfma_f32_16x16x32_bf16 v[118:121], v[140:143], v[166:169], v[118:121]
	v_mfma_f32_16x16x32_bf16 v[114:117], v[144:147], v[166:169], v[114:117]
	v_mfma_f32_16x16x32_bf16 v[110:113], v[140:143], v[174:177], v[110:113]
	v_mfma_f32_16x16x32_bf16 v[106:109], v[144:147], v[174:177], v[106:109]
	v_mfma_f32_16x16x32_bf16 v[102:105], v[140:143], v[182:185], v[102:105]
	v_mfma_f32_16x16x32_bf16 v[98:101], v[144:147], v[182:185], v[98:101]
	s_setprio 0
	s_barrier
	s_add_u32 s42, s75, s26
	s_addc_u32 s54, s35, s27
	s_add_u32 s90, s42, 0x100
	s_addc_u32 s91, s54, 0
	v_readfirstlane_b32 s55, v194
	v_add_u32_e32 v131, s84, v193
	v_lshl_add_u64 v[148:149], s[90:91], 0, v[152:153]
	s_mov_b32 m0, s55
	v_readfirstlane_b32 s55, v195
	ds_read_b128 v[186:189], v131
	ds_read_b128 v[210:213], v131 offset:256
	ds_read_b128 v[214:217], v131 offset:1024
	ds_read_b128 v[218:221], v131 offset:1280
	global_load_lds_dwordx4 v[148:149], off
	v_lshl_add_u64 v[148:149], s[90:91], 0, v[150:151]
	s_mov_b32 m0, s55
	s_nop 0
	global_load_lds_dwordx4 v[148:149], off
	s_barrier
	s_waitcnt lgkmcnt(0)
	s_setprio 1
	v_mfma_f32_16x16x32_bf16 v[94:97], v[186:189], v[154:157], v[94:97]
	v_mfma_f32_16x16x32_bf16 v[78:81], v[210:213], v[154:157], v[78:81]
	v_mfma_f32_16x16x32_bf16 v[62:65], v[186:189], v[162:165], v[62:65]
	v_mfma_f32_16x16x32_bf16 v[50:53], v[210:213], v[162:165], v[50:53]
	v_mfma_f32_16x16x32_bf16 v[46:49], v[186:189], v[170:173], v[46:49]
	v_mfma_f32_16x16x32_bf16 v[42:45], v[210:213], v[170:173], v[42:45]
	v_mfma_f32_16x16x32_bf16 v[38:41], v[186:189], v[178:181], v[38:41]
	v_mfma_f32_16x16x32_bf16 v[34:37], v[210:213], v[178:181], v[34:37]
	v_mfma_f32_16x16x32_bf16 v[94:97], v[214:217], v[158:161], v[94:97]
	v_mfma_f32_16x16x32_bf16 v[78:81], v[218:221], v[158:161], v[78:81]
	v_mfma_f32_16x16x32_bf16 v[62:65], v[214:217], v[166:169], v[62:65]
	v_mfma_f32_16x16x32_bf16 v[50:53], v[218:221], v[166:169], v[50:53]
	v_mfma_f32_16x16x32_bf16 v[46:49], v[214:217], v[174:177], v[46:49]
	v_mfma_f32_16x16x32_bf16 v[42:45], v[218:221], v[174:177], v[42:45]
	v_mfma_f32_16x16x32_bf16 v[38:41], v[214:217], v[182:185], v[38:41]
	v_mfma_f32_16x16x32_bf16 v[34:37], v[218:221], v[182:185], v[34:37]
	s_setprio 0
	s_add_u32 s55, s38, s26
	s_addc_u32 s76, s39, s27
	s_add_u32 s90, s55, 0x100
	s_addc_u32 s91, s76, 0
	v_readfirstlane_b32 s89, v196
	v_lshl_add_u64 v[148:149], s[90:91], 0, v[152:153]
	s_mov_b32 m0, s89
	v_readfirstlane_b32 s89, v197
	s_barrier
	ds_read_b128 v[154:157], v208 offset:16384
	ds_read_b128 v[158:161], v208 offset:17408
	ds_read_b128 v[162:165], v208 offset:18432
	ds_read_b128 v[166:169], v208 offset:19456
	ds_read_b128 v[170:173], v208 offset:20480
	ds_read_b128 v[174:177], v208 offset:21504
	ds_read_b128 v[178:181], v208 offset:22528
	ds_read_b128 v[182:185], v208 offset:23552
	global_load_lds_dwordx4 v[148:149], off
	v_lshl_add_u64 v[148:149], s[90:91], 0, v[150:151]
	s_mov_b32 m0, s89
	s_nop 0
	global_load_lds_dwordx4 v[148:149], off
	s_barrier
	s_waitcnt lgkmcnt(0)
	s_setprio 1
	v_mfma_f32_16x16x32_bf16 v[30:33], v[132:135], v[154:157], v[30:33]
	v_mfma_f32_16x16x32_bf16 v[26:29], v[136:139], v[154:157], v[26:29]
	v_mfma_f32_16x16x32_bf16 v[22:25], v[132:135], v[162:165], v[22:25]
	v_mfma_f32_16x16x32_bf16 v[18:21], v[136:139], v[162:165], v[18:21]
	v_mfma_f32_16x16x32_bf16 v[14:17], v[132:135], v[170:173], v[14:17]
	v_mfma_f32_16x16x32_bf16 v[10:13], v[136:139], v[170:173], v[10:13]
	v_mfma_f32_16x16x32_bf16 v[6:9], v[132:135], v[178:181], v[6:9]
	v_mfma_f32_16x16x32_bf16 v[2:5], v[136:139], v[178:181], v[2:5]
	v_mfma_f32_16x16x32_bf16 v[30:33], v[140:143], v[158:161], v[30:33]
	v_mfma_f32_16x16x32_bf16 v[26:29], v[144:147], v[158:161], v[26:29]
	v_mfma_f32_16x16x32_bf16 v[22:25], v[140:143], v[166:169], v[22:25]
	v_mfma_f32_16x16x32_bf16 v[18:21], v[144:147], v[166:169], v[18:21]
	v_mfma_f32_16x16x32_bf16 v[14:17], v[140:143], v[174:177], v[14:17]
	v_mfma_f32_16x16x32_bf16 v[10:13], v[144:147], v[174:177], v[10:13]
	v_mfma_f32_16x16x32_bf16 v[6:9], v[140:143], v[182:185], v[6:9]
	v_mfma_f32_16x16x32_bf16 v[2:5], v[144:147], v[182:185], v[2:5]
	s_setprio 0
	s_barrier
; #define STAGEA(P, br, kt) do { const char* _g = uptr(A + (size_t)(br) * lda + (size_t)(kt) * BK); \
;     _Pragma("unroll") for (int _i = 0; _i < 2; ++_i) { \
;       __builtin_amdgcn_global_load_lds((const unsigned*)(_g + offA[_i]), (unsigned*)((char*)(P) + tidx * 16 + _i * 8192), 16, 0, 0); } } while (0)
; #define STAGEB(P, br, kt) do { const char* _g = uptr(Bt + (size_t)(br) * ldb + (size_t)(kt) * BK); \
;     _Pragma("unroll") for (int _i = 0; _i < 2; ++_i) { \
;       __builtin_amdgcn_global_load_lds((const unsigned*)(_g + offB[_i]), (unsigned*)((char*)(P) + tidx * 16 + _i * 8192), 16, 0, 0); } } while (0)
; #define LDA(dst, b, h) _Pragma("unroll") for (int m = 0; m < 4; ++m) _Pragma("unroll") for (int k = 0; k < 2; ++k) \
;     dst[m][k] = *reinterpret_cast<const bf16x8*>((char*)SA(b, h) + aoff + m * 2048 + k * 1024)
; #define LDB(dst, b, h) _Pragma("unroll") for (int n = 0; n < 2; ++n) _Pragma("unroll") for (int k = 0; k < 2; ++k) \
;     dst[n][k] = *reinterpret_cast<const bf16x8*>((char*)SB(b, h) + boff + n * (SWAP ? 256 : 2048) + k * 1024)
; #define WAIT_V(n) asm volatile("s_waitcnt vmcnt(" #n ")" ::: "memory")
; #define WAIT_L(n) asm volatile("s_waitcnt lgkmcnt(" #n ")" ::: "memory")
; #define BAR __builtin_amdgcn_s_barrier()
; #define SCHED __builtin_amdgcn_sched_barrier(0)
; template <int EPI>
; DI void gemm_phase(const u16* __restrict__ A, int lda, const u16* __restrict__ Bt, int ldb,
;                    int M, int N, int K, const Epi& e, unsigned char* shmraw, int wv, int slot) {
;     ...
;       STAGEB(SB(0, 1), bcol + HALF, t + 2);
;       WAIT_V(6); BAR; MMA(1, 1, At, B1); BAR;
;       LDB(B0, 1, 0); SCHED; LDA(At, 1, 0); STAGEA(SA(0, 1), brow + HALF, t + 2);
;       WAIT_L(8); BAR; WAIT_L(0); MMA(0, 0, At, B0); BAR; SCHED;
;       LDB(B1, 1, 1); STAGEB(SB(1, 0), bcol, t + 3);
;       BAR; WAIT_L(0); MMA(0, 1, At, B1); BAR;
	s_add_u32 s89, s40, s26
	s_addc_u32 vcc_hi, s41, s27
	s_add_u32 s90, s89, 0x100
	s_addc_u32 s91, vcc_hi, 0
	v_readfirstlane_b32 s11, v198
	v_lshl_add_u64 v[132:133], s[90:91], 0, v[152:153]
	s_mov_b32 m0, s11
	v_readfirstlane_b32 s11, v199
	global_load_lds_dwordx4 v[132:133], off
	v_lshl_add_u64 v[132:133], s[90:91], 0, v[150:151]
	s_mov_b32 m0, s11
	s_nop 0
	global_load_lds_dwordx4 v[132:133], off
	s_waitcnt vmcnt(6)
	s_barrier
	s_setprio 1
	v_mfma_f32_16x16x32_bf16 v[54:57], v[186:189], v[154:157], v[54:57]
	v_mfma_f32_16x16x32_bf16 v[58:61], v[210:213], v[154:157], v[58:61]
	v_mfma_f32_16x16x32_bf16 v[66:69], v[186:189], v[162:165], v[66:69]
	v_mfma_f32_16x16x32_bf16 v[70:73], v[210:213], v[162:165], v[70:73]
	v_mfma_f32_16x16x32_bf16 v[74:77], v[186:189], v[170:173], v[74:77]
	v_mfma_f32_16x16x32_bf16 v[82:85], v[210:213], v[170:173], v[82:85]
	v_mfma_f32_16x16x32_bf16 v[86:89], v[186:189], v[178:181], v[86:89]
	v_mfma_f32_16x16x32_bf16 v[90:93], v[210:213], v[178:181], v[90:93]
	v_mfma_f32_16x16x32_bf16 v[54:57], v[214:217], v[158:161], v[54:57]
	v_mfma_f32_16x16x32_bf16 v[58:61], v[218:221], v[158:161], v[58:61]
	v_mfma_f32_16x16x32_bf16 v[66:69], v[214:217], v[166:169], v[66:69]
	v_mfma_f32_16x16x32_bf16 v[70:73], v[218:221], v[166:169], v[70:73]
	v_mfma_f32_16x16x32_bf16 v[74:77], v[214:217], v[174:177], v[74:77]
	v_mfma_f32_16x16x32_bf16 v[82:85], v[218:221], v[174:177], v[82:85]
	v_mfma_f32_16x16x32_bf16 v[86:89], v[214:217], v[182:185], v[86:89]
	v_mfma_f32_16x16x32_bf16 v[90:93], v[218:221], v[182:185], v[90:93]
	s_setprio 0
	v_add_u32_e32 v131, s85, v193
	s_barrier
	ds_read_b128 v[132:135], v131
	ds_read_b128 v[136:139], v131 offset:256
	ds_read_b128 v[140:143], v131 offset:1024
	ds_read_b128 v[144:147], v131 offset:1280
	s_add_u32 s90, s36, 0x100
	s_addc_u32 s91, s37, 0
	v_readfirstlane_b32 s11, v200
	v_lshl_add_u64 v[148:149], s[90:91], 0, v[152:153]
	s_mov_b32 m0, s11
	v_readfirstlane_b32 s11, v201
	ds_read_b128 v[154:157], v208 offset:32768
	ds_read_b128 v[158:161], v208 offset:33792
	ds_read_b128 v[162:165], v208 offset:34816
	ds_read_b128 v[166:169], v208 offset:35840
	ds_read_b128 v[170:173], v208 offset:36864
	ds_read_b128 v[174:177], v208 offset:37888
	ds_read_b128 v[178:181], v208 offset:38912
	ds_read_b128 v[182:185], v208 offset:39936
	global_load_lds_dwordx4 v[148:149], off
	v_lshl_add_u64 v[148:149], s[90:91], 0, v[150:151]
	s_mov_b32 m0, s11
	s_nop 0
	global_load_lds_dwordx4 v[148:149], off
	s_waitcnt lgkmcnt(8)
	s_barrier
	s_waitcnt lgkmcnt(0)
	s_setprio 1
	v_mfma_f32_16x16x32_bf16 v[126:129], v[132:135], v[154:157], v[126:129]
	v_mfma_f32_16x16x32_bf16 v[122:125], v[136:139], v[154:157], v[122:125]
	v_mfma_f32_16x16x32_bf16 v[118:121], v[132:135], v[162:165], v[118:121]
	v_mfma_f32_16x16x32_bf16 v[114:117], v[136:139], v[162:165], v[114:117]
	v_mfma_f32_16x16x32_bf16 v[110:113], v[132:135], v[170:173], v[110:113]
	v_mfma_f32_16x16x32_bf16 v[106:109], v[136:139], v[170:173], v[106:109]
	v_mfma_f32_16x16x32_bf16 v[102:105], v[132:135], v[178:181], v[102:105]
	v_mfma_f32_16x16x32_bf16 v[98:101], v[136:139], v[178:181], v[98:101]
	v_mfma_f32_16x16x32_bf16 v[126:129], v[140:143], v[158:161], v[126:129]
	v_mfma_f32_16x16x32_bf16 v[122:125], v[144:147], v[158:161], v[122:125]
	v_mfma_f32_16x16x32_bf16 v[118:121], v[140:143], v[166:169], v[118:121]
	v_mfma_f32_16x16x32_bf16 v[114:117], v[144:147], v[166:169], v[114:117]
	v_mfma_f32_16x16x32_bf16 v[110:113], v[140:143], v[174:177], v[110:113]
	v_mfma_f32_16x16x32_bf16 v[106:109], v[144:147], v[174:177], v[106:109]
	v_mfma_f32_16x16x32_bf16 v[102:105], v[140:143], v[182:185], v[102:105]
	v_mfma_f32_16x16x32_bf16 v[98:101], v[144:147], v[182:185], v[98:101]
	s_setprio 0
	s_barrier
	s_add_u32 s90, s42, 0x180
	s_addc_u32 s91, s54, 0
	v_readfirstlane_b32 s11, v202
	v_add_u32_e32 v131, s86, v193
	v_lshl_add_u64 v[148:149], s[90:91], 0, v[152:153]
	s_mov_b32 m0, s11
	v_readfirstlane_b32 s11, v203
	ds_read_b128 v[186:189], v131
	ds_read_b128 v[210:213], v131 offset:256
	ds_read_b128 v[214:217], v131 offset:1024
	ds_read_b128 v[218:221], v131 offset:1280
	global_load_lds_dwordx4 v[148:149], off
	v_lshl_add_u64 v[148:149], s[90:91], 0, v[150:151]
	s_mov_b32 m0, s11
	s_nop 0
	global_load_lds_dwordx4 v[148:149], off
	s_barrier
	s_waitcnt lgkmcnt(0)
	s_setprio 1
	v_mfma_f32_16x16x32_bf16 v[94:97], v[186:189], v[154:157], v[94:97]
	v_mfma_f32_16x16x32_bf16 v[78:81], v[210:213], v[154:157], v[78:81]
	v_mfma_f32_16x16x32_bf16 v[62:65], v[186:189], v[162:165], v[62:65]
	v_mfma_f32_16x16x32_bf16 v[50:53], v[210:213], v[162:165], v[50:53]
	v_mfma_f32_16x16x32_bf16 v[46:49], v[186:189], v[170:173], v[46:49]
	v_mfma_f32_16x16x32_bf16 v[42:45], v[210:213], v[170:173], v[42:45]
	v_mfma_f32_16x16x32_bf16 v[38:41], v[186:189], v[178:181], v[38:41]
	v_mfma_f32_16x16x32_bf16 v[34:37], v[210:213], v[178:181], v[34:37]
	v_mfma_f32_16x16x32_bf16 v[94:97], v[214:217], v[158:161], v[94:97]
	v_mfma_f32_16x16x32_bf16 v[78:81], v[218:221], v[158:161], v[78:81]
	v_mfma_f32_16x16x32_bf16 v[62:65], v[214:217], v[166:169], v[62:65]
	v_mfma_f32_16x16x32_bf16 v[50:53], v[218:221], v[166:169], v[50:53]
	v_mfma_f32_16x16x32_bf16 v[46:49], v[214:217], v[174:177], v[46:49]
	v_mfma_f32_16x16x32_bf16 v[42:45], v[218:221], v[174:177], v[42:45]
	v_mfma_f32_16x16x32_bf16 v[38:41], v[214:217], v[182:185], v[38:41]
	v_mfma_f32_16x16x32_bf16 v[34:37], v[218:221], v[182:185], v[34:37]
	s_setprio 0
	s_add_u32 s90, s55, 0x180
	s_addc_u32 s91, s76, 0
	v_readfirstlane_b32 s11, v204
	v_lshl_add_u64 v[148:149], s[90:91], 0, v[152:153]
	s_mov_b32 m0, s11
	v_readfirstlane_b32 s11, v205
	s_barrier
; #define STAGEA(P, br, kt) do { const char* _g = uptr(A + (size_t)(br) * lda + (size_t)(kt) * BK); \
;     _Pragma("unroll") for (int _i = 0; _i < 2; ++_i) { \
;       __builtin_amdgcn_global_load_lds((const unsigned*)(_g + offA[_i]), (unsigned*)((char*)(P) + tidx * 16 + _i * 8192), 16, 0, 0); } } while (0)
; #define STAGEB(P, br, kt) do { const char* _g = uptr(Bt + (size_t)(br) * ldb + (size_t)(kt) * BK); \
;     _Pragma("unroll") for (int _i = 0; _i < 2; ++_i) { \
;       __builtin_amdgcn_global_load_lds((const unsigned*)(_g + offB[_i]), (unsigned*)((char*)(P) + tidx * 16 + _i * 8192), 16, 0, 0); } } while (0)
; #define LDA(dst, b, h) _Pragma("unroll") for (int m = 0; m < 4; ++m) _Pragma("unroll") for (int k = 0; k < 2; ++k) \
;     dst[m][k] = *reinterpret_cast<const bf16x8*>((char*)SA(b, h) + aoff + m * 2048 + k * 1024)
; #define LDB(dst, b, h) _Pragma("unroll") for (int n = 0; n < 2; ++n) _Pragma("unroll") for (int k = 0; k < 2; ++k) \
;     dst[n][k] = *reinterpret_cast<const bf16x8*>((char*)SB(b, h) + boff + n * (SWAP ? 256 : 2048) + k * 1024)
; #define WAIT_V(n) asm volatile("s_waitcnt vmcnt(" #n ")" ::: "memory")
; #define WAIT_L(n) asm volatile("s_waitcnt lgkmcnt(" #n ")" ::: "memory")
; #define BAR __builtin_amdgcn_s_barrier()
; #define SCHED __builtin_amdgcn_sched_barrier(0)
; template <int EPI>
; DI void gemm_phase(const u16* __restrict__ A, int lda, const u16* __restrict__ Bt, int ldb,
;                    int M, int N, int K, const Epi& e, unsigned char* shmraw, int wv, int slot) {
;     ...
;       LDA(At, 1, 1); STAGEA(SA(1, 0), brow, t + 3);
;       BAR; WAIT_L(0); MMA(1, 0, At, B0); BAR; SCHED;
;       STAGEB(SB(1, 1), bcol + HALF, t + 3);
;       WAIT_V(6); BAR; MMA(1, 1, At, B1); BAR;
;     }
;     { LDB(B0, 0, 0); LDA(At, 0, 0); STAGEA(SA(1, 1), brow + HALF, nt - 1);
;       BAR; WAIT_L(0); MMA(0, 0, At, B0); BAR;
;       LDB(B1, 0, 1); BAR; WAIT_L(0); MMA(0, 1, At, B1); BAR;
	ds_read_b128 v[154:157], v208 offset:49152
	ds_read_b128 v[158:161], v208 offset:50176
	ds_read_b128 v[162:165], v208 offset:51200
	ds_read_b128 v[166:169], v208 offset:52224
	ds_read_b128 v[170:173], v208 offset:53248
	ds_read_b128 v[174:177], v208 offset:54272
	ds_read_b128 v[178:181], v208 offset:55296
	ds_read_b128 v[182:185], v208 offset:56320
	global_load_lds_dwordx4 v[148:149], off
	v_lshl_add_u64 v[148:149], s[90:91], 0, v[150:151]
	s_mov_b32 m0, s11
	s_nop 0
	global_load_lds_dwordx4 v[148:149], off
	s_barrier
	s_waitcnt lgkmcnt(0)
	s_setprio 1
	v_mfma_f32_16x16x32_bf16 v[30:33], v[132:135], v[154:157], v[30:33]
	v_mfma_f32_16x16x32_bf16 v[26:29], v[136:139], v[154:157], v[26:29]
	v_mfma_f32_16x16x32_bf16 v[22:25], v[132:135], v[162:165], v[22:25]
	v_mfma_f32_16x16x32_bf16 v[18:21], v[136:139], v[162:165], v[18:21]
	v_mfma_f32_16x16x32_bf16 v[14:17], v[132:135], v[170:173], v[14:17]
	v_mfma_f32_16x16x32_bf16 v[10:13], v[136:139], v[170:173], v[10:13]
	v_mfma_f32_16x16x32_bf16 v[6:9], v[132:135], v[178:181], v[6:9]
	v_mfma_f32_16x16x32_bf16 v[2:5], v[136:139], v[178:181], v[2:5]
	v_mfma_f32_16x16x32_bf16 v[30:33], v[140:143], v[158:161], v[30:33]
	v_mfma_f32_16x16x32_bf16 v[26:29], v[144:147], v[158:161], v[26:29]
	v_mfma_f32_16x16x32_bf16 v[22:25], v[140:143], v[166:169], v[22:25]
	v_mfma_f32_16x16x32_bf16 v[18:21], v[144:147], v[166:169], v[18:21]
	v_mfma_f32_16x16x32_bf16 v[14:17], v[140:143], v[174:177], v[14:17]
	v_mfma_f32_16x16x32_bf16 v[10:13], v[144:147], v[174:177], v[10:13]
	v_mfma_f32_16x16x32_bf16 v[6:9], v[140:143], v[182:185], v[6:9]
	v_mfma_f32_16x16x32_bf16 v[2:5], v[144:147], v[182:185], v[2:5]
	s_setprio 0
	s_barrier
	s_add_u32 s90, s89, 0x180
	s_addc_u32 s91, vcc_hi, 0
	v_readfirstlane_b32 s11, v206
	v_lshl_add_u64 v[132:133], s[90:91], 0, v[152:153]
	s_mov_b32 m0, s11
	v_readfirstlane_b32 s11, v207
	global_load_lds_dwordx4 v[132:133], off
	v_lshl_add_u64 v[132:133], s[90:91], 0, v[150:151]
	s_mov_b32 m0, s11
	s_nop 0
	global_load_lds_dwordx4 v[132:133], off
	s_waitcnt vmcnt(6)
	s_barrier
	s_setprio 1
	v_mfma_f32_16x16x32_bf16 v[54:57], v[186:189], v[154:157], v[54:57]
	v_mfma_f32_16x16x32_bf16 v[58:61], v[210:213], v[154:157], v[58:61]
	v_mfma_f32_16x16x32_bf16 v[66:69], v[186:189], v[162:165], v[66:69]
	v_mfma_f32_16x16x32_bf16 v[70:73], v[210:213], v[162:165], v[70:73]
	v_mfma_f32_16x16x32_bf16 v[74:77], v[186:189], v[170:173], v[74:77]
	v_mfma_f32_16x16x32_bf16 v[82:85], v[210:213], v[170:173], v[82:85]
	v_mfma_f32_16x16x32_bf16 v[86:89], v[186:189], v[178:181], v[86:89]
	v_mfma_f32_16x16x32_bf16 v[90:93], v[210:213], v[178:181], v[90:93]
	v_mfma_f32_16x16x32_bf16 v[54:57], v[214:217], v[158:161], v[54:57]
	v_mfma_f32_16x16x32_bf16 v[58:61], v[218:221], v[158:161], v[58:61]
	v_mfma_f32_16x16x32_bf16 v[66:69], v[214:217], v[166:169], v[66:69]
	v_mfma_f32_16x16x32_bf16 v[70:73], v[218:221], v[166:169], v[70:73]
	v_mfma_f32_16x16x32_bf16 v[74:77], v[214:217], v[174:177], v[74:77]
	v_mfma_f32_16x16x32_bf16 v[82:85], v[218:221], v[174:177], v[82:85]
	v_mfma_f32_16x16x32_bf16 v[86:89], v[214:217], v[182:185], v[86:89]
	v_mfma_f32_16x16x32_bf16 v[90:93], v[218:221], v[182:185], v[90:93]
	s_setprio 0
	s_add_i32 s1, s1, 2
	s_add_u32 s26, s26, 0x100
	s_addc_u32 s27, s27, 0
	s_cmp_gt_u32 s1, 11
	s_barrier
	s_cbranch_scc0 .LBB0_650
	s_lshl_b64 s[24:25], s[24:25], 1
	s_add_u32 s24, s0, s24
	v_readlane_b32 s1, v253, 4
	v_add_u32_e32 v190, 16, v193
	s_addc_u32 s25, s1, s25
	v_readfirstlane_b32 s1, v0
	v_add_u32_e32 v131, 0x10000, v190
	v_lshl_add_u64 v[148:149], s[24:25], 0, v[152:153]
	s_mov_b32 m0, s1
	v_readfirstlane_b32 s1, v130
	ds_read_b128 v[132:135], v131
	ds_read_b128 v[136:139], v131 offset:256
	ds_read_b128 v[140:143], v131 offset:1024
	ds_read_b128 v[144:147], v131 offset:1280
	ds_read_b128 v[154:157], v208
	ds_read_b128 v[158:161], v208 offset:1024
	ds_read_b128 v[162:165], v208 offset:2048
	ds_read_b128 v[166:169], v208 offset:3072
	ds_read_b128 v[170:173], v208 offset:4096
	ds_read_b128 v[174:177], v208 offset:5120
	ds_read_b128 v[178:181], v208 offset:6144
	ds_read_b128 v[182:185], v208 offset:7168
	global_load_lds_dwordx4 v[148:149], off
	v_lshl_add_u64 v[148:149], s[24:25], 0, v[150:151]
	s_mov_b32 m0, s1
	s_nop 0
	global_load_lds_dwordx4 v[148:149], off
	s_barrier
	s_waitcnt lgkmcnt(0)
	s_setprio 1
	v_mfma_f32_16x16x32_bf16 v[126:129], v[132:135], v[154:157], v[126:129]
	v_mfma_f32_16x16x32_bf16 v[122:125], v[136:139], v[154:157], v[122:125]
	v_mfma_f32_16x16x32_bf16 v[118:121], v[132:135], v[162:165], v[118:121]
	v_mfma_f32_16x16x32_bf16 v[114:117], v[136:139], v[162:165], v[114:117]
	v_mfma_f32_16x16x32_bf16 v[110:113], v[132:135], v[170:173], v[110:113]
	v_mfma_f32_16x16x32_bf16 v[106:109], v[136:139], v[170:173], v[106:109]
	v_mfma_f32_16x16x32_bf16 v[98:101], v[136:139], v[178:181], v[98:101]
	v_mfma_f32_16x16x32_bf16 v[126:129], v[140:143], v[158:161], v[126:129]
	v_mfma_f32_16x16x32_bf16 v[122:125], v[144:147], v[158:161], v[122:125]
	v_mfma_f32_16x16x32_bf16 v[118:121], v[140:143], v[166:169], v[118:121]
	v_mfma_f32_16x16x32_bf16 v[114:117], v[144:147], v[166:169], v[114:117]
	v_mfma_f32_16x16x32_bf16 v[110:113], v[140:143], v[174:177], v[110:113]
	v_mfma_f32_16x16x32_bf16 v[106:109], v[144:147], v[174:177], v[106:109]
	v_mfma_f32_16x16x32_bf16 v[102:105], v[132:135], v[178:181], v[102:105]
	v_mfma_f32_16x16x32_bf16 v[98:101], v[144:147], v[182:185], v[98:101]
	v_mfma_f32_16x16x32_bf16 v[186:189], v[140:143], v[182:185], v[102:105]
	s_setprio 0
	v_add_u32_e32 v0, 0x14000, v190
	s_barrier
	s_nop 2
	ds_read_b128 v[102:105], v0
	ds_read_b128 v[210:213], v0 offset:256
	ds_read_b128 v[214:217], v0 offset:1024
	ds_read_b128 v[218:221], v0 offset:1280
	s_barrier
; #define LDA(dst, b, h) _Pragma("unroll") for (int m = 0; m < 4; ++m) _Pragma("unroll") for (int k = 0; k < 2; ++k) \
;     dst[m][k] = *reinterpret_cast<const bf16x8*>((char*)SA(b, h) + aoff + m * 2048 + k * 1024)
; #define LDB(dst, b, h) _Pragma("unroll") for (int n = 0; n < 2; ++n) _Pragma("unroll") for (int k = 0; k < 2; ++k) \
;     dst[n][k] = *reinterpret_cast<const bf16x8*>((char*)SB(b, h) + boff + n * (SWAP ? 256 : 2048) + k * 1024)
; #define WAIT_V(n) asm volatile("s_waitcnt vmcnt(" #n ")" ::: "memory")
; #define WAIT_L(n) asm volatile("s_waitcnt lgkmcnt(" #n ")" ::: "memory")
; #define BAR __builtin_amdgcn_s_barrier()
; template <int EPI>
; DI void gemm_phase(const u16* __restrict__ A, int lda, const u16* __restrict__ Bt, int ldb,
;                    int M, int N, int K, const Epi& e, unsigned char* shmraw, int wv, int slot) {
;     ...
;       LDB(B1, 0, 1); BAR; WAIT_L(0); MMA(0, 1, At, B1); BAR;
;       LDA(At, 0, 1); WAIT_V(4); BAR; WAIT_L(0); MMA(1, 0, At, B0); MMA(1, 1, At, B1); BAR; }
;     { LDB(B0, 1, 0); LDA(At, 1, 0); WAIT_V(2); BAR; WAIT_L(0); MMA(0, 0, At, B0); BAR;
	s_waitcnt lgkmcnt(0)
	s_setprio 1
	v_mfma_f32_16x16x32_bf16 v[94:97], v[102:105], v[154:157], v[94:97]
	v_mfma_f32_16x16x32_bf16 v[78:81], v[210:213], v[154:157], v[78:81]
	v_mfma_f32_16x16x32_bf16 v[62:65], v[102:105], v[162:165], v[62:65]
	v_mfma_f32_16x16x32_bf16 v[46:49], v[102:105], v[170:173], v[46:49]
	v_mfma_f32_16x16x32_bf16 v[42:45], v[210:213], v[170:173], v[42:45]
	v_mfma_f32_16x16x32_bf16 v[38:41], v[102:105], v[178:181], v[38:41]
	v_mfma_f32_16x16x32_bf16 v[34:37], v[210:213], v[178:181], v[34:37]
	v_mfma_f32_16x16x32_bf16 v[94:97], v[214:217], v[158:161], v[94:97]
	v_mfma_f32_16x16x32_bf16 v[78:81], v[218:221], v[158:161], v[78:81]
	v_mfma_f32_16x16x32_bf16 v[62:65], v[214:217], v[166:169], v[62:65]
	v_mfma_f32_16x16x32_bf16 v[50:53], v[210:213], v[162:165], v[50:53]
	v_mfma_f32_16x16x32_bf16 v[46:49], v[214:217], v[174:177], v[46:49]
	v_mfma_f32_16x16x32_bf16 v[42:45], v[218:221], v[174:177], v[42:45]
	v_mfma_f32_16x16x32_bf16 v[38:41], v[214:217], v[182:185], v[38:41]
	v_mfma_f32_16x16x32_bf16 v[34:37], v[218:221], v[182:185], v[34:37]
	v_mfma_f32_16x16x32_bf16 v[154:157], v[218:221], v[166:169], v[50:53]
	s_setprio 0
	s_barrier
	s_nop 0
	ds_read_b128 v[50:53], v208 offset:16384
	ds_read_b128 v[158:161], v208 offset:17408
	ds_read_b128 v[162:165], v208 offset:18432
	ds_read_b128 v[166:169], v208 offset:19456
	ds_read_b128 v[170:173], v208 offset:20480
	ds_read_b128 v[174:177], v208 offset:21504
	ds_read_b128 v[178:181], v208 offset:22528
	ds_read_b128 v[182:185], v208 offset:23552
	s_waitcnt vmcnt(4)
	s_barrier
	s_waitcnt lgkmcnt(0)
	s_setprio 1
	v_mfma_f32_16x16x32_bf16 v[14:17], v[132:135], v[170:173], v[14:17]
	v_mfma_f32_16x16x32_bf16 v[10:13], v[136:139], v[170:173], v[10:13]
	v_mfma_f32_16x16x32_bf16 v[6:9], v[132:135], v[178:181], v[6:9]
	v_mfma_f32_16x16x32_bf16 v[2:5], v[136:139], v[178:181], v[2:5]
	v_mfma_f32_16x16x32_bf16 v[30:33], v[132:135], v[50:53], v[30:33]
	v_mfma_f32_16x16x32_bf16 v[26:29], v[136:139], v[50:53], v[26:29]
	v_mfma_f32_16x16x32_bf16 v[22:25], v[132:135], v[162:165], v[22:25]
	v_mfma_f32_16x16x32_bf16 v[18:21], v[136:139], v[162:165], v[18:21]
	v_mfma_f32_16x16x32_bf16 v[14:17], v[140:143], v[174:177], v[14:17]
	v_mfma_f32_16x16x32_bf16 v[10:13], v[144:147], v[174:177], v[10:13]
	v_mfma_f32_16x16x32_bf16 v[6:9], v[140:143], v[182:185], v[6:9]
	v_mfma_f32_16x16x32_bf16 v[2:5], v[144:147], v[182:185], v[2:5]
	v_mfma_f32_16x16x32_bf16 v[30:33], v[140:143], v[158:161], v[30:33]
	v_mfma_f32_16x16x32_bf16 v[26:29], v[144:147], v[158:161], v[26:29]
	v_mfma_f32_16x16x32_bf16 v[22:25], v[140:143], v[166:169], v[22:25]
	v_mfma_f32_16x16x32_bf16 v[18:21], v[144:147], v[166:169], v[18:21]
	s_setprio 0
	s_setprio 1
	v_mfma_f32_16x16x32_bf16 v[54:57], v[102:105], v[50:53], v[54:57]
	v_mfma_f32_16x16x32_bf16 v[50:53], v[210:213], v[50:53], v[58:61]
	v_mfma_f32_16x16x32_bf16 v[58:61], v[218:221], v[158:161], v[50:53]
	v_mfma_f32_16x16x32_bf16 v[50:53], v[102:105], v[162:165], v[66:69]
	v_mfma_f32_16x16x32_bf16 v[142:145], v[214:217], v[158:161], v[54:57]
	v_mfma_f32_16x16x32_bf16 v[158:161], v[214:217], v[166:169], v[50:53]
	v_mfma_f32_16x16x32_bf16 v[50:53], v[210:213], v[162:165], v[70:73]
	v_mfma_f32_16x16x32_bf16 v[162:165], v[218:221], v[166:169], v[50:53]
	v_mfma_f32_16x16x32_bf16 v[50:53], v[102:105], v[170:173], v[74:77]
	v_mfma_f32_16x16x32_bf16 v[166:169], v[214:217], v[174:177], v[50:53]
	v_mfma_f32_16x16x32_bf16 v[50:53], v[210:213], v[170:173], v[82:85]
	v_mfma_f32_16x16x32_bf16 v[170:173], v[218:221], v[174:177], v[50:53]
	v_mfma_f32_16x16x32_bf16 v[50:53], v[102:105], v[178:181], v[86:89]
	v_mfma_f32_16x16x32_bf16 v[174:177], v[214:217], v[182:185], v[50:53]
	v_mfma_f32_16x16x32_bf16 v[50:53], v[210:213], v[178:181], v[90:93]
	v_mfma_f32_16x16x32_bf16 v[178:181], v[218:221], v[182:185], v[50:53]
	s_setprio 0
	v_add_u32_e32 v0, 0x18000, v190
	s_barrier
	ds_read_b128 v[90:93], v0
	ds_read_b128 v[182:185], v0 offset:256
	ds_read_b128 v[210:213], v0 offset:1024
	ds_read_b128 v[214:217], v0 offset:1280
	ds_read_b128 v[66:69], v208 offset:32768
	ds_read_b128 v[74:77], v208 offset:33792
	ds_read_b128 v[86:89], v208 offset:34816
	ds_read_b128 v[218:221], v208 offset:35840
	ds_read_b128 v[222:225], v208 offset:36864
	ds_read_b128 v[226:229], v208 offset:37888
	ds_read_b128 v[230:233], v208 offset:38912
	ds_read_b128 v[234:237], v208 offset:39936
	s_waitcnt vmcnt(2)
	s_barrier
; #define LDA(dst, b, h) _Pragma("unroll") for (int m = 0; m < 4; ++m) _Pragma("unroll") for (int k = 0; k < 2; ++k) \
;     dst[m][k] = *reinterpret_cast<const bf16x8*>((char*)SA(b, h) + aoff + m * 2048 + k * 1024)
; #define LDB(dst, b, h) _Pragma("unroll") for (int n = 0; n < 2; ++n) _Pragma("unroll") for (int k = 0; k < 2; ++k) \
;     dst[n][k] = *reinterpret_cast<const bf16x8*>((char*)SB(b, h) + boff + n * (SWAP ? 256 : 2048) + k * 1024)
; #define WAIT_V(n) asm volatile("s_waitcnt vmcnt(" #n ")" ::: "memory")
; #define WAIT_L(n) asm volatile("s_waitcnt lgkmcnt(" #n ")" ::: "memory")
; #define BAR __builtin_amdgcn_s_barrier()
; template <int EPI>
; DI void gemm_phase(const u16* __restrict__ A, int lda, const u16* __restrict__ Bt, int ldb,
;                    int M, int N, int K, const Epi& e, unsigned char* shmraw, int wv, int slot) {
;     ...
;     { LDB(B0, 1, 0); LDA(At, 1, 0); WAIT_V(2); BAR; WAIT_L(0); MMA(0, 0, At, B0); BAR;
;       LDB(B1, 1, 1); WAIT_V(0); BAR; WAIT_L(0); MMA(0, 1, At, B1); BAR;
;       LDA(At, 1, 1); BAR; WAIT_L(0); MMA(1, 0, At, B0); MMA(1, 1, At, B1); BAR; }
;     if (wr == 0) BAR;
	s_waitcnt lgkmcnt(0)
	s_setprio 1
	v_mfma_f32_16x16x32_bf16 v[54:57], v[182:185], v[86:89], v[114:117]
	v_mfma_f32_16x16x32_bf16 v[70:73], v[214:217], v[218:221], v[54:57]
	v_mfma_f32_16x16x32_bf16 v[54:57], v[90:93], v[222:225], v[110:113]
	v_mfma_f32_16x16x32_bf16 v[50:53], v[90:93], v[66:69], v[126:129]
	v_mfma_f32_16x16x32_bf16 v[82:85], v[210:213], v[226:229], v[54:57]
	v_mfma_f32_16x16x32_bf16 v[54:57], v[182:185], v[222:225], v[106:109]
	v_mfma_f32_16x16x32_bf16 v[138:141], v[210:213], v[74:77], v[50:53]
	v_mfma_f32_16x16x32_bf16 v[50:53], v[182:185], v[66:69], v[122:125]
	v_mfma_f32_16x16x32_bf16 v[102:105], v[214:217], v[226:229], v[54:57]
	v_mfma_f32_16x16x32_bf16 v[54:57], v[90:93], v[230:233], v[186:189]
	v_mfma_f32_16x16x32_bf16 v[146:149], v[214:217], v[74:77], v[50:53]
	v_mfma_f32_16x16x32_bf16 v[50:53], v[90:93], v[86:89], v[118:121]
	v_mfma_f32_16x16x32_bf16 v[114:117], v[210:213], v[234:237], v[54:57]
	v_mfma_f32_16x16x32_bf16 v[54:57], v[182:185], v[230:233], v[98:101]
	v_mfma_f32_16x16x32_bf16 v[50:53], v[210:213], v[218:221], v[50:53]
	v_mfma_f32_16x16x32_bf16 v[130:133], v[214:217], v[234:237], v[54:57]
	s_setprio 0
	v_add_u32_e32 v0, 0x1c000, v190
	s_barrier
	ds_read_b128 v[186:189], v0
	ds_read_b128 v[238:241], v0 offset:256
	ds_read_b128 v[242:245], v0 offset:1024
	ds_read_b128 v[246:249], v0 offset:1280
	s_waitcnt vmcnt(0)
	s_barrier
	s_waitcnt lgkmcnt(0)
	s_setprio 1
	v_mfma_f32_16x16x32_bf16 v[54:57], v[186:189], v[66:69], v[94:97]
	v_mfma_f32_16x16x32_bf16 v[66:69], v[238:241], v[66:69], v[78:81]
	v_mfma_f32_16x16x32_bf16 v[62:65], v[186:189], v[86:89], v[62:65]
	v_mfma_f32_16x16x32_bf16 v[134:137], v[246:249], v[74:77], v[66:69]
	v_mfma_f32_16x16x32_bf16 v[66:69], v[242:245], v[218:221], v[62:65]
	v_mfma_f32_16x16x32_bf16 v[62:65], v[238:241], v[86:89], v[154:157]
	v_mfma_f32_16x16x32_bf16 v[46:49], v[186:189], v[222:225], v[46:49]
	v_mfma_f32_16x16x32_bf16 v[42:45], v[238:241], v[222:225], v[42:45]
	v_mfma_f32_16x16x32_bf16 v[38:41], v[186:189], v[230:233], v[38:41]
	v_mfma_f32_16x16x32_bf16 v[34:37], v[238:241], v[230:233], v[34:37]
	v_mfma_f32_16x16x32_bf16 v[54:57], v[242:245], v[74:77], v[54:57]
	v_mfma_f32_16x16x32_bf16 v[86:89], v[246:249], v[218:221], v[62:65]
	v_mfma_f32_16x16x32_bf16 v[98:101], v[242:245], v[226:229], v[46:49]
	v_mfma_f32_16x16x32_bf16 v[118:121], v[246:249], v[226:229], v[42:45]
	v_mfma_f32_16x16x32_bf16 v[122:125], v[242:245], v[234:237], v[38:41]
	v_mfma_f32_16x16x32_bf16 v[126:129], v[246:249], v[234:237], v[34:37]
	s_setprio 0
	s_barrier
	s_nop 0
	ds_read_b128 v[34:37], v208 offset:49152
	ds_read_b128 v[38:41], v208 offset:50176
	ds_read_b128 v[62:65], v208 offset:51200
	ds_read_b128 v[154:157], v208 offset:52224
	ds_read_b128 v[218:221], v208 offset:53248
	ds_read_b128 v[222:225], v208 offset:54272
	ds_read_b128 v[226:229], v208 offset:55296
	ds_read_b128 v[230:233], v208 offset:56320
	s_barrier
	s_waitcnt lgkmcnt(0)
	s_setprio 1
	v_mfma_f32_16x16x32_bf16 v[30:33], v[90:93], v[34:37], v[30:33]
	v_mfma_f32_16x16x32_bf16 v[26:29], v[182:185], v[34:37], v[26:29]
	v_mfma_f32_16x16x32_bf16 v[22:25], v[90:93], v[62:65], v[22:25]
	v_mfma_f32_16x16x32_bf16 v[18:21], v[182:185], v[62:65], v[18:21]
	v_mfma_f32_16x16x32_bf16 v[14:17], v[90:93], v[218:221], v[14:17]
	v_mfma_f32_16x16x32_bf16 v[10:13], v[182:185], v[218:221], v[10:13]
	v_mfma_f32_16x16x32_bf16 v[6:9], v[90:93], v[226:229], v[6:9]
	v_mfma_f32_16x16x32_bf16 v[2:5], v[182:185], v[226:229], v[2:5]
	v_mfma_f32_16x16x32_bf16 v[106:109], v[210:213], v[38:41], v[30:33]
	v_mfma_f32_16x16x32_bf16 v[110:113], v[214:217], v[38:41], v[26:29]
	v_mfma_f32_16x16x32_bf16 v[74:77], v[210:213], v[154:157], v[22:25]
	v_mfma_f32_16x16x32_bf16 v[78:81], v[214:217], v[154:157], v[18:21]
	v_mfma_f32_16x16x32_bf16 v[42:45], v[210:213], v[222:225], v[14:17]
	v_mfma_f32_16x16x32_bf16 v[46:49], v[214:217], v[222:225], v[10:13]
	v_mfma_f32_16x16x32_bf16 v[10:13], v[210:213], v[230:233], v[6:9]
	v_mfma_f32_16x16x32_bf16 v[14:17], v[214:217], v[230:233], v[2:5]
	s_setprio 0
	s_setprio 1
	v_mfma_f32_16x16x32_bf16 v[2:5], v[186:189], v[34:37], v[142:145]
	v_mfma_f32_16x16x32_bf16 v[90:93], v[242:245], v[38:41], v[2:5]
	v_mfma_f32_16x16x32_bf16 v[2:5], v[238:241], v[34:37], v[58:61]
	v_mfma_f32_16x16x32_bf16 v[94:97], v[246:249], v[38:41], v[2:5]
	v_mfma_f32_16x16x32_bf16 v[2:5], v[186:189], v[62:65], v[158:161]
	v_mfma_f32_16x16x32_bf16 v[58:61], v[242:245], v[154:157], v[2:5]
	v_mfma_f32_16x16x32_bf16 v[2:5], v[238:241], v[62:65], v[162:165]
	v_mfma_f32_16x16x32_bf16 v[62:65], v[246:249], v[154:157], v[2:5]
	v_mfma_f32_16x16x32_bf16 v[2:5], v[186:189], v[218:221], v[166:169]
	v_mfma_f32_16x16x32_bf16 v[34:37], v[242:245], v[222:225], v[2:5]
	v_mfma_f32_16x16x32_bf16 v[2:5], v[238:241], v[218:221], v[170:173]
	v_mfma_f32_16x16x32_bf16 v[38:41], v[246:249], v[222:225], v[2:5]
	v_mfma_f32_16x16x32_bf16 v[2:5], v[186:189], v[226:229], v[174:177]
	v_mfma_f32_16x16x32_bf16 v[6:9], v[238:241], v[226:229], v[178:181]
	v_mfma_f32_16x16x32_bf16 v[2:5], v[242:245], v[230:233], v[2:5]
	v_mfma_f32_16x16x32_bf16 v[6:9], v[246:249], v[230:233], v[6:9]
	s_setprio 0
	s_barrier
	s_and_saveexec_b64 s[24:25], s[6:7]
	s_cbranch_execz .LBB0_653
	s_barrier

; #define STAGEA(P, br, kt) do { const char* _g = uptr(A + (size_t)(br) * lda + (size_t)(kt) * BK); \
;     _Pragma("unroll") for (int _i = 0; _i < 2; ++_i) { \
;       __builtin_amdgcn_global_load_lds((const unsigned*)(_g + offA[_i]), (unsigned*)((char*)(P) + tidx * 16 + _i * 8192), 16, 0, 0); } } while (0)
; #define STAGEB(P, br, kt) do { const char* _g = uptr(Bt + (size_t)(br) * ldb + (size_t)(kt) * BK); \
;     _Pragma("unroll") for (int _i = 0; _i < 2; ++_i) { \
;       __builtin_amdgcn_global_load_lds((const unsigned*)(_g + offB[_i]), (unsigned*)((char*)(P) + tidx * 16 + _i * 8192), 16, 0, 0); } } while (0)
; #define LDA(dst, b, h) _Pragma("unroll") for (int m = 0; m < 4; ++m) _Pragma("unroll") for (int k = 0; k < 2; ++k) \
;     dst[m][k] = *reinterpret_cast<const bf16x8*>((char*)SA(b, h) + aoff + m * 2048 + k * 1024)
; #define LDB(dst, b, h) _Pragma("unroll") for (int n = 0; n < 2; ++n) _Pragma("unroll") for (int k = 0; k < 2; ++k) \
;     dst[n][k] = *reinterpret_cast<const bf16x8*>((char*)SB(b, h) + boff + n * (SWAP ? 256 : 2048) + k * 1024)
; #define WAIT_V(n) asm volatile("s_waitcnt vmcnt(" #n ")" ::: "memory")
; #define WAIT_L(n) asm volatile("s_waitcnt lgkmcnt(" #n ")" ::: "memory")
; #define BAR __builtin_amdgcn_s_barrier()
; #define SCHED __builtin_amdgcn_sched_barrier(0)
; template <int EPI>
; DI void gemm_phase(const u16* __restrict__ A, int lda, const u16* __restrict__ Bt, int ldb,
;                    int M, int N, int K, const Epi& e, unsigned char* shmraw, int wv, int slot) {
;     ...
;     for (int t = 0; t < nt - 2; t += 2) {
;       LDB(B0, 0, 0); SCHED; LDA(At, 0, 0); STAGEA(SA(1, 1), brow + HALF, t + 1);
;       WAIT_L(8); BAR; WAIT_L(0); MMA(0, 0, At, B0); BAR; SCHED;
;       LDB(B1, 0, 1); STAGEB(SB(0, 0), bcol, t + 2);
;       BAR; WAIT_L(0); MMA(0, 1, At, B1); BAR;
;       LDA(At, 0, 1); STAGEA(SA(0, 0), brow, t + 2);
;       BAR; WAIT_L(0); MMA(1, 0, At, B0); BAR; SCHED;
;       STAGEB(SB(0, 1), bcol + HALF, t + 2);
;       WAIT_V(6); BAR; MMA(1, 1, At, B1); BAR;
.LBB0_690:
	v_add_u32_e32 v0, s33, v168
	ds_read_b128 v[132:135], v0
	ds_read_b128 v[136:139], v0 offset:256
	ds_read_b128 v[140:143], v0 offset:1024
	ds_read_b128 v[150:153], v0 offset:1280
	s_add_u32 s54, s41, vcc_lo
	s_addc_u32 s55, s1, vcc_hi
	s_add_u32 s74, s54, 0x80
	v_add_u32_e32 v0, 0xc000, v171
	s_addc_u32 s75, s55, 0
	v_readfirstlane_b32 s54, v0
	v_lshl_add_u64 v[130:131], s[74:75], 0, v[148:149]
	s_mov_b32 m0, s54
	ds_read_b128 v[154:157], v196
	ds_read_b128 v[158:161], v196 offset:1024
	ds_read_b128 v[162:165], v196 offset:2048
	ds_read_b128 v[198:201], v196 offset:3072
	ds_read_b128 v[202:205], v196 offset:4096
	ds_read_b128 v[206:209], v196 offset:5120
	ds_read_b128 v[210:213], v196 offset:6144
	ds_read_b128 v[214:217], v196 offset:7168
	global_load_lds_dwordx4 v[130:131], off
	v_add_u32_e32 v130, 0xe000, v171
	v_lshl_add_u64 v[144:145], s[74:75], 0, v[146:147]
	v_readfirstlane_b32 s54, v130
	s_mov_b32 m0, s54
	s_nop 0
	global_load_lds_dwordx4 v[144:145], off
	s_waitcnt lgkmcnt(8)
	s_barrier
	s_waitcnt lgkmcnt(0)
	s_setprio 1
	v_mfma_f32_16x16x32_bf16 v[126:129], v[132:135], v[154:157], v[126:129]
	v_mfma_f32_16x16x32_bf16 v[122:125], v[136:139], v[154:157], v[122:125]
	v_mfma_f32_16x16x32_bf16 v[118:121], v[132:135], v[162:165], v[118:121]
	v_mfma_f32_16x16x32_bf16 v[114:117], v[136:139], v[162:165], v[114:117]
	v_mfma_f32_16x16x32_bf16 v[110:113], v[132:135], v[202:205], v[110:113]
	v_mfma_f32_16x16x32_bf16 v[106:109], v[136:139], v[202:205], v[106:109]
	v_mfma_f32_16x16x32_bf16 v[102:105], v[132:135], v[210:213], v[102:105]
	v_mfma_f32_16x16x32_bf16 v[98:101], v[136:139], v[210:213], v[98:101]
	v_mfma_f32_16x16x32_bf16 v[126:129], v[140:143], v[158:161], v[126:129]
	v_mfma_f32_16x16x32_bf16 v[122:125], v[150:153], v[158:161], v[122:125]
	v_mfma_f32_16x16x32_bf16 v[118:121], v[140:143], v[198:201], v[118:121]
	v_mfma_f32_16x16x32_bf16 v[114:117], v[150:153], v[198:201], v[114:117]
	v_mfma_f32_16x16x32_bf16 v[110:113], v[140:143], v[206:209], v[110:113]
	v_mfma_f32_16x16x32_bf16 v[106:109], v[150:153], v[206:209], v[106:109]
	v_mfma_f32_16x16x32_bf16 v[102:105], v[140:143], v[214:217], v[102:105]
	v_mfma_f32_16x16x32_bf16 v[98:101], v[150:153], v[214:217], v[98:101]
	s_setprio 0
	s_barrier
	s_add_u32 s54, s27, vcc_lo
	s_addc_u32 s55, s72, vcc_hi
	s_add_u32 s74, s54, 0x100
	s_addc_u32 s75, s55, 0
	v_readfirstlane_b32 s90, v169
	v_add_u32_e32 v131, s84, v168
	v_lshl_add_u64 v[144:145], s[74:75], 0, v[148:149]
	s_mov_b32 m0, s90
	ds_read_b128 v[218:221], v131
	ds_read_b128 v[222:225], v131 offset:256
	ds_read_b128 v[226:229], v131 offset:1024
	ds_read_b128 v[230:233], v131 offset:1280
	global_load_lds_dwordx4 v[144:145], off
	v_lshl_add_u64 v[144:145], s[74:75], 0, v[146:147]
	v_readfirstlane_b32 s74, v170
	s_mov_b32 m0, s74
	s_nop 0
	global_load_lds_dwordx4 v[144:145], off
	s_barrier
	s_waitcnt lgkmcnt(0)
	s_setprio 1
	v_mfma_f32_16x16x32_bf16 v[94:97], v[218:221], v[154:157], v[94:97]
	v_mfma_f32_16x16x32_bf16 v[78:81], v[222:225], v[154:157], v[78:81]
	v_mfma_f32_16x16x32_bf16 v[62:65], v[218:221], v[162:165], v[62:65]
	v_mfma_f32_16x16x32_bf16 v[50:53], v[222:225], v[162:165], v[50:53]
	v_mfma_f32_16x16x32_bf16 v[46:49], v[218:221], v[202:205], v[46:49]
	v_mfma_f32_16x16x32_bf16 v[42:45], v[222:225], v[202:205], v[42:45]
	v_mfma_f32_16x16x32_bf16 v[38:41], v[218:221], v[210:213], v[38:41]
	v_mfma_f32_16x16x32_bf16 v[34:37], v[222:225], v[210:213], v[34:37]
	v_mfma_f32_16x16x32_bf16 v[94:97], v[226:229], v[158:161], v[94:97]
	v_mfma_f32_16x16x32_bf16 v[78:81], v[230:233], v[158:161], v[78:81]
	v_mfma_f32_16x16x32_bf16 v[62:65], v[226:229], v[198:201], v[62:65]
	v_mfma_f32_16x16x32_bf16 v[50:53], v[230:233], v[198:201], v[50:53]
	v_mfma_f32_16x16x32_bf16 v[46:49], v[226:229], v[206:209], v[46:49]
	v_mfma_f32_16x16x32_bf16 v[42:45], v[230:233], v[206:209], v[42:45]
	v_mfma_f32_16x16x32_bf16 v[38:41], v[226:229], v[214:217], v[38:41]
	v_mfma_f32_16x16x32_bf16 v[34:37], v[230:233], v[214:217], v[34:37]
	s_setprio 0
	s_add_u32 s90, s29, vcc_lo
	s_addc_u32 s91, s73, vcc_hi
	s_add_u32 s74, s90, 0x100
	s_addc_u32 s75, s91, 0
	v_readfirstlane_b32 s97, v171
	v_lshl_add_u64 v[144:145], s[74:75], 0, v[148:149]
	s_mov_b32 m0, s97
	s_barrier
	ds_read_b128 v[154:157], v196 offset:16384
	ds_read_b128 v[158:161], v196 offset:17408
	ds_read_b128 v[162:165], v196 offset:18432
	ds_read_b128 v[198:201], v196 offset:19456
	ds_read_b128 v[202:205], v196 offset:20480
	ds_read_b128 v[206:209], v196 offset:21504
	ds_read_b128 v[210:213], v196 offset:22528
	ds_read_b128 v[214:217], v196 offset:23552
	global_load_lds_dwordx4 v[144:145], off
	v_lshl_add_u64 v[144:145], s[74:75], 0, v[146:147]
	v_readfirstlane_b32 s74, v172
	s_mov_b32 m0, s74
	s_nop 0
	global_load_lds_dwordx4 v[144:145], off
	s_barrier
	s_waitcnt lgkmcnt(0)
	s_setprio 1
	v_mfma_f32_16x16x32_bf16 v[30:33], v[132:135], v[154:157], v[30:33]
	v_mfma_f32_16x16x32_bf16 v[26:29], v[136:139], v[154:157], v[26:29]
	v_mfma_f32_16x16x32_bf16 v[22:25], v[132:135], v[162:165], v[22:25]
	v_mfma_f32_16x16x32_bf16 v[18:21], v[136:139], v[162:165], v[18:21]
	v_mfma_f32_16x16x32_bf16 v[14:17], v[132:135], v[202:205], v[14:17]
	v_mfma_f32_16x16x32_bf16 v[10:13], v[136:139], v[202:205], v[10:13]
	v_mfma_f32_16x16x32_bf16 v[6:9], v[132:135], v[210:213], v[6:9]
	v_mfma_f32_16x16x32_bf16 v[2:5], v[136:139], v[210:213], v[2:5]
	v_mfma_f32_16x16x32_bf16 v[30:33], v[140:143], v[158:161], v[30:33]
	v_mfma_f32_16x16x32_bf16 v[26:29], v[150:153], v[158:161], v[26:29]
	v_mfma_f32_16x16x32_bf16 v[22:25], v[140:143], v[198:201], v[22:25]
	v_mfma_f32_16x16x32_bf16 v[18:21], v[150:153], v[198:201], v[18:21]
	v_mfma_f32_16x16x32_bf16 v[14:17], v[140:143], v[206:209], v[14:17]
	v_mfma_f32_16x16x32_bf16 v[10:13], v[150:153], v[206:209], v[10:13]
	v_mfma_f32_16x16x32_bf16 v[6:9], v[140:143], v[214:217], v[6:9]
	v_mfma_f32_16x16x32_bf16 v[2:5], v[150:153], v[214:217], v[2:5]
	s_setprio 0
	s_barrier
; #define STAGEA(P, br, kt) do { const char* _g = uptr(A + (size_t)(br) * lda + (size_t)(kt) * BK); \
;     _Pragma("unroll") for (int _i = 0; _i < 2; ++_i) { \
;       __builtin_amdgcn_global_load_lds((const unsigned*)(_g + offA[_i]), (unsigned*)((char*)(P) + tidx * 16 + _i * 8192), 16, 0, 0); } } while (0)
; #define STAGEB(P, br, kt) do { const char* _g = uptr(Bt + (size_t)(br) * ldb + (size_t)(kt) * BK); \
;     _Pragma("unroll") for (int _i = 0; _i < 2; ++_i) { \
;       __builtin_amdgcn_global_load_lds((const unsigned*)(_g + offB[_i]), (unsigned*)((char*)(P) + tidx * 16 + _i * 8192), 16, 0, 0); } } while (0)
; #define LDA(dst, b, h) _Pragma("unroll") for (int m = 0; m < 4; ++m) _Pragma("unroll") for (int k = 0; k < 2; ++k) \
;     dst[m][k] = *reinterpret_cast<const bf16x8*>((char*)SA(b, h) + aoff + m * 2048 + k * 1024)
; #define LDB(dst, b, h) _Pragma("unroll") for (int n = 0; n < 2; ++n) _Pragma("unroll") for (int k = 0; k < 2; ++k) \
;     dst[n][k] = *reinterpret_cast<const bf16x8*>((char*)SB(b, h) + boff + n * (SWAP ? 256 : 2048) + k * 1024)
; #define WAIT_V(n) asm volatile("s_waitcnt vmcnt(" #n ")" ::: "memory")
; #define WAIT_L(n) asm volatile("s_waitcnt lgkmcnt(" #n ")" ::: "memory")
; #define BAR __builtin_amdgcn_s_barrier()
; #define SCHED __builtin_amdgcn_sched_barrier(0)
; template <int EPI>
; DI void gemm_phase(const u16* __restrict__ A, int lda, const u16* __restrict__ Bt, int ldb,
;                    int M, int N, int K, const Epi& e, unsigned char* shmraw, int wv, int slot) {
;     ...
;       STAGEB(SB(0, 1), bcol + HALF, t + 2);
;       WAIT_V(6); BAR; MMA(1, 1, At, B1); BAR;
;       LDB(B0, 1, 0); SCHED; LDA(At, 1, 0); STAGEA(SA(0, 1), brow + HALF, t + 2);
;       WAIT_L(8); BAR; WAIT_L(0); MMA(0, 0, At, B0); BAR; SCHED;
;       LDB(B1, 1, 1); STAGEB(SB(1, 0), bcol, t + 3);
;       BAR; WAIT_L(0); MMA(0, 1, At, B1); BAR;
;       LDA(At, 1, 1); STAGEA(SA(1, 0), brow, t + 3);
;       BAR; WAIT_L(0); MMA(1, 0, At, B0); BAR; SCHED;
	s_add_u32 s97, s35, vcc_lo
	s_addc_u32 s42, s38, vcc_hi
	s_add_u32 s74, s97, 0x100
	s_addc_u32 s75, s42, 0
	v_readfirstlane_b32 s37, v173
	v_lshl_add_u64 v[132:133], s[74:75], 0, v[148:149]
	s_mov_b32 m0, s37
	v_readfirstlane_b32 s37, v174
	global_load_lds_dwordx4 v[132:133], off
	v_lshl_add_u64 v[132:133], s[74:75], 0, v[146:147]
	s_mov_b32 m0, s37
	s_nop 0
	global_load_lds_dwordx4 v[132:133], off
	s_waitcnt vmcnt(6)
	s_barrier
	s_setprio 1
	v_mfma_f32_16x16x32_bf16 v[54:57], v[218:221], v[154:157], v[54:57]
	v_mfma_f32_16x16x32_bf16 v[58:61], v[222:225], v[154:157], v[58:61]
	v_mfma_f32_16x16x32_bf16 v[66:69], v[218:221], v[162:165], v[66:69]
	v_mfma_f32_16x16x32_bf16 v[70:73], v[222:225], v[162:165], v[70:73]
	v_mfma_f32_16x16x32_bf16 v[74:77], v[218:221], v[202:205], v[74:77]
	v_mfma_f32_16x16x32_bf16 v[82:85], v[222:225], v[202:205], v[82:85]
	v_mfma_f32_16x16x32_bf16 v[86:89], v[218:221], v[210:213], v[86:89]
	v_mfma_f32_16x16x32_bf16 v[90:93], v[222:225], v[210:213], v[90:93]
	v_mfma_f32_16x16x32_bf16 v[54:57], v[226:229], v[158:161], v[54:57]
	v_mfma_f32_16x16x32_bf16 v[58:61], v[230:233], v[158:161], v[58:61]
	v_mfma_f32_16x16x32_bf16 v[66:69], v[226:229], v[198:201], v[66:69]
	v_mfma_f32_16x16x32_bf16 v[70:73], v[230:233], v[198:201], v[70:73]
	v_mfma_f32_16x16x32_bf16 v[74:77], v[226:229], v[206:209], v[74:77]
	v_mfma_f32_16x16x32_bf16 v[82:85], v[230:233], v[206:209], v[82:85]
	v_mfma_f32_16x16x32_bf16 v[86:89], v[226:229], v[214:217], v[86:89]
	v_mfma_f32_16x16x32_bf16 v[90:93], v[230:233], v[214:217], v[90:93]
	s_setprio 0
	v_add_u32_e32 v131, s85, v168
	s_barrier
	ds_read_b128 v[132:135], v131
	ds_read_b128 v[136:139], v131 offset:256
	ds_read_b128 v[140:143], v131 offset:1024
	ds_read_b128 v[150:153], v131 offset:1280
	s_add_u32 s74, s39, vcc_lo
	s_addc_u32 s75, s40, vcc_hi
	v_readfirstlane_b32 s37, v175
	v_lshl_add_u64 v[144:145], s[74:75], 0, v[148:149]
	s_mov_b32 m0, s37
	v_readfirstlane_b32 s37, v176
	ds_read_b128 v[154:157], v196 offset:32768
	ds_read_b128 v[158:161], v196 offset:33792
	ds_read_b128 v[162:165], v196 offset:34816
	ds_read_b128 v[198:201], v196 offset:35840
	ds_read_b128 v[202:205], v196 offset:36864
	ds_read_b128 v[206:209], v196 offset:37888
	ds_read_b128 v[210:213], v196 offset:38912
	ds_read_b128 v[214:217], v196 offset:39936
	global_load_lds_dwordx4 v[144:145], off
	v_lshl_add_u64 v[144:145], s[74:75], 0, v[146:147]
	s_mov_b32 m0, s37
	s_nop 0
	global_load_lds_dwordx4 v[144:145], off
	s_waitcnt lgkmcnt(8)
	s_barrier
	s_waitcnt lgkmcnt(0)
	s_setprio 1
	v_mfma_f32_16x16x32_bf16 v[126:129], v[132:135], v[154:157], v[126:129]
	v_mfma_f32_16x16x32_bf16 v[122:125], v[136:139], v[154:157], v[122:125]
	v_mfma_f32_16x16x32_bf16 v[118:121], v[132:135], v[162:165], v[118:121]
	v_mfma_f32_16x16x32_bf16 v[114:117], v[136:139], v[162:165], v[114:117]
	v_mfma_f32_16x16x32_bf16 v[110:113], v[132:135], v[202:205], v[110:113]
	v_mfma_f32_16x16x32_bf16 v[106:109], v[136:139], v[202:205], v[106:109]
	v_mfma_f32_16x16x32_bf16 v[102:105], v[132:135], v[210:213], v[102:105]
	v_mfma_f32_16x16x32_bf16 v[98:101], v[136:139], v[210:213], v[98:101]
	v_mfma_f32_16x16x32_bf16 v[126:129], v[140:143], v[158:161], v[126:129]
	v_mfma_f32_16x16x32_bf16 v[122:125], v[150:153], v[158:161], v[122:125]
	v_mfma_f32_16x16x32_bf16 v[118:121], v[140:143], v[198:201], v[118:121]
	v_mfma_f32_16x16x32_bf16 v[114:117], v[150:153], v[198:201], v[114:117]
	v_mfma_f32_16x16x32_bf16 v[110:113], v[140:143], v[206:209], v[110:113]
	v_mfma_f32_16x16x32_bf16 v[106:109], v[150:153], v[206:209], v[106:109]
	v_mfma_f32_16x16x32_bf16 v[102:105], v[140:143], v[214:217], v[102:105]
	v_mfma_f32_16x16x32_bf16 v[98:101], v[150:153], v[214:217], v[98:101]
	s_setprio 0
	s_barrier
	s_add_u32 s74, s54, 0x180
	s_addc_u32 s75, s55, 0
	v_readfirstlane_b32 s37, v177
	v_add_u32_e32 v131, s86, v168
	v_lshl_add_u64 v[144:145], s[74:75], 0, v[148:149]
	s_mov_b32 m0, s37
	v_readfirstlane_b32 s37, v178
	ds_read_b128 v[218:221], v131
	ds_read_b128 v[222:225], v131 offset:256
	ds_read_b128 v[226:229], v131 offset:1024
	ds_read_b128 v[230:233], v131 offset:1280
	global_load_lds_dwordx4 v[144:145], off
	v_lshl_add_u64 v[144:145], s[74:75], 0, v[146:147]
	s_mov_b32 m0, s37
	s_nop 0
	global_load_lds_dwordx4 v[144:145], off
	s_barrier
	s_waitcnt lgkmcnt(0)
	s_setprio 1
	v_mfma_f32_16x16x32_bf16 v[94:97], v[218:221], v[154:157], v[94:97]
	v_mfma_f32_16x16x32_bf16 v[78:81], v[222:225], v[154:157], v[78:81]
	v_mfma_f32_16x16x32_bf16 v[62:65], v[218:221], v[162:165], v[62:65]
	v_mfma_f32_16x16x32_bf16 v[50:53], v[222:225], v[162:165], v[50:53]
	v_mfma_f32_16x16x32_bf16 v[46:49], v[218:221], v[202:205], v[46:49]
	v_mfma_f32_16x16x32_bf16 v[42:45], v[222:225], v[202:205], v[42:45]
	v_mfma_f32_16x16x32_bf16 v[38:41], v[218:221], v[210:213], v[38:41]
	v_mfma_f32_16x16x32_bf16 v[34:37], v[222:225], v[210:213], v[34:37]
	v_mfma_f32_16x16x32_bf16 v[94:97], v[226:229], v[158:161], v[94:97]
	v_mfma_f32_16x16x32_bf16 v[78:81], v[230:233], v[158:161], v[78:81]
	v_mfma_f32_16x16x32_bf16 v[62:65], v[226:229], v[198:201], v[62:65]
	v_mfma_f32_16x16x32_bf16 v[50:53], v[230:233], v[198:201], v[50:53]
	v_mfma_f32_16x16x32_bf16 v[46:49], v[226:229], v[206:209], v[46:49]
	v_mfma_f32_16x16x32_bf16 v[42:45], v[230:233], v[206:209], v[42:45]
	v_mfma_f32_16x16x32_bf16 v[38:41], v[226:229], v[214:217], v[38:41]
	v_mfma_f32_16x16x32_bf16 v[34:37], v[230:233], v[214:217], v[34:37]
	s_setprio 0
	s_add_u32 s74, s90, 0x180
	s_addc_u32 s75, s91, 0
	v_readfirstlane_b32 s37, v179
	v_lshl_add_u64 v[144:145], s[74:75], 0, v[148:149]
	s_mov_b32 m0, s37
	v_readfirstlane_b32 s37, v193
	s_barrier
; #define STAGEA(P, br, kt) do { const char* _g = uptr(A + (size_t)(br) * lda + (size_t)(kt) * BK); \
;     _Pragma("unroll") for (int _i = 0; _i < 2; ++_i) { \
;       __builtin_amdgcn_global_load_lds((const unsigned*)(_g + offA[_i]), (unsigned*)((char*)(P) + tidx * 16 + _i * 8192), 16, 0, 0); } } while (0)
; #define STAGEB(P, br, kt) do { const char* _g = uptr(Bt + (size_t)(br) * ldb + (size_t)(kt) * BK); \
;     _Pragma("unroll") for (int _i = 0; _i < 2; ++_i) { \
;       __builtin_amdgcn_global_load_lds((const unsigned*)(_g + offB[_i]), (unsigned*)((char*)(P) + tidx * 16 + _i * 8192), 16, 0, 0); } } while (0)
; #define LDA(dst, b, h) _Pragma("unroll") for (int m = 0; m < 4; ++m) _Pragma("unroll") for (int k = 0; k < 2; ++k) \
;     dst[m][k] = *reinterpret_cast<const bf16x8*>((char*)SA(b, h) + aoff + m * 2048 + k * 1024)
; #define LDB(dst, b, h) _Pragma("unroll") for (int n = 0; n < 2; ++n) _Pragma("unroll") for (int k = 0; k < 2; ++k) \
;     dst[n][k] = *reinterpret_cast<const bf16x8*>((char*)SB(b, h) + boff + n * (SWAP ? 256 : 2048) + k * 1024)
; #define WAIT_V(n) asm volatile("s_waitcnt vmcnt(" #n ")" ::: "memory")
; #define WAIT_L(n) asm volatile("s_waitcnt lgkmcnt(" #n ")" ::: "memory")
; #define BAR __builtin_amdgcn_s_barrier()
; #define SCHED __builtin_amdgcn_sched_barrier(0)
; template <int EPI>
; DI void gemm_phase(const u16* __restrict__ A, int lda, const u16* __restrict__ Bt, int ldb,
;                    int M, int N, int K, const Epi& e, unsigned char* shmraw, int wv, int slot) {
;     ...
;       BAR; WAIT_L(0); MMA(0, 1, At, B1); BAR;
;       LDA(At, 1, 1); STAGEA(SA(1, 0), brow, t + 3);
;       BAR; WAIT_L(0); MMA(1, 0, At, B0); BAR; SCHED;
;       STAGEB(SB(1, 1), bcol + HALF, t + 3);
;       WAIT_V(6); BAR; MMA(1, 1, At, B1); BAR;
;     }
;     { LDB(B0, 0, 0); LDA(At, 0, 0); STAGEA(SA(1, 1), brow + HALF, nt - 1);
;       BAR; WAIT_L(0); MMA(0, 0, At, B0); BAR;
	ds_read_b128 v[154:157], v196 offset:49152
	ds_read_b128 v[158:161], v196 offset:50176
	ds_read_b128 v[162:165], v196 offset:51200
	ds_read_b128 v[198:201], v196 offset:52224
	ds_read_b128 v[202:205], v196 offset:53248
	ds_read_b128 v[206:209], v196 offset:54272
	ds_read_b128 v[210:213], v196 offset:55296
	ds_read_b128 v[214:217], v196 offset:56320
	global_load_lds_dwordx4 v[144:145], off
	v_lshl_add_u64 v[144:145], s[74:75], 0, v[146:147]
	s_mov_b32 m0, s37
	s_nop 0
	global_load_lds_dwordx4 v[144:145], off
	s_barrier
	s_waitcnt lgkmcnt(0)
	s_setprio 1
	v_mfma_f32_16x16x32_bf16 v[30:33], v[132:135], v[154:157], v[30:33]
	v_mfma_f32_16x16x32_bf16 v[26:29], v[136:139], v[154:157], v[26:29]
	v_mfma_f32_16x16x32_bf16 v[22:25], v[132:135], v[162:165], v[22:25]
	v_mfma_f32_16x16x32_bf16 v[18:21], v[136:139], v[162:165], v[18:21]
	v_mfma_f32_16x16x32_bf16 v[14:17], v[132:135], v[202:205], v[14:17]
	v_mfma_f32_16x16x32_bf16 v[10:13], v[136:139], v[202:205], v[10:13]
	v_mfma_f32_16x16x32_bf16 v[6:9], v[132:135], v[210:213], v[6:9]
	v_mfma_f32_16x16x32_bf16 v[2:5], v[136:139], v[210:213], v[2:5]
	v_mfma_f32_16x16x32_bf16 v[30:33], v[140:143], v[158:161], v[30:33]
	v_mfma_f32_16x16x32_bf16 v[26:29], v[150:153], v[158:161], v[26:29]
	v_mfma_f32_16x16x32_bf16 v[22:25], v[140:143], v[198:201], v[22:25]
	v_mfma_f32_16x16x32_bf16 v[18:21], v[150:153], v[198:201], v[18:21]
	v_mfma_f32_16x16x32_bf16 v[14:17], v[140:143], v[206:209], v[14:17]
	v_mfma_f32_16x16x32_bf16 v[10:13], v[150:153], v[206:209], v[10:13]
	v_mfma_f32_16x16x32_bf16 v[6:9], v[140:143], v[214:217], v[6:9]
	v_mfma_f32_16x16x32_bf16 v[2:5], v[150:153], v[214:217], v[2:5]
	s_setprio 0
	s_barrier
	s_add_u32 s74, s97, 0x180
	s_addc_u32 s75, s42, 0
	v_readfirstlane_b32 s37, v194
	v_lshl_add_u64 v[132:133], s[74:75], 0, v[148:149]
	s_mov_b32 m0, s37
	v_readfirstlane_b32 s37, v195
	global_load_lds_dwordx4 v[132:133], off
	v_lshl_add_u64 v[132:133], s[74:75], 0, v[146:147]
	s_mov_b32 m0, s37
	s_nop 0
	global_load_lds_dwordx4 v[132:133], off
	s_waitcnt vmcnt(6)
	s_barrier
	s_setprio 1
	v_mfma_f32_16x16x32_bf16 v[54:57], v[218:221], v[154:157], v[54:57]
	v_mfma_f32_16x16x32_bf16 v[58:61], v[222:225], v[154:157], v[58:61]
	v_mfma_f32_16x16x32_bf16 v[66:69], v[218:221], v[162:165], v[66:69]
	v_mfma_f32_16x16x32_bf16 v[70:73], v[222:225], v[162:165], v[70:73]
	v_mfma_f32_16x16x32_bf16 v[74:77], v[218:221], v[202:205], v[74:77]
	v_mfma_f32_16x16x32_bf16 v[82:85], v[222:225], v[202:205], v[82:85]
	v_mfma_f32_16x16x32_bf16 v[86:89], v[218:221], v[210:213], v[86:89]
	v_mfma_f32_16x16x32_bf16 v[90:93], v[222:225], v[210:213], v[90:93]
	v_mfma_f32_16x16x32_bf16 v[54:57], v[226:229], v[158:161], v[54:57]
	v_mfma_f32_16x16x32_bf16 v[58:61], v[230:233], v[158:161], v[58:61]
	v_mfma_f32_16x16x32_bf16 v[66:69], v[226:229], v[198:201], v[66:69]
	v_mfma_f32_16x16x32_bf16 v[70:73], v[230:233], v[198:201], v[70:73]
	v_mfma_f32_16x16x32_bf16 v[74:77], v[226:229], v[206:209], v[74:77]
	v_mfma_f32_16x16x32_bf16 v[82:85], v[230:233], v[206:209], v[82:85]
	v_mfma_f32_16x16x32_bf16 v[86:89], v[226:229], v[214:217], v[86:89]
	v_mfma_f32_16x16x32_bf16 v[90:93], v[230:233], v[214:217], v[90:93]
	s_setprio 0
	s_add_i32 s36, s36, 2
	s_add_u32 vcc_lo, vcc_lo, 0x100
	s_addc_u32 vcc_hi, vcc_hi, 0
	s_cmp_lt_u32 s36, 12
	s_barrier
	s_cbranch_scc1 .LBB0_690
	s_add_u32 s38, s9, 0x780
	v_add_u32_e32 v166, 16, v168
	s_addc_u32 s39, s13, 0
	v_readfirstlane_b32 s1, v0
	v_add_u32_e32 v131, 0x10000, v166
	v_lshl_add_u64 v[144:145], s[38:39], 0, v[148:149]
	s_mov_b32 m0, s1
	v_readfirstlane_b32 s1, v130
	ds_read_b128 v[132:135], v131
	ds_read_b128 v[136:139], v131 offset:256
	ds_read_b128 v[140:143], v131 offset:1024
	ds_read_b128 v[150:153], v131 offset:1280
	ds_read_b128 v[154:157], v196
	ds_read_b128 v[158:161], v196 offset:1024
	ds_read_b128 v[162:165], v196 offset:2048
	ds_read_b128 v[198:201], v196 offset:3072
	ds_read_b128 v[202:205], v196 offset:4096
	ds_read_b128 v[206:209], v196 offset:5120
	ds_read_b128 v[210:213], v196 offset:6144
	ds_read_b128 v[214:217], v196 offset:7168
	global_load_lds_dwordx4 v[144:145], off
	v_lshl_add_u64 v[144:145], s[38:39], 0, v[146:147]
	s_mov_b32 m0, s1
	s_nop 0
	global_load_lds_dwordx4 v[144:145], off
	s_barrier
	s_waitcnt lgkmcnt(0)
	s_setprio 1
	v_mfma_f32_16x16x32_bf16 v[126:129], v[132:135], v[154:157], v[126:129]
	v_mfma_f32_16x16x32_bf16 v[118:121], v[132:135], v[162:165], v[118:121]
	v_mfma_f32_16x16x32_bf16 v[114:117], v[136:139], v[162:165], v[114:117]
	v_mfma_f32_16x16x32_bf16 v[106:109], v[136:139], v[202:205], v[106:109]
	v_mfma_f32_16x16x32_bf16 v[98:101], v[136:139], v[210:213], v[98:101]
	v_mfma_f32_16x16x32_bf16 v[126:129], v[140:143], v[158:161], v[126:129]
	v_mfma_f32_16x16x32_bf16 v[122:125], v[136:139], v[154:157], v[122:125]
	v_mfma_f32_16x16x32_bf16 v[118:121], v[140:143], v[198:201], v[118:121]
	v_mfma_f32_16x16x32_bf16 v[114:117], v[150:153], v[198:201], v[114:117]
	v_mfma_f32_16x16x32_bf16 v[110:113], v[132:135], v[202:205], v[110:113]
	v_mfma_f32_16x16x32_bf16 v[106:109], v[150:153], v[206:209], v[106:109]
	v_mfma_f32_16x16x32_bf16 v[102:105], v[132:135], v[210:213], v[102:105]
	v_mfma_f32_16x16x32_bf16 v[98:101], v[150:153], v[214:217], v[98:101]
	v_mfma_f32_16x16x32_bf16 v[218:221], v[150:153], v[158:161], v[122:125]
	v_mfma_f32_16x16x32_bf16 v[222:225], v[140:143], v[206:209], v[110:113]
	v_mfma_f32_16x16x32_bf16 v[226:229], v[140:143], v[214:217], v[102:105]
	s_setprio 0
	v_add_u32_e32 v0, 0x14000, v166
	s_barrier
	s_nop 0
	ds_read_b128 v[102:105], v0
	ds_read_b128 v[110:113], v0 offset:256
	ds_read_b128 v[122:125], v0 offset:1024
	ds_read_b128 v[230:233], v0 offset:1280
	s_barrier
; #define LDA(dst, b, h) _Pragma("unroll") for (int m = 0; m < 4; ++m) _Pragma("unroll") for (int k = 0; k < 2; ++k) \
;     dst[m][k] = *reinterpret_cast<const bf16x8*>((char*)SA(b, h) + aoff + m * 2048 + k * 1024)
; #define LDB(dst, b, h) _Pragma("unroll") for (int n = 0; n < 2; ++n) _Pragma("unroll") for (int k = 0; k < 2; ++k) \
;     dst[n][k] = *reinterpret_cast<const bf16x8*>((char*)SB(b, h) + boff + n * (SWAP ? 256 : 2048) + k * 1024)
; #define WAIT_V(n) asm volatile("s_waitcnt vmcnt(" #n ")" ::: "memory")
; #define WAIT_L(n) asm volatile("s_waitcnt lgkmcnt(" #n ")" ::: "memory")
; #define BAR __builtin_amdgcn_s_barrier()
; template <int EPI>
; DI void gemm_phase(const u16* __restrict__ A, int lda, const u16* __restrict__ Bt, int ldb,
;                    int M, int N, int K, const Epi& e, unsigned char* shmraw, int wv, int slot) {
;     ...
;       BAR; WAIT_L(0); MMA(0, 0, At, B0); BAR;
;       LDB(B1, 0, 1); BAR; WAIT_L(0); MMA(0, 1, At, B1); BAR;
;       LDA(At, 0, 1); WAIT_V(4); BAR; WAIT_L(0); MMA(1, 0, At, B0); MMA(1, 1, At, B1); BAR; }
;     { LDB(B0, 1, 0); LDA(At, 1, 0); WAIT_V(2); BAR; WAIT_L(0); MMA(0, 0, At, B0); BAR;
	s_waitcnt lgkmcnt(0)
	s_setprio 1
	v_mfma_f32_16x16x32_bf16 v[62:65], v[102:105], v[162:165], v[62:65]
	v_mfma_f32_16x16x32_bf16 v[50:53], v[110:113], v[162:165], v[50:53]
	v_mfma_f32_16x16x32_bf16 v[46:49], v[102:105], v[202:205], v[46:49]
	v_mfma_f32_16x16x32_bf16 v[42:45], v[110:113], v[202:205], v[42:45]
	v_mfma_f32_16x16x32_bf16 v[38:41], v[102:105], v[210:213], v[38:41]
	v_mfma_f32_16x16x32_bf16 v[34:37], v[110:113], v[210:213], v[34:37]
	v_mfma_f32_16x16x32_bf16 v[94:97], v[102:105], v[154:157], v[94:97]
	v_mfma_f32_16x16x32_bf16 v[78:81], v[110:113], v[154:157], v[78:81]
	v_mfma_f32_16x16x32_bf16 v[62:65], v[122:125], v[198:201], v[62:65]
	v_mfma_f32_16x16x32_bf16 v[50:53], v[230:233], v[198:201], v[50:53]
	v_mfma_f32_16x16x32_bf16 v[46:49], v[122:125], v[206:209], v[46:49]
	v_mfma_f32_16x16x32_bf16 v[42:45], v[230:233], v[206:209], v[42:45]
	v_mfma_f32_16x16x32_bf16 v[38:41], v[122:125], v[214:217], v[38:41]
	v_mfma_f32_16x16x32_bf16 v[34:37], v[230:233], v[214:217], v[34:37]
	v_mfma_f32_16x16x32_bf16 v[234:237], v[122:125], v[158:161], v[94:97]
	v_mfma_f32_16x16x32_bf16 v[154:157], v[230:233], v[158:161], v[78:81]
	s_setprio 0
	s_barrier
	s_nop 0
	ds_read_b128 v[78:81], v196 offset:16384
	ds_read_b128 v[94:97], v196 offset:17408
	ds_read_b128 v[158:161], v196 offset:18432
	ds_read_b128 v[162:165], v196 offset:19456
	ds_read_b128 v[198:201], v196 offset:20480
	ds_read_b128 v[202:205], v196 offset:21504
	ds_read_b128 v[206:209], v196 offset:22528
	ds_read_b128 v[210:213], v196 offset:23552
	s_waitcnt vmcnt(4)
	s_barrier
	s_waitcnt lgkmcnt(0)
	s_setprio 1
	v_mfma_f32_16x16x32_bf16 v[30:33], v[132:135], v[78:81], v[30:33]
	v_mfma_f32_16x16x32_bf16 v[26:29], v[136:139], v[78:81], v[26:29]
	v_mfma_f32_16x16x32_bf16 v[22:25], v[132:135], v[158:161], v[22:25]
	v_mfma_f32_16x16x32_bf16 v[18:21], v[136:139], v[158:161], v[18:21]
	v_mfma_f32_16x16x32_bf16 v[14:17], v[132:135], v[198:201], v[14:17]
	v_mfma_f32_16x16x32_bf16 v[10:13], v[136:139], v[198:201], v[10:13]
	v_mfma_f32_16x16x32_bf16 v[6:9], v[132:135], v[206:209], v[6:9]
	v_mfma_f32_16x16x32_bf16 v[2:5], v[136:139], v[206:209], v[2:5]
	v_mfma_f32_16x16x32_bf16 v[30:33], v[140:143], v[94:97], v[30:33]
	v_mfma_f32_16x16x32_bf16 v[26:29], v[150:153], v[94:97], v[26:29]
	v_mfma_f32_16x16x32_bf16 v[22:25], v[140:143], v[162:165], v[22:25]
	v_mfma_f32_16x16x32_bf16 v[18:21], v[150:153], v[162:165], v[18:21]
	v_mfma_f32_16x16x32_bf16 v[14:17], v[140:143], v[202:205], v[14:17]
	v_mfma_f32_16x16x32_bf16 v[10:13], v[150:153], v[202:205], v[10:13]
	v_mfma_f32_16x16x32_bf16 v[6:9], v[140:143], v[210:213], v[6:9]
	v_mfma_f32_16x16x32_bf16 v[2:5], v[150:153], v[210:213], v[2:5]
	s_setprio 0
	s_setprio 1
	v_mfma_f32_16x16x32_bf16 v[58:61], v[110:113], v[78:81], v[58:61]
	v_mfma_f32_16x16x32_bf16 v[130:133], v[230:233], v[94:97], v[58:61]
	v_mfma_f32_16x16x32_bf16 v[58:61], v[102:105], v[158:161], v[66:69]
	v_mfma_f32_16x16x32_bf16 v[134:137], v[122:125], v[162:165], v[58:61]
	v_mfma_f32_16x16x32_bf16 v[58:61], v[110:113], v[158:161], v[70:73]
	v_mfma_f32_16x16x32_bf16 v[138:141], v[230:233], v[162:165], v[58:61]
	v_mfma_f32_16x16x32_bf16 v[58:61], v[102:105], v[198:201], v[74:77]
	v_mfma_f32_16x16x32_bf16 v[142:145], v[122:125], v[202:205], v[58:61]
	v_mfma_f32_16x16x32_bf16 v[58:61], v[110:113], v[198:201], v[82:85]
	v_mfma_f32_16x16x32_bf16 v[54:57], v[102:105], v[78:81], v[54:57]
	v_mfma_f32_16x16x32_bf16 v[150:153], v[230:233], v[202:205], v[58:61]
	v_mfma_f32_16x16x32_bf16 v[58:61], v[102:105], v[206:209], v[86:89]
	v_mfma_f32_16x16x32_bf16 v[54:57], v[122:125], v[94:97], v[54:57]
	v_mfma_f32_16x16x32_bf16 v[158:161], v[122:125], v[210:213], v[58:61]
	v_mfma_f32_16x16x32_bf16 v[58:61], v[110:113], v[206:209], v[90:93]
	v_mfma_f32_16x16x32_bf16 v[162:165], v[230:233], v[210:213], v[58:61]
	s_setprio 0
	v_add_u32_e32 v0, 0x18000, v166
	s_barrier
	ds_read_b128 v[198:201], v0
	ds_read_b128 v[202:205], v0 offset:256
	ds_read_b128 v[206:209], v0 offset:1024
	ds_read_b128 v[210:213], v0 offset:1280
	ds_read_b128 v[58:61], v196 offset:32768
	ds_read_b128 v[66:69], v196 offset:33792
	ds_read_b128 v[74:77], v196 offset:34816
	ds_read_b128 v[82:85], v196 offset:35840
	ds_read_b128 v[86:89], v196 offset:36864
	ds_read_b128 v[214:217], v196 offset:37888
	ds_read_b128 v[230:233], v196 offset:38912
	ds_read_b128 v[238:241], v196 offset:39936
	s_waitcnt vmcnt(2)
	s_barrier
; #define LDA(dst, b, h) _Pragma("unroll") for (int m = 0; m < 4; ++m) _Pragma("unroll") for (int k = 0; k < 2; ++k) \
;     dst[m][k] = *reinterpret_cast<const bf16x8*>((char*)SA(b, h) + aoff + m * 2048 + k * 1024)
; #define LDB(dst, b, h) _Pragma("unroll") for (int n = 0; n < 2; ++n) _Pragma("unroll") for (int k = 0; k < 2; ++k) \
;     dst[n][k] = *reinterpret_cast<const bf16x8*>((char*)SB(b, h) + boff + n * (SWAP ? 256 : 2048) + k * 1024)
; #define WAIT_V(n) asm volatile("s_waitcnt vmcnt(" #n ")" ::: "memory")
; #define WAIT_L(n) asm volatile("s_waitcnt lgkmcnt(" #n ")" ::: "memory")
; #define BAR __builtin_amdgcn_s_barrier()
; template <int EPI>
; DI void gemm_phase(const u16* __restrict__ A, int lda, const u16* __restrict__ Bt, int ldb,
;                    int M, int N, int K, const Epi& e, unsigned char* shmraw, int wv, int slot) {
;     ...
;     { LDB(B0, 1, 0); LDA(At, 1, 0); WAIT_V(2); BAR; WAIT_L(0); MMA(0, 0, At, B0); BAR;
;       LDB(B1, 1, 1); WAIT_V(0); BAR; WAIT_L(0); MMA(0, 1, At, B1); BAR;
;       LDA(At, 1, 1); BAR; WAIT_L(0); MMA(1, 0, At, B0); MMA(1, 1, At, B1); BAR; }
;     if (wr == 0) BAR;
	s_waitcnt lgkmcnt(0)
	s_setprio 1
	v_mfma_f32_16x16x32_bf16 v[70:73], v[198:201], v[58:61], v[126:129]
	v_mfma_f32_16x16x32_bf16 v[122:125], v[206:209], v[66:69], v[70:73]
	v_mfma_f32_16x16x32_bf16 v[70:73], v[202:205], v[58:61], v[218:221]
	v_mfma_f32_16x16x32_bf16 v[126:129], v[210:213], v[66:69], v[70:73]
	v_mfma_f32_16x16x32_bf16 v[70:73], v[198:201], v[74:77], v[118:121]
	v_mfma_f32_16x16x32_bf16 v[102:105], v[206:209], v[82:85], v[70:73]
	v_mfma_f32_16x16x32_bf16 v[70:73], v[202:205], v[74:77], v[114:117]
	v_mfma_f32_16x16x32_bf16 v[110:113], v[210:213], v[82:85], v[70:73]
	v_mfma_f32_16x16x32_bf16 v[70:73], v[198:201], v[86:89], v[222:225]
	v_mfma_f32_16x16x32_bf16 v[90:93], v[206:209], v[214:217], v[70:73]
	v_mfma_f32_16x16x32_bf16 v[70:73], v[202:205], v[86:89], v[106:109]
	v_mfma_f32_16x16x32_bf16 v[94:97], v[210:213], v[214:217], v[70:73]
	v_mfma_f32_16x16x32_bf16 v[70:73], v[198:201], v[230:233], v[226:229]
	v_mfma_f32_16x16x32_bf16 v[78:81], v[202:205], v[230:233], v[98:101]
	v_mfma_f32_16x16x32_bf16 v[70:73], v[206:209], v[238:241], v[70:73]
	v_mfma_f32_16x16x32_bf16 v[78:81], v[210:213], v[238:241], v[78:81]
	s_setprio 0
	v_add_u32_e32 v0, 0x1c000, v166
	s_barrier
	ds_read_b128 v[218:221], v0
	ds_read_b128 v[222:225], v0 offset:256
	ds_read_b128 v[226:229], v0 offset:1024
	ds_read_b128 v[242:245], v0 offset:1280
	s_waitcnt vmcnt(0)
	s_barrier
	s_waitcnt lgkmcnt(0)
	s_setprio 1
	v_mfma_f32_16x16x32_bf16 v[98:101], v[218:221], v[58:61], v[234:237]
	v_mfma_f32_16x16x32_bf16 v[58:61], v[222:225], v[58:61], v[154:157]
	v_mfma_f32_16x16x32_bf16 v[118:121], v[242:245], v[66:69], v[58:61]
	v_mfma_f32_16x16x32_bf16 v[58:61], v[218:221], v[74:77], v[62:65]
	v_mfma_f32_16x16x32_bf16 v[50:53], v[222:225], v[74:77], v[50:53]
	v_mfma_f32_16x16x32_bf16 v[46:49], v[218:221], v[86:89], v[46:49]
	v_mfma_f32_16x16x32_bf16 v[42:45], v[222:225], v[86:89], v[42:45]
	v_mfma_f32_16x16x32_bf16 v[38:41], v[218:221], v[230:233], v[38:41]
	v_mfma_f32_16x16x32_bf16 v[34:37], v[222:225], v[230:233], v[34:37]
	v_mfma_f32_16x16x32_bf16 v[114:117], v[226:229], v[66:69], v[98:101]
	v_mfma_f32_16x16x32_bf16 v[98:101], v[226:229], v[82:85], v[58:61]
	v_mfma_f32_16x16x32_bf16 v[106:109], v[242:245], v[82:85], v[50:53]
	v_mfma_f32_16x16x32_bf16 v[82:85], v[226:229], v[214:217], v[46:49]
	v_mfma_f32_16x16x32_bf16 v[86:89], v[242:245], v[214:217], v[42:45]
	v_mfma_f32_16x16x32_bf16 v[66:69], v[226:229], v[238:241], v[38:41]
	v_mfma_f32_16x16x32_bf16 v[74:77], v[242:245], v[238:241], v[34:37]
	s_setprio 0
	s_barrier
	s_nop 0
	ds_read_b128 v[34:37], v196 offset:49152
	ds_read_b128 v[38:41], v196 offset:50176
	ds_read_b128 v[154:157], v196 offset:51200
	ds_read_b128 v[214:217], v196 offset:52224
	ds_read_b128 v[230:233], v196 offset:53248
	ds_read_b128 v[234:237], v196 offset:54272
	ds_read_b128 v[238:241], v196 offset:55296
	ds_read_b128 v[246:249], v196 offset:56320
	s_barrier
	s_waitcnt lgkmcnt(0)
	s_setprio 1
	v_mfma_f32_16x16x32_bf16 v[30:33], v[198:201], v[34:37], v[30:33]
	v_mfma_f32_16x16x32_bf16 v[26:29], v[202:205], v[34:37], v[26:29]
	v_mfma_f32_16x16x32_bf16 v[22:25], v[198:201], v[154:157], v[22:25]
	v_mfma_f32_16x16x32_bf16 v[18:21], v[202:205], v[154:157], v[18:21]
	v_mfma_f32_16x16x32_bf16 v[14:17], v[198:201], v[230:233], v[14:17]
	v_mfma_f32_16x16x32_bf16 v[10:13], v[202:205], v[230:233], v[10:13]
	v_mfma_f32_16x16x32_bf16 v[6:9], v[198:201], v[238:241], v[6:9]
	v_mfma_f32_16x16x32_bf16 v[2:5], v[202:205], v[238:241], v[2:5]
	v_mfma_f32_16x16x32_bf16 v[58:61], v[206:209], v[38:41], v[30:33]
	v_mfma_f32_16x16x32_bf16 v[62:65], v[210:213], v[38:41], v[26:29]
	v_mfma_f32_16x16x32_bf16 v[42:45], v[206:209], v[214:217], v[22:25]
	v_mfma_f32_16x16x32_bf16 v[46:49], v[210:213], v[214:217], v[18:21]
	v_mfma_f32_16x16x32_bf16 v[26:29], v[206:209], v[234:237], v[14:17]
	v_mfma_f32_16x16x32_bf16 v[30:33], v[210:213], v[234:237], v[10:13]
	v_mfma_f32_16x16x32_bf16 v[10:13], v[206:209], v[246:249], v[6:9]
	v_mfma_f32_16x16x32_bf16 v[14:17], v[210:213], v[246:249], v[2:5]
	s_setprio 0
	s_setprio 1
	v_mfma_f32_16x16x32_bf16 v[2:5], v[218:221], v[34:37], v[54:57]
	v_mfma_f32_16x16x32_bf16 v[50:53], v[226:229], v[38:41], v[2:5]
	v_mfma_f32_16x16x32_bf16 v[2:5], v[222:225], v[34:37], v[130:133]
	v_mfma_f32_16x16x32_bf16 v[54:57], v[242:245], v[38:41], v[2:5]
	v_mfma_f32_16x16x32_bf16 v[2:5], v[218:221], v[154:157], v[134:137]
	v_mfma_f32_16x16x32_bf16 v[34:37], v[226:229], v[214:217], v[2:5]
	v_mfma_f32_16x16x32_bf16 v[2:5], v[222:225], v[154:157], v[138:141]
	v_mfma_f32_16x16x32_bf16 v[38:41], v[242:245], v[214:217], v[2:5]
	v_mfma_f32_16x16x32_bf16 v[2:5], v[218:221], v[230:233], v[142:145]
	v_mfma_f32_16x16x32_bf16 v[18:21], v[226:229], v[234:237], v[2:5]
	v_mfma_f32_16x16x32_bf16 v[2:5], v[222:225], v[230:233], v[150:153]
	v_mfma_f32_16x16x32_bf16 v[22:25], v[242:245], v[234:237], v[2:5]
	v_mfma_f32_16x16x32_bf16 v[2:5], v[218:221], v[238:241], v[158:161]
	v_mfma_f32_16x16x32_bf16 v[6:9], v[222:225], v[238:241], v[162:165]
	v_mfma_f32_16x16x32_bf16 v[2:5], v[226:229], v[246:249], v[2:5]
	v_mfma_f32_16x16x32_bf16 v[6:9], v[242:245], v[246:249], v[6:9]
	s_setprio 0
	s_barrier
	s_and_saveexec_b64 vcc, s[6:7]
	s_cbranch_execz .LBB0_693
	s_barrier

; #define STAGEA(P, br, kt) do { const char* _g = uptr(A + (size_t)(br) * lda + (size_t)(kt) * BK); \
;     _Pragma("unroll") for (int _i = 0; _i < 2; ++_i) { \
;       __builtin_amdgcn_global_load_lds((const unsigned*)(_g + offA[_i]), (unsigned*)((char*)(P) + tidx * 16 + _i * 8192), 16, 0, 0); } } while (0)
; #define STAGEB(P, br, kt) do { const char* _g = uptr(Bt + (size_t)(br) * ldb + (size_t)(kt) * BK); \
;     _Pragma("unroll") for (int _i = 0; _i < 2; ++_i) { \
;       __builtin_amdgcn_global_load_lds((const unsigned*)(_g + offB[_i]), (unsigned*)((char*)(P) + tidx * 16 + _i * 8192), 16, 0, 0); } } while (0)
; #define LDA(dst, b, h) _Pragma("unroll") for (int m = 0; m < 4; ++m) _Pragma("unroll") for (int k = 0; k < 2; ++k) \
;     dst[m][k] = *reinterpret_cast<const bf16x8*>((char*)SA(b, h) + aoff + m * 2048 + k * 1024)
; #define LDB(dst, b, h) _Pragma("unroll") for (int n = 0; n < 2; ++n) _Pragma("unroll") for (int k = 0; k < 2; ++k) \
;     dst[n][k] = *reinterpret_cast<const bf16x8*>((char*)SB(b, h) + boff + n * (SWAP ? 256 : 2048) + k * 1024)
; #define WAIT_V(n) asm volatile("s_waitcnt vmcnt(" #n ")" ::: "memory")
; #define WAIT_L(n) asm volatile("s_waitcnt lgkmcnt(" #n ")" ::: "memory")
; #define BAR __builtin_amdgcn_s_barrier()
; #define SCHED __builtin_amdgcn_sched_barrier(0)
; template <int EPI>
; DI void gemm_phase(const u16* __restrict__ A, int lda, const u16* __restrict__ Bt, int ldb,
;                    int M, int N, int K, const Epi& e, unsigned char* shmraw, int wv, int slot) {
;     ...
;     for (int t = 0; t < nt - 2; t += 2) {
;       LDB(B0, 0, 0); SCHED; LDA(At, 0, 0); STAGEA(SA(1, 1), brow + HALF, t + 1);
;       WAIT_L(8); BAR; WAIT_L(0); MMA(0, 0, At, B0); BAR; SCHED;
;       LDB(B1, 0, 1); STAGEB(SB(0, 0), bcol, t + 2);
;       BAR; WAIT_L(0); MMA(0, 1, At, B1); BAR;
;       LDA(At, 0, 1); STAGEA(SA(0, 0), brow, t + 2);
;       BAR; WAIT_L(0); MMA(1, 0, At, B0); BAR; SCHED;
;       STAGEB(SB(0, 1), bcol + HALF, t + 2);
;       WAIT_V(6); BAR; MMA(1, 1, At, B1); BAR;
.LBB0_728:
	v_add_u32_e32 v0, s33, v153
	ds_read_b128 v[132:135], v0
	ds_read_b128 v[136:139], v0 offset:256
	ds_read_b128 v[140:143], v0 offset:1024
	ds_read_b128 v[170:173], v0 offset:1280
	s_add_u32 s37, s41, s20
	s_addc_u32 s42, s1, s21
	s_add_u32 s70, s37, 0x80
	v_add_u32_e32 v0, 0xc000, v157
	s_addc_u32 s71, s42, 0
	v_readfirstlane_b32 s37, v0
	v_lshl_add_u64 v[130:131], s[70:71], 0, v[148:149]
	s_mov_b32 m0, s37
	ds_read_b128 v[174:177], v169
	ds_read_b128 v[194:197], v169 offset:1024
	ds_read_b128 v[198:201], v169 offset:2048
	ds_read_b128 v[202:205], v169 offset:3072
	ds_read_b128 v[206:209], v169 offset:4096
	ds_read_b128 v[210:213], v169 offset:5120
	ds_read_b128 v[214:217], v169 offset:6144
	ds_read_b128 v[218:221], v169 offset:7168
	global_load_lds_dwordx4 v[130:131], off
	v_add_u32_e32 v130, 0xe000, v157
	v_lshl_add_u64 v[144:145], s[70:71], 0, v[146:147]
	v_readfirstlane_b32 s37, v130
	s_mov_b32 m0, s37
	s_nop 0
	global_load_lds_dwordx4 v[144:145], off
	s_waitcnt lgkmcnt(8)
	s_barrier
	s_waitcnt lgkmcnt(0)
	s_setprio 1
	v_mfma_f32_16x16x32_bf16 v[126:129], v[132:135], v[174:177], v[126:129]
	v_mfma_f32_16x16x32_bf16 v[122:125], v[136:139], v[174:177], v[122:125]
	v_mfma_f32_16x16x32_bf16 v[118:121], v[132:135], v[198:201], v[118:121]
	v_mfma_f32_16x16x32_bf16 v[114:117], v[136:139], v[198:201], v[114:117]
	v_mfma_f32_16x16x32_bf16 v[110:113], v[132:135], v[206:209], v[110:113]
	v_mfma_f32_16x16x32_bf16 v[106:109], v[136:139], v[206:209], v[106:109]
	v_mfma_f32_16x16x32_bf16 v[102:105], v[132:135], v[214:217], v[102:105]
	v_mfma_f32_16x16x32_bf16 v[98:101], v[136:139], v[214:217], v[98:101]
	v_mfma_f32_16x16x32_bf16 v[126:129], v[140:143], v[194:197], v[126:129]
	v_mfma_f32_16x16x32_bf16 v[122:125], v[170:173], v[194:197], v[122:125]
	v_mfma_f32_16x16x32_bf16 v[118:121], v[140:143], v[202:205], v[118:121]
	v_mfma_f32_16x16x32_bf16 v[114:117], v[170:173], v[202:205], v[114:117]
	v_mfma_f32_16x16x32_bf16 v[110:113], v[140:143], v[210:213], v[110:113]
	v_mfma_f32_16x16x32_bf16 v[106:109], v[170:173], v[210:213], v[106:109]
	v_mfma_f32_16x16x32_bf16 v[102:105], v[140:143], v[218:221], v[102:105]
	v_mfma_f32_16x16x32_bf16 v[98:101], v[170:173], v[218:221], v[98:101]
	s_setprio 0
	s_barrier
	s_add_u32 s37, s31, s20
	s_addc_u32 s42, s43, s21
	s_add_u32 s70, s37, 0x100
	s_addc_u32 s71, s42, 0
	v_readfirstlane_b32 s54, v155
	v_add_u32_e32 v131, s84, v153
	v_lshl_add_u64 v[144:145], s[70:71], 0, v[148:149]
	s_mov_b32 m0, s54
	v_readfirstlane_b32 s54, v156
	ds_read_b128 v[222:225], v131
	ds_read_b128 v[226:229], v131 offset:256
	ds_read_b128 v[230:233], v131 offset:1024
	ds_read_b128 v[234:237], v131 offset:1280
	global_load_lds_dwordx4 v[144:145], off
	v_lshl_add_u64 v[144:145], s[70:71], 0, v[146:147]
	s_mov_b32 m0, s54
	s_nop 0
	global_load_lds_dwordx4 v[144:145], off
	s_barrier
	s_waitcnt lgkmcnt(0)
	s_setprio 1
	v_mfma_f32_16x16x32_bf16 v[94:97], v[222:225], v[174:177], v[94:97]
	v_mfma_f32_16x16x32_bf16 v[78:81], v[226:229], v[174:177], v[78:81]
	v_mfma_f32_16x16x32_bf16 v[62:65], v[222:225], v[198:201], v[62:65]
	v_mfma_f32_16x16x32_bf16 v[50:53], v[226:229], v[198:201], v[50:53]
	v_mfma_f32_16x16x32_bf16 v[46:49], v[222:225], v[206:209], v[46:49]
	v_mfma_f32_16x16x32_bf16 v[42:45], v[226:229], v[206:209], v[42:45]
	v_mfma_f32_16x16x32_bf16 v[38:41], v[222:225], v[214:217], v[38:41]
	v_mfma_f32_16x16x32_bf16 v[34:37], v[226:229], v[214:217], v[34:37]
	v_mfma_f32_16x16x32_bf16 v[94:97], v[230:233], v[194:197], v[94:97]
	v_mfma_f32_16x16x32_bf16 v[78:81], v[234:237], v[194:197], v[78:81]
	v_mfma_f32_16x16x32_bf16 v[62:65], v[230:233], v[202:205], v[62:65]
	v_mfma_f32_16x16x32_bf16 v[50:53], v[234:237], v[202:205], v[50:53]
	v_mfma_f32_16x16x32_bf16 v[46:49], v[230:233], v[210:213], v[46:49]
	v_mfma_f32_16x16x32_bf16 v[42:45], v[234:237], v[210:213], v[42:45]
	v_mfma_f32_16x16x32_bf16 v[38:41], v[230:233], v[218:221], v[38:41]
	v_mfma_f32_16x16x32_bf16 v[34:37], v[234:237], v[218:221], v[34:37]
	s_setprio 0
	s_add_u32 s54, s19, s20
	s_addc_u32 s55, s68, s21
	s_add_u32 s70, s54, 0x100
	s_addc_u32 s71, s55, 0
	v_readfirstlane_b32 s69, v157
	v_lshl_add_u64 v[144:145], s[70:71], 0, v[148:149]
	s_mov_b32 m0, s69
	v_readfirstlane_b32 s69, v158
	s_barrier
	ds_read_b128 v[174:177], v169 offset:16384
	ds_read_b128 v[194:197], v169 offset:17408
	ds_read_b128 v[198:201], v169 offset:18432
	ds_read_b128 v[202:205], v169 offset:19456
	ds_read_b128 v[206:209], v169 offset:20480
	ds_read_b128 v[210:213], v169 offset:21504
	ds_read_b128 v[214:217], v169 offset:22528
	ds_read_b128 v[218:221], v169 offset:23552
	global_load_lds_dwordx4 v[144:145], off
	v_lshl_add_u64 v[144:145], s[70:71], 0, v[146:147]
	s_mov_b32 m0, s69
	s_nop 0
	global_load_lds_dwordx4 v[144:145], off
	s_barrier
	s_waitcnt lgkmcnt(0)
	s_setprio 1
	v_mfma_f32_16x16x32_bf16 v[30:33], v[132:135], v[174:177], v[30:33]
	v_mfma_f32_16x16x32_bf16 v[26:29], v[136:139], v[174:177], v[26:29]
	v_mfma_f32_16x16x32_bf16 v[22:25], v[132:135], v[198:201], v[22:25]
	v_mfma_f32_16x16x32_bf16 v[18:21], v[136:139], v[198:201], v[18:21]
	v_mfma_f32_16x16x32_bf16 v[14:17], v[132:135], v[206:209], v[14:17]
	v_mfma_f32_16x16x32_bf16 v[10:13], v[136:139], v[206:209], v[10:13]
	v_mfma_f32_16x16x32_bf16 v[6:9], v[132:135], v[214:217], v[6:9]
	v_mfma_f32_16x16x32_bf16 v[2:5], v[136:139], v[214:217], v[2:5]
	v_mfma_f32_16x16x32_bf16 v[30:33], v[140:143], v[194:197], v[30:33]
	v_mfma_f32_16x16x32_bf16 v[26:29], v[170:173], v[194:197], v[26:29]
	v_mfma_f32_16x16x32_bf16 v[22:25], v[140:143], v[202:205], v[22:25]
	v_mfma_f32_16x16x32_bf16 v[18:21], v[170:173], v[202:205], v[18:21]
	v_mfma_f32_16x16x32_bf16 v[14:17], v[140:143], v[210:213], v[14:17]
	v_mfma_f32_16x16x32_bf16 v[10:13], v[170:173], v[210:213], v[10:13]
	v_mfma_f32_16x16x32_bf16 v[6:9], v[140:143], v[218:221], v[6:9]
	v_mfma_f32_16x16x32_bf16 v[2:5], v[170:173], v[218:221], v[2:5]
	s_setprio 0
	s_barrier
; #define STAGEA(P, br, kt) do { const char* _g = uptr(A + (size_t)(br) * lda + (size_t)(kt) * BK); \
;     _Pragma("unroll") for (int _i = 0; _i < 2; ++_i) { \
;       __builtin_amdgcn_global_load_lds((const unsigned*)(_g + offA[_i]), (unsigned*)((char*)(P) + tidx * 16 + _i * 8192), 16, 0, 0); } } while (0)
; #define STAGEB(P, br, kt) do { const char* _g = uptr(Bt + (size_t)(br) * ldb + (size_t)(kt) * BK); \
;     _Pragma("unroll") for (int _i = 0; _i < 2; ++_i) { \
;       __builtin_amdgcn_global_load_lds((const unsigned*)(_g + offB[_i]), (unsigned*)((char*)(P) + tidx * 16 + _i * 8192), 16, 0, 0); } } while (0)
; #define LDA(dst, b, h) _Pragma("unroll") for (int m = 0; m < 4; ++m) _Pragma("unroll") for (int k = 0; k < 2; ++k) \
;     dst[m][k] = *reinterpret_cast<const bf16x8*>((char*)SA(b, h) + aoff + m * 2048 + k * 1024)
; #define LDB(dst, b, h) _Pragma("unroll") for (int n = 0; n < 2; ++n) _Pragma("unroll") for (int k = 0; k < 2; ++k) \
;     dst[n][k] = *reinterpret_cast<const bf16x8*>((char*)SB(b, h) + boff + n * (SWAP ? 256 : 2048) + k * 1024)
; #define WAIT_V(n) asm volatile("s_waitcnt vmcnt(" #n ")" ::: "memory")
; #define WAIT_L(n) asm volatile("s_waitcnt lgkmcnt(" #n ")" ::: "memory")
; #define BAR __builtin_amdgcn_s_barrier()
; #define SCHED __builtin_amdgcn_sched_barrier(0)
; template <int EPI>
; DI void gemm_phase(const u16* __restrict__ A, int lda, const u16* __restrict__ Bt, int ldb,
;                    int M, int N, int K, const Epi& e, unsigned char* shmraw, int wv, int slot) {
;     ...
;       STAGEB(SB(0, 1), bcol + HALF, t + 2);
;       WAIT_V(6); BAR; MMA(1, 1, At, B1); BAR;
;       LDB(B0, 1, 0); SCHED; LDA(At, 1, 0); STAGEA(SA(0, 1), brow + HALF, t + 2);
;       WAIT_L(8); BAR; WAIT_L(0); MMA(0, 0, At, B0); BAR; SCHED;
;       LDB(B1, 1, 1); STAGEB(SB(1, 0), bcol, t + 3);
;       BAR; WAIT_L(0); MMA(0, 1, At, B1); BAR;
;       LDA(At, 1, 1); STAGEA(SA(1, 0), brow, t + 3);
;       BAR; WAIT_L(0); MMA(1, 0, At, B0); BAR; SCHED;
	s_add_u32 s69, s35, s20
	s_addc_u32 s72, s38, s21
	s_add_u32 s70, s69, 0x100
	s_addc_u32 s71, s72, 0
	v_readfirstlane_b32 s73, v159
	v_lshl_add_u64 v[132:133], s[70:71], 0, v[148:149]
	s_mov_b32 m0, s73
	s_nop 0
	global_load_lds_dwordx4 v[132:133], off
	v_lshl_add_u64 v[132:133], s[70:71], 0, v[146:147]
	v_readfirstlane_b32 s70, v160
	s_mov_b32 m0, s70
	s_nop 0
	global_load_lds_dwordx4 v[132:133], off
	s_waitcnt vmcnt(6)
	s_barrier
	s_setprio 1
	v_mfma_f32_16x16x32_bf16 v[54:57], v[222:225], v[174:177], v[54:57]
	v_mfma_f32_16x16x32_bf16 v[58:61], v[226:229], v[174:177], v[58:61]
	v_mfma_f32_16x16x32_bf16 v[66:69], v[222:225], v[198:201], v[66:69]
	v_mfma_f32_16x16x32_bf16 v[70:73], v[226:229], v[198:201], v[70:73]
	v_mfma_f32_16x16x32_bf16 v[74:77], v[222:225], v[206:209], v[74:77]
	v_mfma_f32_16x16x32_bf16 v[82:85], v[226:229], v[206:209], v[82:85]
	v_mfma_f32_16x16x32_bf16 v[86:89], v[222:225], v[214:217], v[86:89]
	v_mfma_f32_16x16x32_bf16 v[90:93], v[226:229], v[214:217], v[90:93]
	v_mfma_f32_16x16x32_bf16 v[54:57], v[230:233], v[194:197], v[54:57]
	v_mfma_f32_16x16x32_bf16 v[58:61], v[234:237], v[194:197], v[58:61]
	v_mfma_f32_16x16x32_bf16 v[66:69], v[230:233], v[202:205], v[66:69]
	v_mfma_f32_16x16x32_bf16 v[70:73], v[234:237], v[202:205], v[70:73]
	v_mfma_f32_16x16x32_bf16 v[74:77], v[230:233], v[210:213], v[74:77]
	v_mfma_f32_16x16x32_bf16 v[82:85], v[234:237], v[210:213], v[82:85]
	v_mfma_f32_16x16x32_bf16 v[86:89], v[230:233], v[218:221], v[86:89]
	v_mfma_f32_16x16x32_bf16 v[90:93], v[234:237], v[218:221], v[90:93]
	s_setprio 0
	v_add_u32_e32 v131, s85, v153
	s_barrier
	ds_read_b128 v[132:135], v131
	ds_read_b128 v[136:139], v131 offset:256
	ds_read_b128 v[140:143], v131 offset:1024
	ds_read_b128 v[170:173], v131 offset:1280
	s_add_u32 s70, s39, s20
	s_addc_u32 s71, s40, s21
	v_readfirstlane_b32 s73, v161
	v_lshl_add_u64 v[144:145], s[70:71], 0, v[148:149]
	s_mov_b32 m0, s73
	ds_read_b128 v[174:177], v169 offset:32768
	ds_read_b128 v[194:197], v169 offset:33792
	ds_read_b128 v[198:201], v169 offset:34816
	ds_read_b128 v[202:205], v169 offset:35840
	ds_read_b128 v[206:209], v169 offset:36864
	ds_read_b128 v[210:213], v169 offset:37888
	ds_read_b128 v[214:217], v169 offset:38912
	ds_read_b128 v[218:221], v169 offset:39936
	global_load_lds_dwordx4 v[144:145], off
	v_lshl_add_u64 v[144:145], s[70:71], 0, v[146:147]
	v_readfirstlane_b32 s70, v162
	s_mov_b32 m0, s70
	s_nop 0
	global_load_lds_dwordx4 v[144:145], off
	s_waitcnt lgkmcnt(8)
	s_barrier
	s_waitcnt lgkmcnt(0)
	s_setprio 1
	v_mfma_f32_16x16x32_bf16 v[126:129], v[132:135], v[174:177], v[126:129]
	v_mfma_f32_16x16x32_bf16 v[122:125], v[136:139], v[174:177], v[122:125]
	v_mfma_f32_16x16x32_bf16 v[118:121], v[132:135], v[198:201], v[118:121]
	v_mfma_f32_16x16x32_bf16 v[114:117], v[136:139], v[198:201], v[114:117]
	v_mfma_f32_16x16x32_bf16 v[110:113], v[132:135], v[206:209], v[110:113]
	v_mfma_f32_16x16x32_bf16 v[106:109], v[136:139], v[206:209], v[106:109]
	v_mfma_f32_16x16x32_bf16 v[102:105], v[132:135], v[214:217], v[102:105]
	v_mfma_f32_16x16x32_bf16 v[98:101], v[136:139], v[214:217], v[98:101]
	v_mfma_f32_16x16x32_bf16 v[126:129], v[140:143], v[194:197], v[126:129]
	v_mfma_f32_16x16x32_bf16 v[122:125], v[170:173], v[194:197], v[122:125]
	v_mfma_f32_16x16x32_bf16 v[118:121], v[140:143], v[202:205], v[118:121]
	v_mfma_f32_16x16x32_bf16 v[114:117], v[170:173], v[202:205], v[114:117]
	v_mfma_f32_16x16x32_bf16 v[110:113], v[140:143], v[210:213], v[110:113]
	v_mfma_f32_16x16x32_bf16 v[106:109], v[170:173], v[210:213], v[106:109]
	v_mfma_f32_16x16x32_bf16 v[102:105], v[140:143], v[218:221], v[102:105]
	v_mfma_f32_16x16x32_bf16 v[98:101], v[170:173], v[218:221], v[98:101]
	s_setprio 0
	s_barrier
	s_add_u32 s70, s37, 0x180
	s_addc_u32 s71, s42, 0
	v_readfirstlane_b32 s37, v163
	v_add_u32_e32 v131, s86, v153
	v_lshl_add_u64 v[144:145], s[70:71], 0, v[148:149]
	s_mov_b32 m0, s37
	v_readfirstlane_b32 s37, v164
	ds_read_b128 v[222:225], v131
	ds_read_b128 v[226:229], v131 offset:256
	ds_read_b128 v[230:233], v131 offset:1024
	ds_read_b128 v[234:237], v131 offset:1280
	global_load_lds_dwordx4 v[144:145], off
	v_lshl_add_u64 v[144:145], s[70:71], 0, v[146:147]
	s_mov_b32 m0, s37
	s_nop 0
	global_load_lds_dwordx4 v[144:145], off
	s_barrier
	s_waitcnt lgkmcnt(0)
	s_setprio 1
	v_mfma_f32_16x16x32_bf16 v[94:97], v[222:225], v[174:177], v[94:97]
	v_mfma_f32_16x16x32_bf16 v[78:81], v[226:229], v[174:177], v[78:81]
	v_mfma_f32_16x16x32_bf16 v[62:65], v[222:225], v[198:201], v[62:65]
	v_mfma_f32_16x16x32_bf16 v[50:53], v[226:229], v[198:201], v[50:53]
	v_mfma_f32_16x16x32_bf16 v[46:49], v[222:225], v[206:209], v[46:49]
	v_mfma_f32_16x16x32_bf16 v[42:45], v[226:229], v[206:209], v[42:45]
	v_mfma_f32_16x16x32_bf16 v[38:41], v[222:225], v[214:217], v[38:41]
	v_mfma_f32_16x16x32_bf16 v[34:37], v[226:229], v[214:217], v[34:37]
	v_mfma_f32_16x16x32_bf16 v[94:97], v[230:233], v[194:197], v[94:97]
	v_mfma_f32_16x16x32_bf16 v[78:81], v[234:237], v[194:197], v[78:81]
	v_mfma_f32_16x16x32_bf16 v[62:65], v[230:233], v[202:205], v[62:65]
	v_mfma_f32_16x16x32_bf16 v[50:53], v[234:237], v[202:205], v[50:53]
	v_mfma_f32_16x16x32_bf16 v[46:49], v[230:233], v[210:213], v[46:49]
	v_mfma_f32_16x16x32_bf16 v[42:45], v[234:237], v[210:213], v[42:45]
	v_mfma_f32_16x16x32_bf16 v[38:41], v[230:233], v[218:221], v[38:41]
	v_mfma_f32_16x16x32_bf16 v[34:37], v[234:237], v[218:221], v[34:37]
	s_setprio 0
	s_add_u32 s70, s54, 0x180
	s_addc_u32 s71, s55, 0
	v_readfirstlane_b32 s37, v165
	v_lshl_add_u64 v[144:145], s[70:71], 0, v[148:149]
	s_mov_b32 m0, s37
	v_readfirstlane_b32 s37, v166
	s_barrier
; #define STAGEA(P, br, kt) do { const char* _g = uptr(A + (size_t)(br) * lda + (size_t)(kt) * BK); \
;     _Pragma("unroll") for (int _i = 0; _i < 2; ++_i) { \
;       __builtin_amdgcn_global_load_lds((const unsigned*)(_g + offA[_i]), (unsigned*)((char*)(P) + tidx * 16 + _i * 8192), 16, 0, 0); } } while (0)
; #define STAGEB(P, br, kt) do { const char* _g = uptr(Bt + (size_t)(br) * ldb + (size_t)(kt) * BK); \
;     _Pragma("unroll") for (int _i = 0; _i < 2; ++_i) { \
;       __builtin_amdgcn_global_load_lds((const unsigned*)(_g + offB[_i]), (unsigned*)((char*)(P) + tidx * 16 + _i * 8192), 16, 0, 0); } } while (0)
; #define LDA(dst, b, h) _Pragma("unroll") for (int m = 0; m < 4; ++m) _Pragma("unroll") for (int k = 0; k < 2; ++k) \
;     dst[m][k] = *reinterpret_cast<const bf16x8*>((char*)SA(b, h) + aoff + m * 2048 + k * 1024)
; #define LDB(dst, b, h) _Pragma("unroll") for (int n = 0; n < 2; ++n) _Pragma("unroll") for (int k = 0; k < 2; ++k) \
;     dst[n][k] = *reinterpret_cast<const bf16x8*>((char*)SB(b, h) + boff + n * (SWAP ? 256 : 2048) + k * 1024)
; #define WAIT_V(n) asm volatile("s_waitcnt vmcnt(" #n ")" ::: "memory")
; #define WAIT_L(n) asm volatile("s_waitcnt lgkmcnt(" #n ")" ::: "memory")
; #define BAR __builtin_amdgcn_s_barrier()
; #define SCHED __builtin_amdgcn_sched_barrier(0)
; template <int EPI>
; DI void gemm_phase(const u16* __restrict__ A, int lda, const u16* __restrict__ Bt, int ldb,
;                    int M, int N, int K, const Epi& e, unsigned char* shmraw, int wv, int slot) {
;     ...
;       BAR; WAIT_L(0); MMA(0, 1, At, B1); BAR;
;       LDA(At, 1, 1); STAGEA(SA(1, 0), brow, t + 3);
;       BAR; WAIT_L(0); MMA(1, 0, At, B0); BAR; SCHED;
;       STAGEB(SB(1, 1), bcol + HALF, t + 3);
;       WAIT_V(6); BAR; MMA(1, 1, At, B1); BAR;
;     }
;     { LDB(B0, 0, 0); LDA(At, 0, 0); STAGEA(SA(1, 1), brow + HALF, nt - 1);
;       BAR; WAIT_L(0); MMA(0, 0, At, B0); BAR;
;       LDB(B1, 0, 1); BAR; WAIT_L(0); MMA(0, 1, At, B1); BAR;
	ds_read_b128 v[174:177], v169 offset:49152
	ds_read_b128 v[194:197], v169 offset:50176
	ds_read_b128 v[198:201], v169 offset:51200
	ds_read_b128 v[202:205], v169 offset:52224
	ds_read_b128 v[206:209], v169 offset:53248
	ds_read_b128 v[210:213], v169 offset:54272
	ds_read_b128 v[214:217], v169 offset:55296
	ds_read_b128 v[218:221], v169 offset:56320
	global_load_lds_dwordx4 v[144:145], off
	v_lshl_add_u64 v[144:145], s[70:71], 0, v[146:147]
	s_mov_b32 m0, s37
	s_nop 0
	global_load_lds_dwordx4 v[144:145], off
	s_barrier
	s_waitcnt lgkmcnt(0)
	s_setprio 1
	v_mfma_f32_16x16x32_bf16 v[30:33], v[132:135], v[174:177], v[30:33]
	v_mfma_f32_16x16x32_bf16 v[26:29], v[136:139], v[174:177], v[26:29]
	v_mfma_f32_16x16x32_bf16 v[22:25], v[132:135], v[198:201], v[22:25]
	v_mfma_f32_16x16x32_bf16 v[18:21], v[136:139], v[198:201], v[18:21]
	v_mfma_f32_16x16x32_bf16 v[14:17], v[132:135], v[206:209], v[14:17]
	v_mfma_f32_16x16x32_bf16 v[10:13], v[136:139], v[206:209], v[10:13]
	v_mfma_f32_16x16x32_bf16 v[6:9], v[132:135], v[214:217], v[6:9]
	v_mfma_f32_16x16x32_bf16 v[2:5], v[136:139], v[214:217], v[2:5]
	v_mfma_f32_16x16x32_bf16 v[30:33], v[140:143], v[194:197], v[30:33]
	v_mfma_f32_16x16x32_bf16 v[26:29], v[170:173], v[194:197], v[26:29]
	v_mfma_f32_16x16x32_bf16 v[22:25], v[140:143], v[202:205], v[22:25]
	v_mfma_f32_16x16x32_bf16 v[18:21], v[170:173], v[202:205], v[18:21]
	v_mfma_f32_16x16x32_bf16 v[14:17], v[140:143], v[210:213], v[14:17]
	v_mfma_f32_16x16x32_bf16 v[10:13], v[170:173], v[210:213], v[10:13]
	v_mfma_f32_16x16x32_bf16 v[6:9], v[140:143], v[218:221], v[6:9]
	v_mfma_f32_16x16x32_bf16 v[2:5], v[170:173], v[218:221], v[2:5]
	s_setprio 0
	s_barrier
	s_add_u32 s70, s69, 0x180
	s_addc_u32 s71, s72, 0
	v_readfirstlane_b32 s37, v167
	v_lshl_add_u64 v[132:133], s[70:71], 0, v[148:149]
	s_mov_b32 m0, s37
	v_readfirstlane_b32 s37, v168
	global_load_lds_dwordx4 v[132:133], off
	v_lshl_add_u64 v[132:133], s[70:71], 0, v[146:147]
	s_mov_b32 m0, s37
	s_nop 0
	global_load_lds_dwordx4 v[132:133], off
	s_waitcnt vmcnt(6)
	s_barrier
	s_setprio 1
	v_mfma_f32_16x16x32_bf16 v[54:57], v[222:225], v[174:177], v[54:57]
	v_mfma_f32_16x16x32_bf16 v[58:61], v[226:229], v[174:177], v[58:61]
	v_mfma_f32_16x16x32_bf16 v[66:69], v[222:225], v[198:201], v[66:69]
	v_mfma_f32_16x16x32_bf16 v[70:73], v[226:229], v[198:201], v[70:73]
	v_mfma_f32_16x16x32_bf16 v[74:77], v[222:225], v[206:209], v[74:77]
	v_mfma_f32_16x16x32_bf16 v[82:85], v[226:229], v[206:209], v[82:85]
	v_mfma_f32_16x16x32_bf16 v[86:89], v[222:225], v[214:217], v[86:89]
	v_mfma_f32_16x16x32_bf16 v[90:93], v[226:229], v[214:217], v[90:93]
	v_mfma_f32_16x16x32_bf16 v[54:57], v[230:233], v[194:197], v[54:57]
	v_mfma_f32_16x16x32_bf16 v[58:61], v[234:237], v[194:197], v[58:61]
	v_mfma_f32_16x16x32_bf16 v[66:69], v[230:233], v[202:205], v[66:69]
	v_mfma_f32_16x16x32_bf16 v[70:73], v[234:237], v[202:205], v[70:73]
	v_mfma_f32_16x16x32_bf16 v[74:77], v[230:233], v[210:213], v[74:77]
	v_mfma_f32_16x16x32_bf16 v[82:85], v[234:237], v[210:213], v[82:85]
	v_mfma_f32_16x16x32_bf16 v[86:89], v[230:233], v[218:221], v[86:89]
	v_mfma_f32_16x16x32_bf16 v[90:93], v[234:237], v[218:221], v[90:93]
	s_setprio 0
	s_add_i32 s36, s36, 2
	s_add_u32 s20, s20, 0x100
	s_addc_u32 s21, s21, 0
	s_cmp_lt_u32 s36, 12
	s_barrier
	s_cbranch_scc1 .LBB0_728
	v_add_u32_e32 v131, 16, v153
	s_add_u32 s20, s29, 0x780
	v_add_u32_e32 v144, 0x10000, v131
	s_addc_u32 s21, s30, 0
	v_readfirstlane_b32 s1, v0
	ds_read_b128 v[132:135], v144
	ds_read_b128 v[136:139], v144 offset:256
	ds_read_b128 v[140:143], v144 offset:1024
	ds_read_b128 v[170:173], v144 offset:1280
	ds_read_b128 v[174:177], v169
	ds_read_b128 v[194:197], v169 offset:1024
	ds_read_b128 v[198:201], v169 offset:2048
	ds_read_b128 v[202:205], v169 offset:3072
	ds_read_b128 v[206:209], v169 offset:4096
	ds_read_b128 v[210:213], v169 offset:5120
	ds_read_b128 v[214:217], v169 offset:6144
	ds_read_b128 v[218:221], v169 offset:7168
	v_lshl_add_u64 v[144:145], s[20:21], 0, v[148:149]
	s_mov_b32 m0, s1
	v_readfirstlane_b32 s1, v130
	global_load_lds_dwordx4 v[144:145], off
	v_lshl_add_u64 v[144:145], s[20:21], 0, v[146:147]
	s_mov_b32 m0, s1
	s_nop 0
	global_load_lds_dwordx4 v[144:145], off
	s_barrier
	s_waitcnt lgkmcnt(0)
	s_setprio 1
	v_mfma_f32_16x16x32_bf16 v[126:129], v[132:135], v[174:177], v[126:129]
	v_mfma_f32_16x16x32_bf16 v[122:125], v[136:139], v[174:177], v[122:125]
	v_mfma_f32_16x16x32_bf16 v[118:121], v[132:135], v[198:201], v[118:121]
	v_mfma_f32_16x16x32_bf16 v[110:113], v[132:135], v[206:209], v[110:113]
	v_mfma_f32_16x16x32_bf16 v[106:109], v[136:139], v[206:209], v[106:109]
	v_mfma_f32_16x16x32_bf16 v[98:101], v[136:139], v[214:217], v[98:101]
	v_mfma_f32_16x16x32_bf16 v[126:129], v[140:143], v[194:197], v[126:129]
	v_mfma_f32_16x16x32_bf16 v[122:125], v[170:173], v[194:197], v[122:125]
	v_mfma_f32_16x16x32_bf16 v[118:121], v[140:143], v[202:205], v[118:121]
	v_mfma_f32_16x16x32_bf16 v[114:117], v[136:139], v[198:201], v[114:117]
	v_mfma_f32_16x16x32_bf16 v[110:113], v[140:143], v[210:213], v[110:113]
	v_mfma_f32_16x16x32_bf16 v[106:109], v[170:173], v[210:213], v[106:109]
	v_mfma_f32_16x16x32_bf16 v[102:105], v[132:135], v[214:217], v[102:105]
	v_mfma_f32_16x16x32_bf16 v[98:101], v[170:173], v[218:221], v[98:101]
	v_mfma_f32_16x16x32_bf16 v[222:225], v[170:173], v[202:205], v[114:117]
	v_mfma_f32_16x16x32_bf16 v[226:229], v[140:143], v[218:221], v[102:105]
	s_setprio 0
	v_add_u32_e32 v0, 0x14000, v131
	s_barrier
	s_nop 1
	ds_read_b128 v[102:105], v0
	ds_read_b128 v[114:117], v0 offset:256
	ds_read_b128 v[230:233], v0 offset:1024
	ds_read_b128 v[234:237], v0 offset:1280
	s_barrier
; #define LDA(dst, b, h) _Pragma("unroll") for (int m = 0; m < 4; ++m) _Pragma("unroll") for (int k = 0; k < 2; ++k) \
;     dst[m][k] = *reinterpret_cast<const bf16x8*>((char*)SA(b, h) + aoff + m * 2048 + k * 1024)
; #define LDB(dst, b, h) _Pragma("unroll") for (int n = 0; n < 2; ++n) _Pragma("unroll") for (int k = 0; k < 2; ++k) \
;     dst[n][k] = *reinterpret_cast<const bf16x8*>((char*)SB(b, h) + boff + n * (SWAP ? 256 : 2048) + k * 1024)
; #define WAIT_V(n) asm volatile("s_waitcnt vmcnt(" #n ")" ::: "memory")
; #define WAIT_L(n) asm volatile("s_waitcnt lgkmcnt(" #n ")" ::: "memory")
; #define BAR __builtin_amdgcn_s_barrier()
; template <int EPI>
; DI void gemm_phase(const u16* __restrict__ A, int lda, const u16* __restrict__ Bt, int ldb,
;                    int M, int N, int K, const Epi& e, unsigned char* shmraw, int wv, int slot) {
;     ...
;       BAR; WAIT_L(0); MMA(0, 0, At, B0); BAR;
;       LDB(B1, 0, 1); BAR; WAIT_L(0); MMA(0, 1, At, B1); BAR;
;       LDA(At, 0, 1); WAIT_V(4); BAR; WAIT_L(0); MMA(1, 0, At, B0); MMA(1, 1, At, B1); BAR; }
;     { LDB(B0, 1, 0); LDA(At, 1, 0); WAIT_V(2); BAR; WAIT_L(0); MMA(0, 0, At, B0); BAR;
	s_waitcnt lgkmcnt(0)
	s_setprio 1
	v_mfma_f32_16x16x32_bf16 v[94:97], v[102:105], v[174:177], v[94:97]
	v_mfma_f32_16x16x32_bf16 v[78:81], v[114:117], v[174:177], v[78:81]
	v_mfma_f32_16x16x32_bf16 v[62:65], v[102:105], v[198:201], v[62:65]
	v_mfma_f32_16x16x32_bf16 v[50:53], v[114:117], v[198:201], v[50:53]
	v_mfma_f32_16x16x32_bf16 v[94:97], v[230:233], v[194:197], v[94:97]
	v_mfma_f32_16x16x32_bf16 v[78:81], v[234:237], v[194:197], v[78:81]
	v_mfma_f32_16x16x32_bf16 v[62:65], v[230:233], v[202:205], v[62:65]
	v_mfma_f32_16x16x32_bf16 v[50:53], v[234:237], v[202:205], v[50:53]
	v_mfma_f32_16x16x32_bf16 v[46:49], v[102:105], v[206:209], v[46:49]
	v_mfma_f32_16x16x32_bf16 v[42:45], v[114:117], v[206:209], v[42:45]
	v_mfma_f32_16x16x32_bf16 v[38:41], v[102:105], v[214:217], v[38:41]
	v_mfma_f32_16x16x32_bf16 v[34:37], v[114:117], v[214:217], v[34:37]
	v_mfma_f32_16x16x32_bf16 v[46:49], v[230:233], v[210:213], v[46:49]
	v_mfma_f32_16x16x32_bf16 v[42:45], v[234:237], v[210:213], v[42:45]
	v_mfma_f32_16x16x32_bf16 v[38:41], v[230:233], v[218:221], v[38:41]
	v_mfma_f32_16x16x32_bf16 v[34:37], v[234:237], v[218:221], v[34:37]
	s_setprio 0
	s_barrier
	ds_read_b128 v[174:177], v169 offset:16384
	ds_read_b128 v[194:197], v169 offset:17408
	ds_read_b128 v[198:201], v169 offset:18432
	ds_read_b128 v[202:205], v169 offset:19456
	ds_read_b128 v[206:209], v169 offset:20480
	ds_read_b128 v[210:213], v169 offset:21504
	ds_read_b128 v[214:217], v169 offset:22528
	ds_read_b128 v[218:221], v169 offset:23552
	s_waitcnt vmcnt(4)
	s_barrier
	s_waitcnt lgkmcnt(0)
	s_setprio 1
	v_mfma_f32_16x16x32_bf16 v[30:33], v[132:135], v[174:177], v[30:33]
	v_mfma_f32_16x16x32_bf16 v[26:29], v[136:139], v[174:177], v[26:29]
	v_mfma_f32_16x16x32_bf16 v[22:25], v[132:135], v[198:201], v[22:25]
	v_mfma_f32_16x16x32_bf16 v[18:21], v[136:139], v[198:201], v[18:21]
	v_mfma_f32_16x16x32_bf16 v[14:17], v[132:135], v[206:209], v[14:17]
	v_mfma_f32_16x16x32_bf16 v[10:13], v[136:139], v[206:209], v[10:13]
	v_mfma_f32_16x16x32_bf16 v[6:9], v[132:135], v[214:217], v[6:9]
	v_mfma_f32_16x16x32_bf16 v[2:5], v[136:139], v[214:217], v[2:5]
	v_mfma_f32_16x16x32_bf16 v[30:33], v[140:143], v[194:197], v[30:33]
	v_mfma_f32_16x16x32_bf16 v[26:29], v[170:173], v[194:197], v[26:29]
	v_mfma_f32_16x16x32_bf16 v[22:25], v[140:143], v[202:205], v[22:25]
	v_mfma_f32_16x16x32_bf16 v[18:21], v[170:173], v[202:205], v[18:21]
	v_mfma_f32_16x16x32_bf16 v[14:17], v[140:143], v[210:213], v[14:17]
	v_mfma_f32_16x16x32_bf16 v[10:13], v[170:173], v[210:213], v[10:13]
	v_mfma_f32_16x16x32_bf16 v[6:9], v[140:143], v[218:221], v[6:9]
	v_mfma_f32_16x16x32_bf16 v[2:5], v[170:173], v[218:221], v[2:5]
	s_setprio 0
	s_setprio 1
	v_mfma_f32_16x16x32_bf16 v[58:61], v[114:117], v[174:177], v[58:61]
	v_mfma_f32_16x16x32_bf16 v[170:173], v[234:237], v[194:197], v[58:61]
	v_mfma_f32_16x16x32_bf16 v[58:61], v[102:105], v[198:201], v[66:69]
	v_mfma_f32_16x16x32_bf16 v[54:57], v[102:105], v[174:177], v[54:57]
	v_mfma_f32_16x16x32_bf16 v[174:177], v[230:233], v[202:205], v[58:61]
	v_mfma_f32_16x16x32_bf16 v[58:61], v[114:117], v[198:201], v[70:73]
	v_mfma_f32_16x16x32_bf16 v[54:57], v[230:233], v[194:197], v[54:57]
	v_mfma_f32_16x16x32_bf16 v[194:197], v[234:237], v[202:205], v[58:61]
	v_mfma_f32_16x16x32_bf16 v[58:61], v[102:105], v[206:209], v[74:77]
	v_mfma_f32_16x16x32_bf16 v[198:201], v[230:233], v[210:213], v[58:61]
	v_mfma_f32_16x16x32_bf16 v[58:61], v[114:117], v[206:209], v[82:85]
	v_mfma_f32_16x16x32_bf16 v[202:205], v[234:237], v[210:213], v[58:61]
	v_mfma_f32_16x16x32_bf16 v[58:61], v[102:105], v[214:217], v[86:89]
	v_mfma_f32_16x16x32_bf16 v[206:209], v[230:233], v[218:221], v[58:61]
	v_mfma_f32_16x16x32_bf16 v[58:61], v[114:117], v[214:217], v[90:93]
	v_mfma_f32_16x16x32_bf16 v[210:213], v[234:237], v[218:221], v[58:61]
	s_setprio 0
	v_add_u32_e32 v0, 0x18000, v131
	s_barrier
	ds_read_b128 v[66:69], v0
	ds_read_b128 v[70:73], v0 offset:256
	ds_read_b128 v[214:217], v0 offset:1024
	ds_read_b128 v[218:221], v0 offset:1280
	ds_read_b128 v[58:61], v169 offset:32768
	ds_read_b128 v[74:77], v169 offset:33792
	ds_read_b128 v[86:89], v169 offset:34816
	ds_read_b128 v[230:233], v169 offset:35840
	ds_read_b128 v[234:237], v169 offset:36864
	ds_read_b128 v[238:241], v169 offset:37888
	ds_read_b128 v[242:245], v169 offset:38912
	ds_read_b128 v[246:249], v169 offset:39936
	s_waitcnt vmcnt(2)
	s_barrier
; #define LDA(dst, b, h) _Pragma("unroll") for (int m = 0; m < 4; ++m) _Pragma("unroll") for (int k = 0; k < 2; ++k) \
;     dst[m][k] = *reinterpret_cast<const bf16x8*>((char*)SA(b, h) + aoff + m * 2048 + k * 1024)
; #define LDB(dst, b, h) _Pragma("unroll") for (int n = 0; n < 2; ++n) _Pragma("unroll") for (int k = 0; k < 2; ++k) \
;     dst[n][k] = *reinterpret_cast<const bf16x8*>((char*)SB(b, h) + boff + n * (SWAP ? 256 : 2048) + k * 1024)
; #define WAIT_V(n) asm volatile("s_waitcnt vmcnt(" #n ")" ::: "memory")
; #define WAIT_L(n) asm volatile("s_waitcnt lgkmcnt(" #n ")" ::: "memory")
; #define BAR __builtin_amdgcn_s_barrier()
; template <int EPI>
; DI void gemm_phase(const u16* __restrict__ A, int lda, const u16* __restrict__ Bt, int ldb,
;                    int M, int N, int K, const Epi& e, unsigned char* shmraw, int wv, int slot) {
;     ...
;     { LDB(B0, 1, 0); LDA(At, 1, 0); WAIT_V(2); BAR; WAIT_L(0); MMA(0, 0, At, B0); BAR;
;       LDB(B1, 1, 1); WAIT_V(0); BAR; WAIT_L(0); MMA(0, 1, At, B1); BAR;
;       LDA(At, 1, 1); BAR; WAIT_L(0); MMA(1, 0, At, B0); MMA(1, 1, At, B1); BAR; }
;     if (wr == 0) BAR;
	s_waitcnt lgkmcnt(0)
	s_setprio 1
	v_mfma_f32_16x16x32_bf16 v[82:85], v[66:69], v[58:61], v[126:129]
	v_mfma_f32_16x16x32_bf16 v[138:141], v[214:217], v[74:77], v[82:85]
	v_mfma_f32_16x16x32_bf16 v[82:85], v[70:73], v[58:61], v[122:125]
	v_mfma_f32_16x16x32_bf16 v[142:145], v[218:221], v[74:77], v[82:85]
	v_mfma_f32_16x16x32_bf16 v[82:85], v[66:69], v[86:89], v[118:121]
	v_mfma_f32_16x16x32_bf16 v[114:117], v[214:217], v[230:233], v[82:85]
	v_mfma_f32_16x16x32_bf16 v[82:85], v[70:73], v[86:89], v[222:225]
	v_mfma_f32_16x16x32_bf16 v[122:125], v[218:221], v[230:233], v[82:85]
	v_mfma_f32_16x16x32_bf16 v[82:85], v[66:69], v[234:237], v[110:113]
	v_mfma_f32_16x16x32_bf16 v[102:105], v[214:217], v[238:241], v[82:85]
	v_mfma_f32_16x16x32_bf16 v[82:85], v[70:73], v[234:237], v[106:109]
	v_mfma_f32_16x16x32_bf16 v[110:113], v[218:221], v[238:241], v[82:85]
	v_mfma_f32_16x16x32_bf16 v[82:85], v[66:69], v[242:245], v[226:229]
	v_mfma_f32_16x16x32_bf16 v[90:93], v[70:73], v[242:245], v[98:101]
	v_mfma_f32_16x16x32_bf16 v[82:85], v[214:217], v[246:249], v[82:85]
	v_mfma_f32_16x16x32_bf16 v[90:93], v[218:221], v[246:249], v[90:93]
	s_setprio 0
	v_add_u32_e32 v0, 0x1c000, v131
	s_barrier
	ds_read_b128 v[222:225], v0
	ds_read_b128 v[226:229], v0 offset:256
	ds_read_b128 v[182:185], v0 offset:1024
	ds_read_b128 v[190:193], v0 offset:1280
	s_waitcnt vmcnt(0)
	s_barrier
	s_waitcnt lgkmcnt(0)
	s_setprio 1
	v_mfma_f32_16x16x32_bf16 v[94:97], v[222:225], v[58:61], v[94:97]
	v_mfma_f32_16x16x32_bf16 v[58:61], v[226:229], v[58:61], v[78:81]
	v_mfma_f32_16x16x32_bf16 v[134:137], v[190:193], v[74:77], v[58:61]
	v_mfma_f32_16x16x32_bf16 v[58:61], v[222:225], v[86:89], v[62:65]
	v_mfma_f32_16x16x32_bf16 v[50:53], v[226:229], v[86:89], v[50:53]
	v_mfma_f32_16x16x32_bf16 v[46:49], v[222:225], v[234:237], v[46:49]
	v_mfma_f32_16x16x32_bf16 v[42:45], v[226:229], v[234:237], v[42:45]
	v_mfma_f32_16x16x32_bf16 v[38:41], v[222:225], v[242:245], v[38:41]
	v_mfma_f32_16x16x32_bf16 v[34:37], v[226:229], v[242:245], v[34:37]
	v_mfma_f32_16x16x32_bf16 v[130:133], v[182:185], v[74:77], v[94:97]
	v_mfma_f32_16x16x32_bf16 v[118:121], v[182:185], v[230:233], v[58:61]
	v_mfma_f32_16x16x32_bf16 v[126:129], v[190:193], v[230:233], v[50:53]
	v_mfma_f32_16x16x32_bf16 v[98:101], v[182:185], v[238:241], v[46:49]
	v_mfma_f32_16x16x32_bf16 v[106:109], v[190:193], v[238:241], v[42:45]
	v_mfma_f32_16x16x32_bf16 v[86:89], v[182:185], v[246:249], v[38:41]
	v_mfma_f32_16x16x32_bf16 v[94:97], v[190:193], v[246:249], v[34:37]
	s_setprio 0
	s_barrier
	s_nop 0
	ds_read_b128 v[34:37], v169 offset:49152
	ds_read_b128 v[38:41], v169 offset:50176
	ds_read_b128 v[42:45], v169 offset:51200
	ds_read_b128 v[46:49], v169 offset:52224
	ds_read_b128 v[230:233], v169 offset:53248
	ds_read_b128 v[234:237], v169 offset:54272
	ds_read_b128 v[238:241], v169 offset:55296
	ds_read_b128 v[242:245], v169 offset:56320
	s_barrier
	s_waitcnt lgkmcnt(0)
	s_setprio 1
	v_mfma_f32_16x16x32_bf16 v[30:33], v[66:69], v[34:37], v[30:33]
	v_mfma_f32_16x16x32_bf16 v[26:29], v[70:73], v[34:37], v[26:29]
	v_mfma_f32_16x16x32_bf16 v[22:25], v[66:69], v[42:45], v[22:25]
	v_mfma_f32_16x16x32_bf16 v[18:21], v[70:73], v[42:45], v[18:21]
	v_mfma_f32_16x16x32_bf16 v[14:17], v[66:69], v[230:233], v[14:17]
	v_mfma_f32_16x16x32_bf16 v[10:13], v[70:73], v[230:233], v[10:13]
	v_mfma_f32_16x16x32_bf16 v[6:9], v[66:69], v[238:241], v[6:9]
	v_mfma_f32_16x16x32_bf16 v[2:5], v[70:73], v[238:241], v[2:5]
	v_mfma_f32_16x16x32_bf16 v[74:77], v[214:217], v[38:41], v[30:33]
	v_mfma_f32_16x16x32_bf16 v[78:81], v[218:221], v[38:41], v[26:29]
	v_mfma_f32_16x16x32_bf16 v[58:61], v[214:217], v[46:49], v[22:25]
	v_mfma_f32_16x16x32_bf16 v[62:65], v[218:221], v[46:49], v[18:21]
	v_mfma_f32_16x16x32_bf16 v[26:29], v[214:217], v[234:237], v[14:17]
	v_mfma_f32_16x16x32_bf16 v[30:33], v[218:221], v[234:237], v[10:13]
	v_mfma_f32_16x16x32_bf16 v[10:13], v[214:217], v[242:245], v[6:9]
	v_mfma_f32_16x16x32_bf16 v[14:17], v[218:221], v[242:245], v[2:5]
	s_setprio 0
	s_setprio 1
	v_mfma_f32_16x16x32_bf16 v[2:5], v[222:225], v[34:37], v[54:57]
	v_mfma_f32_16x16x32_bf16 v[66:69], v[182:185], v[38:41], v[2:5]
	v_mfma_f32_16x16x32_bf16 v[2:5], v[226:229], v[34:37], v[170:173]
	v_mfma_f32_16x16x32_bf16 v[70:73], v[190:193], v[38:41], v[2:5]
	v_mfma_f32_16x16x32_bf16 v[2:5], v[222:225], v[42:45], v[174:177]
	v_mfma_f32_16x16x32_bf16 v[50:53], v[182:185], v[46:49], v[2:5]
	v_mfma_f32_16x16x32_bf16 v[2:5], v[226:229], v[42:45], v[194:197]
	v_mfma_f32_16x16x32_bf16 v[54:57], v[190:193], v[46:49], v[2:5]
	v_mfma_f32_16x16x32_bf16 v[2:5], v[222:225], v[230:233], v[198:201]
	v_mfma_f32_16x16x32_bf16 v[18:21], v[182:185], v[234:237], v[2:5]
	v_mfma_f32_16x16x32_bf16 v[2:5], v[226:229], v[230:233], v[202:205]
	v_mfma_f32_16x16x32_bf16 v[22:25], v[190:193], v[234:237], v[2:5]
	v_mfma_f32_16x16x32_bf16 v[2:5], v[222:225], v[238:241], v[206:209]
	v_mfma_f32_16x16x32_bf16 v[6:9], v[226:229], v[238:241], v[210:213]
	v_mfma_f32_16x16x32_bf16 v[2:5], v[182:185], v[242:245], v[2:5]
	v_mfma_f32_16x16x32_bf16 v[6:9], v[190:193], v[242:245], v[6:9]
	s_setprio 0
	s_barrier
	s_and_saveexec_b64 s[20:21], s[6:7]
	s_cbranch_execz .LBB0_731
	s_barrier

; #define STAGEA(P, br, kt) do { const char* _g = uptr(A + (size_t)(br) * lda + (size_t)(kt) * BK); \
;     _Pragma("unroll") for (int _i = 0; _i < 2; ++_i) { \
;       __builtin_amdgcn_global_load_lds((const unsigned*)(_g + offA[_i]), (unsigned*)((char*)(P) + tidx * 16 + _i * 8192), 16, 0, 0); } } while (0)
; #define STAGEB(P, br, kt) do { const char* _g = uptr(Bt + (size_t)(br) * ldb + (size_t)(kt) * BK); \
;     _Pragma("unroll") for (int _i = 0; _i < 2; ++_i) { \
;       __builtin_amdgcn_global_load_lds((const unsigned*)(_g + offB[_i]), (unsigned*)((char*)(P) + tidx * 16 + _i * 8192), 16, 0, 0); } } while (0)
; #define LDA(dst, b, h) _Pragma("unroll") for (int m = 0; m < 4; ++m) _Pragma("unroll") for (int k = 0; k < 2; ++k) \
;     dst[m][k] = *reinterpret_cast<const bf16x8*>((char*)SA(b, h) + aoff + m * 2048 + k * 1024)
; #define LDB(dst, b, h) _Pragma("unroll") for (int n = 0; n < 2; ++n) _Pragma("unroll") for (int k = 0; k < 2; ++k) \
;     dst[n][k] = *reinterpret_cast<const bf16x8*>((char*)SB(b, h) + boff + n * (SWAP ? 256 : 2048) + k * 1024)
; #define WAIT_V(n) asm volatile("s_waitcnt vmcnt(" #n ")" ::: "memory")
; #define WAIT_L(n) asm volatile("s_waitcnt lgkmcnt(" #n ")" ::: "memory")
; #define BAR __builtin_amdgcn_s_barrier()
; #define SCHED __builtin_amdgcn_sched_barrier(0)
; template <int EPI>
; DI void gemm_phase(const u16* __restrict__ A, int lda, const u16* __restrict__ Bt, int ldb,
;                    int M, int N, int K, const Epi& e, unsigned char* shmraw, int wv, int slot) {
;     ...
;     for (int t = 0; t < nt - 2; t += 2) {
;       LDB(B0, 0, 0); SCHED; LDA(At, 0, 0); STAGEA(SA(1, 1), brow + HALF, t + 1);
;       WAIT_L(8); BAR; WAIT_L(0); MMA(0, 0, At, B0); BAR; SCHED;
;       LDB(B1, 0, 1); STAGEB(SB(0, 0), bcol, t + 2);
;       BAR; WAIT_L(0); MMA(0, 1, At, B1); BAR;
;       LDA(At, 0, 1); STAGEA(SA(0, 0), brow, t + 2);
;       BAR; WAIT_L(0); MMA(1, 0, At, B0); BAR; SCHED;
;       STAGEB(SB(0, 1), bcol + HALF, t + 2);
;       WAIT_V(6); BAR; MMA(1, 1, At, B1); BAR;
.LBB0_818:
	v_add_u32_e32 v0, s33, v134
	ds_read_b128 v[152:155], v0
	ds_read_b128 v[156:159], v0 offset:256
	ds_read_b128 v[160:163], v0 offset:1024
	ds_read_b128 v[164:167], v0 offset:1280
	s_add_u32 s31, s25, s20
	s_addc_u32 s35, s26, s21
	s_add_u32 s38, s31, 0x80
	v_add_u32_e32 v0, 0xc000, v137
	s_addc_u32 s39, s35, 0
	v_readfirstlane_b32 s36, v0
	v_lshl_add_u64 v[150:151], s[38:39], 0, v[132:133]
	s_mov_b32 m0, s36
	ds_read_b128 v[168:171], v149
	ds_read_b128 v[172:175], v149 offset:1024
	ds_read_b128 v[176:179], v149 offset:2048
	ds_read_b128 v[182:185], v149 offset:3072
	ds_read_b128 v[190:193], v149 offset:4096
	ds_read_b128 v[194:197], v149 offset:5120
	ds_read_b128 v[198:201], v149 offset:6144
	ds_read_b128 v[202:205], v149 offset:7168
	global_load_lds_dwordx4 v[150:151], off
	v_add_u32_e32 v150, 0xe000, v137
	v_lshl_add_u64 v[180:181], s[38:39], 0, v[130:131]
	v_readfirstlane_b32 s36, v150
	s_mov_b32 m0, s36
	s_nop 0
	global_load_lds_dwordx4 v[180:181], off
	s_waitcnt lgkmcnt(8)
	s_barrier
	s_waitcnt lgkmcnt(0)
	s_setprio 1
	v_mfma_f32_16x16x32_bf16 v[126:129], v[152:155], v[168:171], v[126:129]
	v_mfma_f32_16x16x32_bf16 v[122:125], v[156:159], v[168:171], v[122:125]
	v_mfma_f32_16x16x32_bf16 v[118:121], v[152:155], v[176:179], v[118:121]
	v_mfma_f32_16x16x32_bf16 v[114:117], v[156:159], v[176:179], v[114:117]
	v_mfma_f32_16x16x32_bf16 v[110:113], v[152:155], v[190:193], v[110:113]
	v_mfma_f32_16x16x32_bf16 v[106:109], v[156:159], v[190:193], v[106:109]
	v_mfma_f32_16x16x32_bf16 v[102:105], v[152:155], v[198:201], v[102:105]
	v_mfma_f32_16x16x32_bf16 v[98:101], v[156:159], v[198:201], v[98:101]
	v_mfma_f32_16x16x32_bf16 v[126:129], v[160:163], v[172:175], v[126:129]
	v_mfma_f32_16x16x32_bf16 v[122:125], v[164:167], v[172:175], v[122:125]
	v_mfma_f32_16x16x32_bf16 v[118:121], v[160:163], v[182:185], v[118:121]
	v_mfma_f32_16x16x32_bf16 v[114:117], v[164:167], v[182:185], v[114:117]
	v_mfma_f32_16x16x32_bf16 v[110:113], v[160:163], v[194:197], v[110:113]
	v_mfma_f32_16x16x32_bf16 v[106:109], v[164:167], v[194:197], v[106:109]
	v_mfma_f32_16x16x32_bf16 v[102:105], v[160:163], v[202:205], v[102:105]
	v_mfma_f32_16x16x32_bf16 v[98:101], v[164:167], v[202:205], v[98:101]
	s_setprio 0
	s_barrier
	s_add_u32 s36, s9, s20
	s_addc_u32 s37, s27, s21
	s_add_u32 s38, s36, 0x100
	s_addc_u32 s39, s37, 0
	v_readfirstlane_b32 s40, v135
	v_add_u32_e32 v151, s84, v134
	v_lshl_add_u64 v[180:181], s[38:39], 0, v[132:133]
	s_mov_b32 m0, s40
	ds_read_b128 v[206:209], v151
	ds_read_b128 v[210:213], v151 offset:256
	ds_read_b128 v[214:217], v151 offset:1024
	ds_read_b128 v[218:221], v151 offset:1280
	global_load_lds_dwordx4 v[180:181], off
	v_lshl_add_u64 v[180:181], s[38:39], 0, v[130:131]
	v_readfirstlane_b32 s38, v136
	s_mov_b32 m0, s38
	s_nop 0
	global_load_lds_dwordx4 v[180:181], off
	s_barrier
	s_waitcnt lgkmcnt(0)
	s_setprio 1
	v_mfma_f32_16x16x32_bf16 v[54:57], v[206:209], v[168:171], v[54:57]
	v_mfma_f32_16x16x32_bf16 v[42:45], v[210:213], v[168:171], v[42:45]
	v_mfma_f32_16x16x32_bf16 v[38:41], v[206:209], v[176:179], v[38:41]
	v_mfma_f32_16x16x32_bf16 v[34:37], v[210:213], v[176:179], v[34:37]
	v_mfma_f32_16x16x32_bf16 v[30:33], v[206:209], v[190:193], v[30:33]
	v_mfma_f32_16x16x32_bf16 v[26:29], v[210:213], v[190:193], v[26:29]
	v_mfma_f32_16x16x32_bf16 v[22:25], v[206:209], v[198:201], v[22:25]
	v_mfma_f32_16x16x32_bf16 v[18:21], v[210:213], v[198:201], v[18:21]
	v_mfma_f32_16x16x32_bf16 v[54:57], v[214:217], v[172:175], v[54:57]
	v_mfma_f32_16x16x32_bf16 v[42:45], v[218:221], v[172:175], v[42:45]
	v_mfma_f32_16x16x32_bf16 v[38:41], v[214:217], v[182:185], v[38:41]
	v_mfma_f32_16x16x32_bf16 v[34:37], v[218:221], v[182:185], v[34:37]
	v_mfma_f32_16x16x32_bf16 v[30:33], v[214:217], v[194:197], v[30:33]
	v_mfma_f32_16x16x32_bf16 v[26:29], v[218:221], v[194:197], v[26:29]
	v_mfma_f32_16x16x32_bf16 v[22:25], v[214:217], v[202:205], v[22:25]
	v_mfma_f32_16x16x32_bf16 v[18:21], v[218:221], v[202:205], v[18:21]
	s_setprio 0
	s_add_u32 s40, s13, s20
	s_addc_u32 s41, s28, s21
	s_add_u32 s38, s40, 0x100
	s_addc_u32 s39, s41, 0
	v_readfirstlane_b32 s42, v137
	v_lshl_add_u64 v[180:181], s[38:39], 0, v[132:133]
	s_mov_b32 m0, s42
	s_barrier
	ds_read_b128 v[168:171], v149 offset:16384
	ds_read_b128 v[172:175], v149 offset:17408
	ds_read_b128 v[176:179], v149 offset:18432
	ds_read_b128 v[182:185], v149 offset:19456
	ds_read_b128 v[190:193], v149 offset:20480
	ds_read_b128 v[194:197], v149 offset:21504
	ds_read_b128 v[198:201], v149 offset:22528
	ds_read_b128 v[202:205], v149 offset:23552
	global_load_lds_dwordx4 v[180:181], off
	v_lshl_add_u64 v[180:181], s[38:39], 0, v[130:131]
	v_readfirstlane_b32 s38, v138
	s_mov_b32 m0, s38
	s_nop 0
	global_load_lds_dwordx4 v[180:181], off
	s_barrier
	s_waitcnt lgkmcnt(0)
	s_setprio 1
	v_mfma_f32_16x16x32_bf16 v[14:17], v[152:155], v[168:171], v[14:17]
	v_mfma_f32_16x16x32_bf16 v[10:13], v[156:159], v[168:171], v[10:13]
	v_mfma_f32_16x16x32_bf16 v[6:9], v[152:155], v[176:179], v[6:9]
	v_mfma_f32_16x16x32_bf16 v[2:5], v[156:159], v[176:179], v[2:5]
	v_mfma_f32_16x16x32_bf16 v[46:49], v[152:155], v[190:193], v[46:49]
	v_mfma_f32_16x16x32_bf16 v[50:53], v[156:159], v[190:193], v[50:53]
	v_mfma_f32_16x16x32_bf16 v[58:61], v[152:155], v[198:201], v[58:61]
	v_mfma_f32_16x16x32_bf16 v[66:69], v[156:159], v[198:201], v[66:69]
	v_mfma_f32_16x16x32_bf16 v[14:17], v[160:163], v[172:175], v[14:17]
	v_mfma_f32_16x16x32_bf16 v[10:13], v[164:167], v[172:175], v[10:13]
	v_mfma_f32_16x16x32_bf16 v[6:9], v[160:163], v[182:185], v[6:9]
	v_mfma_f32_16x16x32_bf16 v[2:5], v[164:167], v[182:185], v[2:5]
	v_mfma_f32_16x16x32_bf16 v[46:49], v[160:163], v[194:197], v[46:49]
	v_mfma_f32_16x16x32_bf16 v[50:53], v[164:167], v[194:197], v[50:53]
	v_mfma_f32_16x16x32_bf16 v[58:61], v[160:163], v[202:205], v[58:61]
	v_mfma_f32_16x16x32_bf16 v[66:69], v[164:167], v[202:205], v[66:69]
	s_setprio 0
	s_barrier
; #define STAGEA(P, br, kt) do { const char* _g = uptr(A + (size_t)(br) * lda + (size_t)(kt) * BK); \
;     _Pragma("unroll") for (int _i = 0; _i < 2; ++_i) { \
;       __builtin_amdgcn_global_load_lds((const unsigned*)(_g + offA[_i]), (unsigned*)((char*)(P) + tidx * 16 + _i * 8192), 16, 0, 0); } } while (0)
; #define STAGEB(P, br, kt) do { const char* _g = uptr(Bt + (size_t)(br) * ldb + (size_t)(kt) * BK); \
;     _Pragma("unroll") for (int _i = 0; _i < 2; ++_i) { \
;       __builtin_amdgcn_global_load_lds((const unsigned*)(_g + offB[_i]), (unsigned*)((char*)(P) + tidx * 16 + _i * 8192), 16, 0, 0); } } while (0)
; #define LDA(dst, b, h) _Pragma("unroll") for (int m = 0; m < 4; ++m) _Pragma("unroll") for (int k = 0; k < 2; ++k) \
;     dst[m][k] = *reinterpret_cast<const bf16x8*>((char*)SA(b, h) + aoff + m * 2048 + k * 1024)
; #define LDB(dst, b, h) _Pragma("unroll") for (int n = 0; n < 2; ++n) _Pragma("unroll") for (int k = 0; k < 2; ++k) \
;     dst[n][k] = *reinterpret_cast<const bf16x8*>((char*)SB(b, h) + boff + n * (SWAP ? 256 : 2048) + k * 1024)
; #define WAIT_V(n) asm volatile("s_waitcnt vmcnt(" #n ")" ::: "memory")
; #define WAIT_L(n) asm volatile("s_waitcnt lgkmcnt(" #n ")" ::: "memory")
; #define BAR __builtin_amdgcn_s_barrier()
; #define SCHED __builtin_amdgcn_sched_barrier(0)
; template <int EPI>
; DI void gemm_phase(const u16* __restrict__ A, int lda, const u16* __restrict__ Bt, int ldb,
;                    int M, int N, int K, const Epi& e, unsigned char* shmraw, int wv, int slot) {
;     ...
;       STAGEB(SB(0, 1), bcol + HALF, t + 2);
;       WAIT_V(6); BAR; MMA(1, 1, At, B1); BAR;
;       LDB(B0, 1, 0); SCHED; LDA(At, 1, 0); STAGEA(SA(0, 1), brow + HALF, t + 2);
;       WAIT_L(8); BAR; WAIT_L(0); MMA(0, 0, At, B0); BAR; SCHED;
;       LDB(B1, 1, 1); STAGEB(SB(1, 0), bcol, t + 3);
;       BAR; WAIT_L(0); MMA(0, 1, At, B1); BAR;
;       LDA(At, 1, 1); STAGEA(SA(1, 0), brow, t + 3);
;       BAR; WAIT_L(0); MMA(1, 0, At, B0); BAR; SCHED;
	s_add_u32 s42, s29, s20
	s_addc_u32 s43, s30, s21
	s_add_u32 s38, s42, 0x100
	s_addc_u32 s39, s43, 0
	v_readfirstlane_b32 s48, v139
	v_lshl_add_u64 v[152:153], s[38:39], 0, v[132:133]
	s_mov_b32 m0, s48
	s_nop 0
	global_load_lds_dwordx4 v[152:153], off
	v_lshl_add_u64 v[152:153], s[38:39], 0, v[130:131]
	v_readfirstlane_b32 s38, v140
	s_mov_b32 m0, s38
	s_nop 0
	global_load_lds_dwordx4 v[152:153], off
	s_waitcnt vmcnt(6)
	s_barrier
	s_setprio 1
	v_mfma_f32_16x16x32_bf16 v[62:65], v[206:209], v[168:171], v[62:65]
	v_mfma_f32_16x16x32_bf16 v[70:73], v[210:213], v[168:171], v[70:73]
	v_mfma_f32_16x16x32_bf16 v[74:77], v[206:209], v[176:179], v[74:77]
	v_mfma_f32_16x16x32_bf16 v[78:81], v[210:213], v[176:179], v[78:81]
	v_mfma_f32_16x16x32_bf16 v[82:85], v[206:209], v[190:193], v[82:85]
	v_mfma_f32_16x16x32_bf16 v[86:89], v[210:213], v[190:193], v[86:89]
	v_mfma_f32_16x16x32_bf16 v[90:93], v[206:209], v[198:201], v[90:93]
	v_mfma_f32_16x16x32_bf16 v[94:97], v[210:213], v[198:201], v[94:97]
	v_mfma_f32_16x16x32_bf16 v[62:65], v[214:217], v[172:175], v[62:65]
	v_mfma_f32_16x16x32_bf16 v[70:73], v[218:221], v[172:175], v[70:73]
	v_mfma_f32_16x16x32_bf16 v[74:77], v[214:217], v[182:185], v[74:77]
	v_mfma_f32_16x16x32_bf16 v[78:81], v[218:221], v[182:185], v[78:81]
	v_mfma_f32_16x16x32_bf16 v[82:85], v[214:217], v[194:197], v[82:85]
	v_mfma_f32_16x16x32_bf16 v[86:89], v[218:221], v[194:197], v[86:89]
	v_mfma_f32_16x16x32_bf16 v[90:93], v[214:217], v[202:205], v[90:93]
	v_mfma_f32_16x16x32_bf16 v[94:97], v[218:221], v[202:205], v[94:97]
	s_setprio 0
	v_add_u32_e32 v151, s85, v134
	s_barrier
	ds_read_b128 v[152:155], v151
	ds_read_b128 v[156:159], v151 offset:256
	ds_read_b128 v[160:163], v151 offset:1024
	ds_read_b128 v[164:167], v151 offset:1280
	s_add_u32 s38, s31, 0x100
	s_addc_u32 s39, s35, 0
	v_readfirstlane_b32 s31, v141
	v_lshl_add_u64 v[180:181], s[38:39], 0, v[132:133]
	s_mov_b32 m0, s31
	v_readfirstlane_b32 s31, v142
	ds_read_b128 v[168:171], v149 offset:32768
	ds_read_b128 v[172:175], v149 offset:33792
	ds_read_b128 v[176:179], v149 offset:34816
	ds_read_b128 v[182:185], v149 offset:35840
	ds_read_b128 v[190:193], v149 offset:36864
	ds_read_b128 v[194:197], v149 offset:37888
	ds_read_b128 v[198:201], v149 offset:38912
	ds_read_b128 v[202:205], v149 offset:39936
	global_load_lds_dwordx4 v[180:181], off
	v_lshl_add_u64 v[180:181], s[38:39], 0, v[130:131]
	s_mov_b32 m0, s31
	s_nop 0
	global_load_lds_dwordx4 v[180:181], off
	s_waitcnt lgkmcnt(8)
	s_barrier
	s_waitcnt lgkmcnt(0)
	s_setprio 1
	v_mfma_f32_16x16x32_bf16 v[126:129], v[152:155], v[168:171], v[126:129]
	v_mfma_f32_16x16x32_bf16 v[122:125], v[156:159], v[168:171], v[122:125]
	v_mfma_f32_16x16x32_bf16 v[118:121], v[152:155], v[176:179], v[118:121]
	v_mfma_f32_16x16x32_bf16 v[114:117], v[156:159], v[176:179], v[114:117]
	v_mfma_f32_16x16x32_bf16 v[110:113], v[152:155], v[190:193], v[110:113]
	v_mfma_f32_16x16x32_bf16 v[106:109], v[156:159], v[190:193], v[106:109]
	v_mfma_f32_16x16x32_bf16 v[102:105], v[152:155], v[198:201], v[102:105]
	v_mfma_f32_16x16x32_bf16 v[98:101], v[156:159], v[198:201], v[98:101]
	v_mfma_f32_16x16x32_bf16 v[126:129], v[160:163], v[172:175], v[126:129]
	v_mfma_f32_16x16x32_bf16 v[122:125], v[164:167], v[172:175], v[122:125]
	v_mfma_f32_16x16x32_bf16 v[118:121], v[160:163], v[182:185], v[118:121]
	v_mfma_f32_16x16x32_bf16 v[114:117], v[164:167], v[182:185], v[114:117]
	v_mfma_f32_16x16x32_bf16 v[110:113], v[160:163], v[194:197], v[110:113]
	v_mfma_f32_16x16x32_bf16 v[106:109], v[164:167], v[194:197], v[106:109]
	v_mfma_f32_16x16x32_bf16 v[102:105], v[160:163], v[202:205], v[102:105]
	v_mfma_f32_16x16x32_bf16 v[98:101], v[164:167], v[202:205], v[98:101]
	s_setprio 0
	s_barrier
	s_add_u32 s38, s36, 0x180
	s_addc_u32 s39, s37, 0
	v_readfirstlane_b32 s31, v143
	v_add_u32_e32 v151, s86, v134
	v_lshl_add_u64 v[180:181], s[38:39], 0, v[132:133]
	s_mov_b32 m0, s31
	v_readfirstlane_b32 s31, v144
	ds_read_b128 v[206:209], v151
	ds_read_b128 v[210:213], v151 offset:256
	ds_read_b128 v[214:217], v151 offset:1024
	ds_read_b128 v[218:221], v151 offset:1280
	global_load_lds_dwordx4 v[180:181], off
	v_lshl_add_u64 v[180:181], s[38:39], 0, v[130:131]
	s_mov_b32 m0, s31
	s_nop 0
	global_load_lds_dwordx4 v[180:181], off
	s_barrier
	s_waitcnt lgkmcnt(0)
	s_setprio 1
	v_mfma_f32_16x16x32_bf16 v[54:57], v[206:209], v[168:171], v[54:57]
	v_mfma_f32_16x16x32_bf16 v[42:45], v[210:213], v[168:171], v[42:45]
	v_mfma_f32_16x16x32_bf16 v[38:41], v[206:209], v[176:179], v[38:41]
	v_mfma_f32_16x16x32_bf16 v[34:37], v[210:213], v[176:179], v[34:37]
	v_mfma_f32_16x16x32_bf16 v[30:33], v[206:209], v[190:193], v[30:33]
	v_mfma_f32_16x16x32_bf16 v[26:29], v[210:213], v[190:193], v[26:29]
	v_mfma_f32_16x16x32_bf16 v[22:25], v[206:209], v[198:201], v[22:25]
	v_mfma_f32_16x16x32_bf16 v[18:21], v[210:213], v[198:201], v[18:21]
	v_mfma_f32_16x16x32_bf16 v[54:57], v[214:217], v[172:175], v[54:57]
	v_mfma_f32_16x16x32_bf16 v[42:45], v[218:221], v[172:175], v[42:45]
	v_mfma_f32_16x16x32_bf16 v[38:41], v[214:217], v[182:185], v[38:41]
	v_mfma_f32_16x16x32_bf16 v[34:37], v[218:221], v[182:185], v[34:37]
	v_mfma_f32_16x16x32_bf16 v[30:33], v[214:217], v[194:197], v[30:33]
	v_mfma_f32_16x16x32_bf16 v[26:29], v[218:221], v[194:197], v[26:29]
	v_mfma_f32_16x16x32_bf16 v[22:25], v[214:217], v[202:205], v[22:25]
	v_mfma_f32_16x16x32_bf16 v[18:21], v[218:221], v[202:205], v[18:21]
	s_setprio 0
	s_add_u32 s38, s40, 0x180
	s_addc_u32 s39, s41, 0
	v_readfirstlane_b32 s31, v145
	v_lshl_add_u64 v[180:181], s[38:39], 0, v[132:133]
	s_mov_b32 m0, s31
	v_readfirstlane_b32 s31, v146
	s_barrier
; #define STAGEA(P, br, kt) do { const char* _g = uptr(A + (size_t)(br) * lda + (size_t)(kt) * BK); \
;     _Pragma("unroll") for (int _i = 0; _i < 2; ++_i) { \
;       __builtin_amdgcn_global_load_lds((const unsigned*)(_g + offA[_i]), (unsigned*)((char*)(P) + tidx * 16 + _i * 8192), 16, 0, 0); } } while (0)
; #define STAGEB(P, br, kt) do { const char* _g = uptr(Bt + (size_t)(br) * ldb + (size_t)(kt) * BK); \
;     _Pragma("unroll") for (int _i = 0; _i < 2; ++_i) { \
;       __builtin_amdgcn_global_load_lds((const unsigned*)(_g + offB[_i]), (unsigned*)((char*)(P) + tidx * 16 + _i * 8192), 16, 0, 0); } } while (0)
; #define LDA(dst, b, h) _Pragma("unroll") for (int m = 0; m < 4; ++m) _Pragma("unroll") for (int k = 0; k < 2; ++k) \
;     dst[m][k] = *reinterpret_cast<const bf16x8*>((char*)SA(b, h) + aoff + m * 2048 + k * 1024)
; #define LDB(dst, b, h) _Pragma("unroll") for (int n = 0; n < 2; ++n) _Pragma("unroll") for (int k = 0; k < 2; ++k) \
;     dst[n][k] = *reinterpret_cast<const bf16x8*>((char*)SB(b, h) + boff + n * (SWAP ? 256 : 2048) + k * 1024)
; #define WAIT_V(n) asm volatile("s_waitcnt vmcnt(" #n ")" ::: "memory")
; #define WAIT_L(n) asm volatile("s_waitcnt lgkmcnt(" #n ")" ::: "memory")
; #define BAR __builtin_amdgcn_s_barrier()
; #define SCHED __builtin_amdgcn_sched_barrier(0)
; template <int EPI>
; DI void gemm_phase(const u16* __restrict__ A, int lda, const u16* __restrict__ Bt, int ldb,
;                    int M, int N, int K, const Epi& e, unsigned char* shmraw, int wv, int slot) {
;     ...
;       BAR; WAIT_L(0); MMA(0, 1, At, B1); BAR;
;       LDA(At, 1, 1); STAGEA(SA(1, 0), brow, t + 3);
;       BAR; WAIT_L(0); MMA(1, 0, At, B0); BAR; SCHED;
;       STAGEB(SB(1, 1), bcol + HALF, t + 3);
;       WAIT_V(6); BAR; MMA(1, 1, At, B1); BAR;
;     }
;     { LDB(B0, 0, 0); LDA(At, 0, 0); STAGEA(SA(1, 1), brow + HALF, nt - 1);
;       BAR; WAIT_L(0); MMA(0, 0, At, B0); BAR;
	ds_read_b128 v[168:171], v149 offset:49152
	ds_read_b128 v[172:175], v149 offset:50176
	ds_read_b128 v[176:179], v149 offset:51200
	ds_read_b128 v[182:185], v149 offset:52224
	ds_read_b128 v[190:193], v149 offset:53248
	ds_read_b128 v[194:197], v149 offset:54272
	ds_read_b128 v[198:201], v149 offset:55296
	ds_read_b128 v[202:205], v149 offset:56320
	global_load_lds_dwordx4 v[180:181], off
	v_lshl_add_u64 v[180:181], s[38:39], 0, v[130:131]
	s_mov_b32 m0, s31
	s_nop 0
	global_load_lds_dwordx4 v[180:181], off
	s_barrier
	s_waitcnt lgkmcnt(0)
	s_setprio 1
	v_mfma_f32_16x16x32_bf16 v[14:17], v[152:155], v[168:171], v[14:17]
	v_mfma_f32_16x16x32_bf16 v[10:13], v[156:159], v[168:171], v[10:13]
	v_mfma_f32_16x16x32_bf16 v[6:9], v[152:155], v[176:179], v[6:9]
	v_mfma_f32_16x16x32_bf16 v[2:5], v[156:159], v[176:179], v[2:5]
	v_mfma_f32_16x16x32_bf16 v[46:49], v[152:155], v[190:193], v[46:49]
	v_mfma_f32_16x16x32_bf16 v[50:53], v[156:159], v[190:193], v[50:53]
	v_mfma_f32_16x16x32_bf16 v[58:61], v[152:155], v[198:201], v[58:61]
	v_mfma_f32_16x16x32_bf16 v[66:69], v[156:159], v[198:201], v[66:69]
	v_mfma_f32_16x16x32_bf16 v[14:17], v[160:163], v[172:175], v[14:17]
	v_mfma_f32_16x16x32_bf16 v[10:13], v[164:167], v[172:175], v[10:13]
	v_mfma_f32_16x16x32_bf16 v[6:9], v[160:163], v[182:185], v[6:9]
	v_mfma_f32_16x16x32_bf16 v[2:5], v[164:167], v[182:185], v[2:5]
	v_mfma_f32_16x16x32_bf16 v[46:49], v[160:163], v[194:197], v[46:49]
	v_mfma_f32_16x16x32_bf16 v[50:53], v[164:167], v[194:197], v[50:53]
	v_mfma_f32_16x16x32_bf16 v[58:61], v[160:163], v[202:205], v[58:61]
	v_mfma_f32_16x16x32_bf16 v[66:69], v[164:167], v[202:205], v[66:69]
	s_setprio 0
	s_barrier
	s_add_u32 s38, s42, 0x180
	s_addc_u32 s39, s43, 0
	v_readfirstlane_b32 s31, v147
	v_lshl_add_u64 v[152:153], s[38:39], 0, v[132:133]
	s_mov_b32 m0, s31
	v_readfirstlane_b32 s31, v148
	global_load_lds_dwordx4 v[152:153], off
	v_lshl_add_u64 v[152:153], s[38:39], 0, v[130:131]
	s_mov_b32 m0, s31
	s_nop 0
	global_load_lds_dwordx4 v[152:153], off
	s_waitcnt vmcnt(6)
	s_barrier
	s_setprio 1
	v_mfma_f32_16x16x32_bf16 v[62:65], v[206:209], v[168:171], v[62:65]
	v_mfma_f32_16x16x32_bf16 v[70:73], v[210:213], v[168:171], v[70:73]
	v_mfma_f32_16x16x32_bf16 v[74:77], v[206:209], v[176:179], v[74:77]
	v_mfma_f32_16x16x32_bf16 v[78:81], v[210:213], v[176:179], v[78:81]
	v_mfma_f32_16x16x32_bf16 v[82:85], v[206:209], v[190:193], v[82:85]
	v_mfma_f32_16x16x32_bf16 v[86:89], v[210:213], v[190:193], v[86:89]
	v_mfma_f32_16x16x32_bf16 v[90:93], v[206:209], v[198:201], v[90:93]
	v_mfma_f32_16x16x32_bf16 v[94:97], v[210:213], v[198:201], v[94:97]
	v_mfma_f32_16x16x32_bf16 v[62:65], v[214:217], v[172:175], v[62:65]
	v_mfma_f32_16x16x32_bf16 v[70:73], v[218:221], v[172:175], v[70:73]
	v_mfma_f32_16x16x32_bf16 v[74:77], v[214:217], v[182:185], v[74:77]
	v_mfma_f32_16x16x32_bf16 v[78:81], v[218:221], v[182:185], v[78:81]
	v_mfma_f32_16x16x32_bf16 v[82:85], v[214:217], v[194:197], v[82:85]
	v_mfma_f32_16x16x32_bf16 v[86:89], v[218:221], v[194:197], v[86:89]
	v_mfma_f32_16x16x32_bf16 v[90:93], v[214:217], v[202:205], v[90:93]
	v_mfma_f32_16x16x32_bf16 v[94:97], v[218:221], v[202:205], v[94:97]
	s_setprio 0
	s_add_i32 s1, s1, 2
	s_add_u32 s20, s20, 0x100
	s_addc_u32 s21, s21, 0
	s_cmp_gt_u32 s1, 59
	s_barrier
	s_cbranch_scc0 .LBB0_818
	s_lshl_b64 s[18:19], s[18:19], 1
	v_readlane_b32 s0, v253, 28
	s_add_u32 s18, s0, s18
	v_readlane_b32 s0, v253, 29
	v_add_u32_e32 v186, 16, v134
	s_addc_u32 s19, s0, s19
	v_readfirstlane_b32 s1, v0
	v_add_u32_e32 v151, 0x10000, v186
	v_lshl_add_u64 v[180:181], s[18:19], 0, v[132:133]
	s_mov_b32 m0, s1
	v_readfirstlane_b32 s1, v150
	ds_read_b128 v[152:155], v151
	ds_read_b128 v[156:159], v151 offset:256
	ds_read_b128 v[160:163], v151 offset:1024
	ds_read_b128 v[164:167], v151 offset:1280
	ds_read_b128 v[168:171], v149
	ds_read_b128 v[172:175], v149 offset:1024
	ds_read_b128 v[176:179], v149 offset:2048
	ds_read_b128 v[182:185], v149 offset:3072
	ds_read_b128 v[190:193], v149 offset:4096
	ds_read_b128 v[194:197], v149 offset:5120
	ds_read_b128 v[198:201], v149 offset:6144
	ds_read_b128 v[202:205], v149 offset:7168
	global_load_lds_dwordx4 v[180:181], off
	v_lshl_add_u64 v[180:181], s[18:19], 0, v[130:131]
	s_mov_b32 m0, s1
	s_nop 0
	global_load_lds_dwordx4 v[180:181], off
	s_barrier
	s_waitcnt lgkmcnt(0)
	s_setprio 1
	v_mfma_f32_16x16x32_bf16 v[126:129], v[152:155], v[168:171], v[126:129]
	v_mfma_f32_16x16x32_bf16 v[122:125], v[156:159], v[168:171], v[122:125]
	v_mfma_f32_16x16x32_bf16 v[110:113], v[152:155], v[190:193], v[110:113]
	v_mfma_f32_16x16x32_bf16 v[106:109], v[156:159], v[190:193], v[106:109]
	v_mfma_f32_16x16x32_bf16 v[126:129], v[160:163], v[172:175], v[126:129]
	v_mfma_f32_16x16x32_bf16 v[122:125], v[164:167], v[172:175], v[122:125]
	v_mfma_f32_16x16x32_bf16 v[118:121], v[152:155], v[176:179], v[118:121]
	v_mfma_f32_16x16x32_bf16 v[114:117], v[156:159], v[176:179], v[114:117]
	v_mfma_f32_16x16x32_bf16 v[110:113], v[160:163], v[194:197], v[110:113]
	v_mfma_f32_16x16x32_bf16 v[106:109], v[164:167], v[194:197], v[106:109]
	v_mfma_f32_16x16x32_bf16 v[102:105], v[152:155], v[198:201], v[102:105]
	v_mfma_f32_16x16x32_bf16 v[98:101], v[156:159], v[198:201], v[98:101]
	v_mfma_f32_16x16x32_bf16 v[206:209], v[160:163], v[182:185], v[118:121]
	v_mfma_f32_16x16x32_bf16 v[210:213], v[164:167], v[182:185], v[114:117]
	v_mfma_f32_16x16x32_bf16 v[214:217], v[160:163], v[202:205], v[102:105]
	v_mfma_f32_16x16x32_bf16 v[218:221], v[164:167], v[202:205], v[98:101]
	s_setprio 0
	v_add_u32_e32 v0, 0x14000, v186
	s_barrier
; #define LDA(dst, b, h) _Pragma("unroll") for (int m = 0; m < 4; ++m) _Pragma("unroll") for (int k = 0; k < 2; ++k) \
;     dst[m][k] = *reinterpret_cast<const bf16x8*>((char*)SA(b, h) + aoff + m * 2048 + k * 1024)
; #define LDB(dst, b, h) _Pragma("unroll") for (int n = 0; n < 2; ++n) _Pragma("unroll") for (int k = 0; k < 2; ++k) \
;     dst[n][k] = *reinterpret_cast<const bf16x8*>((char*)SB(b, h) + boff + n * (SWAP ? 256 : 2048) + k * 1024)
; #define WAIT_V(n) asm volatile("s_waitcnt vmcnt(" #n ")" ::: "memory")
; #define WAIT_L(n) asm volatile("s_waitcnt lgkmcnt(" #n ")" ::: "memory")
; #define BAR __builtin_amdgcn_s_barrier()
; template <int EPI>
; DI void gemm_phase(const u16* __restrict__ A, int lda, const u16* __restrict__ Bt, int ldb,
;                    int M, int N, int K, const Epi& e, unsigned char* shmraw, int wv, int slot) {
;     ...
;       BAR; WAIT_L(0); MMA(0, 0, At, B0); BAR;
;       LDB(B1, 0, 1); BAR; WAIT_L(0); MMA(0, 1, At, B1); BAR;
;       LDA(At, 0, 1); WAIT_V(4); BAR; WAIT_L(0); MMA(1, 0, At, B0); MMA(1, 1, At, B1); BAR; }
;     { LDB(B0, 1, 0); LDA(At, 1, 0); WAIT_V(2); BAR; WAIT_L(0); MMA(0, 0, At, B0); BAR;
	s_nop 0
	ds_read_b128 v[98:101], v0
	ds_read_b128 v[102:105], v0 offset:256
	ds_read_b128 v[114:117], v0 offset:1024
	ds_read_b128 v[118:121], v0 offset:1280
	s_barrier
	s_waitcnt lgkmcnt(0)
	s_setprio 1
	v_mfma_f32_16x16x32_bf16 v[54:57], v[98:101], v[168:171], v[54:57]
	v_mfma_f32_16x16x32_bf16 v[38:41], v[98:101], v[176:179], v[38:41]
	v_mfma_f32_16x16x32_bf16 v[34:37], v[102:105], v[176:179], v[34:37]
	v_mfma_f32_16x16x32_bf16 v[30:33], v[98:101], v[190:193], v[30:33]
	v_mfma_f32_16x16x32_bf16 v[26:29], v[102:105], v[190:193], v[26:29]
	v_mfma_f32_16x16x32_bf16 v[22:25], v[98:101], v[198:201], v[22:25]
	v_mfma_f32_16x16x32_bf16 v[18:21], v[102:105], v[198:201], v[18:21]
	v_mfma_f32_16x16x32_bf16 v[54:57], v[114:117], v[172:175], v[54:57]
	v_mfma_f32_16x16x32_bf16 v[42:45], v[102:105], v[168:171], v[42:45]
	v_mfma_f32_16x16x32_bf16 v[38:41], v[114:117], v[182:185], v[38:41]
	v_mfma_f32_16x16x32_bf16 v[34:37], v[118:121], v[182:185], v[34:37]
	v_mfma_f32_16x16x32_bf16 v[30:33], v[114:117], v[194:197], v[30:33]
	v_mfma_f32_16x16x32_bf16 v[26:29], v[118:121], v[194:197], v[26:29]
	v_mfma_f32_16x16x32_bf16 v[22:25], v[114:117], v[202:205], v[22:25]
	v_mfma_f32_16x16x32_bf16 v[18:21], v[118:121], v[202:205], v[18:21]
	v_mfma_f32_16x16x32_bf16 v[168:171], v[118:121], v[172:175], v[42:45]
	s_setprio 0
	s_barrier
	s_nop 0
	ds_read_b128 v[42:45], v149 offset:16384
	ds_read_b128 v[172:175], v149 offset:17408
	ds_read_b128 v[176:179], v149 offset:18432
	ds_read_b128 v[182:185], v149 offset:19456
	ds_read_b128 v[190:193], v149 offset:20480
	ds_read_b128 v[194:197], v149 offset:21504
	ds_read_b128 v[198:201], v149 offset:22528
	ds_read_b128 v[202:205], v149 offset:23552
	s_waitcnt vmcnt(4)
	s_barrier
	s_waitcnt lgkmcnt(0)
	s_setprio 1
	v_mfma_f32_16x16x32_bf16 v[46:49], v[152:155], v[190:193], v[46:49]
	v_mfma_f32_16x16x32_bf16 v[222:225], v[160:163], v[194:197], v[46:49]
	v_mfma_f32_16x16x32_bf16 v[46:49], v[156:159], v[190:193], v[50:53]
	v_mfma_f32_16x16x32_bf16 v[14:17], v[152:155], v[42:45], v[14:17]
	v_mfma_f32_16x16x32_bf16 v[10:13], v[156:159], v[42:45], v[10:13]
	v_mfma_f32_16x16x32_bf16 v[6:9], v[152:155], v[176:179], v[6:9]
	v_mfma_f32_16x16x32_bf16 v[2:5], v[156:159], v[176:179], v[2:5]
	v_mfma_f32_16x16x32_bf16 v[50:53], v[164:167], v[194:197], v[46:49]
	v_mfma_f32_16x16x32_bf16 v[46:49], v[152:155], v[198:201], v[58:61]
	v_mfma_f32_16x16x32_bf16 v[14:17], v[160:163], v[172:175], v[14:17]
	v_mfma_f32_16x16x32_bf16 v[10:13], v[164:167], v[172:175], v[10:13]
	v_mfma_f32_16x16x32_bf16 v[6:9], v[160:163], v[182:185], v[6:9]
	v_mfma_f32_16x16x32_bf16 v[2:5], v[164:167], v[182:185], v[2:5]
	v_mfma_f32_16x16x32_bf16 v[150:153], v[160:163], v[202:205], v[46:49]
	v_mfma_f32_16x16x32_bf16 v[46:49], v[156:159], v[198:201], v[66:69]
	v_mfma_f32_16x16x32_bf16 v[154:157], v[164:167], v[202:205], v[46:49]
	s_setprio 0
	s_setprio 1
	v_mfma_f32_16x16x32_bf16 v[46:49], v[98:101], v[42:45], v[62:65]
	v_mfma_f32_16x16x32_bf16 v[42:45], v[102:105], v[42:45], v[70:73]
	v_mfma_f32_16x16x32_bf16 v[162:165], v[118:121], v[172:175], v[42:45]
	v_mfma_f32_16x16x32_bf16 v[42:45], v[98:101], v[176:179], v[74:77]
	v_mfma_f32_16x16x32_bf16 v[158:161], v[114:117], v[172:175], v[46:49]
	v_mfma_f32_16x16x32_bf16 v[172:175], v[114:117], v[182:185], v[42:45]
	v_mfma_f32_16x16x32_bf16 v[42:45], v[102:105], v[176:179], v[78:81]
	v_mfma_f32_16x16x32_bf16 v[176:179], v[118:121], v[182:185], v[42:45]
	v_mfma_f32_16x16x32_bf16 v[42:45], v[98:101], v[190:193], v[82:85]
	v_mfma_f32_16x16x32_bf16 v[182:185], v[114:117], v[194:197], v[42:45]
	v_mfma_f32_16x16x32_bf16 v[42:45], v[102:105], v[190:193], v[86:89]
	v_mfma_f32_16x16x32_bf16 v[190:193], v[118:121], v[194:197], v[42:45]
	v_mfma_f32_16x16x32_bf16 v[42:45], v[98:101], v[198:201], v[90:93]
	v_mfma_f32_16x16x32_bf16 v[194:197], v[114:117], v[202:205], v[42:45]
	v_mfma_f32_16x16x32_bf16 v[42:45], v[102:105], v[198:201], v[94:97]
	v_mfma_f32_16x16x32_bf16 v[198:201], v[118:121], v[202:205], v[42:45]
	s_setprio 0
	v_add_u32_e32 v0, 0x18000, v186
	s_barrier
	ds_read_b128 v[82:85], v0
	ds_read_b128 v[86:89], v0 offset:256
	ds_read_b128 v[202:205], v0 offset:1024
	ds_read_b128 v[226:229], v0 offset:1280
	ds_read_b128 v[58:61], v149 offset:32768
	ds_read_b128 v[62:65], v149 offset:33792
	ds_read_b128 v[66:69], v149 offset:34816
	ds_read_b128 v[70:73], v149 offset:35840
	ds_read_b128 v[94:97], v149 offset:36864
	ds_read_b128 v[230:233], v149 offset:37888
	ds_read_b128 v[234:237], v149 offset:38912
	ds_read_b128 v[238:241], v149 offset:39936
	s_waitcnt vmcnt(2)
	s_barrier
; #define LDA(dst, b, h) _Pragma("unroll") for (int m = 0; m < 4; ++m) _Pragma("unroll") for (int k = 0; k < 2; ++k) \
;     dst[m][k] = *reinterpret_cast<const bf16x8*>((char*)SA(b, h) + aoff + m * 2048 + k * 1024)
; #define LDB(dst, b, h) _Pragma("unroll") for (int n = 0; n < 2; ++n) _Pragma("unroll") for (int k = 0; k < 2; ++k) \
;     dst[n][k] = *reinterpret_cast<const bf16x8*>((char*)SB(b, h) + boff + n * (SWAP ? 256 : 2048) + k * 1024)
; #define WAIT_V(n) asm volatile("s_waitcnt vmcnt(" #n ")" ::: "memory")
; #define WAIT_L(n) asm volatile("s_waitcnt lgkmcnt(" #n ")" ::: "memory")
; #define BAR __builtin_amdgcn_s_barrier()
; template <int EPI>
; DI void gemm_phase(const u16* __restrict__ A, int lda, const u16* __restrict__ Bt, int ldb,
;                    int M, int N, int K, const Epi& e, unsigned char* shmraw, int wv, int slot) {
;     ...
;     { LDB(B0, 1, 0); LDA(At, 1, 0); WAIT_V(2); BAR; WAIT_L(0); MMA(0, 0, At, B0); BAR;
;       LDB(B1, 1, 1); WAIT_V(0); BAR; WAIT_L(0); MMA(0, 1, At, B1); BAR;
;       LDA(At, 1, 1); BAR; WAIT_L(0); MMA(1, 0, At, B0); MMA(1, 1, At, B1); BAR; }
;     if (wr == 0) BAR;
	s_waitcnt lgkmcnt(0)
	s_setprio 1
	v_mfma_f32_16x16x32_bf16 v[42:45], v[82:85], v[58:61], v[126:129]
	v_mfma_f32_16x16x32_bf16 v[114:117], v[202:205], v[62:65], v[42:45]
	v_mfma_f32_16x16x32_bf16 v[42:45], v[86:89], v[58:61], v[122:125]
	v_mfma_f32_16x16x32_bf16 v[118:121], v[226:229], v[62:65], v[42:45]
	v_mfma_f32_16x16x32_bf16 v[42:45], v[82:85], v[66:69], v[206:209]
	v_mfma_f32_16x16x32_bf16 v[98:101], v[202:205], v[70:73], v[42:45]
	v_mfma_f32_16x16x32_bf16 v[42:45], v[86:89], v[66:69], v[210:213]
	v_mfma_f32_16x16x32_bf16 v[102:105], v[226:229], v[70:73], v[42:45]
	v_mfma_f32_16x16x32_bf16 v[42:45], v[82:85], v[94:97], v[110:113]
	v_mfma_f32_16x16x32_bf16 v[74:77], v[202:205], v[230:233], v[42:45]
	v_mfma_f32_16x16x32_bf16 v[42:45], v[86:89], v[94:97], v[106:109]
	v_mfma_f32_16x16x32_bf16 v[78:81], v[226:229], v[230:233], v[42:45]
	v_mfma_f32_16x16x32_bf16 v[42:45], v[82:85], v[234:237], v[214:217]
	v_mfma_f32_16x16x32_bf16 v[46:49], v[86:89], v[234:237], v[218:221]
	v_mfma_f32_16x16x32_bf16 v[42:45], v[202:205], v[238:241], v[42:45]
	v_mfma_f32_16x16x32_bf16 v[46:49], v[226:229], v[238:241], v[46:49]
	s_setprio 0
	v_add_u32_e32 v0, 0x1c000, v186
	s_barrier
	ds_read_b128 v[206:209], v0
	ds_read_b128 v[210:213], v0 offset:256
	ds_read_b128 v[214:217], v0 offset:1024
	ds_read_b128 v[218:221], v0 offset:1280
	s_waitcnt vmcnt(0)
	s_barrier
	s_waitcnt lgkmcnt(0)
	s_setprio 1
	v_mfma_f32_16x16x32_bf16 v[54:57], v[206:209], v[58:61], v[54:57]
	v_mfma_f32_16x16x32_bf16 v[122:125], v[214:217], v[62:65], v[54:57]
	v_mfma_f32_16x16x32_bf16 v[54:57], v[210:213], v[58:61], v[168:171]
	v_mfma_f32_16x16x32_bf16 v[38:41], v[206:209], v[66:69], v[38:41]
	v_mfma_f32_16x16x32_bf16 v[34:37], v[210:213], v[66:69], v[34:37]
	v_mfma_f32_16x16x32_bf16 v[30:33], v[206:209], v[94:97], v[30:33]
	v_mfma_f32_16x16x32_bf16 v[26:29], v[210:213], v[94:97], v[26:29]
	v_mfma_f32_16x16x32_bf16 v[22:25], v[206:209], v[234:237], v[22:25]
	v_mfma_f32_16x16x32_bf16 v[18:21], v[210:213], v[234:237], v[18:21]
	v_mfma_f32_16x16x32_bf16 v[126:129], v[218:221], v[62:65], v[54:57]
	v_mfma_f32_16x16x32_bf16 v[106:109], v[214:217], v[70:73], v[38:41]
	v_mfma_f32_16x16x32_bf16 v[110:113], v[218:221], v[70:73], v[34:37]
	v_mfma_f32_16x16x32_bf16 v[90:93], v[214:217], v[230:233], v[30:33]
	v_mfma_f32_16x16x32_bf16 v[94:97], v[218:221], v[230:233], v[26:29]
	v_mfma_f32_16x16x32_bf16 v[58:61], v[214:217], v[238:241], v[22:25]
	v_mfma_f32_16x16x32_bf16 v[62:65], v[218:221], v[238:241], v[18:21]
	s_setprio 0
	s_barrier
	ds_read_b128 v[26:29], v149 offset:49152
	ds_read_b128 v[30:33], v149 offset:50176
	ds_read_b128 v[54:57], v149 offset:51200
	ds_read_b128 v[166:169], v149 offset:52224
	ds_read_b128 v[230:233], v149 offset:53248
	ds_read_b128 v[234:237], v149 offset:54272
	ds_read_b128 v[238:241], v149 offset:55296
	ds_read_b128 v[242:245], v149 offset:56320
	s_barrier
	s_waitcnt lgkmcnt(0)
	s_setprio 1
	v_mfma_f32_16x16x32_bf16 v[2:5], v[86:89], v[54:57], v[2:5]
	v_mfma_f32_16x16x32_bf16 v[38:41], v[226:229], v[166:169], v[2:5]
	v_mfma_f32_16x16x32_bf16 v[2:5], v[82:85], v[230:233], v[222:225]
	v_mfma_f32_16x16x32_bf16 v[6:9], v[82:85], v[54:57], v[6:9]
	v_mfma_f32_16x16x32_bf16 v[18:21], v[202:205], v[234:237], v[2:5]
	v_mfma_f32_16x16x32_bf16 v[2:5], v[86:89], v[230:233], v[50:53]
	v_mfma_f32_16x16x32_bf16 v[14:17], v[82:85], v[26:29], v[14:17]
	v_mfma_f32_16x16x32_bf16 v[10:13], v[86:89], v[26:29], v[10:13]
	v_mfma_f32_16x16x32_bf16 v[34:37], v[202:205], v[166:169], v[6:9]
	v_mfma_f32_16x16x32_bf16 v[22:25], v[226:229], v[234:237], v[2:5]
	v_mfma_f32_16x16x32_bf16 v[2:5], v[82:85], v[238:241], v[150:153]
	v_mfma_f32_16x16x32_bf16 v[6:9], v[86:89], v[238:241], v[154:157]
	v_mfma_f32_16x16x32_bf16 v[66:69], v[202:205], v[30:33], v[14:17]
	v_mfma_f32_16x16x32_bf16 v[70:73], v[226:229], v[30:33], v[10:13]
	v_mfma_f32_16x16x32_bf16 v[2:5], v[202:205], v[242:245], v[2:5]
	v_mfma_f32_16x16x32_bf16 v[6:9], v[226:229], v[242:245], v[6:9]
	s_setprio 0
	s_setprio 1
	v_mfma_f32_16x16x32_bf16 v[10:13], v[206:209], v[26:29], v[158:161]
	v_mfma_f32_16x16x32_bf16 v[82:85], v[214:217], v[30:33], v[10:13]
	v_mfma_f32_16x16x32_bf16 v[10:13], v[210:213], v[26:29], v[162:165]
	v_mfma_f32_16x16x32_bf16 v[86:89], v[218:221], v[30:33], v[10:13]
	v_mfma_f32_16x16x32_bf16 v[10:13], v[206:209], v[54:57], v[172:175]
	v_mfma_f32_16x16x32_bf16 v[50:53], v[214:217], v[166:169], v[10:13]
	v_mfma_f32_16x16x32_bf16 v[10:13], v[210:213], v[54:57], v[176:179]
	v_mfma_f32_16x16x32_bf16 v[54:57], v[218:221], v[166:169], v[10:13]
	v_mfma_f32_16x16x32_bf16 v[10:13], v[206:209], v[230:233], v[182:185]
	v_mfma_f32_16x16x32_bf16 v[26:29], v[214:217], v[234:237], v[10:13]
	v_mfma_f32_16x16x32_bf16 v[10:13], v[210:213], v[230:233], v[190:193]
	v_mfma_f32_16x16x32_bf16 v[30:33], v[218:221], v[234:237], v[10:13]
	v_mfma_f32_16x16x32_bf16 v[10:13], v[206:209], v[238:241], v[194:197]
	v_mfma_f32_16x16x32_bf16 v[14:17], v[210:213], v[238:241], v[198:201]
	v_mfma_f32_16x16x32_bf16 v[10:13], v[214:217], v[242:245], v[10:13]
	v_mfma_f32_16x16x32_bf16 v[14:17], v[218:221], v[242:245], v[14:17]
	s_setprio 0
	s_barrier
	s_and_saveexec_b64 s[18:19], s[4:5]
	s_cbranch_execz .LBB0_821
	s_barrier

; #define STAGEA(P, br, kt) do { const char* _g = uptr(A + (size_t)(br) * lda + (size_t)(kt) * BK); \
;     _Pragma("unroll") for (int _i = 0; _i < 2; ++_i) { \
;       __builtin_amdgcn_global_load_lds((const unsigned*)(_g + offA[_i]), (unsigned*)((char*)(P) + tidx * 16 + _i * 8192), 16, 0, 0); } } while (0)
; #define STAGEB(P, br, kt) do { const char* _g = uptr(Bt + (size_t)(br) * ldb + (size_t)(kt) * BK); \
;     _Pragma("unroll") for (int _i = 0; _i < 2; ++_i) { \
;       __builtin_amdgcn_global_load_lds((const unsigned*)(_g + offB[_i]), (unsigned*)((char*)(P) + tidx * 16 + _i * 8192), 16, 0, 0); } } while (0)
; #define LDA(dst, b, h) _Pragma("unroll") for (int m = 0; m < 4; ++m) _Pragma("unroll") for (int k = 0; k < 2; ++k) \
;     dst[m][k] = *reinterpret_cast<const bf16x8*>((char*)SA(b, h) + aoff + m * 2048 + k * 1024)
; #define LDB(dst, b, h) _Pragma("unroll") for (int n = 0; n < 2; ++n) _Pragma("unroll") for (int k = 0; k < 2; ++k) \
;     dst[n][k] = *reinterpret_cast<const bf16x8*>((char*)SB(b, h) + boff + n * (SWAP ? 256 : 2048) + k * 1024)
; #define WAIT_V(n) asm volatile("s_waitcnt vmcnt(" #n ")" ::: "memory")
; #define WAIT_L(n) asm volatile("s_waitcnt lgkmcnt(" #n ")" ::: "memory")
; #define BAR __builtin_amdgcn_s_barrier()
; #define SCHED __builtin_amdgcn_sched_barrier(0)
; template <int EPI>
; DI void gemm_phase(const u16* __restrict__ A, int lda, const u16* __restrict__ Bt, int ldb,
;                    int M, int N, int K, const Epi& e, unsigned char* shmraw, int wv, int slot) {
;     ...
;     for (int t = 0; t < nt - 2; t += 2) {
;       LDB(B0, 0, 0); SCHED; LDA(At, 0, 0); STAGEA(SA(1, 1), brow + HALF, t + 1);
;       WAIT_L(8); BAR; WAIT_L(0); MMA(0, 0, At, B0); BAR; SCHED;
;       LDB(B1, 0, 1); STAGEB(SB(0, 0), bcol, t + 2);
;       BAR; WAIT_L(0); MMA(0, 1, At, B1); BAR;
;       LDA(At, 0, 1); STAGEA(SA(0, 0), brow, t + 2);
;       BAR; WAIT_L(0); MMA(1, 0, At, B0); BAR; SCHED;
;       STAGEB(SB(0, 1), bcol + HALF, t + 2);
;       WAIT_V(6); BAR; MMA(1, 1, At, B1); BAR;
.LBB0_836:
	v_add_u32_e32 v0, s33, v134
	ds_read_b128 v[152:155], v0
	ds_read_b128 v[156:159], v0 offset:256
	ds_read_b128 v[160:163], v0 offset:1024
	ds_read_b128 v[164:167], v0 offset:1280
	s_add_u32 s31, s25, s20
	s_addc_u32 s35, s26, s21
	s_add_u32 s38, s31, 0x80
	v_add_u32_e32 v0, 0xc000, v137
	s_addc_u32 s39, s35, 0
	v_readfirstlane_b32 s36, v0
	v_lshl_add_u64 v[150:151], s[38:39], 0, v[132:133]
	s_mov_b32 m0, s36
	ds_read_b128 v[168:171], v149
	ds_read_b128 v[172:175], v149 offset:1024
	ds_read_b128 v[176:179], v149 offset:2048
	ds_read_b128 v[182:185], v149 offset:3072
	ds_read_b128 v[190:193], v149 offset:4096
	ds_read_b128 v[194:197], v149 offset:5120
	ds_read_b128 v[198:201], v149 offset:6144
	ds_read_b128 v[202:205], v149 offset:7168
	global_load_lds_dwordx4 v[150:151], off
	v_add_u32_e32 v150, 0xe000, v137
	v_lshl_add_u64 v[180:181], s[38:39], 0, v[130:131]
	v_readfirstlane_b32 s36, v150
	s_mov_b32 m0, s36
	s_nop 0
	global_load_lds_dwordx4 v[180:181], off
	s_waitcnt lgkmcnt(8)
	s_barrier
	s_waitcnt lgkmcnt(0)
	s_setprio 1
	v_mfma_f32_16x16x32_bf16 v[126:129], v[152:155], v[168:171], v[126:129]
	v_mfma_f32_16x16x32_bf16 v[122:125], v[156:159], v[168:171], v[122:125]
	v_mfma_f32_16x16x32_bf16 v[118:121], v[152:155], v[176:179], v[118:121]
	v_mfma_f32_16x16x32_bf16 v[114:117], v[156:159], v[176:179], v[114:117]
	v_mfma_f32_16x16x32_bf16 v[110:113], v[152:155], v[190:193], v[110:113]
	v_mfma_f32_16x16x32_bf16 v[106:109], v[156:159], v[190:193], v[106:109]
	v_mfma_f32_16x16x32_bf16 v[102:105], v[152:155], v[198:201], v[102:105]
	v_mfma_f32_16x16x32_bf16 v[98:101], v[156:159], v[198:201], v[98:101]
	v_mfma_f32_16x16x32_bf16 v[126:129], v[160:163], v[172:175], v[126:129]
	v_mfma_f32_16x16x32_bf16 v[122:125], v[164:167], v[172:175], v[122:125]
	v_mfma_f32_16x16x32_bf16 v[118:121], v[160:163], v[182:185], v[118:121]
	v_mfma_f32_16x16x32_bf16 v[114:117], v[164:167], v[182:185], v[114:117]
	v_mfma_f32_16x16x32_bf16 v[110:113], v[160:163], v[194:197], v[110:113]
	v_mfma_f32_16x16x32_bf16 v[106:109], v[164:167], v[194:197], v[106:109]
	v_mfma_f32_16x16x32_bf16 v[102:105], v[160:163], v[202:205], v[102:105]
	v_mfma_f32_16x16x32_bf16 v[98:101], v[164:167], v[202:205], v[98:101]
	s_setprio 0
	s_barrier
	s_add_u32 s36, s9, s20
	s_addc_u32 s37, s27, s21
	s_add_u32 s38, s36, 0x100
	s_addc_u32 s39, s37, 0
	v_readfirstlane_b32 s40, v135
	v_add_u32_e32 v151, s84, v134
	v_lshl_add_u64 v[180:181], s[38:39], 0, v[132:133]
	s_mov_b32 m0, s40
	ds_read_b128 v[206:209], v151
	ds_read_b128 v[210:213], v151 offset:256
	ds_read_b128 v[214:217], v151 offset:1024
	ds_read_b128 v[218:221], v151 offset:1280
	global_load_lds_dwordx4 v[180:181], off
	v_lshl_add_u64 v[180:181], s[38:39], 0, v[130:131]
	v_readfirstlane_b32 s38, v136
	s_mov_b32 m0, s38
	s_nop 0
	global_load_lds_dwordx4 v[180:181], off
	s_barrier
	s_waitcnt lgkmcnt(0)
	s_setprio 1
	v_mfma_f32_16x16x32_bf16 v[54:57], v[206:209], v[168:171], v[54:57]
	v_mfma_f32_16x16x32_bf16 v[42:45], v[210:213], v[168:171], v[42:45]
	v_mfma_f32_16x16x32_bf16 v[38:41], v[206:209], v[176:179], v[38:41]
	v_mfma_f32_16x16x32_bf16 v[34:37], v[210:213], v[176:179], v[34:37]
	v_mfma_f32_16x16x32_bf16 v[30:33], v[206:209], v[190:193], v[30:33]
	v_mfma_f32_16x16x32_bf16 v[26:29], v[210:213], v[190:193], v[26:29]
	v_mfma_f32_16x16x32_bf16 v[22:25], v[206:209], v[198:201], v[22:25]
	v_mfma_f32_16x16x32_bf16 v[18:21], v[210:213], v[198:201], v[18:21]
	v_mfma_f32_16x16x32_bf16 v[54:57], v[214:217], v[172:175], v[54:57]
	v_mfma_f32_16x16x32_bf16 v[42:45], v[218:221], v[172:175], v[42:45]
	v_mfma_f32_16x16x32_bf16 v[38:41], v[214:217], v[182:185], v[38:41]
	v_mfma_f32_16x16x32_bf16 v[34:37], v[218:221], v[182:185], v[34:37]
	v_mfma_f32_16x16x32_bf16 v[30:33], v[214:217], v[194:197], v[30:33]
	v_mfma_f32_16x16x32_bf16 v[26:29], v[218:221], v[194:197], v[26:29]
	v_mfma_f32_16x16x32_bf16 v[22:25], v[214:217], v[202:205], v[22:25]
	v_mfma_f32_16x16x32_bf16 v[18:21], v[218:221], v[202:205], v[18:21]
	s_setprio 0
	s_add_u32 s40, s13, s20
	s_addc_u32 s41, s28, s21
	s_add_u32 s38, s40, 0x100
	s_addc_u32 s39, s41, 0
	v_readfirstlane_b32 s42, v137
	v_lshl_add_u64 v[180:181], s[38:39], 0, v[132:133]
	s_mov_b32 m0, s42
	s_barrier
	ds_read_b128 v[168:171], v149 offset:16384
	ds_read_b128 v[172:175], v149 offset:17408
	ds_read_b128 v[176:179], v149 offset:18432
	ds_read_b128 v[182:185], v149 offset:19456
	ds_read_b128 v[190:193], v149 offset:20480
	ds_read_b128 v[194:197], v149 offset:21504
	ds_read_b128 v[198:201], v149 offset:22528
	ds_read_b128 v[202:205], v149 offset:23552
	global_load_lds_dwordx4 v[180:181], off
	v_lshl_add_u64 v[180:181], s[38:39], 0, v[130:131]
	v_readfirstlane_b32 s38, v138
	s_mov_b32 m0, s38
	s_nop 0
	global_load_lds_dwordx4 v[180:181], off
	s_barrier
	s_waitcnt lgkmcnt(0)
	s_setprio 1
	v_mfma_f32_16x16x32_bf16 v[14:17], v[152:155], v[168:171], v[14:17]
	v_mfma_f32_16x16x32_bf16 v[10:13], v[156:159], v[168:171], v[10:13]
	v_mfma_f32_16x16x32_bf16 v[6:9], v[152:155], v[176:179], v[6:9]
	v_mfma_f32_16x16x32_bf16 v[2:5], v[156:159], v[176:179], v[2:5]
	v_mfma_f32_16x16x32_bf16 v[46:49], v[152:155], v[190:193], v[46:49]
	v_mfma_f32_16x16x32_bf16 v[50:53], v[156:159], v[190:193], v[50:53]
	v_mfma_f32_16x16x32_bf16 v[58:61], v[152:155], v[198:201], v[58:61]
	v_mfma_f32_16x16x32_bf16 v[66:69], v[156:159], v[198:201], v[66:69]
	v_mfma_f32_16x16x32_bf16 v[14:17], v[160:163], v[172:175], v[14:17]
	v_mfma_f32_16x16x32_bf16 v[10:13], v[164:167], v[172:175], v[10:13]
	v_mfma_f32_16x16x32_bf16 v[6:9], v[160:163], v[182:185], v[6:9]
	v_mfma_f32_16x16x32_bf16 v[2:5], v[164:167], v[182:185], v[2:5]
	v_mfma_f32_16x16x32_bf16 v[46:49], v[160:163], v[194:197], v[46:49]
	v_mfma_f32_16x16x32_bf16 v[50:53], v[164:167], v[194:197], v[50:53]
	v_mfma_f32_16x16x32_bf16 v[58:61], v[160:163], v[202:205], v[58:61]
	v_mfma_f32_16x16x32_bf16 v[66:69], v[164:167], v[202:205], v[66:69]
	s_setprio 0
	s_barrier
; #define STAGEA(P, br, kt) do { const char* _g = uptr(A + (size_t)(br) * lda + (size_t)(kt) * BK); \
;     _Pragma("unroll") for (int _i = 0; _i < 2; ++_i) { \
;       __builtin_amdgcn_global_load_lds((const unsigned*)(_g + offA[_i]), (unsigned*)((char*)(P) + tidx * 16 + _i * 8192), 16, 0, 0); } } while (0)
; #define STAGEB(P, br, kt) do { const char* _g = uptr(Bt + (size_t)(br) * ldb + (size_t)(kt) * BK); \
;     _Pragma("unroll") for (int _i = 0; _i < 2; ++_i) { \
;       __builtin_amdgcn_global_load_lds((const unsigned*)(_g + offB[_i]), (unsigned*)((char*)(P) + tidx * 16 + _i * 8192), 16, 0, 0); } } while (0)
; #define LDA(dst, b, h) _Pragma("unroll") for (int m = 0; m < 4; ++m) _Pragma("unroll") for (int k = 0; k < 2; ++k) \
;     dst[m][k] = *reinterpret_cast<const bf16x8*>((char*)SA(b, h) + aoff + m * 2048 + k * 1024)
; #define LDB(dst, b, h) _Pragma("unroll") for (int n = 0; n < 2; ++n) _Pragma("unroll") for (int k = 0; k < 2; ++k) \
;     dst[n][k] = *reinterpret_cast<const bf16x8*>((char*)SB(b, h) + boff + n * (SWAP ? 256 : 2048) + k * 1024)
; #define WAIT_V(n) asm volatile("s_waitcnt vmcnt(" #n ")" ::: "memory")
; #define WAIT_L(n) asm volatile("s_waitcnt lgkmcnt(" #n ")" ::: "memory")
; #define BAR __builtin_amdgcn_s_barrier()
; #define SCHED __builtin_amdgcn_sched_barrier(0)
; template <int EPI>
; DI void gemm_phase(const u16* __restrict__ A, int lda, const u16* __restrict__ Bt, int ldb,
;                    int M, int N, int K, const Epi& e, unsigned char* shmraw, int wv, int slot) {
;     ...
;       STAGEB(SB(0, 1), bcol + HALF, t + 2);
;       WAIT_V(6); BAR; MMA(1, 1, At, B1); BAR;
;       LDB(B0, 1, 0); SCHED; LDA(At, 1, 0); STAGEA(SA(0, 1), brow + HALF, t + 2);
;       WAIT_L(8); BAR; WAIT_L(0); MMA(0, 0, At, B0); BAR; SCHED;
;       LDB(B1, 1, 1); STAGEB(SB(1, 0), bcol, t + 3);
;       BAR; WAIT_L(0); MMA(0, 1, At, B1); BAR;
;       LDA(At, 1, 1); STAGEA(SA(1, 0), brow, t + 3);
;       BAR; WAIT_L(0); MMA(1, 0, At, B0); BAR; SCHED;
	s_add_u32 s42, s29, s20
	s_addc_u32 s43, s30, s21
	s_add_u32 s38, s42, 0x100
	s_addc_u32 s39, s43, 0
	v_readfirstlane_b32 s48, v139
	v_lshl_add_u64 v[152:153], s[38:39], 0, v[132:133]
	s_mov_b32 m0, s48
	s_nop 0
	global_load_lds_dwordx4 v[152:153], off
	v_lshl_add_u64 v[152:153], s[38:39], 0, v[130:131]
	v_readfirstlane_b32 s38, v140
	s_mov_b32 m0, s38
	s_nop 0
	global_load_lds_dwordx4 v[152:153], off
	s_waitcnt vmcnt(6)
	s_barrier
	s_setprio 1
	v_mfma_f32_16x16x32_bf16 v[62:65], v[206:209], v[168:171], v[62:65]
	v_mfma_f32_16x16x32_bf16 v[70:73], v[210:213], v[168:171], v[70:73]
	v_mfma_f32_16x16x32_bf16 v[74:77], v[206:209], v[176:179], v[74:77]
	v_mfma_f32_16x16x32_bf16 v[78:81], v[210:213], v[176:179], v[78:81]
	v_mfma_f32_16x16x32_bf16 v[82:85], v[206:209], v[190:193], v[82:85]
	v_mfma_f32_16x16x32_bf16 v[86:89], v[210:213], v[190:193], v[86:89]
	v_mfma_f32_16x16x32_bf16 v[90:93], v[206:209], v[198:201], v[90:93]
	v_mfma_f32_16x16x32_bf16 v[94:97], v[210:213], v[198:201], v[94:97]
	v_mfma_f32_16x16x32_bf16 v[62:65], v[214:217], v[172:175], v[62:65]
	v_mfma_f32_16x16x32_bf16 v[70:73], v[218:221], v[172:175], v[70:73]
	v_mfma_f32_16x16x32_bf16 v[74:77], v[214:217], v[182:185], v[74:77]
	v_mfma_f32_16x16x32_bf16 v[78:81], v[218:221], v[182:185], v[78:81]
	v_mfma_f32_16x16x32_bf16 v[82:85], v[214:217], v[194:197], v[82:85]
	v_mfma_f32_16x16x32_bf16 v[86:89], v[218:221], v[194:197], v[86:89]
	v_mfma_f32_16x16x32_bf16 v[90:93], v[214:217], v[202:205], v[90:93]
	v_mfma_f32_16x16x32_bf16 v[94:97], v[218:221], v[202:205], v[94:97]
	s_setprio 0
	v_add_u32_e32 v151, s85, v134
	s_barrier
	ds_read_b128 v[152:155], v151
	ds_read_b128 v[156:159], v151 offset:256
	ds_read_b128 v[160:163], v151 offset:1024
	ds_read_b128 v[164:167], v151 offset:1280
	s_add_u32 s38, s31, 0x100
	s_addc_u32 s39, s35, 0
	v_readfirstlane_b32 s31, v141
	v_lshl_add_u64 v[180:181], s[38:39], 0, v[132:133]
	s_mov_b32 m0, s31
	v_readfirstlane_b32 s31, v142
	ds_read_b128 v[168:171], v149 offset:32768
	ds_read_b128 v[172:175], v149 offset:33792
	ds_read_b128 v[176:179], v149 offset:34816
	ds_read_b128 v[182:185], v149 offset:35840
	ds_read_b128 v[190:193], v149 offset:36864
	ds_read_b128 v[194:197], v149 offset:37888
	ds_read_b128 v[198:201], v149 offset:38912
	ds_read_b128 v[202:205], v149 offset:39936
	global_load_lds_dwordx4 v[180:181], off
	v_lshl_add_u64 v[180:181], s[38:39], 0, v[130:131]
	s_mov_b32 m0, s31
	s_nop 0
	global_load_lds_dwordx4 v[180:181], off
	s_waitcnt lgkmcnt(8)
	s_barrier
	s_waitcnt lgkmcnt(0)
	s_setprio 1
	v_mfma_f32_16x16x32_bf16 v[126:129], v[152:155], v[168:171], v[126:129]
	v_mfma_f32_16x16x32_bf16 v[122:125], v[156:159], v[168:171], v[122:125]
	v_mfma_f32_16x16x32_bf16 v[118:121], v[152:155], v[176:179], v[118:121]
	v_mfma_f32_16x16x32_bf16 v[114:117], v[156:159], v[176:179], v[114:117]
	v_mfma_f32_16x16x32_bf16 v[110:113], v[152:155], v[190:193], v[110:113]
	v_mfma_f32_16x16x32_bf16 v[106:109], v[156:159], v[190:193], v[106:109]
	v_mfma_f32_16x16x32_bf16 v[102:105], v[152:155], v[198:201], v[102:105]
	v_mfma_f32_16x16x32_bf16 v[98:101], v[156:159], v[198:201], v[98:101]
	v_mfma_f32_16x16x32_bf16 v[126:129], v[160:163], v[172:175], v[126:129]
	v_mfma_f32_16x16x32_bf16 v[122:125], v[164:167], v[172:175], v[122:125]
	v_mfma_f32_16x16x32_bf16 v[118:121], v[160:163], v[182:185], v[118:121]
	v_mfma_f32_16x16x32_bf16 v[114:117], v[164:167], v[182:185], v[114:117]
	v_mfma_f32_16x16x32_bf16 v[110:113], v[160:163], v[194:197], v[110:113]
	v_mfma_f32_16x16x32_bf16 v[106:109], v[164:167], v[194:197], v[106:109]
	v_mfma_f32_16x16x32_bf16 v[102:105], v[160:163], v[202:205], v[102:105]
	v_mfma_f32_16x16x32_bf16 v[98:101], v[164:167], v[202:205], v[98:101]
	s_setprio 0
	s_barrier
	s_add_u32 s38, s36, 0x180
	s_addc_u32 s39, s37, 0
	v_readfirstlane_b32 s31, v143
	v_add_u32_e32 v151, s86, v134
	v_lshl_add_u64 v[180:181], s[38:39], 0, v[132:133]
	s_mov_b32 m0, s31
	v_readfirstlane_b32 s31, v144
	ds_read_b128 v[206:209], v151
	ds_read_b128 v[210:213], v151 offset:256
	ds_read_b128 v[214:217], v151 offset:1024
	ds_read_b128 v[218:221], v151 offset:1280
	global_load_lds_dwordx4 v[180:181], off
	v_lshl_add_u64 v[180:181], s[38:39], 0, v[130:131]
	s_mov_b32 m0, s31
	s_nop 0
	global_load_lds_dwordx4 v[180:181], off
	s_barrier
	s_waitcnt lgkmcnt(0)
	s_setprio 1
	v_mfma_f32_16x16x32_bf16 v[54:57], v[206:209], v[168:171], v[54:57]
	v_mfma_f32_16x16x32_bf16 v[42:45], v[210:213], v[168:171], v[42:45]
	v_mfma_f32_16x16x32_bf16 v[38:41], v[206:209], v[176:179], v[38:41]
	v_mfma_f32_16x16x32_bf16 v[34:37], v[210:213], v[176:179], v[34:37]
	v_mfma_f32_16x16x32_bf16 v[30:33], v[206:209], v[190:193], v[30:33]
	v_mfma_f32_16x16x32_bf16 v[26:29], v[210:213], v[190:193], v[26:29]
	v_mfma_f32_16x16x32_bf16 v[22:25], v[206:209], v[198:201], v[22:25]
	v_mfma_f32_16x16x32_bf16 v[18:21], v[210:213], v[198:201], v[18:21]
	v_mfma_f32_16x16x32_bf16 v[54:57], v[214:217], v[172:175], v[54:57]
	v_mfma_f32_16x16x32_bf16 v[42:45], v[218:221], v[172:175], v[42:45]
	v_mfma_f32_16x16x32_bf16 v[38:41], v[214:217], v[182:185], v[38:41]
	v_mfma_f32_16x16x32_bf16 v[34:37], v[218:221], v[182:185], v[34:37]
	v_mfma_f32_16x16x32_bf16 v[30:33], v[214:217], v[194:197], v[30:33]
	v_mfma_f32_16x16x32_bf16 v[26:29], v[218:221], v[194:197], v[26:29]
	v_mfma_f32_16x16x32_bf16 v[22:25], v[214:217], v[202:205], v[22:25]
	v_mfma_f32_16x16x32_bf16 v[18:21], v[218:221], v[202:205], v[18:21]
	s_setprio 0
	s_add_u32 s38, s40, 0x180
	s_addc_u32 s39, s41, 0
	v_readfirstlane_b32 s31, v145
	v_lshl_add_u64 v[180:181], s[38:39], 0, v[132:133]
	s_mov_b32 m0, s31
	v_readfirstlane_b32 s31, v146
	s_barrier
; #define STAGEA(P, br, kt) do { const char* _g = uptr(A + (size_t)(br) * lda + (size_t)(kt) * BK); \
;     _Pragma("unroll") for (int _i = 0; _i < 2; ++_i) { \
;       __builtin_amdgcn_global_load_lds((const unsigned*)(_g + offA[_i]), (unsigned*)((char*)(P) + tidx * 16 + _i * 8192), 16, 0, 0); } } while (0)
; #define STAGEB(P, br, kt) do { const char* _g = uptr(Bt + (size_t)(br) * ldb + (size_t)(kt) * BK); \
;     _Pragma("unroll") for (int _i = 0; _i < 2; ++_i) { \
;       __builtin_amdgcn_global_load_lds((const unsigned*)(_g + offB[_i]), (unsigned*)((char*)(P) + tidx * 16 + _i * 8192), 16, 0, 0); } } while (0)
; #define LDA(dst, b, h) _Pragma("unroll") for (int m = 0; m < 4; ++m) _Pragma("unroll") for (int k = 0; k < 2; ++k) \
;     dst[m][k] = *reinterpret_cast<const bf16x8*>((char*)SA(b, h) + aoff + m * 2048 + k * 1024)
; #define LDB(dst, b, h) _Pragma("unroll") for (int n = 0; n < 2; ++n) _Pragma("unroll") for (int k = 0; k < 2; ++k) \
;     dst[n][k] = *reinterpret_cast<const bf16x8*>((char*)SB(b, h) + boff + n * (SWAP ? 256 : 2048) + k * 1024)
; #define WAIT_V(n) asm volatile("s_waitcnt vmcnt(" #n ")" ::: "memory")
; #define WAIT_L(n) asm volatile("s_waitcnt lgkmcnt(" #n ")" ::: "memory")
; #define BAR __builtin_amdgcn_s_barrier()
; #define SCHED __builtin_amdgcn_sched_barrier(0)
; template <int EPI>
; DI void gemm_phase(const u16* __restrict__ A, int lda, const u16* __restrict__ Bt, int ldb,
;                    int M, int N, int K, const Epi& e, unsigned char* shmraw, int wv, int slot) {
;     ...
;       BAR; WAIT_L(0); MMA(0, 1, At, B1); BAR;
;       LDA(At, 1, 1); STAGEA(SA(1, 0), brow, t + 3);
;       BAR; WAIT_L(0); MMA(1, 0, At, B0); BAR; SCHED;
;       STAGEB(SB(1, 1), bcol + HALF, t + 3);
;       WAIT_V(6); BAR; MMA(1, 1, At, B1); BAR;
;     }
;     { LDB(B0, 0, 0); LDA(At, 0, 0); STAGEA(SA(1, 1), brow + HALF, nt - 1);
;       BAR; WAIT_L(0); MMA(0, 0, At, B0); BAR;
	ds_read_b128 v[168:171], v149 offset:49152
	ds_read_b128 v[172:175], v149 offset:50176
	ds_read_b128 v[176:179], v149 offset:51200
	ds_read_b128 v[182:185], v149 offset:52224
	ds_read_b128 v[190:193], v149 offset:53248
	ds_read_b128 v[194:197], v149 offset:54272
	ds_read_b128 v[198:201], v149 offset:55296
	ds_read_b128 v[202:205], v149 offset:56320
	global_load_lds_dwordx4 v[180:181], off
	v_lshl_add_u64 v[180:181], s[38:39], 0, v[130:131]
	s_mov_b32 m0, s31
	s_nop 0
	global_load_lds_dwordx4 v[180:181], off
	s_barrier
	s_waitcnt lgkmcnt(0)
	s_setprio 1
	v_mfma_f32_16x16x32_bf16 v[14:17], v[152:155], v[168:171], v[14:17]
	v_mfma_f32_16x16x32_bf16 v[10:13], v[156:159], v[168:171], v[10:13]
	v_mfma_f32_16x16x32_bf16 v[6:9], v[152:155], v[176:179], v[6:9]
	v_mfma_f32_16x16x32_bf16 v[2:5], v[156:159], v[176:179], v[2:5]
	v_mfma_f32_16x16x32_bf16 v[46:49], v[152:155], v[190:193], v[46:49]
	v_mfma_f32_16x16x32_bf16 v[50:53], v[156:159], v[190:193], v[50:53]
	v_mfma_f32_16x16x32_bf16 v[58:61], v[152:155], v[198:201], v[58:61]
	v_mfma_f32_16x16x32_bf16 v[66:69], v[156:159], v[198:201], v[66:69]
	v_mfma_f32_16x16x32_bf16 v[14:17], v[160:163], v[172:175], v[14:17]
	v_mfma_f32_16x16x32_bf16 v[10:13], v[164:167], v[172:175], v[10:13]
	v_mfma_f32_16x16x32_bf16 v[6:9], v[160:163], v[182:185], v[6:9]
	v_mfma_f32_16x16x32_bf16 v[2:5], v[164:167], v[182:185], v[2:5]
	v_mfma_f32_16x16x32_bf16 v[46:49], v[160:163], v[194:197], v[46:49]
	v_mfma_f32_16x16x32_bf16 v[50:53], v[164:167], v[194:197], v[50:53]
	v_mfma_f32_16x16x32_bf16 v[58:61], v[160:163], v[202:205], v[58:61]
	v_mfma_f32_16x16x32_bf16 v[66:69], v[164:167], v[202:205], v[66:69]
	s_setprio 0
	s_barrier
	s_add_u32 s38, s42, 0x180
	s_addc_u32 s39, s43, 0
	v_readfirstlane_b32 s31, v147
	v_lshl_add_u64 v[152:153], s[38:39], 0, v[132:133]
	s_mov_b32 m0, s31
	v_readfirstlane_b32 s31, v148
	global_load_lds_dwordx4 v[152:153], off
	v_lshl_add_u64 v[152:153], s[38:39], 0, v[130:131]
	s_mov_b32 m0, s31
	s_nop 0
	global_load_lds_dwordx4 v[152:153], off
	s_waitcnt vmcnt(6)
	s_barrier
	s_setprio 1
	v_mfma_f32_16x16x32_bf16 v[62:65], v[206:209], v[168:171], v[62:65]
	v_mfma_f32_16x16x32_bf16 v[70:73], v[210:213], v[168:171], v[70:73]
	v_mfma_f32_16x16x32_bf16 v[74:77], v[206:209], v[176:179], v[74:77]
	v_mfma_f32_16x16x32_bf16 v[78:81], v[210:213], v[176:179], v[78:81]
	v_mfma_f32_16x16x32_bf16 v[82:85], v[206:209], v[190:193], v[82:85]
	v_mfma_f32_16x16x32_bf16 v[86:89], v[210:213], v[190:193], v[86:89]
	v_mfma_f32_16x16x32_bf16 v[90:93], v[206:209], v[198:201], v[90:93]
	v_mfma_f32_16x16x32_bf16 v[94:97], v[210:213], v[198:201], v[94:97]
	v_mfma_f32_16x16x32_bf16 v[62:65], v[214:217], v[172:175], v[62:65]
	v_mfma_f32_16x16x32_bf16 v[70:73], v[218:221], v[172:175], v[70:73]
	v_mfma_f32_16x16x32_bf16 v[74:77], v[214:217], v[182:185], v[74:77]
	v_mfma_f32_16x16x32_bf16 v[78:81], v[218:221], v[182:185], v[78:81]
	v_mfma_f32_16x16x32_bf16 v[82:85], v[214:217], v[194:197], v[82:85]
	v_mfma_f32_16x16x32_bf16 v[86:89], v[218:221], v[194:197], v[86:89]
	v_mfma_f32_16x16x32_bf16 v[90:93], v[214:217], v[202:205], v[90:93]
	v_mfma_f32_16x16x32_bf16 v[94:97], v[218:221], v[202:205], v[94:97]
	s_setprio 0
	s_add_i32 s1, s1, 2
	s_add_u32 s20, s20, 0x100
	s_addc_u32 s21, s21, 0
	s_cmp_gt_u32 s1, 3
	s_barrier
	s_cbranch_scc0 .LBB0_836
	s_lshl_b64 s[18:19], s[18:19], 1
	v_readlane_b32 s0, v253, 50
	s_add_u32 s18, s0, s18
	v_readlane_b32 s0, v253, 51
	v_add_u32_e32 v186, 16, v134
	s_addc_u32 s19, s0, s19
	v_readfirstlane_b32 s1, v0
	v_add_u32_e32 v151, 0x10000, v186
	v_lshl_add_u64 v[180:181], s[18:19], 0, v[132:133]
	s_mov_b32 m0, s1
	v_readfirstlane_b32 s1, v150
	ds_read_b128 v[152:155], v151
	ds_read_b128 v[156:159], v151 offset:256
	ds_read_b128 v[160:163], v151 offset:1024
	ds_read_b128 v[164:167], v151 offset:1280
	ds_read_b128 v[168:171], v149
	ds_read_b128 v[172:175], v149 offset:1024
	ds_read_b128 v[176:179], v149 offset:2048
	ds_read_b128 v[182:185], v149 offset:3072
	ds_read_b128 v[190:193], v149 offset:4096
	ds_read_b128 v[194:197], v149 offset:5120
	ds_read_b128 v[198:201], v149 offset:6144
	ds_read_b128 v[202:205], v149 offset:7168
	global_load_lds_dwordx4 v[180:181], off
	v_lshl_add_u64 v[180:181], s[18:19], 0, v[130:131]
	s_mov_b32 m0, s1
	s_nop 0
	global_load_lds_dwordx4 v[180:181], off
	s_barrier
	s_waitcnt lgkmcnt(0)
	s_setprio 1
	v_mfma_f32_16x16x32_bf16 v[126:129], v[152:155], v[168:171], v[126:129]
	v_mfma_f32_16x16x32_bf16 v[122:125], v[156:159], v[168:171], v[122:125]
	v_mfma_f32_16x16x32_bf16 v[110:113], v[152:155], v[190:193], v[110:113]
	v_mfma_f32_16x16x32_bf16 v[106:109], v[156:159], v[190:193], v[106:109]
	v_mfma_f32_16x16x32_bf16 v[126:129], v[160:163], v[172:175], v[126:129]
	v_mfma_f32_16x16x32_bf16 v[122:125], v[164:167], v[172:175], v[122:125]
	v_mfma_f32_16x16x32_bf16 v[118:121], v[152:155], v[176:179], v[118:121]
	v_mfma_f32_16x16x32_bf16 v[114:117], v[156:159], v[176:179], v[114:117]
	v_mfma_f32_16x16x32_bf16 v[110:113], v[160:163], v[194:197], v[110:113]
	v_mfma_f32_16x16x32_bf16 v[106:109], v[164:167], v[194:197], v[106:109]
	v_mfma_f32_16x16x32_bf16 v[102:105], v[152:155], v[198:201], v[102:105]
	v_mfma_f32_16x16x32_bf16 v[98:101], v[156:159], v[198:201], v[98:101]
	v_mfma_f32_16x16x32_bf16 v[206:209], v[160:163], v[182:185], v[118:121]
	v_mfma_f32_16x16x32_bf16 v[210:213], v[164:167], v[182:185], v[114:117]
	v_mfma_f32_16x16x32_bf16 v[214:217], v[160:163], v[202:205], v[102:105]
	v_mfma_f32_16x16x32_bf16 v[218:221], v[164:167], v[202:205], v[98:101]
	s_setprio 0
	v_add_u32_e32 v0, 0x14000, v186
	s_barrier
; #define LDA(dst, b, h) _Pragma("unroll") for (int m = 0; m < 4; ++m) _Pragma("unroll") for (int k = 0; k < 2; ++k) \
;     dst[m][k] = *reinterpret_cast<const bf16x8*>((char*)SA(b, h) + aoff + m * 2048 + k * 1024)
; #define LDB(dst, b, h) _Pragma("unroll") for (int n = 0; n < 2; ++n) _Pragma("unroll") for (int k = 0; k < 2; ++k) \
;     dst[n][k] = *reinterpret_cast<const bf16x8*>((char*)SB(b, h) + boff + n * (SWAP ? 256 : 2048) + k * 1024)
; #define WAIT_V(n) asm volatile("s_waitcnt vmcnt(" #n ")" ::: "memory")
; #define WAIT_L(n) asm volatile("s_waitcnt lgkmcnt(" #n ")" ::: "memory")
; #define BAR __builtin_amdgcn_s_barrier()
; template <int EPI>
; DI void gemm_phase(const u16* __restrict__ A, int lda, const u16* __restrict__ Bt, int ldb,
;                    int M, int N, int K, const Epi& e, unsigned char* shmraw, int wv, int slot) {
;     ...
;       BAR; WAIT_L(0); MMA(0, 0, At, B0); BAR;
;       LDB(B1, 0, 1); BAR; WAIT_L(0); MMA(0, 1, At, B1); BAR;
;       LDA(At, 0, 1); WAIT_V(4); BAR; WAIT_L(0); MMA(1, 0, At, B0); MMA(1, 1, At, B1); BAR; }
;     { LDB(B0, 1, 0); LDA(At, 1, 0); WAIT_V(2); BAR; WAIT_L(0); MMA(0, 0, At, B0); BAR;
	s_nop 0
	ds_read_b128 v[98:101], v0
	ds_read_b128 v[102:105], v0 offset:256
	ds_read_b128 v[114:117], v0 offset:1024
	ds_read_b128 v[118:121], v0 offset:1280
	s_barrier
	s_waitcnt lgkmcnt(0)
	s_setprio 1
	v_mfma_f32_16x16x32_bf16 v[42:45], v[102:105], v[168:171], v[42:45]
	v_mfma_f32_16x16x32_bf16 v[38:41], v[98:101], v[176:179], v[38:41]
	v_mfma_f32_16x16x32_bf16 v[34:37], v[102:105], v[176:179], v[34:37]
	v_mfma_f32_16x16x32_bf16 v[30:33], v[98:101], v[190:193], v[30:33]
	v_mfma_f32_16x16x32_bf16 v[26:29], v[102:105], v[190:193], v[26:29]
	v_mfma_f32_16x16x32_bf16 v[22:25], v[98:101], v[198:201], v[22:25]
	v_mfma_f32_16x16x32_bf16 v[18:21], v[102:105], v[198:201], v[18:21]
	v_mfma_f32_16x16x32_bf16 v[54:57], v[98:101], v[168:171], v[54:57]
	v_mfma_f32_16x16x32_bf16 v[42:45], v[118:121], v[172:175], v[42:45]
	v_mfma_f32_16x16x32_bf16 v[38:41], v[114:117], v[182:185], v[38:41]
	v_mfma_f32_16x16x32_bf16 v[34:37], v[118:121], v[182:185], v[34:37]
	v_mfma_f32_16x16x32_bf16 v[30:33], v[114:117], v[194:197], v[30:33]
	v_mfma_f32_16x16x32_bf16 v[26:29], v[118:121], v[194:197], v[26:29]
	v_mfma_f32_16x16x32_bf16 v[22:25], v[114:117], v[202:205], v[22:25]
	v_mfma_f32_16x16x32_bf16 v[18:21], v[118:121], v[202:205], v[18:21]
	v_mfma_f32_16x16x32_bf16 v[222:225], v[114:117], v[172:175], v[54:57]
	s_setprio 0
	s_barrier
	s_nop 0
	ds_read_b128 v[54:57], v149 offset:16384
	ds_read_b128 v[168:171], v149 offset:17408
	ds_read_b128 v[172:175], v149 offset:18432
	ds_read_b128 v[176:179], v149 offset:19456
	ds_read_b128 v[182:185], v149 offset:20480
	ds_read_b128 v[190:193], v149 offset:21504
	ds_read_b128 v[194:197], v149 offset:22528
	ds_read_b128 v[198:201], v149 offset:23552
	s_waitcnt vmcnt(4)
	s_barrier
	s_waitcnt lgkmcnt(0)
	s_setprio 1
	v_mfma_f32_16x16x32_bf16 v[50:53], v[156:159], v[182:185], v[50:53]
	v_mfma_f32_16x16x32_bf16 v[14:17], v[152:155], v[54:57], v[14:17]
	v_mfma_f32_16x16x32_bf16 v[10:13], v[156:159], v[54:57], v[10:13]
	v_mfma_f32_16x16x32_bf16 v[6:9], v[152:155], v[172:175], v[6:9]
	v_mfma_f32_16x16x32_bf16 v[2:5], v[156:159], v[172:175], v[2:5]
	v_mfma_f32_16x16x32_bf16 v[46:49], v[152:155], v[182:185], v[46:49]
	v_mfma_f32_16x16x32_bf16 v[202:205], v[164:167], v[190:193], v[50:53]
	v_mfma_f32_16x16x32_bf16 v[50:53], v[152:155], v[194:197], v[58:61]
	v_mfma_f32_16x16x32_bf16 v[14:17], v[160:163], v[168:171], v[14:17]
	v_mfma_f32_16x16x32_bf16 v[10:13], v[164:167], v[168:171], v[10:13]
	v_mfma_f32_16x16x32_bf16 v[6:9], v[160:163], v[176:179], v[6:9]
	v_mfma_f32_16x16x32_bf16 v[2:5], v[164:167], v[176:179], v[2:5]
	v_mfma_f32_16x16x32_bf16 v[46:49], v[160:163], v[190:193], v[46:49]
	v_mfma_f32_16x16x32_bf16 v[150:153], v[160:163], v[198:201], v[50:53]
	v_mfma_f32_16x16x32_bf16 v[50:53], v[156:159], v[194:197], v[66:69]
	v_mfma_f32_16x16x32_bf16 v[154:157], v[164:167], v[198:201], v[50:53]
	s_setprio 0
	s_setprio 1
	v_mfma_f32_16x16x32_bf16 v[50:53], v[98:101], v[54:57], v[62:65]
	v_mfma_f32_16x16x32_bf16 v[158:161], v[114:117], v[168:171], v[50:53]
	v_mfma_f32_16x16x32_bf16 v[50:53], v[102:105], v[54:57], v[70:73]
	v_mfma_f32_16x16x32_bf16 v[162:165], v[118:121], v[168:171], v[50:53]
	v_mfma_f32_16x16x32_bf16 v[50:53], v[98:101], v[172:175], v[74:77]
	v_mfma_f32_16x16x32_bf16 v[166:169], v[114:117], v[176:179], v[50:53]
	v_mfma_f32_16x16x32_bf16 v[50:53], v[102:105], v[172:175], v[78:81]
	v_mfma_f32_16x16x32_bf16 v[170:173], v[118:121], v[176:179], v[50:53]
	v_mfma_f32_16x16x32_bf16 v[50:53], v[98:101], v[182:185], v[82:85]
	v_mfma_f32_16x16x32_bf16 v[174:177], v[114:117], v[190:193], v[50:53]
	v_mfma_f32_16x16x32_bf16 v[50:53], v[102:105], v[182:185], v[86:89]
	v_mfma_f32_16x16x32_bf16 v[182:185], v[118:121], v[190:193], v[50:53]
	v_mfma_f32_16x16x32_bf16 v[50:53], v[98:101], v[194:197], v[90:93]
	v_mfma_f32_16x16x32_bf16 v[190:193], v[114:117], v[198:201], v[50:53]
	v_mfma_f32_16x16x32_bf16 v[50:53], v[102:105], v[194:197], v[94:97]
	v_mfma_f32_16x16x32_bf16 v[194:197], v[118:121], v[198:201], v[50:53]
	s_setprio 0
	v_add_u32_e32 v0, 0x18000, v186
	s_barrier
	ds_read_b128 v[74:77], v0
	ds_read_b128 v[78:81], v0 offset:256
	ds_read_b128 v[198:201], v0 offset:1024
	ds_read_b128 v[226:229], v0 offset:1280
	ds_read_b128 v[58:61], v149 offset:32768
	ds_read_b128 v[62:65], v149 offset:33792
	ds_read_b128 v[66:69], v149 offset:34816
	ds_read_b128 v[70:73], v149 offset:35840
	ds_read_b128 v[94:97], v149 offset:36864
	ds_read_b128 v[230:233], v149 offset:37888
	ds_read_b128 v[234:237], v149 offset:38912
	ds_read_b128 v[238:241], v149 offset:39936
	s_waitcnt vmcnt(2)
	s_barrier
; #define LDA(dst, b, h) _Pragma("unroll") for (int m = 0; m < 4; ++m) _Pragma("unroll") for (int k = 0; k < 2; ++k) \
;     dst[m][k] = *reinterpret_cast<const bf16x8*>((char*)SA(b, h) + aoff + m * 2048 + k * 1024)
; #define LDB(dst, b, h) _Pragma("unroll") for (int n = 0; n < 2; ++n) _Pragma("unroll") for (int k = 0; k < 2; ++k) \
;     dst[n][k] = *reinterpret_cast<const bf16x8*>((char*)SB(b, h) + boff + n * (SWAP ? 256 : 2048) + k * 1024)
; #define WAIT_V(n) asm volatile("s_waitcnt vmcnt(" #n ")" ::: "memory")
; #define WAIT_L(n) asm volatile("s_waitcnt lgkmcnt(" #n ")" ::: "memory")
; #define BAR __builtin_amdgcn_s_barrier()
; template <int EPI>
; DI void gemm_phase(const u16* __restrict__ A, int lda, const u16* __restrict__ Bt, int ldb,
;                    int M, int N, int K, const Epi& e, unsigned char* shmraw, int wv, int slot) {
;     ...
;     { LDB(B0, 1, 0); LDA(At, 1, 0); WAIT_V(2); BAR; WAIT_L(0); MMA(0, 0, At, B0); BAR;
;       LDB(B1, 1, 1); WAIT_V(0); BAR; WAIT_L(0); MMA(0, 1, At, B1); BAR;
;       LDA(At, 1, 1); BAR; WAIT_L(0); MMA(1, 0, At, B0); MMA(1, 1, At, B1); BAR; }
;     if (wr == 0) BAR;
	s_waitcnt lgkmcnt(0)
	s_setprio 1
	v_mfma_f32_16x16x32_bf16 v[50:53], v[74:77], v[58:61], v[126:129]
	v_mfma_f32_16x16x32_bf16 v[114:117], v[198:201], v[62:65], v[50:53]
	v_mfma_f32_16x16x32_bf16 v[50:53], v[78:81], v[58:61], v[122:125]
	v_mfma_f32_16x16x32_bf16 v[118:121], v[226:229], v[62:65], v[50:53]
	v_mfma_f32_16x16x32_bf16 v[50:53], v[74:77], v[66:69], v[206:209]
	v_mfma_f32_16x16x32_bf16 v[98:101], v[198:201], v[70:73], v[50:53]
	v_mfma_f32_16x16x32_bf16 v[50:53], v[78:81], v[66:69], v[210:213]
	v_mfma_f32_16x16x32_bf16 v[102:105], v[226:229], v[70:73], v[50:53]
	v_mfma_f32_16x16x32_bf16 v[50:53], v[74:77], v[94:97], v[110:113]
	v_mfma_f32_16x16x32_bf16 v[82:85], v[198:201], v[230:233], v[50:53]
	v_mfma_f32_16x16x32_bf16 v[50:53], v[78:81], v[94:97], v[106:109]
	v_mfma_f32_16x16x32_bf16 v[86:89], v[226:229], v[230:233], v[50:53]
	v_mfma_f32_16x16x32_bf16 v[50:53], v[74:77], v[234:237], v[214:217]
	v_mfma_f32_16x16x32_bf16 v[54:57], v[78:81], v[234:237], v[218:221]
	v_mfma_f32_16x16x32_bf16 v[50:53], v[198:201], v[238:241], v[50:53]
	v_mfma_f32_16x16x32_bf16 v[54:57], v[226:229], v[238:241], v[54:57]
	s_setprio 0
	v_add_u32_e32 v0, 0x1c000, v186
	s_barrier
	ds_read_b128 v[206:209], v0
	ds_read_b128 v[210:213], v0 offset:256
	ds_read_b128 v[214:217], v0 offset:1024
	ds_read_b128 v[218:221], v0 offset:1280
	s_waitcnt vmcnt(0)
	s_barrier
	s_waitcnt lgkmcnt(0)
	s_setprio 1
	v_mfma_f32_16x16x32_bf16 v[90:93], v[206:209], v[58:61], v[222:225]
	v_mfma_f32_16x16x32_bf16 v[42:45], v[210:213], v[58:61], v[42:45]
	v_mfma_f32_16x16x32_bf16 v[38:41], v[206:209], v[66:69], v[38:41]
	v_mfma_f32_16x16x32_bf16 v[34:37], v[210:213], v[66:69], v[34:37]
	v_mfma_f32_16x16x32_bf16 v[30:33], v[206:209], v[94:97], v[30:33]
	v_mfma_f32_16x16x32_bf16 v[26:29], v[210:213], v[94:97], v[26:29]
	v_mfma_f32_16x16x32_bf16 v[22:25], v[206:209], v[234:237], v[22:25]
	v_mfma_f32_16x16x32_bf16 v[18:21], v[210:213], v[234:237], v[18:21]
	v_mfma_f32_16x16x32_bf16 v[122:125], v[214:217], v[62:65], v[90:93]
	v_mfma_f32_16x16x32_bf16 v[126:129], v[218:221], v[62:65], v[42:45]
	v_mfma_f32_16x16x32_bf16 v[106:109], v[214:217], v[70:73], v[38:41]
	v_mfma_f32_16x16x32_bf16 v[110:113], v[218:221], v[70:73], v[34:37]
	v_mfma_f32_16x16x32_bf16 v[90:93], v[214:217], v[230:233], v[30:33]
	v_mfma_f32_16x16x32_bf16 v[94:97], v[218:221], v[230:233], v[26:29]
	v_mfma_f32_16x16x32_bf16 v[58:61], v[214:217], v[238:241], v[22:25]
	v_mfma_f32_16x16x32_bf16 v[62:65], v[218:221], v[238:241], v[18:21]
	s_setprio 0
	s_barrier
	ds_read_b128 v[26:29], v149 offset:49152
	ds_read_b128 v[30:33], v149 offset:50176
	ds_read_b128 v[222:225], v149 offset:51200
	ds_read_b128 v[230:233], v149 offset:52224
	ds_read_b128 v[234:237], v149 offset:53248
	ds_read_b128 v[238:241], v149 offset:54272
	ds_read_b128 v[242:245], v149 offset:55296
	ds_read_b128 v[246:249], v149 offset:56320
	s_barrier
	s_waitcnt lgkmcnt(0)
	s_setprio 1
	v_mfma_f32_16x16x32_bf16 v[2:5], v[78:81], v[222:225], v[2:5]
	v_mfma_f32_16x16x32_bf16 v[38:41], v[226:229], v[230:233], v[2:5]
	v_mfma_f32_16x16x32_bf16 v[2:5], v[74:77], v[234:237], v[46:49]
	v_mfma_f32_16x16x32_bf16 v[6:9], v[74:77], v[222:225], v[6:9]
	v_mfma_f32_16x16x32_bf16 v[18:21], v[198:201], v[238:241], v[2:5]
	v_mfma_f32_16x16x32_bf16 v[2:5], v[78:81], v[234:237], v[202:205]
	v_mfma_f32_16x16x32_bf16 v[14:17], v[74:77], v[26:29], v[14:17]
	v_mfma_f32_16x16x32_bf16 v[10:13], v[78:81], v[26:29], v[10:13]
	v_mfma_f32_16x16x32_bf16 v[34:37], v[198:201], v[230:233], v[6:9]
	v_mfma_f32_16x16x32_bf16 v[22:25], v[226:229], v[238:241], v[2:5]
	v_mfma_f32_16x16x32_bf16 v[2:5], v[74:77], v[242:245], v[150:153]
	v_mfma_f32_16x16x32_bf16 v[6:9], v[78:81], v[242:245], v[154:157]
	v_mfma_f32_16x16x32_bf16 v[66:69], v[198:201], v[30:33], v[14:17]
	v_mfma_f32_16x16x32_bf16 v[70:73], v[226:229], v[30:33], v[10:13]
	v_mfma_f32_16x16x32_bf16 v[2:5], v[198:201], v[246:249], v[2:5]
	v_mfma_f32_16x16x32_bf16 v[6:9], v[226:229], v[246:249], v[6:9]
	s_setprio 0
	s_setprio 1
	v_mfma_f32_16x16x32_bf16 v[10:13], v[206:209], v[26:29], v[158:161]
	v_mfma_f32_16x16x32_bf16 v[74:77], v[214:217], v[30:33], v[10:13]
	v_mfma_f32_16x16x32_bf16 v[10:13], v[210:213], v[26:29], v[162:165]
	v_mfma_f32_16x16x32_bf16 v[78:81], v[218:221], v[30:33], v[10:13]
	v_mfma_f32_16x16x32_bf16 v[10:13], v[206:209], v[222:225], v[166:169]
	v_mfma_f32_16x16x32_bf16 v[42:45], v[214:217], v[230:233], v[10:13]
	v_mfma_f32_16x16x32_bf16 v[10:13], v[210:213], v[222:225], v[170:173]
	v_mfma_f32_16x16x32_bf16 v[46:49], v[218:221], v[230:233], v[10:13]
	v_mfma_f32_16x16x32_bf16 v[10:13], v[206:209], v[234:237], v[174:177]
	v_mfma_f32_16x16x32_bf16 v[26:29], v[214:217], v[238:241], v[10:13]
	v_mfma_f32_16x16x32_bf16 v[10:13], v[210:213], v[234:237], v[182:185]
	v_mfma_f32_16x16x32_bf16 v[30:33], v[218:221], v[238:241], v[10:13]
	v_mfma_f32_16x16x32_bf16 v[10:13], v[206:209], v[242:245], v[190:193]
	v_mfma_f32_16x16x32_bf16 v[14:17], v[210:213], v[242:245], v[194:197]
	v_mfma_f32_16x16x32_bf16 v[10:13], v[214:217], v[246:249], v[10:13]
	v_mfma_f32_16x16x32_bf16 v[14:17], v[218:221], v[246:249], v[14:17]
	s_setprio 0
	s_barrier
	s_and_saveexec_b64 s[18:19], s[4:5]
	s_cbranch_execz .LBB0_839
	s_barrier

; #define STAGEA(P, br, kt) do { const char* _g = uptr(A + (size_t)(br) * lda + (size_t)(kt) * BK); \
;     _Pragma("unroll") for (int _i = 0; _i < 2; ++_i) { \
;       __builtin_amdgcn_global_load_lds((const unsigned*)(_g + offA[_i]), (unsigned*)((char*)(P) + tidx * 16 + _i * 8192), 16, 0, 0); } } while (0)
; #define STAGEB(P, br, kt) do { const char* _g = uptr(Bt + (size_t)(br) * ldb + (size_t)(kt) * BK); \
;     _Pragma("unroll") for (int _i = 0; _i < 2; ++_i) { \
;       __builtin_amdgcn_global_load_lds((const unsigned*)(_g + offB[_i]), (unsigned*)((char*)(P) + tidx * 16 + _i * 8192), 16, 0, 0); } } while (0)
; #define LDA(dst, b, h) _Pragma("unroll") for (int m = 0; m < 4; ++m) _Pragma("unroll") for (int k = 0; k < 2; ++k) \
;     dst[m][k] = *reinterpret_cast<const bf16x8*>((char*)SA(b, h) + aoff + m * 2048 + k * 1024)
; #define LDB(dst, b, h) _Pragma("unroll") for (int n = 0; n < 2; ++n) _Pragma("unroll") for (int k = 0; k < 2; ++k) \
;     dst[n][k] = *reinterpret_cast<const bf16x8*>((char*)SB(b, h) + boff + n * (SWAP ? 256 : 2048) + k * 1024)
; #define WAIT_V(n) asm volatile("s_waitcnt vmcnt(" #n ")" ::: "memory")
; #define WAIT_L(n) asm volatile("s_waitcnt lgkmcnt(" #n ")" ::: "memory")
; template <int EPI>
; DI void gemm_phase(const u16* __restrict__ A, int lda, const u16* __restrict__ Bt, int ldb,
;                    int M, int N, int K, const Epi& e, unsigned char* shmraw, int wv, int slot) {
;     ...
;     if (first_tile) WAIT_V(0);
;     else if constexpr (EPI == EPI_STORE || EPI == EPI_SQRELU || EPI == EPI_GLU || EPI == EPI_FOUT || EPI == EPI_FT) WAIT_V(16);
;     else if constexpr (EPI == EPI_TRANS_F || EPI == EPI_TRANS_V || EPI == EPI_VT) WAIT_V(32);
;     else if constexpr (EPI == EPI_RESID) { if (e.hout) WAIT_V(48); else WAIT_V(32); }
;     else WAIT_V(0);
;     first_tile = false;
;     if (wr == 1) BAR;
;     BAR;
;     for (int t = 0; t < nt - 2; t += 2) {
;       LDB(B0, 0, 0); SCHED; LDA(At, 0, 0); STAGEA(SA(1, 1), brow + HALF, t + 1);
;       WAIT_L(8); BAR; WAIT_L(0); MMA(0, 0, At, B0); BAR; SCHED;
;       LDB(B1, 0, 1); STAGEB(SB(0, 0), bcol, t + 2);
;       BAR; WAIT_L(0); MMA(0, 1, At, B1); BAR;
;       LDA(At, 0, 1); STAGEA(SA(0, 0), brow, t + 2);
;       BAR; WAIT_L(0); MMA(1, 0, At, B0); BAR; SCHED;
;       STAGEB(SB(0, 1), bcol + HALF, t + 2);
;       WAIT_V(6); BAR; MMA(1, 1, At, B1); BAR;
.LBB0_943:
	s_or_b64 exec, exec, s[12:13]
	s_lshl_b32 s12, s1, 8
	s_or_b32 s22, s12, 0x80
	s_ashr_i32 s23, s22, 31
	v_add_u32_e32 v0, s33, v154
	s_barrier
	s_lshl_b64 s[22:23], s[22:23], 10
	ds_read_b128 v[8:11], v0
	ds_read_b128 v[12:15], v0 offset:256
	ds_read_b128 v[16:19], v0 offset:1024
	ds_read_b128 v[20:23], v0 offset:1280
	s_add_u32 s15, s46, s22
	s_addc_u32 s22, s47, s23
	s_lshl_b32 s1, s28, 18
	s_add_u32 s1, s17, s1
	s_addc_u32 s23, s24, 0
	s_ashr_i32 s13, s12, 31
	s_lshl_b64 s[30:31], s[12:13], 10
	s_add_u32 s13, s46, s30
	s_addc_u32 s29, s47, s31
	s_add_u32 s30, s15, 0x80
	v_add_u32_e32 v5, 0xc000, v157
	s_addc_u32 s31, s22, 0
	v_readfirstlane_b32 s68, v5
	v_lshl_add_u64 v[2:3], s[30:31], 0, v[148:149]
	s_mov_b32 m0, s68
	v_add_u32_e32 v6, 0xe000, v157
	ds_read_b128 v[24:27], v169
	ds_read_b128 v[28:31], v169 offset:1024
	ds_read_b128 v[32:35], v169 offset:2048
	ds_read_b128 v[36:39], v169 offset:3072
	ds_read_b128 v[40:43], v169 offset:4096
	ds_read_b128 v[44:47], v169 offset:5120
	ds_read_b128 v[48:51], v169 offset:6144
	ds_read_b128 v[52:55], v169 offset:7168
	global_load_lds_dwordx4 v[2:3], off
	v_lshl_add_u64 v[2:3], s[30:31], 0, v[146:147]
	v_readfirstlane_b32 s30, v6
	s_mov_b32 m0, s30
	s_nop 0
	global_load_lds_dwordx4 v[2:3], off
	s_waitcnt lgkmcnt(8)
	s_barrier
	s_waitcnt lgkmcnt(0)
	s_setprio 1
	v_mfma_f32_16x16x32_bf16 v[56:59], v[8:11], v[24:27], 0
	v_mfma_f32_16x16x32_bf16 v[60:63], v[12:15], v[24:27], 0
	v_mfma_f32_16x16x32_bf16 v[64:67], v[8:11], v[32:35], 0
	v_mfma_f32_16x16x32_bf16 v[68:71], v[12:15], v[32:35], 0
	v_mfma_f32_16x16x32_bf16 v[72:75], v[8:11], v[40:43], 0
	v_mfma_f32_16x16x32_bf16 v[76:79], v[12:15], v[40:43], 0
	v_mfma_f32_16x16x32_bf16 v[80:83], v[8:11], v[48:51], 0
	v_mfma_f32_16x16x32_bf16 v[84:87], v[12:15], v[48:51], 0
	v_mfma_f32_16x16x32_bf16 v[56:59], v[16:19], v[28:31], v[56:59]
	v_mfma_f32_16x16x32_bf16 v[60:63], v[20:23], v[28:31], v[60:63]
	v_mfma_f32_16x16x32_bf16 v[64:67], v[16:19], v[36:39], v[64:67]
	v_mfma_f32_16x16x32_bf16 v[68:71], v[20:23], v[36:39], v[68:71]
	v_mfma_f32_16x16x32_bf16 v[72:75], v[16:19], v[44:47], v[72:75]
	v_mfma_f32_16x16x32_bf16 v[76:79], v[20:23], v[44:47], v[76:79]
	v_mfma_f32_16x16x32_bf16 v[80:83], v[16:19], v[52:55], v[80:83]
	v_mfma_f32_16x16x32_bf16 v[84:87], v[20:23], v[52:55], v[84:87]
	s_setprio 0
	s_barrier
	s_add_u32 s38, s1, 0x100
	s_addc_u32 s39, s23, 0
	v_readfirstlane_b32 s48, v155
	v_add_u32_e32 v158, 0x2000, v155
	v_add_u32_e32 v2, s84, v154
	v_lshl_add_u64 v[104:105], s[38:39], 0, v[148:149]
	s_mov_b32 m0, s48
	v_readfirstlane_b32 s31, v158
	ds_read_b128 v[88:91], v2
	ds_read_b128 v[92:95], v2 offset:256
	ds_read_b128 v[96:99], v2 offset:1024
	ds_read_b128 v[100:103], v2 offset:1280
	global_load_lds_dwordx4 v[104:105], off
	v_lshl_add_u64 v[104:105], s[38:39], 0, v[146:147]
	s_mov_b32 m0, s31
	s_nop 0
	global_load_lds_dwordx4 v[104:105], off
	s_barrier
	s_waitcnt lgkmcnt(0)
	s_setprio 1
	v_mfma_f32_16x16x32_bf16 v[104:107], v[88:91], v[24:27], 0
	v_mfma_f32_16x16x32_bf16 v[24:27], v[92:95], v[24:27], 0
	v_mfma_f32_16x16x32_bf16 v[104:107], v[96:99], v[28:31], v[104:107]
	v_mfma_f32_16x16x32_bf16 v[24:27], v[100:103], v[28:31], v[24:27]
	v_mfma_f32_16x16x32_bf16 v[28:31], v[88:91], v[32:35], 0
	v_mfma_f32_16x16x32_bf16 v[32:35], v[92:95], v[32:35], 0
	v_mfma_f32_16x16x32_bf16 v[28:31], v[96:99], v[36:39], v[28:31]
	v_mfma_f32_16x16x32_bf16 v[32:35], v[100:103], v[36:39], v[32:35]
	v_mfma_f32_16x16x32_bf16 v[36:39], v[88:91], v[40:43], 0
	v_mfma_f32_16x16x32_bf16 v[40:43], v[92:95], v[40:43], 0
	v_mfma_f32_16x16x32_bf16 v[36:39], v[96:99], v[44:47], v[36:39]
	v_mfma_f32_16x16x32_bf16 v[40:43], v[100:103], v[44:47], v[40:43]
	v_mfma_f32_16x16x32_bf16 v[44:47], v[88:91], v[48:51], 0
	v_mfma_f32_16x16x32_bf16 v[48:51], v[92:95], v[48:51], 0
	v_mfma_f32_16x16x32_bf16 v[44:47], v[96:99], v[52:55], v[44:47]
	v_mfma_f32_16x16x32_bf16 v[48:51], v[100:103], v[52:55], v[48:51]
	s_setprio 0
	s_add_u32 s38, s13, 0x100
	s_addc_u32 s39, s29, 0
	v_readfirstlane_b32 s70, v157
	v_add_u32_e32 v159, 0x2000, v157
	v_lshl_add_u64 v[136:137], s[38:39], 0, v[148:149]
	s_mov_b32 m0, s70
	v_readfirstlane_b32 s35, v159
	s_barrier
	ds_read_b128 v[52:55], v169 offset:16384
	ds_read_b128 v[108:111], v169 offset:17408
	ds_read_b128 v[112:115], v169 offset:18432
	ds_read_b128 v[116:119], v169 offset:19456
	ds_read_b128 v[120:123], v169 offset:20480
	ds_read_b128 v[124:127], v169 offset:21504
	ds_read_b128 v[128:131], v169 offset:22528
	ds_read_b128 v[132:135], v169 offset:23552
	global_load_lds_dwordx4 v[136:137], off
	v_lshl_add_u64 v[136:137], s[38:39], 0, v[146:147]
	s_mov_b32 m0, s35
	s_nop 0
	global_load_lds_dwordx4 v[136:137], off
	s_barrier
	s_waitcnt lgkmcnt(0)
	s_setprio 1
	v_mfma_f32_16x16x32_bf16 v[136:139], v[8:11], v[52:55], 0
	v_mfma_f32_16x16x32_bf16 v[140:143], v[12:15], v[52:55], 0
	v_mfma_f32_16x16x32_bf16 v[150:153], v[8:11], v[112:115], 0
	v_mfma_f32_16x16x32_bf16 v[174:177], v[8:11], v[120:123], 0
	v_mfma_f32_16x16x32_bf16 v[8:11], v[8:11], v[128:131], 0
	v_mfma_f32_16x16x32_bf16 v[136:139], v[16:19], v[108:111], v[136:139]
	v_mfma_f32_16x16x32_bf16 v[140:143], v[20:23], v[108:111], v[140:143]
	v_mfma_f32_16x16x32_bf16 v[170:173], v[12:15], v[112:115], 0
	v_mfma_f32_16x16x32_bf16 v[182:185], v[12:15], v[120:123], 0
	v_mfma_f32_16x16x32_bf16 v[8:11], v[16:19], v[132:135], v[8:11]
	v_mfma_f32_16x16x32_bf16 v[12:15], v[12:15], v[128:131], 0
	v_mfma_f32_16x16x32_bf16 v[150:153], v[16:19], v[116:119], v[150:153]
	v_mfma_f32_16x16x32_bf16 v[170:173], v[20:23], v[116:119], v[170:173]
	v_mfma_f32_16x16x32_bf16 v[174:177], v[16:19], v[124:127], v[174:177]
	v_mfma_f32_16x16x32_bf16 v[182:185], v[20:23], v[124:127], v[182:185]
	v_mfma_f32_16x16x32_bf16 v[12:15], v[20:23], v[132:135], v[12:15]
	s_setprio 0
	s_barrier
; #define STAGEA(P, br, kt) do { const char* _g = uptr(A + (size_t)(br) * lda + (size_t)(kt) * BK); \
;     _Pragma("unroll") for (int _i = 0; _i < 2; ++_i) { \
;       __builtin_amdgcn_global_load_lds((const unsigned*)(_g + offA[_i]), (unsigned*)((char*)(P) + tidx * 16 + _i * 8192), 16, 0, 0); } } while (0)
; #define STAGEB(P, br, kt) do { const char* _g = uptr(Bt + (size_t)(br) * ldb + (size_t)(kt) * BK); \
;     _Pragma("unroll") for (int _i = 0; _i < 2; ++_i) { \
;       __builtin_amdgcn_global_load_lds((const unsigned*)(_g + offB[_i]), (unsigned*)((char*)(P) + tidx * 16 + _i * 8192), 16, 0, 0); } } while (0)
; #define LDA(dst, b, h) _Pragma("unroll") for (int m = 0; m < 4; ++m) _Pragma("unroll") for (int k = 0; k < 2; ++k) \
;     dst[m][k] = *reinterpret_cast<const bf16x8*>((char*)SA(b, h) + aoff + m * 2048 + k * 1024)
; #define LDB(dst, b, h) _Pragma("unroll") for (int n = 0; n < 2; ++n) _Pragma("unroll") for (int k = 0; k < 2; ++k) \
;     dst[n][k] = *reinterpret_cast<const bf16x8*>((char*)SB(b, h) + boff + n * (SWAP ? 256 : 2048) + k * 1024)
; #define WAIT_V(n) asm volatile("s_waitcnt vmcnt(" #n ")" ::: "memory")
; #define WAIT_L(n) asm volatile("s_waitcnt lgkmcnt(" #n ")" ::: "memory")
; #define BAR __builtin_amdgcn_s_barrier()
; #define SCHED __builtin_amdgcn_sched_barrier(0)
; template <int EPI>
; DI void gemm_phase(const u16* __restrict__ A, int lda, const u16* __restrict__ Bt, int ldb,
;                    int M, int N, int K, const Epi& e, unsigned char* shmraw, int wv, int slot) {
;     ...
;       STAGEB(SB(0, 1), bcol + HALF, t + 2);
;       WAIT_V(6); BAR; MMA(1, 1, At, B1); BAR;
;       LDB(B0, 1, 0); SCHED; LDA(At, 1, 0); STAGEA(SA(0, 1), brow + HALF, t + 2);
;       WAIT_L(8); BAR; WAIT_L(0); MMA(0, 0, At, B0); BAR; SCHED;
;       LDB(B1, 1, 1); STAGEB(SB(1, 0), bcol, t + 3);
;       BAR; WAIT_L(0); MMA(0, 1, At, B1); BAR;
;       LDA(At, 1, 1); STAGEA(SA(1, 0), brow, t + 3);
;       BAR; WAIT_L(0); MMA(1, 0, At, B0); BAR; SCHED;
	s_add_u32 s38, s1, 0x20100
	s_addc_u32 s39, s23, 0
	v_readfirstlane_b32 s41, v156
	v_add_u32_e32 v160, 0x2000, v156
	v_lshl_add_u64 v[16:17], s[38:39], 0, v[148:149]
	s_mov_b32 m0, s41
	v_readfirstlane_b32 s36, v160
	global_load_lds_dwordx4 v[16:17], off
	v_lshl_add_u64 v[16:17], s[38:39], 0, v[146:147]
	s_mov_b32 m0, s36
	s_nop 0
	global_load_lds_dwordx4 v[16:17], off
	s_waitcnt vmcnt(6)
	s_barrier
	s_setprio 1
	v_mfma_f32_16x16x32_bf16 v[16:19], v[88:91], v[52:55], 0
	v_mfma_f32_16x16x32_bf16 v[20:23], v[92:95], v[52:55], 0
	v_mfma_f32_16x16x32_bf16 v[16:19], v[96:99], v[108:111], v[16:19]
	v_mfma_f32_16x16x32_bf16 v[20:23], v[100:103], v[108:111], v[20:23]
	v_mfma_f32_16x16x32_bf16 v[52:55], v[88:91], v[112:115], 0
	v_mfma_f32_16x16x32_bf16 v[108:111], v[92:95], v[112:115], 0
	v_mfma_f32_16x16x32_bf16 v[52:55], v[96:99], v[116:119], v[52:55]
	v_mfma_f32_16x16x32_bf16 v[108:111], v[100:103], v[116:119], v[108:111]
	v_mfma_f32_16x16x32_bf16 v[112:115], v[88:91], v[120:123], 0
	v_mfma_f32_16x16x32_bf16 v[116:119], v[92:95], v[120:123], 0
	v_mfma_f32_16x16x32_bf16 v[88:91], v[88:91], v[128:131], 0
	v_mfma_f32_16x16x32_bf16 v[92:95], v[92:95], v[128:131], 0
	v_mfma_f32_16x16x32_bf16 v[112:115], v[96:99], v[124:127], v[112:115]
	v_mfma_f32_16x16x32_bf16 v[116:119], v[100:103], v[124:127], v[116:119]
	v_mfma_f32_16x16x32_bf16 v[88:91], v[96:99], v[132:135], v[88:91]
	v_mfma_f32_16x16x32_bf16 v[92:95], v[100:103], v[132:135], v[92:95]
	s_setprio 0
	v_add_u32_e32 v3, s85, v154
	s_barrier
	ds_read_b128 v[96:99], v3
	ds_read_b128 v[100:103], v3 offset:256
	ds_read_b128 v[120:123], v3 offset:1024
	ds_read_b128 v[124:127], v3 offset:1280
	s_add_u32 s38, s15, 0x100
	v_add_u32_e32 v161, 0x4000, v157
	s_addc_u32 s39, s22, 0
	v_readfirstlane_b32 s72, v161
	v_lshl_add_u64 v[144:145], s[38:39], 0, v[148:149]
	s_mov_b32 m0, s72
	v_add_u32_e32 v162, 0x6000, v157
	ds_read_b128 v[128:131], v169 offset:32768
	ds_read_b128 v[132:135], v169 offset:33792
	ds_read_b128 v[190:193], v169 offset:34816
	ds_read_b128 v[194:197], v169 offset:35840
	ds_read_b128 v[198:201], v169 offset:36864
	ds_read_b128 v[202:205], v169 offset:37888
	ds_read_b128 v[206:209], v169 offset:38912
	ds_read_b128 v[210:213], v169 offset:39936
	global_load_lds_dwordx4 v[144:145], off
	v_lshl_add_u64 v[144:145], s[38:39], 0, v[146:147]
	v_readfirstlane_b32 s38, v162
	s_mov_b32 m0, s38
	s_nop 0
	global_load_lds_dwordx4 v[144:145], off
	s_waitcnt lgkmcnt(8)
	s_barrier
	s_waitcnt lgkmcnt(0)
	s_setprio 1
	v_mfma_f32_16x16x32_bf16 v[56:59], v[96:99], v[128:131], v[56:59]
	v_mfma_f32_16x16x32_bf16 v[60:63], v[100:103], v[128:131], v[60:63]
	v_mfma_f32_16x16x32_bf16 v[64:67], v[96:99], v[190:193], v[64:67]
	v_mfma_f32_16x16x32_bf16 v[68:71], v[100:103], v[190:193], v[68:71]
	v_mfma_f32_16x16x32_bf16 v[72:75], v[96:99], v[198:201], v[72:75]
	v_mfma_f32_16x16x32_bf16 v[76:79], v[100:103], v[198:201], v[76:79]
	v_mfma_f32_16x16x32_bf16 v[80:83], v[96:99], v[206:209], v[80:83]
	v_mfma_f32_16x16x32_bf16 v[84:87], v[100:103], v[206:209], v[84:87]
	v_mfma_f32_16x16x32_bf16 v[56:59], v[120:123], v[132:135], v[56:59]
	v_mfma_f32_16x16x32_bf16 v[60:63], v[124:127], v[132:135], v[60:63]
	v_mfma_f32_16x16x32_bf16 v[64:67], v[120:123], v[194:197], v[64:67]
	v_mfma_f32_16x16x32_bf16 v[68:71], v[124:127], v[194:197], v[68:71]
	v_mfma_f32_16x16x32_bf16 v[72:75], v[120:123], v[202:205], v[72:75]
	v_mfma_f32_16x16x32_bf16 v[76:79], v[124:127], v[202:205], v[76:79]
	v_mfma_f32_16x16x32_bf16 v[80:83], v[120:123], v[210:213], v[80:83]
	v_mfma_f32_16x16x32_bf16 v[84:87], v[124:127], v[210:213], v[84:87]
	s_setprio 0
	s_barrier
	s_add_u32 s74, s1, 0x180
	s_addc_u32 s75, s23, 0
	v_readfirstlane_b32 s71, v166
	v_add_u32_e32 v163, 0x2000, v166
	v_add_u32_e32 v4, s86, v154
	v_lshl_add_u64 v[144:145], s[74:75], 0, v[148:149]
	s_mov_b32 m0, s71
	v_readfirstlane_b32 s39, v163
	ds_read_b128 v[214:217], v4
	ds_read_b128 v[218:221], v4 offset:256
	ds_read_b128 v[222:225], v4 offset:1024
	ds_read_b128 v[226:229], v4 offset:1280
	global_load_lds_dwordx4 v[144:145], off
	v_lshl_add_u64 v[144:145], s[74:75], 0, v[146:147]
	s_mov_b32 m0, s39
	s_nop 0
	global_load_lds_dwordx4 v[144:145], off
	s_barrier
	s_waitcnt lgkmcnt(0)
	s_setprio 1
	v_mfma_f32_16x16x32_bf16 v[104:107], v[214:217], v[128:131], v[104:107]
	v_mfma_f32_16x16x32_bf16 v[24:27], v[218:221], v[128:131], v[24:27]
	v_mfma_f32_16x16x32_bf16 v[32:35], v[218:221], v[190:193], v[32:35]
	v_mfma_f32_16x16x32_bf16 v[36:39], v[214:217], v[198:201], v[36:39]
	v_mfma_f32_16x16x32_bf16 v[40:43], v[218:221], v[198:201], v[40:43]
	v_mfma_f32_16x16x32_bf16 v[44:47], v[214:217], v[206:209], v[44:47]
	v_mfma_f32_16x16x32_bf16 v[48:51], v[218:221], v[206:209], v[48:51]
	v_mfma_f32_16x16x32_bf16 v[104:107], v[222:225], v[132:135], v[104:107]
	v_mfma_f32_16x16x32_bf16 v[24:27], v[226:229], v[132:135], v[24:27]
	v_mfma_f32_16x16x32_bf16 v[28:31], v[214:217], v[190:193], v[28:31]
	v_mfma_f32_16x16x32_bf16 v[32:35], v[226:229], v[194:197], v[32:35]
	v_mfma_f32_16x16x32_bf16 v[36:39], v[222:225], v[202:205], v[36:39]
	v_mfma_f32_16x16x32_bf16 v[40:43], v[226:229], v[202:205], v[40:43]
	v_mfma_f32_16x16x32_bf16 v[44:47], v[222:225], v[210:213], v[44:47]
	v_mfma_f32_16x16x32_bf16 v[48:51], v[226:229], v[210:213], v[48:51]
	v_mfma_f32_16x16x32_bf16 v[28:31], v[222:225], v[194:197], v[28:31]
	s_setprio 0
	s_add_u32 s74, s13, 0x180
	v_add_u32_e32 v164, 0x8000, v157
	s_addc_u32 s75, s29, 0
	v_readfirstlane_b32 s73, v164
	v_add_u32_e32 v165, 0xa000, v157
	v_lshl_add_u64 v[144:145], s[74:75], 0, v[148:149]
	s_mov_b32 m0, s73
	v_readfirstlane_b32 s40, v165
	s_barrier
; #define STAGEA(P, br, kt) do { const char* _g = uptr(A + (size_t)(br) * lda + (size_t)(kt) * BK); \
;     _Pragma("unroll") for (int _i = 0; _i < 2; ++_i) { \
;       __builtin_amdgcn_global_load_lds((const unsigned*)(_g + offA[_i]), (unsigned*)((char*)(P) + tidx * 16 + _i * 8192), 16, 0, 0); } } while (0)
; #define STAGEB(P, br, kt) do { const char* _g = uptr(Bt + (size_t)(br) * ldb + (size_t)(kt) * BK); \
;     _Pragma("unroll") for (int _i = 0; _i < 2; ++_i) { \
;       __builtin_amdgcn_global_load_lds((const unsigned*)(_g + offB[_i]), (unsigned*)((char*)(P) + tidx * 16 + _i * 8192), 16, 0, 0); } } while (0)
; #define LDA(dst, b, h) _Pragma("unroll") for (int m = 0; m < 4; ++m) _Pragma("unroll") for (int k = 0; k < 2; ++k) \
;     dst[m][k] = *reinterpret_cast<const bf16x8*>((char*)SA(b, h) + aoff + m * 2048 + k * 1024)
; #define LDB(dst, b, h) _Pragma("unroll") for (int n = 0; n < 2; ++n) _Pragma("unroll") for (int k = 0; k < 2; ++k) \
;     dst[n][k] = *reinterpret_cast<const bf16x8*>((char*)SB(b, h) + boff + n * (SWAP ? 256 : 2048) + k * 1024)
; #define WAIT_V(n) asm volatile("s_waitcnt vmcnt(" #n ")" ::: "memory")
; #define WAIT_L(n) asm volatile("s_waitcnt lgkmcnt(" #n ")" ::: "memory")
; #define BAR __builtin_amdgcn_s_barrier()
; template <int EPI>
; DI void gemm_phase(const u16* __restrict__ A, int lda, const u16* __restrict__ Bt, int ldb,
;                    int M, int N, int K, const Epi& e, unsigned char* shmraw, int wv, int slot) {
;     ...
;       LDB(B0, 0, 0); SCHED; LDA(At, 0, 0); STAGEA(SA(1, 1), brow + HALF, t + 1);
;       WAIT_L(8); BAR; WAIT_L(0); MMA(0, 0, At, B0); BAR; SCHED;
;       LDB(B1, 0, 1); STAGEB(SB(0, 0), bcol, t + 2);
;       BAR; WAIT_L(0); MMA(0, 1, At, B1); BAR;
;       LDA(At, 0, 1); STAGEA(SA(0, 0), brow, t + 2);
;       BAR; WAIT_L(0); MMA(1, 0, At, B0); BAR; SCHED;
;       STAGEB(SB(0, 1), bcol + HALF, t + 2);
;       WAIT_V(6); BAR; MMA(1, 1, At, B1); BAR;
;       LDB(B0, 1, 0); SCHED; LDA(At, 1, 0); STAGEA(SA(0, 1), brow + HALF, t + 2);
;       WAIT_L(8); BAR; WAIT_L(0); MMA(0, 0, At, B0); BAR; SCHED;
;       LDB(B1, 1, 1); STAGEB(SB(1, 0), bcol, t + 3);
;       BAR; WAIT_L(0); MMA(0, 1, At, B1); BAR;
;       LDA(At, 1, 1); STAGEA(SA(1, 0), brow, t + 3);
;       BAR; WAIT_L(0); MMA(1, 0, At, B0); BAR; SCHED;
;       STAGEB(SB(1, 1), bcol + HALF, t + 3);
;       WAIT_V(6); BAR; MMA(1, 1, At, B1); BAR;
	ds_read_b128 v[128:131], v169 offset:49152
	ds_read_b128 v[132:135], v169 offset:50176
	ds_read_b128 v[190:193], v169 offset:51200
	ds_read_b128 v[194:197], v169 offset:52224
	ds_read_b128 v[198:201], v169 offset:53248
	ds_read_b128 v[202:205], v169 offset:54272
	ds_read_b128 v[206:209], v169 offset:55296
	ds_read_b128 v[210:213], v169 offset:56320
	global_load_lds_dwordx4 v[144:145], off
	v_lshl_add_u64 v[144:145], s[74:75], 0, v[146:147]
	s_mov_b32 m0, s40
	s_nop 0
	global_load_lds_dwordx4 v[144:145], off
	s_barrier
	s_waitcnt lgkmcnt(0)
	s_setprio 1
	v_mfma_f32_16x16x32_bf16 v[136:139], v[96:99], v[128:131], v[136:139]
	v_mfma_f32_16x16x32_bf16 v[140:143], v[100:103], v[128:131], v[140:143]
	v_mfma_f32_16x16x32_bf16 v[8:11], v[96:99], v[206:209], v[8:11]
	v_mfma_f32_16x16x32_bf16 v[136:139], v[120:123], v[132:135], v[136:139]
	v_mfma_f32_16x16x32_bf16 v[140:143], v[124:127], v[132:135], v[140:143]
	v_mfma_f32_16x16x32_bf16 v[150:153], v[96:99], v[190:193], v[150:153]
	v_mfma_f32_16x16x32_bf16 v[170:173], v[100:103], v[190:193], v[170:173]
	v_mfma_f32_16x16x32_bf16 v[174:177], v[96:99], v[198:201], v[174:177]
	v_mfma_f32_16x16x32_bf16 v[182:185], v[100:103], v[198:201], v[182:185]
	v_mfma_f32_16x16x32_bf16 v[8:11], v[120:123], v[210:213], v[8:11]
	v_mfma_f32_16x16x32_bf16 v[12:15], v[100:103], v[206:209], v[12:15]
	v_mfma_f32_16x16x32_bf16 v[150:153], v[120:123], v[194:197], v[150:153]
	v_mfma_f32_16x16x32_bf16 v[170:173], v[124:127], v[194:197], v[170:173]
	v_mfma_f32_16x16x32_bf16 v[174:177], v[120:123], v[202:205], v[174:177]
	v_mfma_f32_16x16x32_bf16 v[182:185], v[124:127], v[202:205], v[182:185]
	v_mfma_f32_16x16x32_bf16 v[12:15], v[124:127], v[210:213], v[12:15]
	s_setprio 0
	s_barrier
	s_add_u32 s74, s1, 0x20180
	s_addc_u32 s75, s23, 0
	v_readfirstlane_b32 s69, v167
	v_lshl_add_u64 v[96:97], s[74:75], 0, v[148:149]
	s_mov_b32 m0, s69
	v_readfirstlane_b32 s43, v168
	global_load_lds_dwordx4 v[96:97], off
	v_lshl_add_u64 v[96:97], s[74:75], 0, v[146:147]
	s_mov_b32 m0, s43
	s_nop 0
	global_load_lds_dwordx4 v[96:97], off
	s_waitcnt vmcnt(6)
	s_barrier
	s_setprio 1
	v_mfma_f32_16x16x32_bf16 v[16:19], v[214:217], v[128:131], v[16:19]
	v_mfma_f32_16x16x32_bf16 v[20:23], v[218:221], v[128:131], v[20:23]
	v_mfma_f32_16x16x32_bf16 v[52:55], v[214:217], v[190:193], v[52:55]
	v_mfma_f32_16x16x32_bf16 v[96:99], v[218:221], v[190:193], v[108:111]
	v_mfma_f32_16x16x32_bf16 v[100:103], v[214:217], v[198:201], v[112:115]
	v_mfma_f32_16x16x32_bf16 v[108:111], v[218:221], v[198:201], v[116:119]
	v_mfma_f32_16x16x32_bf16 v[88:91], v[214:217], v[206:209], v[88:91]
	v_mfma_f32_16x16x32_bf16 v[92:95], v[218:221], v[206:209], v[92:95]
	v_mfma_f32_16x16x32_bf16 v[16:19], v[222:225], v[132:135], v[16:19]
	v_mfma_f32_16x16x32_bf16 v[20:23], v[226:229], v[132:135], v[20:23]
	v_mfma_f32_16x16x32_bf16 v[52:55], v[222:225], v[194:197], v[52:55]
	v_mfma_f32_16x16x32_bf16 v[96:99], v[226:229], v[194:197], v[96:99]
	v_mfma_f32_16x16x32_bf16 v[100:103], v[222:225], v[202:205], v[100:103]
	v_mfma_f32_16x16x32_bf16 v[108:111], v[226:229], v[202:205], v[108:111]
	v_mfma_f32_16x16x32_bf16 v[88:91], v[222:225], v[210:213], v[88:91]
	v_mfma_f32_16x16x32_bf16 v[92:95], v[226:229], v[210:213], v[92:95]
	s_setprio 0
	s_barrier
	ds_read_b128 v[112:115], v0
	ds_read_b128 v[116:119], v0 offset:256
	ds_read_b128 v[120:123], v0 offset:1024
	ds_read_b128 v[124:127], v0 offset:1280
	s_add_u32 s74, s15, 0x180
	s_addc_u32 s75, s22, 0
	s_mov_b32 m0, s68
	v_lshl_add_u64 v[144:145], s[74:75], 0, v[148:149]
	ds_read_b128 v[128:131], v169
	ds_read_b128 v[132:135], v169 offset:1024
	ds_read_b128 v[190:193], v169 offset:2048
	ds_read_b128 v[194:197], v169 offset:3072
	ds_read_b128 v[198:201], v169 offset:4096
	ds_read_b128 v[202:205], v169 offset:5120
	ds_read_b128 v[206:209], v169 offset:6144
	ds_read_b128 v[210:213], v169 offset:7168
	global_load_lds_dwordx4 v[144:145], off
	v_lshl_add_u64 v[144:145], s[74:75], 0, v[146:147]
	s_mov_b32 m0, s30
	s_nop 0
	global_load_lds_dwordx4 v[144:145], off
	s_waitcnt lgkmcnt(8)
	s_barrier
	s_waitcnt lgkmcnt(0)
	s_setprio 1
	v_mfma_f32_16x16x32_bf16 v[56:59], v[112:115], v[128:131], v[56:59]
	v_mfma_f32_16x16x32_bf16 v[60:63], v[116:119], v[128:131], v[60:63]
	v_mfma_f32_16x16x32_bf16 v[64:67], v[112:115], v[190:193], v[64:67]
	v_mfma_f32_16x16x32_bf16 v[68:71], v[116:119], v[190:193], v[68:71]
	v_mfma_f32_16x16x32_bf16 v[72:75], v[112:115], v[198:201], v[72:75]
	v_mfma_f32_16x16x32_bf16 v[76:79], v[116:119], v[198:201], v[76:79]
	v_mfma_f32_16x16x32_bf16 v[80:83], v[112:115], v[206:209], v[80:83]
	v_mfma_f32_16x16x32_bf16 v[84:87], v[116:119], v[206:209], v[84:87]
	v_mfma_f32_16x16x32_bf16 v[56:59], v[120:123], v[132:135], v[56:59]
	v_mfma_f32_16x16x32_bf16 v[60:63], v[124:127], v[132:135], v[60:63]
	v_mfma_f32_16x16x32_bf16 v[64:67], v[120:123], v[194:197], v[64:67]
	v_mfma_f32_16x16x32_bf16 v[68:71], v[124:127], v[194:197], v[68:71]
	v_mfma_f32_16x16x32_bf16 v[72:75], v[120:123], v[202:205], v[72:75]
	v_mfma_f32_16x16x32_bf16 v[76:79], v[124:127], v[202:205], v[76:79]
	v_mfma_f32_16x16x32_bf16 v[80:83], v[120:123], v[210:213], v[80:83]
	v_mfma_f32_16x16x32_bf16 v[84:87], v[124:127], v[210:213], v[84:87]
	s_setprio 0
	s_barrier
	s_add_u32 s74, s1, 0x200
	s_addc_u32 s75, s23, 0
	s_mov_b32 m0, s48
	v_lshl_add_u64 v[144:145], s[74:75], 0, v[148:149]
	ds_read_b128 v[214:217], v2
	ds_read_b128 v[218:221], v2 offset:256
	ds_read_b128 v[222:225], v2 offset:1024
	ds_read_b128 v[226:229], v2 offset:1280
	global_load_lds_dwordx4 v[144:145], off
	v_lshl_add_u64 v[144:145], s[74:75], 0, v[146:147]
	s_mov_b32 m0, s31
	s_nop 0
	global_load_lds_dwordx4 v[144:145], off
	s_barrier
; #define STAGEA(P, br, kt) do { const char* _g = uptr(A + (size_t)(br) * lda + (size_t)(kt) * BK); \
;     _Pragma("unroll") for (int _i = 0; _i < 2; ++_i) { \
;       __builtin_amdgcn_global_load_lds((const unsigned*)(_g + offA[_i]), (unsigned*)((char*)(P) + tidx * 16 + _i * 8192), 16, 0, 0); } } while (0)
; #define STAGEB(P, br, kt) do { const char* _g = uptr(Bt + (size_t)(br) * ldb + (size_t)(kt) * BK); \
;     _Pragma("unroll") for (int _i = 0; _i < 2; ++_i) { \
;       __builtin_amdgcn_global_load_lds((const unsigned*)(_g + offB[_i]), (unsigned*)((char*)(P) + tidx * 16 + _i * 8192), 16, 0, 0); } } while (0)
; #define LDA(dst, b, h) _Pragma("unroll") for (int m = 0; m < 4; ++m) _Pragma("unroll") for (int k = 0; k < 2; ++k) \
;     dst[m][k] = *reinterpret_cast<const bf16x8*>((char*)SA(b, h) + aoff + m * 2048 + k * 1024)
; #define LDB(dst, b, h) _Pragma("unroll") for (int n = 0; n < 2; ++n) _Pragma("unroll") for (int k = 0; k < 2; ++k) \
;     dst[n][k] = *reinterpret_cast<const bf16x8*>((char*)SB(b, h) + boff + n * (SWAP ? 256 : 2048) + k * 1024)
; #define WAIT_V(n) asm volatile("s_waitcnt vmcnt(" #n ")" ::: "memory")
; #define WAIT_L(n) asm volatile("s_waitcnt lgkmcnt(" #n ")" ::: "memory")
; #define BAR __builtin_amdgcn_s_barrier()
; template <int EPI>
; DI void gemm_phase(const u16* __restrict__ A, int lda, const u16* __restrict__ Bt, int ldb,
;                    int M, int N, int K, const Epi& e, unsigned char* shmraw, int wv, int slot) {
;     ...
;       LDB(B0, 0, 0); SCHED; LDA(At, 0, 0); STAGEA(SA(1, 1), brow + HALF, t + 1);
;       WAIT_L(8); BAR; WAIT_L(0); MMA(0, 0, At, B0); BAR; SCHED;
;       LDB(B1, 0, 1); STAGEB(SB(0, 0), bcol, t + 2);
;       BAR; WAIT_L(0); MMA(0, 1, At, B1); BAR;
;       LDA(At, 0, 1); STAGEA(SA(0, 0), brow, t + 2);
;       BAR; WAIT_L(0); MMA(1, 0, At, B0); BAR; SCHED;
;       STAGEB(SB(0, 1), bcol + HALF, t + 2);
;       WAIT_V(6); BAR; MMA(1, 1, At, B1); BAR;
;       LDB(B0, 1, 0); SCHED; LDA(At, 1, 0); STAGEA(SA(0, 1), brow + HALF, t + 2);
;       WAIT_L(8); BAR; WAIT_L(0); MMA(0, 0, At, B0); BAR; SCHED;
;       LDB(B1, 1, 1); STAGEB(SB(1, 0), bcol, t + 3);
;       BAR; WAIT_L(0); MMA(0, 1, At, B1); BAR;
;       LDA(At, 1, 1); STAGEA(SA(1, 0), brow, t + 3);
;       BAR; WAIT_L(0); MMA(1, 0, At, B0); BAR; SCHED;
;       STAGEB(SB(1, 1), bcol + HALF, t + 3);
;       WAIT_V(6); BAR; MMA(1, 1, At, B1); BAR;
	s_waitcnt lgkmcnt(0)
	s_setprio 1
	v_mfma_f32_16x16x32_bf16 v[104:107], v[214:217], v[128:131], v[104:107]
	v_mfma_f32_16x16x32_bf16 v[24:27], v[218:221], v[128:131], v[24:27]
	v_mfma_f32_16x16x32_bf16 v[32:35], v[218:221], v[190:193], v[32:35]
	v_mfma_f32_16x16x32_bf16 v[36:39], v[214:217], v[198:201], v[36:39]
	v_mfma_f32_16x16x32_bf16 v[40:43], v[218:221], v[198:201], v[40:43]
	v_mfma_f32_16x16x32_bf16 v[44:47], v[214:217], v[206:209], v[44:47]
	v_mfma_f32_16x16x32_bf16 v[48:51], v[218:221], v[206:209], v[48:51]
	v_mfma_f32_16x16x32_bf16 v[104:107], v[222:225], v[132:135], v[104:107]
	v_mfma_f32_16x16x32_bf16 v[24:27], v[226:229], v[132:135], v[24:27]
	v_mfma_f32_16x16x32_bf16 v[28:31], v[214:217], v[190:193], v[28:31]
	v_mfma_f32_16x16x32_bf16 v[32:35], v[226:229], v[194:197], v[32:35]
	v_mfma_f32_16x16x32_bf16 v[36:39], v[222:225], v[202:205], v[36:39]
	v_mfma_f32_16x16x32_bf16 v[40:43], v[226:229], v[202:205], v[40:43]
	v_mfma_f32_16x16x32_bf16 v[44:47], v[222:225], v[210:213], v[44:47]
	v_mfma_f32_16x16x32_bf16 v[48:51], v[226:229], v[210:213], v[48:51]
	v_mfma_f32_16x16x32_bf16 v[28:31], v[222:225], v[194:197], v[28:31]
	s_setprio 0
	s_add_u32 s30, s13, 0x200
	s_addc_u32 s31, s29, 0
	s_mov_b32 m0, s70
	v_lshl_add_u64 v[144:145], s[30:31], 0, v[148:149]
	s_barrier
	ds_read_b128 v[128:131], v169 offset:16384
	ds_read_b128 v[132:135], v169 offset:17408
	ds_read_b128 v[190:193], v169 offset:18432
	ds_read_b128 v[194:197], v169 offset:19456
	ds_read_b128 v[198:201], v169 offset:20480
	ds_read_b128 v[202:205], v169 offset:21504
	ds_read_b128 v[206:209], v169 offset:22528
	ds_read_b128 v[210:213], v169 offset:23552
	global_load_lds_dwordx4 v[144:145], off
	v_lshl_add_u64 v[144:145], s[30:31], 0, v[146:147]
	s_mov_b32 m0, s35
	s_nop 0
	global_load_lds_dwordx4 v[144:145], off
	s_barrier
	s_waitcnt lgkmcnt(0)
	s_setprio 1
	v_mfma_f32_16x16x32_bf16 v[136:139], v[112:115], v[128:131], v[136:139]
	v_mfma_f32_16x16x32_bf16 v[140:143], v[116:119], v[128:131], v[140:143]
	v_mfma_f32_16x16x32_bf16 v[8:11], v[112:115], v[206:209], v[8:11]
	v_mfma_f32_16x16x32_bf16 v[136:139], v[120:123], v[132:135], v[136:139]
	v_mfma_f32_16x16x32_bf16 v[140:143], v[124:127], v[132:135], v[140:143]
	v_mfma_f32_16x16x32_bf16 v[150:153], v[112:115], v[190:193], v[150:153]
	v_mfma_f32_16x16x32_bf16 v[170:173], v[116:119], v[190:193], v[170:173]
	v_mfma_f32_16x16x32_bf16 v[174:177], v[112:115], v[198:201], v[174:177]
	v_mfma_f32_16x16x32_bf16 v[182:185], v[116:119], v[198:201], v[182:185]
	v_mfma_f32_16x16x32_bf16 v[8:11], v[120:123], v[210:213], v[8:11]
	v_mfma_f32_16x16x32_bf16 v[12:15], v[116:119], v[206:209], v[12:15]
	v_mfma_f32_16x16x32_bf16 v[150:153], v[120:123], v[194:197], v[150:153]
	v_mfma_f32_16x16x32_bf16 v[170:173], v[124:127], v[194:197], v[170:173]
	v_mfma_f32_16x16x32_bf16 v[174:177], v[120:123], v[202:205], v[174:177]
	v_mfma_f32_16x16x32_bf16 v[182:185], v[124:127], v[202:205], v[182:185]
	v_mfma_f32_16x16x32_bf16 v[12:15], v[124:127], v[210:213], v[12:15]
	s_setprio 0
	s_barrier
	s_add_u32 s30, s1, 0x20200
	s_addc_u32 s31, s23, 0
	s_mov_b32 m0, s41
	v_lshl_add_u64 v[112:113], s[30:31], 0, v[148:149]
	global_load_lds_dwordx4 v[112:113], off
	v_lshl_add_u64 v[112:113], s[30:31], 0, v[146:147]
	s_mov_b32 m0, s36
	s_nop 0
	global_load_lds_dwordx4 v[112:113], off
	s_waitcnt vmcnt(6)
	s_barrier
	s_setprio 1
	v_mfma_f32_16x16x32_bf16 v[16:19], v[214:217], v[128:131], v[16:19]
	v_mfma_f32_16x16x32_bf16 v[20:23], v[218:221], v[128:131], v[20:23]
	v_mfma_f32_16x16x32_bf16 v[52:55], v[214:217], v[190:193], v[52:55]
	v_mfma_f32_16x16x32_bf16 v[96:99], v[218:221], v[190:193], v[96:99]
	v_mfma_f32_16x16x32_bf16 v[100:103], v[214:217], v[198:201], v[100:103]
	v_mfma_f32_16x16x32_bf16 v[108:111], v[218:221], v[198:201], v[108:111]
	v_mfma_f32_16x16x32_bf16 v[88:91], v[214:217], v[206:209], v[88:91]
	v_mfma_f32_16x16x32_bf16 v[92:95], v[218:221], v[206:209], v[92:95]
	v_mfma_f32_16x16x32_bf16 v[16:19], v[222:225], v[132:135], v[16:19]
	v_mfma_f32_16x16x32_bf16 v[20:23], v[226:229], v[132:135], v[20:23]
	v_mfma_f32_16x16x32_bf16 v[52:55], v[222:225], v[194:197], v[52:55]
	v_mfma_f32_16x16x32_bf16 v[96:99], v[226:229], v[194:197], v[96:99]
	v_mfma_f32_16x16x32_bf16 v[100:103], v[222:225], v[202:205], v[100:103]
	v_mfma_f32_16x16x32_bf16 v[108:111], v[226:229], v[202:205], v[108:111]
	v_mfma_f32_16x16x32_bf16 v[88:91], v[222:225], v[210:213], v[88:91]
	v_mfma_f32_16x16x32_bf16 v[92:95], v[226:229], v[210:213], v[92:95]
	s_setprio 0
	s_barrier
	ds_read_b128 v[112:115], v3
	ds_read_b128 v[116:119], v3 offset:256
	ds_read_b128 v[120:123], v3 offset:1024
	ds_read_b128 v[124:127], v3 offset:1280
	s_add_u32 s30, s15, 0x200
	s_addc_u32 s31, s22, 0
	s_mov_b32 m0, s72
	v_lshl_add_u64 v[144:145], s[30:31], 0, v[148:149]
	ds_read_b128 v[128:131], v169 offset:32768
	ds_read_b128 v[132:135], v169 offset:33792
	ds_read_b128 v[190:193], v169 offset:34816
	ds_read_b128 v[194:197], v169 offset:35840
	ds_read_b128 v[198:201], v169 offset:36864
	ds_read_b128 v[202:205], v169 offset:37888
	ds_read_b128 v[206:209], v169 offset:38912
	ds_read_b128 v[210:213], v169 offset:39936
	global_load_lds_dwordx4 v[144:145], off
	v_lshl_add_u64 v[144:145], s[30:31], 0, v[146:147]
	s_mov_b32 m0, s38
	s_nop 0
	global_load_lds_dwordx4 v[144:145], off
	s_waitcnt lgkmcnt(8)
	s_barrier
; #define STAGEA(P, br, kt) do { const char* _g = uptr(A + (size_t)(br) * lda + (size_t)(kt) * BK); \
;     _Pragma("unroll") for (int _i = 0; _i < 2; ++_i) { \
;       __builtin_amdgcn_global_load_lds((const unsigned*)(_g + offA[_i]), (unsigned*)((char*)(P) + tidx * 16 + _i * 8192), 16, 0, 0); } } while (0)
; #define STAGEB(P, br, kt) do { const char* _g = uptr(Bt + (size_t)(br) * ldb + (size_t)(kt) * BK); \
;     _Pragma("unroll") for (int _i = 0; _i < 2; ++_i) { \
;       __builtin_amdgcn_global_load_lds((const unsigned*)(_g + offB[_i]), (unsigned*)((char*)(P) + tidx * 16 + _i * 8192), 16, 0, 0); } } while (0)
; #define LDA(dst, b, h) _Pragma("unroll") for (int m = 0; m < 4; ++m) _Pragma("unroll") for (int k = 0; k < 2; ++k) \
;     dst[m][k] = *reinterpret_cast<const bf16x8*>((char*)SA(b, h) + aoff + m * 2048 + k * 1024)
; #define LDB(dst, b, h) _Pragma("unroll") for (int n = 0; n < 2; ++n) _Pragma("unroll") for (int k = 0; k < 2; ++k) \
;     dst[n][k] = *reinterpret_cast<const bf16x8*>((char*)SB(b, h) + boff + n * (SWAP ? 256 : 2048) + k * 1024)
; #define WAIT_V(n) asm volatile("s_waitcnt vmcnt(" #n ")" ::: "memory")
; #define WAIT_L(n) asm volatile("s_waitcnt lgkmcnt(" #n ")" ::: "memory")
; #define BAR __builtin_amdgcn_s_barrier()
; template <int EPI>
; DI void gemm_phase(const u16* __restrict__ A, int lda, const u16* __restrict__ Bt, int ldb,
;                    int M, int N, int K, const Epi& e, unsigned char* shmraw, int wv, int slot) {
;     ...
;       LDB(B0, 0, 0); SCHED; LDA(At, 0, 0); STAGEA(SA(1, 1), brow + HALF, t + 1);
;       WAIT_L(8); BAR; WAIT_L(0); MMA(0, 0, At, B0); BAR; SCHED;
;       LDB(B1, 0, 1); STAGEB(SB(0, 0), bcol, t + 2);
;       BAR; WAIT_L(0); MMA(0, 1, At, B1); BAR;
;       LDA(At, 0, 1); STAGEA(SA(0, 0), brow, t + 2);
;       BAR; WAIT_L(0); MMA(1, 0, At, B0); BAR; SCHED;
;       STAGEB(SB(0, 1), bcol + HALF, t + 2);
;       WAIT_V(6); BAR; MMA(1, 1, At, B1); BAR;
;       LDB(B0, 1, 0); SCHED; LDA(At, 1, 0); STAGEA(SA(0, 1), brow + HALF, t + 2);
;       WAIT_L(8); BAR; WAIT_L(0); MMA(0, 0, At, B0); BAR; SCHED;
;       LDB(B1, 1, 1); STAGEB(SB(1, 0), bcol, t + 3);
;       BAR; WAIT_L(0); MMA(0, 1, At, B1); BAR;
;       LDA(At, 1, 1); STAGEA(SA(1, 0), brow, t + 3);
;       BAR; WAIT_L(0); MMA(1, 0, At, B0); BAR; SCHED;
;       STAGEB(SB(1, 1), bcol + HALF, t + 3);
;       WAIT_V(6); BAR; MMA(1, 1, At, B1); BAR;
	s_waitcnt lgkmcnt(0)
	s_setprio 1
	v_mfma_f32_16x16x32_bf16 v[56:59], v[112:115], v[128:131], v[56:59]
	v_mfma_f32_16x16x32_bf16 v[60:63], v[116:119], v[128:131], v[60:63]
	v_mfma_f32_16x16x32_bf16 v[64:67], v[112:115], v[190:193], v[64:67]
	v_mfma_f32_16x16x32_bf16 v[68:71], v[116:119], v[190:193], v[68:71]
	v_mfma_f32_16x16x32_bf16 v[72:75], v[112:115], v[198:201], v[72:75]
	v_mfma_f32_16x16x32_bf16 v[76:79], v[116:119], v[198:201], v[76:79]
	v_mfma_f32_16x16x32_bf16 v[80:83], v[112:115], v[206:209], v[80:83]
	v_mfma_f32_16x16x32_bf16 v[84:87], v[116:119], v[206:209], v[84:87]
	v_mfma_f32_16x16x32_bf16 v[56:59], v[120:123], v[132:135], v[56:59]
	v_mfma_f32_16x16x32_bf16 v[60:63], v[124:127], v[132:135], v[60:63]
	v_mfma_f32_16x16x32_bf16 v[64:67], v[120:123], v[194:197], v[64:67]
	v_mfma_f32_16x16x32_bf16 v[68:71], v[124:127], v[194:197], v[68:71]
	v_mfma_f32_16x16x32_bf16 v[72:75], v[120:123], v[202:205], v[72:75]
	v_mfma_f32_16x16x32_bf16 v[76:79], v[124:127], v[202:205], v[76:79]
	v_mfma_f32_16x16x32_bf16 v[80:83], v[120:123], v[210:213], v[80:83]
	v_mfma_f32_16x16x32_bf16 v[84:87], v[124:127], v[210:213], v[84:87]
	s_setprio 0
	s_barrier
	s_add_u32 s30, s1, 0x280
	s_addc_u32 s31, s23, 0
	s_mov_b32 m0, s71
	v_lshl_add_u64 v[144:145], s[30:31], 0, v[148:149]
	ds_read_b128 v[214:217], v4
	ds_read_b128 v[218:221], v4 offset:256
	ds_read_b128 v[222:225], v4 offset:1024
	ds_read_b128 v[226:229], v4 offset:1280
	global_load_lds_dwordx4 v[144:145], off
	v_lshl_add_u64 v[144:145], s[30:31], 0, v[146:147]
	s_mov_b32 m0, s39
	s_nop 0
	global_load_lds_dwordx4 v[144:145], off
	s_barrier
	s_waitcnt lgkmcnt(0)
	s_setprio 1
	v_mfma_f32_16x16x32_bf16 v[104:107], v[214:217], v[128:131], v[104:107]
	v_mfma_f32_16x16x32_bf16 v[24:27], v[218:221], v[128:131], v[24:27]
	v_mfma_f32_16x16x32_bf16 v[32:35], v[218:221], v[190:193], v[32:35]
	v_mfma_f32_16x16x32_bf16 v[36:39], v[214:217], v[198:201], v[36:39]
	v_mfma_f32_16x16x32_bf16 v[40:43], v[218:221], v[198:201], v[40:43]
	v_mfma_f32_16x16x32_bf16 v[44:47], v[214:217], v[206:209], v[44:47]
	v_mfma_f32_16x16x32_bf16 v[48:51], v[218:221], v[206:209], v[48:51]
	v_mfma_f32_16x16x32_bf16 v[104:107], v[222:225], v[132:135], v[104:107]
	v_mfma_f32_16x16x32_bf16 v[24:27], v[226:229], v[132:135], v[24:27]
	v_mfma_f32_16x16x32_bf16 v[28:31], v[214:217], v[190:193], v[28:31]
	v_mfma_f32_16x16x32_bf16 v[32:35], v[226:229], v[194:197], v[32:35]
	v_mfma_f32_16x16x32_bf16 v[36:39], v[222:225], v[202:205], v[36:39]
	v_mfma_f32_16x16x32_bf16 v[40:43], v[226:229], v[202:205], v[40:43]
	v_mfma_f32_16x16x32_bf16 v[44:47], v[222:225], v[210:213], v[44:47]
	v_mfma_f32_16x16x32_bf16 v[48:51], v[226:229], v[210:213], v[48:51]
	v_mfma_f32_16x16x32_bf16 v[28:31], v[222:225], v[194:197], v[28:31]
	s_setprio 0
	s_add_u32 s30, s13, 0x280
	s_addc_u32 s31, s29, 0
	s_mov_b32 m0, s73
	v_lshl_add_u64 v[144:145], s[30:31], 0, v[148:149]
	s_barrier
	ds_read_b128 v[128:131], v169 offset:49152
	ds_read_b128 v[132:135], v169 offset:50176
	ds_read_b128 v[190:193], v169 offset:51200
	ds_read_b128 v[194:197], v169 offset:52224
	ds_read_b128 v[198:201], v169 offset:53248
	ds_read_b128 v[202:205], v169 offset:54272
	ds_read_b128 v[206:209], v169 offset:55296
	ds_read_b128 v[210:213], v169 offset:56320
	global_load_lds_dwordx4 v[144:145], off
	v_lshl_add_u64 v[144:145], s[30:31], 0, v[146:147]
	s_mov_b32 m0, s40
	s_nop 0
	global_load_lds_dwordx4 v[144:145], off
	s_barrier
	s_waitcnt lgkmcnt(0)
	s_setprio 1
	v_mfma_f32_16x16x32_bf16 v[136:139], v[112:115], v[128:131], v[136:139]
	v_mfma_f32_16x16x32_bf16 v[140:143], v[116:119], v[128:131], v[140:143]
	v_mfma_f32_16x16x32_bf16 v[8:11], v[112:115], v[206:209], v[8:11]
	v_mfma_f32_16x16x32_bf16 v[136:139], v[120:123], v[132:135], v[136:139]
	v_mfma_f32_16x16x32_bf16 v[140:143], v[124:127], v[132:135], v[140:143]
	v_mfma_f32_16x16x32_bf16 v[150:153], v[112:115], v[190:193], v[150:153]
	v_mfma_f32_16x16x32_bf16 v[170:173], v[116:119], v[190:193], v[170:173]
	v_mfma_f32_16x16x32_bf16 v[174:177], v[112:115], v[198:201], v[174:177]
	v_mfma_f32_16x16x32_bf16 v[182:185], v[116:119], v[198:201], v[182:185]
	v_mfma_f32_16x16x32_bf16 v[8:11], v[120:123], v[210:213], v[8:11]
	v_mfma_f32_16x16x32_bf16 v[12:15], v[116:119], v[206:209], v[12:15]
	v_mfma_f32_16x16x32_bf16 v[150:153], v[120:123], v[194:197], v[150:153]
	v_mfma_f32_16x16x32_bf16 v[170:173], v[124:127], v[194:197], v[170:173]
	v_mfma_f32_16x16x32_bf16 v[174:177], v[120:123], v[202:205], v[174:177]
	v_mfma_f32_16x16x32_bf16 v[182:185], v[124:127], v[202:205], v[182:185]
	v_mfma_f32_16x16x32_bf16 v[12:15], v[124:127], v[210:213], v[12:15]
	s_setprio 0
	s_barrier
	s_add_u32 s30, s1, 0x20280
	s_addc_u32 s31, s23, 0
	s_mov_b32 m0, s69
	v_lshl_add_u64 v[112:113], s[30:31], 0, v[148:149]
	global_load_lds_dwordx4 v[112:113], off
	v_lshl_add_u64 v[112:113], s[30:31], 0, v[146:147]
	s_mov_b32 m0, s43
	s_nop 0
	global_load_lds_dwordx4 v[112:113], off
	s_waitcnt vmcnt(6)
	s_barrier
	s_setprio 1
	v_mfma_f32_16x16x32_bf16 v[16:19], v[214:217], v[128:131], v[16:19]
	v_mfma_f32_16x16x32_bf16 v[20:23], v[218:221], v[128:131], v[20:23]
	v_mfma_f32_16x16x32_bf16 v[52:55], v[214:217], v[190:193], v[52:55]
	v_mfma_f32_16x16x32_bf16 v[96:99], v[218:221], v[190:193], v[96:99]
	v_mfma_f32_16x16x32_bf16 v[100:103], v[214:217], v[198:201], v[100:103]
	v_mfma_f32_16x16x32_bf16 v[108:111], v[218:221], v[198:201], v[108:111]
	v_mfma_f32_16x16x32_bf16 v[88:91], v[214:217], v[206:209], v[88:91]
	v_mfma_f32_16x16x32_bf16 v[92:95], v[218:221], v[206:209], v[92:95]
	v_mfma_f32_16x16x32_bf16 v[16:19], v[222:225], v[132:135], v[16:19]
	v_mfma_f32_16x16x32_bf16 v[20:23], v[226:229], v[132:135], v[20:23]
	v_mfma_f32_16x16x32_bf16 v[52:55], v[222:225], v[194:197], v[52:55]
	v_mfma_f32_16x16x32_bf16 v[96:99], v[226:229], v[194:197], v[96:99]
	v_mfma_f32_16x16x32_bf16 v[100:103], v[222:225], v[202:205], v[100:103]
	v_mfma_f32_16x16x32_bf16 v[108:111], v[226:229], v[202:205], v[108:111]
	v_mfma_f32_16x16x32_bf16 v[88:91], v[222:225], v[210:213], v[88:91]
	v_mfma_f32_16x16x32_bf16 v[92:95], v[226:229], v[210:213], v[92:95]
	s_setprio 0
	s_barrier
; #define STAGEA(P, br, kt) do { const char* _g = uptr(A + (size_t)(br) * lda + (size_t)(kt) * BK); \
;     _Pragma("unroll") for (int _i = 0; _i < 2; ++_i) { \
;       __builtin_amdgcn_global_load_lds((const unsigned*)(_g + offA[_i]), (unsigned*)((char*)(P) + tidx * 16 + _i * 8192), 16, 0, 0); } } while (0)
; #define STAGEB(P, br, kt) do { const char* _g = uptr(Bt + (size_t)(br) * ldb + (size_t)(kt) * BK); \
;     _Pragma("unroll") for (int _i = 0; _i < 2; ++_i) { \
;       __builtin_amdgcn_global_load_lds((const unsigned*)(_g + offB[_i]), (unsigned*)((char*)(P) + tidx * 16 + _i * 8192), 16, 0, 0); } } while (0)
; #define LDA(dst, b, h) _Pragma("unroll") for (int m = 0; m < 4; ++m) _Pragma("unroll") for (int k = 0; k < 2; ++k) \
;     dst[m][k] = *reinterpret_cast<const bf16x8*>((char*)SA(b, h) + aoff + m * 2048 + k * 1024)
; #define LDB(dst, b, h) _Pragma("unroll") for (int n = 0; n < 2; ++n) _Pragma("unroll") for (int k = 0; k < 2; ++k) \
;     dst[n][k] = *reinterpret_cast<const bf16x8*>((char*)SB(b, h) + boff + n * (SWAP ? 256 : 2048) + k * 1024)
; #define WAIT_V(n) asm volatile("s_waitcnt vmcnt(" #n ")" ::: "memory")
; #define WAIT_L(n) asm volatile("s_waitcnt lgkmcnt(" #n ")" ::: "memory")
; #define BAR __builtin_amdgcn_s_barrier()
; template <int EPI>
; DI void gemm_phase(const u16* __restrict__ A, int lda, const u16* __restrict__ Bt, int ldb,
;                    int M, int N, int K, const Epi& e, unsigned char* shmraw, int wv, int slot) {
;     ...
;       LDB(B0, 0, 0); SCHED; LDA(At, 0, 0); STAGEA(SA(1, 1), brow + HALF, t + 1);
;       WAIT_L(8); BAR; WAIT_L(0); MMA(0, 0, At, B0); BAR; SCHED;
;       LDB(B1, 0, 1); STAGEB(SB(0, 0), bcol, t + 2);
;       BAR; WAIT_L(0); MMA(0, 1, At, B1); BAR;
;       LDA(At, 0, 1); STAGEA(SA(0, 0), brow, t + 2);
;       BAR; WAIT_L(0); MMA(1, 0, At, B0); BAR; SCHED;
;       STAGEB(SB(0, 1), bcol + HALF, t + 2);
;       WAIT_V(6); BAR; MMA(1, 1, At, B1); BAR;
;       LDB(B0, 1, 0); SCHED; LDA(At, 1, 0); STAGEA(SA(0, 1), brow + HALF, t + 2);
;       WAIT_L(8); BAR; WAIT_L(0); MMA(0, 0, At, B0); BAR; SCHED;
;       LDB(B1, 1, 1); STAGEB(SB(1, 0), bcol, t + 3);
;       BAR; WAIT_L(0); MMA(0, 1, At, B1); BAR;
;       LDA(At, 1, 1); STAGEA(SA(1, 0), brow, t + 3);
;       BAR; WAIT_L(0); MMA(1, 0, At, B0); BAR; SCHED;
;       STAGEB(SB(1, 1), bcol + HALF, t + 3);
;       WAIT_V(6); BAR; MMA(1, 1, At, B1); BAR;
	ds_read_b128 v[112:115], v0
	ds_read_b128 v[116:119], v0 offset:256
	ds_read_b128 v[120:123], v0 offset:1024
	ds_read_b128 v[124:127], v0 offset:1280
	s_add_u32 s38, s15, 0x280
	s_addc_u32 s39, s22, 0
	v_readfirstlane_b32 s31, v5
	v_lshl_add_u64 v[144:145], s[38:39], 0, v[148:149]
	s_mov_b32 m0, s31
	v_readfirstlane_b32 s30, v6
	ds_read_b128 v[128:131], v169
	ds_read_b128 v[132:135], v169 offset:1024
	ds_read_b128 v[190:193], v169 offset:2048
	ds_read_b128 v[194:197], v169 offset:3072
	ds_read_b128 v[198:201], v169 offset:4096
	ds_read_b128 v[202:205], v169 offset:5120
	ds_read_b128 v[206:209], v169 offset:6144
	ds_read_b128 v[210:213], v169 offset:7168
	global_load_lds_dwordx4 v[144:145], off
	v_lshl_add_u64 v[144:145], s[38:39], 0, v[146:147]
	s_mov_b32 m0, s30
	s_nop 0
	global_load_lds_dwordx4 v[144:145], off
	s_waitcnt lgkmcnt(8)
	s_barrier
	s_waitcnt lgkmcnt(0)
	s_setprio 1
	v_mfma_f32_16x16x32_bf16 v[56:59], v[112:115], v[128:131], v[56:59]
	v_mfma_f32_16x16x32_bf16 v[60:63], v[116:119], v[128:131], v[60:63]
	v_mfma_f32_16x16x32_bf16 v[64:67], v[112:115], v[190:193], v[64:67]
	v_mfma_f32_16x16x32_bf16 v[68:71], v[116:119], v[190:193], v[68:71]
	v_mfma_f32_16x16x32_bf16 v[72:75], v[112:115], v[198:201], v[72:75]
	v_mfma_f32_16x16x32_bf16 v[76:79], v[116:119], v[198:201], v[76:79]
	v_mfma_f32_16x16x32_bf16 v[80:83], v[112:115], v[206:209], v[80:83]
	v_mfma_f32_16x16x32_bf16 v[84:87], v[116:119], v[206:209], v[84:87]
	v_mfma_f32_16x16x32_bf16 v[56:59], v[120:123], v[132:135], v[56:59]
	v_mfma_f32_16x16x32_bf16 v[60:63], v[124:127], v[132:135], v[60:63]
	v_mfma_f32_16x16x32_bf16 v[64:67], v[120:123], v[194:197], v[64:67]
	v_mfma_f32_16x16x32_bf16 v[68:71], v[124:127], v[194:197], v[68:71]
	v_mfma_f32_16x16x32_bf16 v[72:75], v[120:123], v[202:205], v[72:75]
	v_mfma_f32_16x16x32_bf16 v[76:79], v[124:127], v[202:205], v[76:79]
	v_mfma_f32_16x16x32_bf16 v[80:83], v[120:123], v[210:213], v[80:83]
	v_mfma_f32_16x16x32_bf16 v[84:87], v[124:127], v[210:213], v[84:87]
	s_setprio 0
	s_barrier
	s_add_u32 s38, s1, 0x300
	s_addc_u32 s39, s23, 0
	v_readfirstlane_b32 s35, v155
	v_lshl_add_u64 v[6:7], s[38:39], 0, v[148:149]
	s_mov_b32 m0, s35
	v_readfirstlane_b32 s35, v158
	ds_read_b128 v[214:217], v2
	ds_read_b128 v[218:221], v2 offset:256
	ds_read_b128 v[222:225], v2 offset:1024
	ds_read_b128 v[226:229], v2 offset:1280
	global_load_lds_dwordx4 v[6:7], off
	v_lshl_add_u64 v[6:7], s[38:39], 0, v[146:147]
	s_mov_b32 m0, s35
	s_nop 0
	global_load_lds_dwordx4 v[6:7], off
	s_barrier
	s_waitcnt lgkmcnt(0)
	s_setprio 1
	v_mfma_f32_16x16x32_bf16 v[104:107], v[214:217], v[128:131], v[104:107]
	v_mfma_f32_16x16x32_bf16 v[24:27], v[218:221], v[128:131], v[24:27]
	v_mfma_f32_16x16x32_bf16 v[32:35], v[218:221], v[190:193], v[32:35]
	v_mfma_f32_16x16x32_bf16 v[36:39], v[214:217], v[198:201], v[36:39]
	v_mfma_f32_16x16x32_bf16 v[40:43], v[218:221], v[198:201], v[40:43]
	v_mfma_f32_16x16x32_bf16 v[44:47], v[214:217], v[206:209], v[44:47]
	v_mfma_f32_16x16x32_bf16 v[48:51], v[218:221], v[206:209], v[48:51]
	v_mfma_f32_16x16x32_bf16 v[104:107], v[222:225], v[132:135], v[104:107]
	v_mfma_f32_16x16x32_bf16 v[24:27], v[226:229], v[132:135], v[24:27]
	v_mfma_f32_16x16x32_bf16 v[28:31], v[214:217], v[190:193], v[28:31]
	v_mfma_f32_16x16x32_bf16 v[32:35], v[226:229], v[194:197], v[32:35]
	v_mfma_f32_16x16x32_bf16 v[36:39], v[222:225], v[202:205], v[36:39]
	v_mfma_f32_16x16x32_bf16 v[40:43], v[226:229], v[202:205], v[40:43]
	v_mfma_f32_16x16x32_bf16 v[44:47], v[222:225], v[210:213], v[44:47]
	v_mfma_f32_16x16x32_bf16 v[48:51], v[226:229], v[210:213], v[48:51]
	v_mfma_f32_16x16x32_bf16 v[28:31], v[222:225], v[194:197], v[28:31]
	s_setprio 0
	s_add_u32 s38, s13, 0x300
	s_addc_u32 s39, s29, 0
	v_readfirstlane_b32 s35, v157
	v_lshl_add_u64 v[6:7], s[38:39], 0, v[148:149]
	s_mov_b32 m0, s35
	v_readfirstlane_b32 s35, v159
	s_barrier
	ds_read_b128 v[128:131], v169 offset:16384
	ds_read_b128 v[132:135], v169 offset:17408
	ds_read_b128 v[190:193], v169 offset:18432
	ds_read_b128 v[194:197], v169 offset:19456
	ds_read_b128 v[198:201], v169 offset:20480
	ds_read_b128 v[202:205], v169 offset:21504
	ds_read_b128 v[206:209], v169 offset:22528
	ds_read_b128 v[210:213], v169 offset:23552
	global_load_lds_dwordx4 v[6:7], off
	v_lshl_add_u64 v[6:7], s[38:39], 0, v[146:147]
	s_mov_b32 m0, s35
	s_nop 0
	global_load_lds_dwordx4 v[6:7], off
	s_barrier
	s_waitcnt lgkmcnt(0)
	s_setprio 1
	v_mfma_f32_16x16x32_bf16 v[136:139], v[112:115], v[128:131], v[136:139]
	v_mfma_f32_16x16x32_bf16 v[140:143], v[116:119], v[128:131], v[140:143]
	v_mfma_f32_16x16x32_bf16 v[6:9], v[112:115], v[206:209], v[8:11]
	v_mfma_f32_16x16x32_bf16 v[136:139], v[120:123], v[132:135], v[136:139]
	v_mfma_f32_16x16x32_bf16 v[140:143], v[124:127], v[132:135], v[140:143]
	v_mfma_f32_16x16x32_bf16 v[150:153], v[112:115], v[190:193], v[150:153]
	v_mfma_f32_16x16x32_bf16 v[170:173], v[116:119], v[190:193], v[170:173]
	v_mfma_f32_16x16x32_bf16 v[174:177], v[112:115], v[198:201], v[174:177]
	v_mfma_f32_16x16x32_bf16 v[182:185], v[116:119], v[198:201], v[182:185]
	v_mfma_f32_16x16x32_bf16 v[6:9], v[120:123], v[210:213], v[6:9]
	v_mfma_f32_16x16x32_bf16 v[10:13], v[116:119], v[206:209], v[12:15]
	v_mfma_f32_16x16x32_bf16 v[150:153], v[120:123], v[194:197], v[150:153]
	v_mfma_f32_16x16x32_bf16 v[170:173], v[124:127], v[194:197], v[170:173]
	v_mfma_f32_16x16x32_bf16 v[174:177], v[120:123], v[202:205], v[174:177]
	v_mfma_f32_16x16x32_bf16 v[182:185], v[124:127], v[202:205], v[182:185]
	v_mfma_f32_16x16x32_bf16 v[10:13], v[124:127], v[210:213], v[10:13]
	s_setprio 0
	s_barrier
; #define STAGEA(P, br, kt) do { const char* _g = uptr(A + (size_t)(br) * lda + (size_t)(kt) * BK); \
;     _Pragma("unroll") for (int _i = 0; _i < 2; ++_i) { \
;       __builtin_amdgcn_global_load_lds((const unsigned*)(_g + offA[_i]), (unsigned*)((char*)(P) + tidx * 16 + _i * 8192), 16, 0, 0); } } while (0)
; #define STAGEB(P, br, kt) do { const char* _g = uptr(Bt + (size_t)(br) * ldb + (size_t)(kt) * BK); \
;     _Pragma("unroll") for (int _i = 0; _i < 2; ++_i) { \
;       __builtin_amdgcn_global_load_lds((const unsigned*)(_g + offB[_i]), (unsigned*)((char*)(P) + tidx * 16 + _i * 8192), 16, 0, 0); } } while (0)
; #define LDA(dst, b, h) _Pragma("unroll") for (int m = 0; m < 4; ++m) _Pragma("unroll") for (int k = 0; k < 2; ++k) \
;     dst[m][k] = *reinterpret_cast<const bf16x8*>((char*)SA(b, h) + aoff + m * 2048 + k * 1024)
; #define LDB(dst, b, h) _Pragma("unroll") for (int n = 0; n < 2; ++n) _Pragma("unroll") for (int k = 0; k < 2; ++k) \
;     dst[n][k] = *reinterpret_cast<const bf16x8*>((char*)SB(b, h) + boff + n * (SWAP ? 256 : 2048) + k * 1024)
; #define WAIT_V(n) asm volatile("s_waitcnt vmcnt(" #n ")" ::: "memory")
; #define WAIT_L(n) asm volatile("s_waitcnt lgkmcnt(" #n ")" ::: "memory")
; #define BAR __builtin_amdgcn_s_barrier()
; template <int EPI>
; DI void gemm_phase(const u16* __restrict__ A, int lda, const u16* __restrict__ Bt, int ldb,
;                    int M, int N, int K, const Epi& e, unsigned char* shmraw, int wv, int slot) {
;     ...
;       LDB(B0, 0, 0); SCHED; LDA(At, 0, 0); STAGEA(SA(1, 1), brow + HALF, t + 1);
;       WAIT_L(8); BAR; WAIT_L(0); MMA(0, 0, At, B0); BAR; SCHED;
;       LDB(B1, 0, 1); STAGEB(SB(0, 0), bcol, t + 2);
;       BAR; WAIT_L(0); MMA(0, 1, At, B1); BAR;
;       LDA(At, 0, 1); STAGEA(SA(0, 0), brow, t + 2);
;       BAR; WAIT_L(0); MMA(1, 0, At, B0); BAR; SCHED;
;       STAGEB(SB(0, 1), bcol + HALF, t + 2);
;       WAIT_V(6); BAR; MMA(1, 1, At, B1); BAR;
;       LDB(B0, 1, 0); SCHED; LDA(At, 1, 0); STAGEA(SA(0, 1), brow + HALF, t + 2);
;       WAIT_L(8); BAR; WAIT_L(0); MMA(0, 0, At, B0); BAR; SCHED;
;       LDB(B1, 1, 1); STAGEB(SB(1, 0), bcol, t + 3);
;       BAR; WAIT_L(0); MMA(0, 1, At, B1); BAR;
;       LDA(At, 1, 1); STAGEA(SA(1, 0), brow, t + 3);
;       BAR; WAIT_L(0); MMA(1, 0, At, B0); BAR; SCHED;
;       STAGEB(SB(1, 1), bcol + HALF, t + 3);
;       WAIT_V(6); BAR; MMA(1, 1, At, B1); BAR;
	s_add_u32 s38, s1, 0x20300
	s_addc_u32 s39, s23, 0
	v_readfirstlane_b32 s35, v156
	v_lshl_add_u64 v[14:15], s[38:39], 0, v[148:149]
	s_mov_b32 m0, s35
	v_readfirstlane_b32 s35, v160
	global_load_lds_dwordx4 v[14:15], off
	v_lshl_add_u64 v[14:15], s[38:39], 0, v[146:147]
	s_mov_b32 m0, s35
	s_nop 0
	global_load_lds_dwordx4 v[14:15], off
	s_waitcnt vmcnt(6)
	s_barrier
	s_setprio 1
	v_mfma_f32_16x16x32_bf16 v[14:17], v[214:217], v[128:131], v[16:19]
	v_mfma_f32_16x16x32_bf16 v[18:21], v[218:221], v[128:131], v[20:23]
	v_mfma_f32_16x16x32_bf16 v[52:55], v[214:217], v[190:193], v[52:55]
	v_mfma_f32_16x16x32_bf16 v[96:99], v[218:221], v[190:193], v[96:99]
	v_mfma_f32_16x16x32_bf16 v[100:103], v[214:217], v[198:201], v[100:103]
	v_mfma_f32_16x16x32_bf16 v[108:111], v[218:221], v[198:201], v[108:111]
	v_mfma_f32_16x16x32_bf16 v[88:91], v[214:217], v[206:209], v[88:91]
	v_mfma_f32_16x16x32_bf16 v[92:95], v[218:221], v[206:209], v[92:95]
	v_mfma_f32_16x16x32_bf16 v[18:21], v[226:229], v[132:135], v[18:21]
	v_mfma_f32_16x16x32_bf16 v[52:55], v[222:225], v[194:197], v[52:55]
	v_mfma_f32_16x16x32_bf16 v[96:99], v[226:229], v[194:197], v[96:99]
	v_mfma_f32_16x16x32_bf16 v[100:103], v[222:225], v[202:205], v[100:103]
	v_mfma_f32_16x16x32_bf16 v[108:111], v[226:229], v[202:205], v[108:111]
	v_mfma_f32_16x16x32_bf16 v[88:91], v[222:225], v[210:213], v[88:91]
	v_mfma_f32_16x16x32_bf16 v[92:95], v[226:229], v[210:213], v[92:95]
	v_mfma_f32_16x16x32_bf16 v[14:17], v[222:225], v[132:135], v[14:17]
	s_setprio 0
	s_barrier
	ds_read_b128 v[112:115], v3
	ds_read_b128 v[116:119], v3 offset:256
	ds_read_b128 v[120:123], v3 offset:1024
	ds_read_b128 v[124:127], v3 offset:1280
	s_add_u32 s38, s15, 0x300
	s_addc_u32 s39, s22, 0
	v_readfirstlane_b32 s35, v161
	v_lshl_add_u64 v[22:23], s[38:39], 0, v[148:149]
	s_mov_b32 m0, s35
	v_readfirstlane_b32 s35, v162
	ds_read_b128 v[128:131], v169 offset:32768
	ds_read_b128 v[132:135], v169 offset:33792
	ds_read_b128 v[190:193], v169 offset:34816
	ds_read_b128 v[194:197], v169 offset:35840
	ds_read_b128 v[198:201], v169 offset:36864
	ds_read_b128 v[202:205], v169 offset:37888
	ds_read_b128 v[206:209], v169 offset:38912
	ds_read_b128 v[210:213], v169 offset:39936
	global_load_lds_dwordx4 v[22:23], off
	v_lshl_add_u64 v[22:23], s[38:39], 0, v[146:147]
	s_mov_b32 m0, s35
	s_nop 0
	global_load_lds_dwordx4 v[22:23], off
	s_waitcnt lgkmcnt(8)
	s_barrier
	s_waitcnt lgkmcnt(0)
	s_setprio 1
	v_mfma_f32_16x16x32_bf16 v[56:59], v[112:115], v[128:131], v[56:59]
	v_mfma_f32_16x16x32_bf16 v[60:63], v[116:119], v[128:131], v[60:63]
	v_mfma_f32_16x16x32_bf16 v[64:67], v[112:115], v[190:193], v[64:67]
	v_mfma_f32_16x16x32_bf16 v[68:71], v[116:119], v[190:193], v[68:71]
	v_mfma_f32_16x16x32_bf16 v[72:75], v[112:115], v[198:201], v[72:75]
	v_mfma_f32_16x16x32_bf16 v[76:79], v[116:119], v[198:201], v[76:79]
	v_mfma_f32_16x16x32_bf16 v[80:83], v[112:115], v[206:209], v[80:83]
	v_mfma_f32_16x16x32_bf16 v[84:87], v[116:119], v[206:209], v[84:87]
	v_mfma_f32_16x16x32_bf16 v[56:59], v[120:123], v[132:135], v[56:59]
	v_mfma_f32_16x16x32_bf16 v[60:63], v[124:127], v[132:135], v[60:63]
	v_mfma_f32_16x16x32_bf16 v[64:67], v[120:123], v[194:197], v[64:67]
	v_mfma_f32_16x16x32_bf16 v[68:71], v[124:127], v[194:197], v[68:71]
	v_mfma_f32_16x16x32_bf16 v[72:75], v[120:123], v[202:205], v[72:75]
	v_mfma_f32_16x16x32_bf16 v[76:79], v[124:127], v[202:205], v[76:79]
	v_mfma_f32_16x16x32_bf16 v[80:83], v[120:123], v[210:213], v[80:83]
	v_mfma_f32_16x16x32_bf16 v[84:87], v[124:127], v[210:213], v[84:87]
	s_setprio 0
	s_barrier
	s_add_u32 s38, s1, 0x380
	s_addc_u32 s39, s23, 0
	v_readfirstlane_b32 s35, v166
	v_lshl_add_u64 v[22:23], s[38:39], 0, v[148:149]
	s_mov_b32 m0, s35
	v_readfirstlane_b32 s35, v163
	ds_read_b128 v[214:217], v4
	ds_read_b128 v[218:221], v4 offset:256
	ds_read_b128 v[222:225], v4 offset:1024
	ds_read_b128 v[226:229], v4 offset:1280
	global_load_lds_dwordx4 v[22:23], off
	v_lshl_add_u64 v[22:23], s[38:39], 0, v[146:147]
	s_mov_b32 m0, s35
	s_nop 0
	global_load_lds_dwordx4 v[22:23], off
	s_barrier
	s_waitcnt lgkmcnt(0)
	s_setprio 1
	v_mfma_f32_16x16x32_bf16 v[104:107], v[214:217], v[128:131], v[104:107]
	v_mfma_f32_16x16x32_bf16 v[22:25], v[218:221], v[128:131], v[24:27]
	v_mfma_f32_16x16x32_bf16 v[26:29], v[214:217], v[190:193], v[28:31]
	v_mfma_f32_16x16x32_bf16 v[30:33], v[218:221], v[190:193], v[32:35]
	v_mfma_f32_16x16x32_bf16 v[34:37], v[214:217], v[198:201], v[36:39]
	v_mfma_f32_16x16x32_bf16 v[38:41], v[218:221], v[198:201], v[40:43]
	v_mfma_f32_16x16x32_bf16 v[42:45], v[214:217], v[206:209], v[44:47]
	v_mfma_f32_16x16x32_bf16 v[46:49], v[218:221], v[206:209], v[48:51]
	v_mfma_f32_16x16x32_bf16 v[104:107], v[222:225], v[132:135], v[104:107]
	v_mfma_f32_16x16x32_bf16 v[22:25], v[226:229], v[132:135], v[22:25]
	v_mfma_f32_16x16x32_bf16 v[34:37], v[222:225], v[202:205], v[34:37]
	v_mfma_f32_16x16x32_bf16 v[38:41], v[226:229], v[202:205], v[38:41]
	v_mfma_f32_16x16x32_bf16 v[42:45], v[222:225], v[210:213], v[42:45]
	v_mfma_f32_16x16x32_bf16 v[46:49], v[226:229], v[210:213], v[46:49]
	v_mfma_f32_16x16x32_bf16 v[26:29], v[222:225], v[194:197], v[26:29]
	v_mfma_f32_16x16x32_bf16 v[30:33], v[226:229], v[194:197], v[30:33]
	s_setprio 0
	s_add_u32 s38, s13, 0x380
	s_addc_u32 s39, s29, 0
	v_readfirstlane_b32 s13, v164
	v_lshl_add_u64 v[50:51], s[38:39], 0, v[148:149]
	s_mov_b32 m0, s13
	v_readfirstlane_b32 s13, v165
	s_barrier
; #define STAGEA(P, br, kt) do { const char* _g = uptr(A + (size_t)(br) * lda + (size_t)(kt) * BK); \
;     _Pragma("unroll") for (int _i = 0; _i < 2; ++_i) { \
;       __builtin_amdgcn_global_load_lds((const unsigned*)(_g + offA[_i]), (unsigned*)((char*)(P) + tidx * 16 + _i * 8192), 16, 0, 0); } } while (0)
; #define STAGEB(P, br, kt) do { const char* _g = uptr(Bt + (size_t)(br) * ldb + (size_t)(kt) * BK); \
;     _Pragma("unroll") for (int _i = 0; _i < 2; ++_i) { \
;       __builtin_amdgcn_global_load_lds((const unsigned*)(_g + offB[_i]), (unsigned*)((char*)(P) + tidx * 16 + _i * 8192), 16, 0, 0); } } while (0)
; #define LDA(dst, b, h) _Pragma("unroll") for (int m = 0; m < 4; ++m) _Pragma("unroll") for (int k = 0; k < 2; ++k) \
;     dst[m][k] = *reinterpret_cast<const bf16x8*>((char*)SA(b, h) + aoff + m * 2048 + k * 1024)
; #define LDB(dst, b, h) _Pragma("unroll") for (int n = 0; n < 2; ++n) _Pragma("unroll") for (int k = 0; k < 2; ++k) \
;     dst[n][k] = *reinterpret_cast<const bf16x8*>((char*)SB(b, h) + boff + n * (SWAP ? 256 : 2048) + k * 1024)
; #define WAIT_V(n) asm volatile("s_waitcnt vmcnt(" #n ")" ::: "memory")
; #define WAIT_L(n) asm volatile("s_waitcnt lgkmcnt(" #n ")" ::: "memory")
; #define BAR __builtin_amdgcn_s_barrier()
; #define SCHED __builtin_amdgcn_sched_barrier(0)
; template <int EPI>
; DI void gemm_phase(const u16* __restrict__ A, int lda, const u16* __restrict__ Bt, int ldb,
;                    int M, int N, int K, const Epi& e, unsigned char* shmraw, int wv, int slot) {
;     ...
;       BAR; WAIT_L(0); MMA(0, 1, At, B1); BAR;
;       LDA(At, 1, 1); STAGEA(SA(1, 0), brow, t + 3);
;       BAR; WAIT_L(0); MMA(1, 0, At, B0); BAR; SCHED;
;       STAGEB(SB(1, 1), bcol + HALF, t + 3);
;       WAIT_V(6); BAR; MMA(1, 1, At, B1); BAR;
;     }
;     { LDB(B0, 0, 0); LDA(At, 0, 0); STAGEA(SA(1, 1), brow + HALF, nt - 1);
;       BAR; WAIT_L(0); MMA(0, 0, At, B0); BAR;
;       LDB(B1, 0, 1); BAR; WAIT_L(0); MMA(0, 1, At, B1); BAR;
	ds_read_b128 v[128:131], v169 offset:49152
	ds_read_b128 v[132:135], v169 offset:50176
	ds_read_b128 v[190:193], v169 offset:51200
	ds_read_b128 v[194:197], v169 offset:52224
	ds_read_b128 v[198:201], v169 offset:53248
	ds_read_b128 v[202:205], v169 offset:54272
	ds_read_b128 v[206:209], v169 offset:55296
	ds_read_b128 v[210:213], v169 offset:56320
	global_load_lds_dwordx4 v[50:51], off
	v_lshl_add_u64 v[50:51], s[38:39], 0, v[146:147]
	s_mov_b32 m0, s13
	s_nop 0
	global_load_lds_dwordx4 v[50:51], off
	s_barrier
	s_waitcnt lgkmcnt(0)
	s_setprio 1
	v_mfma_f32_16x16x32_bf16 v[136:139], v[112:115], v[128:131], v[136:139]
	v_mfma_f32_16x16x32_bf16 v[140:143], v[116:119], v[128:131], v[140:143]
	v_mfma_f32_16x16x32_bf16 v[6:9], v[112:115], v[206:209], v[6:9]
	v_mfma_f32_16x16x32_bf16 v[136:139], v[120:123], v[132:135], v[136:139]
	v_mfma_f32_16x16x32_bf16 v[140:143], v[124:127], v[132:135], v[140:143]
	v_mfma_f32_16x16x32_bf16 v[150:153], v[112:115], v[190:193], v[150:153]
	v_mfma_f32_16x16x32_bf16 v[170:173], v[116:119], v[190:193], v[170:173]
	v_mfma_f32_16x16x32_bf16 v[174:177], v[112:115], v[198:201], v[174:177]
	v_mfma_f32_16x16x32_bf16 v[182:185], v[116:119], v[198:201], v[182:185]
	v_mfma_f32_16x16x32_bf16 v[6:9], v[120:123], v[210:213], v[6:9]
	v_mfma_f32_16x16x32_bf16 v[10:13], v[116:119], v[206:209], v[10:13]
	v_mfma_f32_16x16x32_bf16 v[150:153], v[120:123], v[194:197], v[150:153]
	v_mfma_f32_16x16x32_bf16 v[170:173], v[124:127], v[194:197], v[170:173]
	v_mfma_f32_16x16x32_bf16 v[174:177], v[120:123], v[202:205], v[174:177]
	v_mfma_f32_16x16x32_bf16 v[182:185], v[124:127], v[202:205], v[182:185]
	v_mfma_f32_16x16x32_bf16 v[10:13], v[124:127], v[210:213], v[10:13]
	s_setprio 0
	s_barrier
	s_add_u32 s38, s1, 0x20380
	s_addc_u32 s39, s23, 0
	v_readfirstlane_b32 s1, v167
	v_lshl_add_u64 v[50:51], s[38:39], 0, v[148:149]
	s_mov_b32 m0, s1
	v_readfirstlane_b32 s1, v168
	global_load_lds_dwordx4 v[50:51], off
	v_lshl_add_u64 v[50:51], s[38:39], 0, v[146:147]
	s_mov_b32 m0, s1
	s_nop 0
	global_load_lds_dwordx4 v[50:51], off
	s_waitcnt vmcnt(6)
	s_barrier
	s_setprio 1
	v_mfma_f32_16x16x32_bf16 v[18:21], v[218:221], v[128:131], v[18:21]
	v_mfma_f32_16x16x32_bf16 v[50:53], v[214:217], v[190:193], v[52:55]
	v_mfma_f32_16x16x32_bf16 v[96:99], v[218:221], v[190:193], v[96:99]
	v_mfma_f32_16x16x32_bf16 v[100:103], v[214:217], v[198:201], v[100:103]
	v_mfma_f32_16x16x32_bf16 v[108:111], v[218:221], v[198:201], v[108:111]
	v_mfma_f32_16x16x32_bf16 v[88:91], v[214:217], v[206:209], v[88:91]
	v_mfma_f32_16x16x32_bf16 v[92:95], v[218:221], v[206:209], v[92:95]
	v_mfma_f32_16x16x32_bf16 v[14:17], v[214:217], v[128:131], v[14:17]
	v_mfma_f32_16x16x32_bf16 v[18:21], v[226:229], v[132:135], v[18:21]
	v_mfma_f32_16x16x32_bf16 v[50:53], v[222:225], v[194:197], v[50:53]
	v_mfma_f32_16x16x32_bf16 v[96:99], v[226:229], v[194:197], v[96:99]
	v_mfma_f32_16x16x32_bf16 v[100:103], v[222:225], v[202:205], v[100:103]
	v_mfma_f32_16x16x32_bf16 v[108:111], v[226:229], v[202:205], v[108:111]
	v_mfma_f32_16x16x32_bf16 v[88:91], v[222:225], v[210:213], v[88:91]
	v_mfma_f32_16x16x32_bf16 v[92:95], v[226:229], v[210:213], v[92:95]
	v_mfma_f32_16x16x32_bf16 v[14:17], v[222:225], v[132:135], v[14:17]
	s_setprio 0
	s_add_u32 s38, s15, 0x380
	s_addc_u32 s39, s22, 0
	s_mov_b32 m0, s31
	v_lshl_add_u64 v[54:55], s[38:39], 0, v[148:149]
	s_barrier
	ds_read_b128 v[112:115], v0
	ds_read_b128 v[116:119], v0 offset:256
	ds_read_b128 v[120:123], v0 offset:1024
	ds_read_b128 v[124:127], v0 offset:1280
	ds_read_b128 v[128:131], v169
	ds_read_b128 v[132:135], v169 offset:1024
	ds_read_b128 v[190:193], v169 offset:2048
	ds_read_b128 v[194:197], v169 offset:3072
	ds_read_b128 v[198:201], v169 offset:4096
	ds_read_b128 v[202:205], v169 offset:5120
	ds_read_b128 v[206:209], v169 offset:6144
	ds_read_b128 v[210:213], v169 offset:7168
	global_load_lds_dwordx4 v[54:55], off
	v_lshl_add_u64 v[54:55], s[38:39], 0, v[146:147]
	s_mov_b32 m0, s30
	s_nop 0
	global_load_lds_dwordx4 v[54:55], off
	s_barrier
	s_waitcnt lgkmcnt(0)
	s_setprio 1
	v_mfma_f32_16x16x32_bf16 v[54:57], v[112:115], v[128:131], v[56:59]
	v_mfma_f32_16x16x32_bf16 v[58:61], v[116:119], v[128:131], v[60:63]
	v_mfma_f32_16x16x32_bf16 v[62:65], v[112:115], v[190:193], v[64:67]
	v_mfma_f32_16x16x32_bf16 v[66:69], v[116:119], v[190:193], v[68:71]
	v_mfma_f32_16x16x32_bf16 v[70:73], v[112:115], v[198:201], v[72:75]
	v_mfma_f32_16x16x32_bf16 v[74:77], v[116:119], v[198:201], v[76:79]
	v_mfma_f32_16x16x32_bf16 v[78:81], v[112:115], v[206:209], v[80:83]
	v_mfma_f32_16x16x32_bf16 v[82:85], v[116:119], v[206:209], v[84:87]
	v_mfma_f32_16x16x32_bf16 v[54:57], v[120:123], v[132:135], v[54:57]
	v_mfma_f32_16x16x32_bf16 v[58:61], v[124:127], v[132:135], v[58:61]
	v_mfma_f32_16x16x32_bf16 v[62:65], v[120:123], v[194:197], v[62:65]
	v_mfma_f32_16x16x32_bf16 v[66:69], v[124:127], v[194:197], v[66:69]
	v_mfma_f32_16x16x32_bf16 v[70:73], v[120:123], v[202:205], v[70:73]
	v_mfma_f32_16x16x32_bf16 v[74:77], v[124:127], v[202:205], v[74:77]
	v_mfma_f32_16x16x32_bf16 v[78:81], v[120:123], v[210:213], v[78:81]
	v_mfma_f32_16x16x32_bf16 v[82:85], v[124:127], v[210:213], v[82:85]
	s_setprio 0
	s_barrier
	ds_read_b128 v[214:217], v2
	ds_read_b128 v[218:221], v2 offset:256
	ds_read_b128 v[222:225], v2 offset:1024
	ds_read_b128 v[226:229], v2 offset:1280
	s_barrier
; #define LDA(dst, b, h) _Pragma("unroll") for (int m = 0; m < 4; ++m) _Pragma("unroll") for (int k = 0; k < 2; ++k) \
;     dst[m][k] = *reinterpret_cast<const bf16x8*>((char*)SA(b, h) + aoff + m * 2048 + k * 1024)
; #define LDB(dst, b, h) _Pragma("unroll") for (int n = 0; n < 2; ++n) _Pragma("unroll") for (int k = 0; k < 2; ++k) \
;     dst[n][k] = *reinterpret_cast<const bf16x8*>((char*)SB(b, h) + boff + n * (SWAP ? 256 : 2048) + k * 1024)
; #define WAIT_V(n) asm volatile("s_waitcnt vmcnt(" #n ")" ::: "memory")
; #define WAIT_L(n) asm volatile("s_waitcnt lgkmcnt(" #n ")" ::: "memory")
; #define BAR __builtin_amdgcn_s_barrier()
; template <int EPI>
; DI void gemm_phase(const u16* __restrict__ A, int lda, const u16* __restrict__ Bt, int ldb,
;                    int M, int N, int K, const Epi& e, unsigned char* shmraw, int wv, int slot) {
;     ...
;       LDB(B1, 0, 1); BAR; WAIT_L(0); MMA(0, 1, At, B1); BAR;
;       LDA(At, 0, 1); WAIT_V(4); BAR; WAIT_L(0); MMA(1, 0, At, B0); MMA(1, 1, At, B1); BAR; }
;     { LDB(B0, 1, 0); LDA(At, 1, 0); WAIT_V(2); BAR; WAIT_L(0); MMA(0, 0, At, B0); BAR;
	s_waitcnt lgkmcnt(0)
	s_setprio 1
	v_mfma_f32_16x16x32_bf16 v[22:25], v[218:221], v[128:131], v[22:25]
	v_mfma_f32_16x16x32_bf16 v[34:37], v[214:217], v[198:201], v[34:37]
	v_mfma_f32_16x16x32_bf16 v[38:41], v[218:221], v[198:201], v[38:41]
	v_mfma_f32_16x16x32_bf16 v[42:45], v[214:217], v[206:209], v[42:45]
	v_mfma_f32_16x16x32_bf16 v[46:49], v[218:221], v[206:209], v[46:49]
	v_mfma_f32_16x16x32_bf16 v[104:107], v[214:217], v[128:131], v[104:107]
	v_mfma_f32_16x16x32_bf16 v[22:25], v[226:229], v[132:135], v[22:25]
	v_mfma_f32_16x16x32_bf16 v[26:29], v[214:217], v[190:193], v[26:29]
	v_mfma_f32_16x16x32_bf16 v[30:33], v[218:221], v[190:193], v[30:33]
	v_mfma_f32_16x16x32_bf16 v[34:37], v[222:225], v[202:205], v[34:37]
	v_mfma_f32_16x16x32_bf16 v[38:41], v[226:229], v[202:205], v[38:41]
	v_mfma_f32_16x16x32_bf16 v[42:45], v[222:225], v[210:213], v[42:45]
	v_mfma_f32_16x16x32_bf16 v[46:49], v[226:229], v[210:213], v[46:49]
	v_mfma_f32_16x16x32_bf16 v[230:233], v[222:225], v[132:135], v[104:107]
	v_mfma_f32_16x16x32_bf16 v[26:29], v[222:225], v[194:197], v[26:29]
	v_mfma_f32_16x16x32_bf16 v[30:33], v[226:229], v[194:197], v[30:33]
	s_setprio 0
	s_barrier
	ds_read_b128 v[104:107], v169 offset:16384
	ds_read_b128 v[128:131], v169 offset:17408
	ds_read_b128 v[132:135], v169 offset:18432
	ds_read_b128 v[190:193], v169 offset:19456
	ds_read_b128 v[194:197], v169 offset:20480
	ds_read_b128 v[198:201], v169 offset:21504
	ds_read_b128 v[202:205], v169 offset:22528
	ds_read_b128 v[206:209], v169 offset:23552
	s_waitcnt vmcnt(4)
	s_barrier
	s_waitcnt lgkmcnt(0)
	s_setprio 1
	v_mfma_f32_16x16x32_bf16 v[136:139], v[112:115], v[104:107], v[136:139]
	v_mfma_f32_16x16x32_bf16 v[210:213], v[120:123], v[128:131], v[136:139]
	v_mfma_f32_16x16x32_bf16 v[136:139], v[116:119], v[104:107], v[140:143]
	v_mfma_f32_16x16x32_bf16 v[234:237], v[124:127], v[128:131], v[136:139]
	v_mfma_f32_16x16x32_bf16 v[136:139], v[112:115], v[132:135], v[150:153]
	v_mfma_f32_16x16x32_bf16 v[150:153], v[120:123], v[190:193], v[136:139]
	v_mfma_f32_16x16x32_bf16 v[136:139], v[116:119], v[132:135], v[170:173]
	v_mfma_f32_16x16x32_bf16 v[170:173], v[124:127], v[190:193], v[136:139]
	v_mfma_f32_16x16x32_bf16 v[136:139], v[112:115], v[194:197], v[174:177]
	v_mfma_f32_16x16x32_bf16 v[6:9], v[112:115], v[202:205], v[6:9]
	v_mfma_f32_16x16x32_bf16 v[174:177], v[120:123], v[198:201], v[136:139]
	v_mfma_f32_16x16x32_bf16 v[136:139], v[116:119], v[194:197], v[182:185]
	v_mfma_f32_16x16x32_bf16 v[6:9], v[120:123], v[206:209], v[6:9]
	v_mfma_f32_16x16x32_bf16 v[10:13], v[116:119], v[202:205], v[10:13]
	v_mfma_f32_16x16x32_bf16 v[182:185], v[124:127], v[198:201], v[136:139]
	v_mfma_f32_16x16x32_bf16 v[10:13], v[124:127], v[206:209], v[10:13]
	s_setprio 0
	s_setprio 1
	v_mfma_f32_16x16x32_bf16 v[18:21], v[218:221], v[104:107], v[18:21]
	v_mfma_f32_16x16x32_bf16 v[238:241], v[226:229], v[128:131], v[18:21]
	v_mfma_f32_16x16x32_bf16 v[18:21], v[214:217], v[132:135], v[50:53]
	v_mfma_f32_16x16x32_bf16 v[50:53], v[222:225], v[190:193], v[18:21]
	v_mfma_f32_16x16x32_bf16 v[18:21], v[218:221], v[132:135], v[96:99]
	v_mfma_f32_16x16x32_bf16 v[190:193], v[226:229], v[190:193], v[18:21]
	v_mfma_f32_16x16x32_bf16 v[18:21], v[214:217], v[194:197], v[100:103]
	v_mfma_f32_16x16x32_bf16 v[242:245], v[222:225], v[198:201], v[18:21]
	v_mfma_f32_16x16x32_bf16 v[18:21], v[218:221], v[194:197], v[108:111]
	v_mfma_f32_16x16x32_bf16 v[194:197], v[226:229], v[198:201], v[18:21]
	v_mfma_f32_16x16x32_bf16 v[18:21], v[214:217], v[202:205], v[88:91]
	v_mfma_f32_16x16x32_bf16 v[14:17], v[214:217], v[104:107], v[14:17]
	v_mfma_f32_16x16x32_bf16 v[198:201], v[222:225], v[206:209], v[18:21]
	v_mfma_f32_16x16x32_bf16 v[18:21], v[218:221], v[202:205], v[92:95]
	v_mfma_f32_16x16x32_bf16 v[14:17], v[222:225], v[128:131], v[14:17]
	v_mfma_f32_16x16x32_bf16 v[202:205], v[226:229], v[206:209], v[18:21]
	s_setprio 0
	s_barrier
	s_nop 3
	ds_read_b128 v[18:21], v3
	ds_read_b128 v[206:209], v3 offset:256
	ds_read_b128 v[214:217], v3 offset:1024
	ds_read_b128 v[218:221], v3 offset:1280
	ds_read_b128 v[86:89], v169 offset:32768
	ds_read_b128 v[98:101], v169 offset:33792
	ds_read_b128 v[102:105], v169 offset:34816
	ds_read_b128 v[114:117], v169 offset:35840
	ds_read_b128 v[222:225], v169 offset:36864
	ds_read_b128 v[226:229], v169 offset:37888
	ds_read_b128 v[246:249], v169 offset:38912
	ds_read_b128 v[186:189], v169 offset:39936
	s_waitcnt vmcnt(2)
	s_barrier
; #define LDA(dst, b, h) _Pragma("unroll") for (int m = 0; m < 4; ++m) _Pragma("unroll") for (int k = 0; k < 2; ++k) \
;     dst[m][k] = *reinterpret_cast<const bf16x8*>((char*)SA(b, h) + aoff + m * 2048 + k * 1024)
; #define LDB(dst, b, h) _Pragma("unroll") for (int n = 0; n < 2; ++n) _Pragma("unroll") for (int k = 0; k < 2; ++k) \
;     dst[n][k] = *reinterpret_cast<const bf16x8*>((char*)SB(b, h) + boff + n * (SWAP ? 256 : 2048) + k * 1024)
; #define WAIT_V(n) asm volatile("s_waitcnt vmcnt(" #n ")" ::: "memory")
; #define WAIT_L(n) asm volatile("s_waitcnt lgkmcnt(" #n ")" ::: "memory")
; #define BAR __builtin_amdgcn_s_barrier()
; template <int EPI>
; DI void gemm_phase(const u16* __restrict__ A, int lda, const u16* __restrict__ Bt, int ldb,
;                    int M, int N, int K, const Epi& e, unsigned char* shmraw, int wv, int slot) {
;     ...
;     { LDB(B0, 1, 0); LDA(At, 1, 0); WAIT_V(2); BAR; WAIT_L(0); MMA(0, 0, At, B0); BAR;
;       LDB(B1, 1, 1); WAIT_V(0); BAR; WAIT_L(0); MMA(0, 1, At, B1); BAR;
;       LDA(At, 1, 1); BAR; WAIT_L(0); MMA(1, 0, At, B0); MMA(1, 1, At, B1); BAR; }
;     if (wr == 0) BAR;
	s_waitcnt lgkmcnt(0)
	s_setprio 1
	v_mfma_f32_16x16x32_bf16 v[54:57], v[18:21], v[86:89], v[54:57]
	v_mfma_f32_16x16x32_bf16 v[142:145], v[214:217], v[98:101], v[54:57]
	v_mfma_f32_16x16x32_bf16 v[54:57], v[206:209], v[86:89], v[58:61]
	v_mfma_f32_16x16x32_bf16 v[138:141], v[218:221], v[98:101], v[54:57]
	v_mfma_f32_16x16x32_bf16 v[54:57], v[18:21], v[102:105], v[62:65]
	v_mfma_f32_16x16x32_bf16 v[126:129], v[214:217], v[114:117], v[54:57]
	v_mfma_f32_16x16x32_bf16 v[54:57], v[206:209], v[102:105], v[66:69]
	v_mfma_f32_16x16x32_bf16 v[122:125], v[218:221], v[114:117], v[54:57]
	v_mfma_f32_16x16x32_bf16 v[54:57], v[18:21], v[222:225], v[70:73]
	v_mfma_f32_16x16x32_bf16 v[110:113], v[214:217], v[226:229], v[54:57]
	v_mfma_f32_16x16x32_bf16 v[54:57], v[206:209], v[222:225], v[74:77]
	v_mfma_f32_16x16x32_bf16 v[106:109], v[218:221], v[226:229], v[54:57]
	v_mfma_f32_16x16x32_bf16 v[54:57], v[18:21], v[246:249], v[78:81]
	v_mfma_f32_16x16x32_bf16 v[94:97], v[214:217], v[186:189], v[54:57]
	v_mfma_f32_16x16x32_bf16 v[54:57], v[206:209], v[246:249], v[82:85]
	v_mfma_f32_16x16x32_bf16 v[90:93], v[218:221], v[186:189], v[54:57]
	s_setprio 0
	s_barrier
	ds_read_b128 v[178:181], v4
	ds_read_b128 v[158:161], v4 offset:256
	ds_read_b128 v[162:165], v4 offset:1024
	ds_read_b128 v[2:5], v4 offset:1280
	s_waitcnt vmcnt(0)
	s_barrier
	s_waitcnt lgkmcnt(0)
	s_setprio 1
	v_mfma_f32_16x16x32_bf16 v[22:25], v[158:161], v[86:89], v[22:25]
	v_mfma_f32_16x16x32_bf16 v[130:133], v[2:5], v[98:101], v[22:25]
	v_mfma_f32_16x16x32_bf16 v[22:25], v[178:181], v[102:105], v[26:29]
	v_mfma_f32_16x16x32_bf16 v[118:121], v[162:165], v[114:117], v[22:25]
	v_mfma_f32_16x16x32_bf16 v[22:25], v[158:161], v[102:105], v[30:33]
	v_mfma_f32_16x16x32_bf16 v[114:117], v[2:5], v[114:117], v[22:25]
	v_mfma_f32_16x16x32_bf16 v[22:25], v[178:181], v[222:225], v[34:37]
	v_mfma_f32_16x16x32_bf16 v[54:57], v[178:181], v[86:89], v[230:233]
	v_mfma_f32_16x16x32_bf16 v[102:105], v[162:165], v[226:229], v[22:25]
	v_mfma_f32_16x16x32_bf16 v[22:25], v[158:161], v[222:225], v[38:41]
	v_mfma_f32_16x16x32_bf16 v[134:137], v[162:165], v[98:101], v[54:57]
	v_mfma_f32_16x16x32_bf16 v[98:101], v[2:5], v[226:229], v[22:25]
	v_mfma_f32_16x16x32_bf16 v[22:25], v[178:181], v[246:249], v[42:45]
	v_mfma_f32_16x16x32_bf16 v[86:89], v[162:165], v[186:189], v[22:25]
	v_mfma_f32_16x16x32_bf16 v[22:25], v[158:161], v[246:249], v[46:49]
	v_mfma_f32_16x16x32_bf16 v[82:85], v[2:5], v[186:189], v[22:25]
	s_setprio 0
	s_barrier
	ds_read_b128 v[26:29], v169 offset:49152
	ds_read_b128 v[30:33], v169 offset:50176
	ds_read_b128 v[34:37], v169 offset:51200
	ds_read_b128 v[38:41], v169 offset:52224
	ds_read_b128 v[186:189], v169 offset:53248
	ds_read_b128 v[222:225], v169 offset:54272
	ds_read_b128 v[226:229], v169 offset:55296
	ds_read_b128 v[230:233], v169 offset:56320
	s_barrier
	s_waitcnt lgkmcnt(0)
	s_setprio 1
	v_mfma_f32_16x16x32_bf16 v[22:25], v[18:21], v[26:29], v[210:213]
	v_mfma_f32_16x16x32_bf16 v[78:81], v[214:217], v[30:33], v[22:25]
	v_mfma_f32_16x16x32_bf16 v[22:25], v[206:209], v[26:29], v[234:237]
	v_mfma_f32_16x16x32_bf16 v[74:77], v[218:221], v[30:33], v[22:25]
	v_mfma_f32_16x16x32_bf16 v[22:25], v[18:21], v[34:37], v[150:153]
	v_mfma_f32_16x16x32_bf16 v[62:65], v[214:217], v[38:41], v[22:25]
	v_mfma_f32_16x16x32_bf16 v[22:25], v[206:209], v[34:37], v[170:173]
	v_mfma_f32_16x16x32_bf16 v[58:61], v[218:221], v[38:41], v[22:25]
	v_mfma_f32_16x16x32_bf16 v[22:25], v[18:21], v[186:189], v[174:177]
	v_mfma_f32_16x16x32_bf16 v[46:49], v[214:217], v[222:225], v[22:25]
	v_mfma_f32_16x16x32_bf16 v[22:25], v[206:209], v[186:189], v[182:185]
	v_mfma_f32_16x16x32_bf16 v[6:9], v[18:21], v[226:229], v[6:9]
	v_mfma_f32_16x16x32_bf16 v[42:45], v[218:221], v[222:225], v[22:25]
	v_mfma_f32_16x16x32_bf16 v[22:25], v[214:217], v[230:233], v[6:9]
	v_mfma_f32_16x16x32_bf16 v[6:9], v[206:209], v[226:229], v[10:13]
	v_mfma_f32_16x16x32_bf16 v[18:21], v[218:221], v[230:233], v[6:9]
	s_setprio 0
	s_setprio 1
	v_mfma_f32_16x16x32_bf16 v[6:9], v[178:181], v[26:29], v[14:17]
	v_mfma_f32_16x16x32_bf16 v[70:73], v[162:165], v[30:33], v[6:9]
	v_mfma_f32_16x16x32_bf16 v[6:9], v[158:161], v[26:29], v[238:241]
	v_mfma_f32_16x16x32_bf16 v[66:69], v[2:5], v[30:33], v[6:9]
	v_mfma_f32_16x16x32_bf16 v[6:9], v[178:181], v[34:37], v[50:53]
	v_mfma_f32_16x16x32_bf16 v[54:57], v[162:165], v[38:41], v[6:9]
	v_mfma_f32_16x16x32_bf16 v[6:9], v[158:161], v[34:37], v[190:193]
	v_mfma_f32_16x16x32_bf16 v[50:53], v[2:5], v[38:41], v[6:9]
	v_mfma_f32_16x16x32_bf16 v[6:9], v[178:181], v[186:189], v[242:245]
	v_mfma_f32_16x16x32_bf16 v[38:41], v[162:165], v[222:225], v[6:9]
	v_mfma_f32_16x16x32_bf16 v[6:9], v[158:161], v[186:189], v[194:197]
	v_mfma_f32_16x16x32_bf16 v[34:37], v[2:5], v[222:225], v[6:9]
	v_mfma_f32_16x16x32_bf16 v[6:9], v[178:181], v[226:229], v[198:201]
	v_mfma_f32_16x16x32_bf16 v[10:13], v[158:161], v[226:229], v[202:205]
	v_mfma_f32_16x16x32_bf16 v[6:9], v[162:165], v[230:233], v[6:9]
	v_mfma_f32_16x16x32_bf16 v[2:5], v[2:5], v[230:233], v[10:13]
	s_setprio 0
	s_barrier
	s_and_saveexec_b64 s[22:23], s[4:5]
	s_cbranch_execz .LBB0_945
	s_barrier

; #define STAGEA(P, br, kt) do { const char* _g = uptr(A + (size_t)(br) * lda + (size_t)(kt) * BK); \
;     _Pragma("unroll") for (int _i = 0; _i < 2; ++_i) { \
;       __builtin_amdgcn_global_load_lds((const unsigned*)(_g + offA[_i]), (unsigned*)((char*)(P) + tidx * 16 + _i * 8192), 16, 0, 0); } } while (0)
; #define STAGEB(P, br, kt) do { const char* _g = uptr(Bt + (size_t)(br) * ldb + (size_t)(kt) * BK); \
;     _Pragma("unroll") for (int _i = 0; _i < 2; ++_i) { \
;       __builtin_amdgcn_global_load_lds((const unsigned*)(_g + offB[_i]), (unsigned*)((char*)(P) + tidx * 16 + _i * 8192), 16, 0, 0); } } while (0)
; #define LDA(dst, b, h) _Pragma("unroll") for (int m = 0; m < 4; ++m) _Pragma("unroll") for (int k = 0; k < 2; ++k) \
;     dst[m][k] = *reinterpret_cast<const bf16x8*>((char*)SA(b, h) + aoff + m * 2048 + k * 1024)
; #define LDB(dst, b, h) _Pragma("unroll") for (int n = 0; n < 2; ++n) _Pragma("unroll") for (int k = 0; k < 2; ++k) \
;     dst[n][k] = *reinterpret_cast<const bf16x8*>((char*)SB(b, h) + boff + n * (SWAP ? 256 : 2048) + k * 1024)
; #define WAIT_V(n) asm volatile("s_waitcnt vmcnt(" #n ")" ::: "memory")
; #define WAIT_L(n) asm volatile("s_waitcnt lgkmcnt(" #n ")" ::: "memory")
; template <int EPI>
; DI void gemm_phase(const u16* __restrict__ A, int lda, const u16* __restrict__ Bt, int ldb,
;                    int M, int N, int K, const Epi& e, unsigned char* shmraw, int wv, int slot) {
;     ...
;     for (int t = 0; t < nt - 2; t += 2) {
;       LDB(B0, 0, 0); SCHED; LDA(At, 0, 0); STAGEA(SA(1, 1), brow + HALF, t + 1);
;       WAIT_L(8); BAR; WAIT_L(0); MMA(0, 0, At, B0); BAR; SCHED;
;       LDB(B1, 0, 1); STAGEB(SB(0, 0), bcol, t + 2);
;       BAR; WAIT_L(0); MMA(0, 1, At, B1); BAR;
;       LDA(At, 0, 1); STAGEA(SA(0, 0), brow, t + 2);
;       BAR; WAIT_L(0); MMA(1, 0, At, B0); BAR; SCHED;
;       STAGEB(SB(0, 1), bcol + HALF, t + 2);
;       WAIT_V(6); BAR; MMA(1, 1, At, B1); BAR;
;       LDB(B0, 1, 0); SCHED; LDA(At, 1, 0); STAGEA(SA(0, 1), brow + HALF, t + 2);
;       WAIT_L(8); BAR; WAIT_L(0); MMA(0, 0, At, B0); BAR; SCHED;
;       LDB(B1, 1, 1); STAGEB(SB(1, 0), bcol, t + 3);
;       BAR; WAIT_L(0); MMA(0, 1, At, B1); BAR;
;       LDA(At, 1, 1); STAGEA(SA(1, 0), brow, t + 3);
;       BAR; WAIT_L(0); MMA(1, 0, At, B0); BAR; SCHED;
;       STAGEB(SB(1, 1), bcol + HALF, t + 3);
;       WAIT_V(6); BAR; MMA(1, 1, At, B1); BAR;
.LBB0_1012:
	s_waitcnt lgkmcnt(0)
	v_add_u32_e32 v0, s33, v193
	ds_read_b128 v[132:135], v0
	ds_read_b128 v[136:139], v0 offset:256
	ds_read_b128 v[140:143], v0 offset:1024
	ds_read_b128 v[144:147], v0 offset:1280
	s_add_u32 s36, s48, s22
	s_addc_u32 s37, s68, s23
	s_add_u32 s70, s36, 0x80
	v_add_u32_e32 v0, 0xc000, v196
	s_addc_u32 s71, s37, 0
	v_readfirstlane_b32 s42, v0
	v_lshl_add_u64 v[130:131], s[70:71], 0, v[152:153]
	s_mov_b32 m0, s42
	ds_read_b128 v[154:157], v208
	ds_read_b128 v[158:161], v208 offset:1024
	ds_read_b128 v[162:165], v208 offset:2048
	ds_read_b128 v[166:169], v208 offset:3072
	ds_read_b128 v[170:173], v208 offset:4096
	ds_read_b128 v[174:177], v208 offset:5120
	ds_read_b128 v[178:181], v208 offset:6144
	ds_read_b128 v[182:185], v208 offset:7168
	global_load_lds_dwordx4 v[130:131], off
	v_add_u32_e32 v130, 0xe000, v196
	v_lshl_add_u64 v[148:149], s[70:71], 0, v[150:151]
	v_readfirstlane_b32 s42, v130
	s_mov_b32 m0, s42
	s_nop 0
	global_load_lds_dwordx4 v[148:149], off
	s_waitcnt lgkmcnt(8)
	s_barrier
	s_waitcnt lgkmcnt(0)
	s_setprio 1
	v_mfma_f32_16x16x32_bf16 v[126:129], v[132:135], v[154:157], v[126:129]
	v_mfma_f32_16x16x32_bf16 v[122:125], v[136:139], v[154:157], v[122:125]
	v_mfma_f32_16x16x32_bf16 v[118:121], v[132:135], v[162:165], v[118:121]
	v_mfma_f32_16x16x32_bf16 v[114:117], v[136:139], v[162:165], v[114:117]
	v_mfma_f32_16x16x32_bf16 v[110:113], v[132:135], v[170:173], v[110:113]
	v_mfma_f32_16x16x32_bf16 v[106:109], v[136:139], v[170:173], v[106:109]
	v_mfma_f32_16x16x32_bf16 v[102:105], v[132:135], v[178:181], v[102:105]
	v_mfma_f32_16x16x32_bf16 v[98:101], v[136:139], v[178:181], v[98:101]
	v_mfma_f32_16x16x32_bf16 v[126:129], v[140:143], v[158:161], v[126:129]
	v_mfma_f32_16x16x32_bf16 v[122:125], v[144:147], v[158:161], v[122:125]
	v_mfma_f32_16x16x32_bf16 v[118:121], v[140:143], v[166:169], v[118:121]
	v_mfma_f32_16x16x32_bf16 v[114:117], v[144:147], v[166:169], v[114:117]
	v_mfma_f32_16x16x32_bf16 v[110:113], v[140:143], v[174:177], v[110:113]
	v_mfma_f32_16x16x32_bf16 v[106:109], v[144:147], v[174:177], v[106:109]
	v_mfma_f32_16x16x32_bf16 v[102:105], v[140:143], v[182:185], v[102:105]
	v_mfma_f32_16x16x32_bf16 v[98:101], v[144:147], v[182:185], v[98:101]
	s_setprio 0
	s_barrier
	s_add_u32 s42, s69, s22
	s_addc_u32 s54, s35, s23
	s_add_u32 s70, s42, 0x100
	s_addc_u32 s71, s54, 0
	v_readfirstlane_b32 s55, v194
	v_add_u32_e32 v131, s84, v193
	v_lshl_add_u64 v[148:149], s[70:71], 0, v[152:153]
	s_mov_b32 m0, s55
	v_readfirstlane_b32 s55, v195
	ds_read_b128 v[186:189], v131
	ds_read_b128 v[210:213], v131 offset:256
	ds_read_b128 v[214:217], v131 offset:1024
	ds_read_b128 v[218:221], v131 offset:1280
	global_load_lds_dwordx4 v[148:149], off
	v_lshl_add_u64 v[148:149], s[70:71], 0, v[150:151]
	s_mov_b32 m0, s55
	s_nop 0
	global_load_lds_dwordx4 v[148:149], off
	s_barrier
	s_waitcnt lgkmcnt(0)
	s_setprio 1
	v_mfma_f32_16x16x32_bf16 v[94:97], v[186:189], v[154:157], v[94:97]
	v_mfma_f32_16x16x32_bf16 v[78:81], v[210:213], v[154:157], v[78:81]
	v_mfma_f32_16x16x32_bf16 v[62:65], v[186:189], v[162:165], v[62:65]
	v_mfma_f32_16x16x32_bf16 v[50:53], v[210:213], v[162:165], v[50:53]
	v_mfma_f32_16x16x32_bf16 v[46:49], v[186:189], v[170:173], v[46:49]
	v_mfma_f32_16x16x32_bf16 v[42:45], v[210:213], v[170:173], v[42:45]
	v_mfma_f32_16x16x32_bf16 v[38:41], v[186:189], v[178:181], v[38:41]
	v_mfma_f32_16x16x32_bf16 v[34:37], v[210:213], v[178:181], v[34:37]
	v_mfma_f32_16x16x32_bf16 v[94:97], v[214:217], v[158:161], v[94:97]
	v_mfma_f32_16x16x32_bf16 v[78:81], v[218:221], v[158:161], v[78:81]
	v_mfma_f32_16x16x32_bf16 v[62:65], v[214:217], v[166:169], v[62:65]
	v_mfma_f32_16x16x32_bf16 v[50:53], v[218:221], v[166:169], v[50:53]
	v_mfma_f32_16x16x32_bf16 v[46:49], v[214:217], v[174:177], v[46:49]
	v_mfma_f32_16x16x32_bf16 v[42:45], v[218:221], v[174:177], v[42:45]
	v_mfma_f32_16x16x32_bf16 v[38:41], v[214:217], v[182:185], v[38:41]
	v_mfma_f32_16x16x32_bf16 v[34:37], v[218:221], v[182:185], v[34:37]
	s_setprio 0
	s_add_u32 s55, s38, s22
	s_addc_u32 s72, s39, s23
	s_add_u32 s70, s55, 0x100
	s_addc_u32 s71, s72, 0
	v_readfirstlane_b32 s73, v196
	v_lshl_add_u64 v[148:149], s[70:71], 0, v[152:153]
	s_mov_b32 m0, s73
	s_barrier
	ds_read_b128 v[154:157], v208 offset:16384
	ds_read_b128 v[158:161], v208 offset:17408
	ds_read_b128 v[162:165], v208 offset:18432
	ds_read_b128 v[166:169], v208 offset:19456
	ds_read_b128 v[170:173], v208 offset:20480
	ds_read_b128 v[174:177], v208 offset:21504
	ds_read_b128 v[178:181], v208 offset:22528
	ds_read_b128 v[182:185], v208 offset:23552
	global_load_lds_dwordx4 v[148:149], off
	v_lshl_add_u64 v[148:149], s[70:71], 0, v[150:151]
	v_readfirstlane_b32 s70, v197
	s_mov_b32 m0, s70
	s_nop 0
	global_load_lds_dwordx4 v[148:149], off
	s_barrier
	s_waitcnt lgkmcnt(0)
	s_setprio 1
	v_mfma_f32_16x16x32_bf16 v[30:33], v[132:135], v[154:157], v[30:33]
	v_mfma_f32_16x16x32_bf16 v[26:29], v[136:139], v[154:157], v[26:29]
	v_mfma_f32_16x16x32_bf16 v[22:25], v[132:135], v[162:165], v[22:25]
	v_mfma_f32_16x16x32_bf16 v[18:21], v[136:139], v[162:165], v[18:21]
	v_mfma_f32_16x16x32_bf16 v[14:17], v[132:135], v[170:173], v[14:17]
	v_mfma_f32_16x16x32_bf16 v[10:13], v[136:139], v[170:173], v[10:13]
	v_mfma_f32_16x16x32_bf16 v[6:9], v[132:135], v[178:181], v[6:9]
	v_mfma_f32_16x16x32_bf16 v[2:5], v[136:139], v[178:181], v[2:5]
	v_mfma_f32_16x16x32_bf16 v[30:33], v[140:143], v[158:161], v[30:33]
	v_mfma_f32_16x16x32_bf16 v[26:29], v[144:147], v[158:161], v[26:29]
	v_mfma_f32_16x16x32_bf16 v[22:25], v[140:143], v[166:169], v[22:25]
	v_mfma_f32_16x16x32_bf16 v[18:21], v[144:147], v[166:169], v[18:21]
	v_mfma_f32_16x16x32_bf16 v[14:17], v[140:143], v[174:177], v[14:17]
	v_mfma_f32_16x16x32_bf16 v[10:13], v[144:147], v[174:177], v[10:13]
	v_mfma_f32_16x16x32_bf16 v[6:9], v[140:143], v[182:185], v[6:9]
	v_mfma_f32_16x16x32_bf16 v[2:5], v[144:147], v[182:185], v[2:5]
	s_setprio 0
	s_barrier
; #define STAGEA(P, br, kt) do { const char* _g = uptr(A + (size_t)(br) * lda + (size_t)(kt) * BK); \
;     _Pragma("unroll") for (int _i = 0; _i < 2; ++_i) { \
;       __builtin_amdgcn_global_load_lds((const unsigned*)(_g + offA[_i]), (unsigned*)((char*)(P) + tidx * 16 + _i * 8192), 16, 0, 0); } } while (0)
; #define STAGEB(P, br, kt) do { const char* _g = uptr(Bt + (size_t)(br) * ldb + (size_t)(kt) * BK); \
;     _Pragma("unroll") for (int _i = 0; _i < 2; ++_i) { \
;       __builtin_amdgcn_global_load_lds((const unsigned*)(_g + offB[_i]), (unsigned*)((char*)(P) + tidx * 16 + _i * 8192), 16, 0, 0); } } while (0)
; #define LDA(dst, b, h) _Pragma("unroll") for (int m = 0; m < 4; ++m) _Pragma("unroll") for (int k = 0; k < 2; ++k) \
;     dst[m][k] = *reinterpret_cast<const bf16x8*>((char*)SA(b, h) + aoff + m * 2048 + k * 1024)
; #define LDB(dst, b, h) _Pragma("unroll") for (int n = 0; n < 2; ++n) _Pragma("unroll") for (int k = 0; k < 2; ++k) \
;     dst[n][k] = *reinterpret_cast<const bf16x8*>((char*)SB(b, h) + boff + n * (SWAP ? 256 : 2048) + k * 1024)
; #define WAIT_V(n) asm volatile("s_waitcnt vmcnt(" #n ")" ::: "memory")
; #define WAIT_L(n) asm volatile("s_waitcnt lgkmcnt(" #n ")" ::: "memory")
; template <int EPI>
; DI void gemm_phase(const u16* __restrict__ A, int lda, const u16* __restrict__ Bt, int ldb,
;                    int M, int N, int K, const Epi& e, unsigned char* shmraw, int wv, int slot) {
;     ...
;     for (int t = 0; t < nt - 2; t += 2) {
;       LDB(B0, 0, 0); SCHED; LDA(At, 0, 0); STAGEA(SA(1, 1), brow + HALF, t + 1);
;       WAIT_L(8); BAR; WAIT_L(0); MMA(0, 0, At, B0); BAR; SCHED;
;       LDB(B1, 0, 1); STAGEB(SB(0, 0), bcol, t + 2);
;       BAR; WAIT_L(0); MMA(0, 1, At, B1); BAR;
;       LDA(At, 0, 1); STAGEA(SA(0, 0), brow, t + 2);
;       BAR; WAIT_L(0); MMA(1, 0, At, B0); BAR; SCHED;
;       STAGEB(SB(0, 1), bcol + HALF, t + 2);
;       WAIT_V(6); BAR; MMA(1, 1, At, B1); BAR;
;       LDB(B0, 1, 0); SCHED; LDA(At, 1, 0); STAGEA(SA(0, 1), brow + HALF, t + 2);
;       WAIT_L(8); BAR; WAIT_L(0); MMA(0, 0, At, B0); BAR; SCHED;
;       LDB(B1, 1, 1); STAGEB(SB(1, 0), bcol, t + 3);
;       BAR; WAIT_L(0); MMA(0, 1, At, B1); BAR;
;       LDA(At, 1, 1); STAGEA(SA(1, 0), brow, t + 3);
;       BAR; WAIT_L(0); MMA(1, 0, At, B0); BAR; SCHED;
;       STAGEB(SB(1, 1), bcol + HALF, t + 3);
;       WAIT_V(6); BAR; MMA(1, 1, At, B1); BAR;
	s_add_u32 s73, s40, s22
	s_addc_u32 s74, s41, s23
	s_add_u32 s70, s73, 0x100
	s_addc_u32 s71, s74, 0
	v_readfirstlane_b32 s75, v198
	v_lshl_add_u64 v[132:133], s[70:71], 0, v[152:153]
	s_mov_b32 m0, s75
	s_nop 0
	global_load_lds_dwordx4 v[132:133], off
	v_lshl_add_u64 v[132:133], s[70:71], 0, v[150:151]
	v_readfirstlane_b32 s70, v199
	s_mov_b32 m0, s70
	s_nop 0
	global_load_lds_dwordx4 v[132:133], off
	s_waitcnt vmcnt(6)
	s_barrier
	s_setprio 1
	v_mfma_f32_16x16x32_bf16 v[54:57], v[186:189], v[154:157], v[54:57]
	v_mfma_f32_16x16x32_bf16 v[58:61], v[210:213], v[154:157], v[58:61]
	v_mfma_f32_16x16x32_bf16 v[66:69], v[186:189], v[162:165], v[66:69]
	v_mfma_f32_16x16x32_bf16 v[70:73], v[210:213], v[162:165], v[70:73]
	v_mfma_f32_16x16x32_bf16 v[74:77], v[186:189], v[170:173], v[74:77]
	v_mfma_f32_16x16x32_bf16 v[82:85], v[210:213], v[170:173], v[82:85]
	v_mfma_f32_16x16x32_bf16 v[86:89], v[186:189], v[178:181], v[86:89]
	v_mfma_f32_16x16x32_bf16 v[90:93], v[210:213], v[178:181], v[90:93]
	v_mfma_f32_16x16x32_bf16 v[54:57], v[214:217], v[158:161], v[54:57]
	v_mfma_f32_16x16x32_bf16 v[58:61], v[218:221], v[158:161], v[58:61]
	v_mfma_f32_16x16x32_bf16 v[66:69], v[214:217], v[166:169], v[66:69]
	v_mfma_f32_16x16x32_bf16 v[70:73], v[218:221], v[166:169], v[70:73]
	v_mfma_f32_16x16x32_bf16 v[74:77], v[214:217], v[174:177], v[74:77]
	v_mfma_f32_16x16x32_bf16 v[82:85], v[218:221], v[174:177], v[82:85]
	v_mfma_f32_16x16x32_bf16 v[86:89], v[214:217], v[182:185], v[86:89]
	v_mfma_f32_16x16x32_bf16 v[90:93], v[218:221], v[182:185], v[90:93]
	s_setprio 0
	v_add_u32_e32 v131, s85, v193
	s_barrier
	ds_read_b128 v[132:135], v131
	ds_read_b128 v[136:139], v131 offset:256
	ds_read_b128 v[140:143], v131 offset:1024
	ds_read_b128 v[144:147], v131 offset:1280
	s_add_u32 s70, s36, 0x100
	s_addc_u32 s71, s37, 0
	v_readfirstlane_b32 s36, v200
	v_lshl_add_u64 v[148:149], s[70:71], 0, v[152:153]
	s_mov_b32 m0, s36
	v_readfirstlane_b32 s36, v201
	ds_read_b128 v[154:157], v208 offset:32768
	ds_read_b128 v[158:161], v208 offset:33792
	ds_read_b128 v[162:165], v208 offset:34816
	ds_read_b128 v[166:169], v208 offset:35840
	ds_read_b128 v[170:173], v208 offset:36864
	ds_read_b128 v[174:177], v208 offset:37888
	ds_read_b128 v[178:181], v208 offset:38912
	ds_read_b128 v[182:185], v208 offset:39936
	global_load_lds_dwordx4 v[148:149], off
	v_lshl_add_u64 v[148:149], s[70:71], 0, v[150:151]
	s_mov_b32 m0, s36
	s_nop 0
	global_load_lds_dwordx4 v[148:149], off
	s_waitcnt lgkmcnt(8)
	s_barrier
	s_waitcnt lgkmcnt(0)
	s_setprio 1
	v_mfma_f32_16x16x32_bf16 v[126:129], v[132:135], v[154:157], v[126:129]
	v_mfma_f32_16x16x32_bf16 v[122:125], v[136:139], v[154:157], v[122:125]
	v_mfma_f32_16x16x32_bf16 v[118:121], v[132:135], v[162:165], v[118:121]
	v_mfma_f32_16x16x32_bf16 v[114:117], v[136:139], v[162:165], v[114:117]
	v_mfma_f32_16x16x32_bf16 v[110:113], v[132:135], v[170:173], v[110:113]
	v_mfma_f32_16x16x32_bf16 v[106:109], v[136:139], v[170:173], v[106:109]
	v_mfma_f32_16x16x32_bf16 v[102:105], v[132:135], v[178:181], v[102:105]
	v_mfma_f32_16x16x32_bf16 v[98:101], v[136:139], v[178:181], v[98:101]
	v_mfma_f32_16x16x32_bf16 v[126:129], v[140:143], v[158:161], v[126:129]
	v_mfma_f32_16x16x32_bf16 v[122:125], v[144:147], v[158:161], v[122:125]
	v_mfma_f32_16x16x32_bf16 v[118:121], v[140:143], v[166:169], v[118:121]
	v_mfma_f32_16x16x32_bf16 v[114:117], v[144:147], v[166:169], v[114:117]
	v_mfma_f32_16x16x32_bf16 v[110:113], v[140:143], v[174:177], v[110:113]
	v_mfma_f32_16x16x32_bf16 v[106:109], v[144:147], v[174:177], v[106:109]
	v_mfma_f32_16x16x32_bf16 v[102:105], v[140:143], v[182:185], v[102:105]
	v_mfma_f32_16x16x32_bf16 v[98:101], v[144:147], v[182:185], v[98:101]
	s_setprio 0
	s_barrier
	s_add_u32 s70, s42, 0x180
	s_addc_u32 s71, s54, 0
	v_readfirstlane_b32 s36, v202
	v_add_u32_e32 v131, s86, v193
	v_lshl_add_u64 v[148:149], s[70:71], 0, v[152:153]
	s_mov_b32 m0, s36
	v_readfirstlane_b32 s36, v203
	ds_read_b128 v[186:189], v131
	ds_read_b128 v[210:213], v131 offset:256
	ds_read_b128 v[214:217], v131 offset:1024
	ds_read_b128 v[218:221], v131 offset:1280
	global_load_lds_dwordx4 v[148:149], off
	v_lshl_add_u64 v[148:149], s[70:71], 0, v[150:151]
	s_mov_b32 m0, s36
	s_nop 0
	global_load_lds_dwordx4 v[148:149], off
	s_barrier
	s_waitcnt lgkmcnt(0)
	s_setprio 1
	v_mfma_f32_16x16x32_bf16 v[94:97], v[186:189], v[154:157], v[94:97]
	v_mfma_f32_16x16x32_bf16 v[78:81], v[210:213], v[154:157], v[78:81]
	v_mfma_f32_16x16x32_bf16 v[62:65], v[186:189], v[162:165], v[62:65]
	v_mfma_f32_16x16x32_bf16 v[50:53], v[210:213], v[162:165], v[50:53]
	v_mfma_f32_16x16x32_bf16 v[46:49], v[186:189], v[170:173], v[46:49]
	v_mfma_f32_16x16x32_bf16 v[42:45], v[210:213], v[170:173], v[42:45]
	v_mfma_f32_16x16x32_bf16 v[38:41], v[186:189], v[178:181], v[38:41]
	v_mfma_f32_16x16x32_bf16 v[34:37], v[210:213], v[178:181], v[34:37]
	v_mfma_f32_16x16x32_bf16 v[94:97], v[214:217], v[158:161], v[94:97]
	v_mfma_f32_16x16x32_bf16 v[78:81], v[218:221], v[158:161], v[78:81]
	v_mfma_f32_16x16x32_bf16 v[62:65], v[214:217], v[166:169], v[62:65]
	v_mfma_f32_16x16x32_bf16 v[50:53], v[218:221], v[166:169], v[50:53]
	v_mfma_f32_16x16x32_bf16 v[46:49], v[214:217], v[174:177], v[46:49]
	v_mfma_f32_16x16x32_bf16 v[42:45], v[218:221], v[174:177], v[42:45]
	v_mfma_f32_16x16x32_bf16 v[38:41], v[214:217], v[182:185], v[38:41]
	v_mfma_f32_16x16x32_bf16 v[34:37], v[218:221], v[182:185], v[34:37]
	s_setprio 0
	s_add_u32 s70, s55, 0x180
	s_addc_u32 s71, s72, 0
	v_readfirstlane_b32 s36, v204
	v_lshl_add_u64 v[148:149], s[70:71], 0, v[152:153]
	s_mov_b32 m0, s36
	v_readfirstlane_b32 s36, v205
	s_barrier
; #define STAGEA(P, br, kt) do { const char* _g = uptr(A + (size_t)(br) * lda + (size_t)(kt) * BK); \
;     _Pragma("unroll") for (int _i = 0; _i < 2; ++_i) { \
;       __builtin_amdgcn_global_load_lds((const unsigned*)(_g + offA[_i]), (unsigned*)((char*)(P) + tidx * 16 + _i * 8192), 16, 0, 0); } } while (0)
; #define STAGEB(P, br, kt) do { const char* _g = uptr(Bt + (size_t)(br) * ldb + (size_t)(kt) * BK); \
;     _Pragma("unroll") for (int _i = 0; _i < 2; ++_i) { \
;       __builtin_amdgcn_global_load_lds((const unsigned*)(_g + offB[_i]), (unsigned*)((char*)(P) + tidx * 16 + _i * 8192), 16, 0, 0); } } while (0)
; #define LDA(dst, b, h) _Pragma("unroll") for (int m = 0; m < 4; ++m) _Pragma("unroll") for (int k = 0; k < 2; ++k) \
;     dst[m][k] = *reinterpret_cast<const bf16x8*>((char*)SA(b, h) + aoff + m * 2048 + k * 1024)
; #define LDB(dst, b, h) _Pragma("unroll") for (int n = 0; n < 2; ++n) _Pragma("unroll") for (int k = 0; k < 2; ++k) \
;     dst[n][k] = *reinterpret_cast<const bf16x8*>((char*)SB(b, h) + boff + n * (SWAP ? 256 : 2048) + k * 1024)
; #define WAIT_V(n) asm volatile("s_waitcnt vmcnt(" #n ")" ::: "memory")
; #define WAIT_L(n) asm volatile("s_waitcnt lgkmcnt(" #n ")" ::: "memory")
; #define BAR __builtin_amdgcn_s_barrier()
; #define SCHED __builtin_amdgcn_sched_barrier(0)
; template <int EPI>
; DI void gemm_phase(const u16* __restrict__ A, int lda, const u16* __restrict__ Bt, int ldb,
;                    int M, int N, int K, const Epi& e, unsigned char* shmraw, int wv, int slot) {
;     ...
;       LDA(At, 1, 1); STAGEA(SA(1, 0), brow, t + 3);
;       BAR; WAIT_L(0); MMA(1, 0, At, B0); BAR; SCHED;
;       STAGEB(SB(1, 1), bcol + HALF, t + 3);
;       WAIT_V(6); BAR; MMA(1, 1, At, B1); BAR;
;     }
;     { LDB(B0, 0, 0); LDA(At, 0, 0); STAGEA(SA(1, 1), brow + HALF, nt - 1);
;       BAR; WAIT_L(0); MMA(0, 0, At, B0); BAR;
	ds_read_b128 v[154:157], v208 offset:49152
	ds_read_b128 v[158:161], v208 offset:50176
	ds_read_b128 v[162:165], v208 offset:51200
	ds_read_b128 v[166:169], v208 offset:52224
	ds_read_b128 v[170:173], v208 offset:53248
	ds_read_b128 v[174:177], v208 offset:54272
	ds_read_b128 v[178:181], v208 offset:55296
	ds_read_b128 v[182:185], v208 offset:56320
	global_load_lds_dwordx4 v[148:149], off
	v_lshl_add_u64 v[148:149], s[70:71], 0, v[150:151]
	s_mov_b32 m0, s36
	s_nop 0
	global_load_lds_dwordx4 v[148:149], off
	s_barrier
	s_waitcnt lgkmcnt(0)
	s_setprio 1
	v_mfma_f32_16x16x32_bf16 v[30:33], v[132:135], v[154:157], v[30:33]
	v_mfma_f32_16x16x32_bf16 v[26:29], v[136:139], v[154:157], v[26:29]
	v_mfma_f32_16x16x32_bf16 v[22:25], v[132:135], v[162:165], v[22:25]
	v_mfma_f32_16x16x32_bf16 v[18:21], v[136:139], v[162:165], v[18:21]
	v_mfma_f32_16x16x32_bf16 v[14:17], v[132:135], v[170:173], v[14:17]
	v_mfma_f32_16x16x32_bf16 v[10:13], v[136:139], v[170:173], v[10:13]
	v_mfma_f32_16x16x32_bf16 v[6:9], v[132:135], v[178:181], v[6:9]
	v_mfma_f32_16x16x32_bf16 v[2:5], v[136:139], v[178:181], v[2:5]
	v_mfma_f32_16x16x32_bf16 v[30:33], v[140:143], v[158:161], v[30:33]
	v_mfma_f32_16x16x32_bf16 v[26:29], v[144:147], v[158:161], v[26:29]
	v_mfma_f32_16x16x32_bf16 v[22:25], v[140:143], v[166:169], v[22:25]
	v_mfma_f32_16x16x32_bf16 v[18:21], v[144:147], v[166:169], v[18:21]
	v_mfma_f32_16x16x32_bf16 v[14:17], v[140:143], v[174:177], v[14:17]
	v_mfma_f32_16x16x32_bf16 v[10:13], v[144:147], v[174:177], v[10:13]
	v_mfma_f32_16x16x32_bf16 v[6:9], v[140:143], v[182:185], v[6:9]
	v_mfma_f32_16x16x32_bf16 v[2:5], v[144:147], v[182:185], v[2:5]
	s_setprio 0
	s_barrier
	s_add_u32 s70, s73, 0x180
	s_addc_u32 s71, s74, 0
	v_readfirstlane_b32 s36, v206
	v_lshl_add_u64 v[132:133], s[70:71], 0, v[152:153]
	s_mov_b32 m0, s36
	v_readfirstlane_b32 s36, v207
	global_load_lds_dwordx4 v[132:133], off
	v_lshl_add_u64 v[132:133], s[70:71], 0, v[150:151]
	s_mov_b32 m0, s36
	s_nop 0
	global_load_lds_dwordx4 v[132:133], off
	s_waitcnt vmcnt(6)
	s_barrier
	s_setprio 1
	v_mfma_f32_16x16x32_bf16 v[54:57], v[186:189], v[154:157], v[54:57]
	v_mfma_f32_16x16x32_bf16 v[58:61], v[210:213], v[154:157], v[58:61]
	v_mfma_f32_16x16x32_bf16 v[66:69], v[186:189], v[162:165], v[66:69]
	v_mfma_f32_16x16x32_bf16 v[70:73], v[210:213], v[162:165], v[70:73]
	v_mfma_f32_16x16x32_bf16 v[74:77], v[186:189], v[170:173], v[74:77]
	v_mfma_f32_16x16x32_bf16 v[82:85], v[210:213], v[170:173], v[82:85]
	v_mfma_f32_16x16x32_bf16 v[86:89], v[186:189], v[178:181], v[86:89]
	v_mfma_f32_16x16x32_bf16 v[90:93], v[210:213], v[178:181], v[90:93]
	v_mfma_f32_16x16x32_bf16 v[54:57], v[214:217], v[158:161], v[54:57]
	v_mfma_f32_16x16x32_bf16 v[58:61], v[218:221], v[158:161], v[58:61]
	v_mfma_f32_16x16x32_bf16 v[66:69], v[214:217], v[166:169], v[66:69]
	v_mfma_f32_16x16x32_bf16 v[70:73], v[218:221], v[166:169], v[70:73]
	v_mfma_f32_16x16x32_bf16 v[74:77], v[214:217], v[174:177], v[74:77]
	v_mfma_f32_16x16x32_bf16 v[82:85], v[218:221], v[174:177], v[82:85]
	v_mfma_f32_16x16x32_bf16 v[86:89], v[214:217], v[182:185], v[86:89]
	v_mfma_f32_16x16x32_bf16 v[90:93], v[218:221], v[182:185], v[90:93]
	s_setprio 0
	s_add_i32 s1, s1, 2
	s_add_u32 s22, s22, 0x100
	s_addc_u32 s23, s23, 0
	s_cmp_gt_u32 s1, 11
	s_barrier
	s_cbranch_scc0 .LBB0_1012
	s_lshl_b64 s[20:21], s[20:21], 1
	s_add_u32 s20, s0, s20
	v_readlane_b32 s1, v253, 4
	v_add_u32_e32 v190, 16, v193
	s_addc_u32 s21, s1, s21
	v_readfirstlane_b32 s1, v0
	v_add_u32_e32 v131, 0x10000, v190
	v_lshl_add_u64 v[148:149], s[20:21], 0, v[152:153]
	s_mov_b32 m0, s1
	v_readfirstlane_b32 s1, v130
	ds_read_b128 v[132:135], v131
	ds_read_b128 v[136:139], v131 offset:256
	ds_read_b128 v[140:143], v131 offset:1024
	ds_read_b128 v[144:147], v131 offset:1280
	ds_read_b128 v[154:157], v208
	ds_read_b128 v[158:161], v208 offset:1024
	ds_read_b128 v[162:165], v208 offset:2048
	ds_read_b128 v[166:169], v208 offset:3072
	ds_read_b128 v[170:173], v208 offset:4096
	ds_read_b128 v[174:177], v208 offset:5120
	ds_read_b128 v[178:181], v208 offset:6144
	ds_read_b128 v[182:185], v208 offset:7168
	global_load_lds_dwordx4 v[148:149], off
	v_lshl_add_u64 v[148:149], s[20:21], 0, v[150:151]
	s_mov_b32 m0, s1
	s_nop 0
	global_load_lds_dwordx4 v[148:149], off
	s_barrier
	s_waitcnt lgkmcnt(0)
	s_setprio 1
	v_mfma_f32_16x16x32_bf16 v[126:129], v[132:135], v[154:157], v[126:129]
	v_mfma_f32_16x16x32_bf16 v[122:125], v[136:139], v[154:157], v[122:125]
	v_mfma_f32_16x16x32_bf16 v[118:121], v[132:135], v[162:165], v[118:121]
	v_mfma_f32_16x16x32_bf16 v[114:117], v[136:139], v[162:165], v[114:117]
	v_mfma_f32_16x16x32_bf16 v[110:113], v[132:135], v[170:173], v[110:113]
	v_mfma_f32_16x16x32_bf16 v[106:109], v[136:139], v[170:173], v[106:109]
	v_mfma_f32_16x16x32_bf16 v[98:101], v[136:139], v[178:181], v[98:101]
	v_mfma_f32_16x16x32_bf16 v[126:129], v[140:143], v[158:161], v[126:129]
	v_mfma_f32_16x16x32_bf16 v[122:125], v[144:147], v[158:161], v[122:125]
	v_mfma_f32_16x16x32_bf16 v[118:121], v[140:143], v[166:169], v[118:121]
	v_mfma_f32_16x16x32_bf16 v[114:117], v[144:147], v[166:169], v[114:117]
	v_mfma_f32_16x16x32_bf16 v[110:113], v[140:143], v[174:177], v[110:113]
	v_mfma_f32_16x16x32_bf16 v[106:109], v[144:147], v[174:177], v[106:109]
	v_mfma_f32_16x16x32_bf16 v[102:105], v[132:135], v[178:181], v[102:105]
	v_mfma_f32_16x16x32_bf16 v[98:101], v[144:147], v[182:185], v[98:101]
	v_mfma_f32_16x16x32_bf16 v[186:189], v[140:143], v[182:185], v[102:105]
	s_setprio 0
	v_add_u32_e32 v0, 0x14000, v190
	s_barrier
	s_nop 2
	ds_read_b128 v[102:105], v0
	ds_read_b128 v[210:213], v0 offset:256
	ds_read_b128 v[214:217], v0 offset:1024
	ds_read_b128 v[218:221], v0 offset:1280
	s_barrier
; #define LDA(dst, b, h) _Pragma("unroll") for (int m = 0; m < 4; ++m) _Pragma("unroll") for (int k = 0; k < 2; ++k) \
;     dst[m][k] = *reinterpret_cast<const bf16x8*>((char*)SA(b, h) + aoff + m * 2048 + k * 1024)
; #define LDB(dst, b, h) _Pragma("unroll") for (int n = 0; n < 2; ++n) _Pragma("unroll") for (int k = 0; k < 2; ++k) \
;     dst[n][k] = *reinterpret_cast<const bf16x8*>((char*)SB(b, h) + boff + n * (SWAP ? 256 : 2048) + k * 1024)
; #define WAIT_V(n) asm volatile("s_waitcnt vmcnt(" #n ")" ::: "memory")
; #define WAIT_L(n) asm volatile("s_waitcnt lgkmcnt(" #n ")" ::: "memory")
; #define BAR __builtin_amdgcn_s_barrier()
; template <int EPI>
; DI void gemm_phase(const u16* __restrict__ A, int lda, const u16* __restrict__ Bt, int ldb,
;                    int M, int N, int K, const Epi& e, unsigned char* shmraw, int wv, int slot) {
;     ...
;       BAR; WAIT_L(0); MMA(0, 0, At, B0); BAR;
;       LDB(B1, 0, 1); BAR; WAIT_L(0); MMA(0, 1, At, B1); BAR;
;       LDA(At, 0, 1); WAIT_V(4); BAR; WAIT_L(0); MMA(1, 0, At, B0); MMA(1, 1, At, B1); BAR; }
;     { LDB(B0, 1, 0); LDA(At, 1, 0); WAIT_V(2); BAR; WAIT_L(0); MMA(0, 0, At, B0); BAR;
	s_waitcnt lgkmcnt(0)
	s_setprio 1
	v_mfma_f32_16x16x32_bf16 v[94:97], v[102:105], v[154:157], v[94:97]
	v_mfma_f32_16x16x32_bf16 v[78:81], v[210:213], v[154:157], v[78:81]
	v_mfma_f32_16x16x32_bf16 v[62:65], v[102:105], v[162:165], v[62:65]
	v_mfma_f32_16x16x32_bf16 v[46:49], v[102:105], v[170:173], v[46:49]
	v_mfma_f32_16x16x32_bf16 v[42:45], v[210:213], v[170:173], v[42:45]
	v_mfma_f32_16x16x32_bf16 v[38:41], v[102:105], v[178:181], v[38:41]
	v_mfma_f32_16x16x32_bf16 v[34:37], v[210:213], v[178:181], v[34:37]
	v_mfma_f32_16x16x32_bf16 v[94:97], v[214:217], v[158:161], v[94:97]
	v_mfma_f32_16x16x32_bf16 v[78:81], v[218:221], v[158:161], v[78:81]
	v_mfma_f32_16x16x32_bf16 v[62:65], v[214:217], v[166:169], v[62:65]
	v_mfma_f32_16x16x32_bf16 v[50:53], v[210:213], v[162:165], v[50:53]
	v_mfma_f32_16x16x32_bf16 v[46:49], v[214:217], v[174:177], v[46:49]
	v_mfma_f32_16x16x32_bf16 v[42:45], v[218:221], v[174:177], v[42:45]
	v_mfma_f32_16x16x32_bf16 v[38:41], v[214:217], v[182:185], v[38:41]
	v_mfma_f32_16x16x32_bf16 v[34:37], v[218:221], v[182:185], v[34:37]
	v_mfma_f32_16x16x32_bf16 v[154:157], v[218:221], v[166:169], v[50:53]
	s_setprio 0
	s_barrier
	s_nop 0
	ds_read_b128 v[50:53], v208 offset:16384
	ds_read_b128 v[158:161], v208 offset:17408
	ds_read_b128 v[162:165], v208 offset:18432
	ds_read_b128 v[166:169], v208 offset:19456
	ds_read_b128 v[170:173], v208 offset:20480
	ds_read_b128 v[174:177], v208 offset:21504
	ds_read_b128 v[178:181], v208 offset:22528
	ds_read_b128 v[182:185], v208 offset:23552
	s_waitcnt vmcnt(4)
	s_barrier
	s_waitcnt lgkmcnt(0)
	s_setprio 1
	v_mfma_f32_16x16x32_bf16 v[14:17], v[132:135], v[170:173], v[14:17]
	v_mfma_f32_16x16x32_bf16 v[10:13], v[136:139], v[170:173], v[10:13]
	v_mfma_f32_16x16x32_bf16 v[6:9], v[132:135], v[178:181], v[6:9]
	v_mfma_f32_16x16x32_bf16 v[2:5], v[136:139], v[178:181], v[2:5]
	v_mfma_f32_16x16x32_bf16 v[30:33], v[132:135], v[50:53], v[30:33]
	v_mfma_f32_16x16x32_bf16 v[26:29], v[136:139], v[50:53], v[26:29]
	v_mfma_f32_16x16x32_bf16 v[22:25], v[132:135], v[162:165], v[22:25]
	v_mfma_f32_16x16x32_bf16 v[18:21], v[136:139], v[162:165], v[18:21]
	v_mfma_f32_16x16x32_bf16 v[14:17], v[140:143], v[174:177], v[14:17]
	v_mfma_f32_16x16x32_bf16 v[10:13], v[144:147], v[174:177], v[10:13]
	v_mfma_f32_16x16x32_bf16 v[6:9], v[140:143], v[182:185], v[6:9]
	v_mfma_f32_16x16x32_bf16 v[2:5], v[144:147], v[182:185], v[2:5]
	v_mfma_f32_16x16x32_bf16 v[30:33], v[140:143], v[158:161], v[30:33]
	v_mfma_f32_16x16x32_bf16 v[26:29], v[144:147], v[158:161], v[26:29]
	v_mfma_f32_16x16x32_bf16 v[22:25], v[140:143], v[166:169], v[22:25]
	v_mfma_f32_16x16x32_bf16 v[18:21], v[144:147], v[166:169], v[18:21]
	s_setprio 0
	s_setprio 1
	v_mfma_f32_16x16x32_bf16 v[54:57], v[102:105], v[50:53], v[54:57]
	v_mfma_f32_16x16x32_bf16 v[50:53], v[210:213], v[50:53], v[58:61]
	v_mfma_f32_16x16x32_bf16 v[58:61], v[218:221], v[158:161], v[50:53]
	v_mfma_f32_16x16x32_bf16 v[50:53], v[102:105], v[162:165], v[66:69]
	v_mfma_f32_16x16x32_bf16 v[142:145], v[214:217], v[158:161], v[54:57]
	v_mfma_f32_16x16x32_bf16 v[158:161], v[214:217], v[166:169], v[50:53]
	v_mfma_f32_16x16x32_bf16 v[50:53], v[210:213], v[162:165], v[70:73]
	v_mfma_f32_16x16x32_bf16 v[162:165], v[218:221], v[166:169], v[50:53]
	v_mfma_f32_16x16x32_bf16 v[50:53], v[102:105], v[170:173], v[74:77]
	v_mfma_f32_16x16x32_bf16 v[166:169], v[214:217], v[174:177], v[50:53]
	v_mfma_f32_16x16x32_bf16 v[50:53], v[210:213], v[170:173], v[82:85]
	v_mfma_f32_16x16x32_bf16 v[170:173], v[218:221], v[174:177], v[50:53]
	v_mfma_f32_16x16x32_bf16 v[50:53], v[102:105], v[178:181], v[86:89]
	v_mfma_f32_16x16x32_bf16 v[174:177], v[214:217], v[182:185], v[50:53]
	v_mfma_f32_16x16x32_bf16 v[50:53], v[210:213], v[178:181], v[90:93]
	v_mfma_f32_16x16x32_bf16 v[178:181], v[218:221], v[182:185], v[50:53]
	s_setprio 0
	v_add_u32_e32 v0, 0x18000, v190
	s_barrier
	ds_read_b128 v[90:93], v0
	ds_read_b128 v[182:185], v0 offset:256
	ds_read_b128 v[210:213], v0 offset:1024
	ds_read_b128 v[214:217], v0 offset:1280
	ds_read_b128 v[66:69], v208 offset:32768
	ds_read_b128 v[74:77], v208 offset:33792
	ds_read_b128 v[86:89], v208 offset:34816
	ds_read_b128 v[218:221], v208 offset:35840
	ds_read_b128 v[222:225], v208 offset:36864
	ds_read_b128 v[226:229], v208 offset:37888
	ds_read_b128 v[230:233], v208 offset:38912
	ds_read_b128 v[234:237], v208 offset:39936
	s_waitcnt vmcnt(2)
	s_barrier
; #define LDA(dst, b, h) _Pragma("unroll") for (int m = 0; m < 4; ++m) _Pragma("unroll") for (int k = 0; k < 2; ++k) \
;     dst[m][k] = *reinterpret_cast<const bf16x8*>((char*)SA(b, h) + aoff + m * 2048 + k * 1024)
; #define LDB(dst, b, h) _Pragma("unroll") for (int n = 0; n < 2; ++n) _Pragma("unroll") for (int k = 0; k < 2; ++k) \
;     dst[n][k] = *reinterpret_cast<const bf16x8*>((char*)SB(b, h) + boff + n * (SWAP ? 256 : 2048) + k * 1024)
; #define WAIT_V(n) asm volatile("s_waitcnt vmcnt(" #n ")" ::: "memory")
; #define WAIT_L(n) asm volatile("s_waitcnt lgkmcnt(" #n ")" ::: "memory")
; #define BAR __builtin_amdgcn_s_barrier()
; template <int EPI>
; DI void gemm_phase(const u16* __restrict__ A, int lda, const u16* __restrict__ Bt, int ldb,
;                    int M, int N, int K, const Epi& e, unsigned char* shmraw, int wv, int slot) {
;     ...
;     { LDB(B0, 1, 0); LDA(At, 1, 0); WAIT_V(2); BAR; WAIT_L(0); MMA(0, 0, At, B0); BAR;
;       LDB(B1, 1, 1); WAIT_V(0); BAR; WAIT_L(0); MMA(0, 1, At, B1); BAR;
;       LDA(At, 1, 1); BAR; WAIT_L(0); MMA(1, 0, At, B0); MMA(1, 1, At, B1); BAR; }
;     if (wr == 0) BAR;
	s_waitcnt lgkmcnt(0)
	s_setprio 1
	v_mfma_f32_16x16x32_bf16 v[54:57], v[182:185], v[86:89], v[114:117]
	v_mfma_f32_16x16x32_bf16 v[70:73], v[214:217], v[218:221], v[54:57]
	v_mfma_f32_16x16x32_bf16 v[54:57], v[90:93], v[222:225], v[110:113]
	v_mfma_f32_16x16x32_bf16 v[50:53], v[90:93], v[66:69], v[126:129]
	v_mfma_f32_16x16x32_bf16 v[82:85], v[210:213], v[226:229], v[54:57]
	v_mfma_f32_16x16x32_bf16 v[54:57], v[182:185], v[222:225], v[106:109]
	v_mfma_f32_16x16x32_bf16 v[138:141], v[210:213], v[74:77], v[50:53]
	v_mfma_f32_16x16x32_bf16 v[50:53], v[182:185], v[66:69], v[122:125]
	v_mfma_f32_16x16x32_bf16 v[102:105], v[214:217], v[226:229], v[54:57]
	v_mfma_f32_16x16x32_bf16 v[54:57], v[90:93], v[230:233], v[186:189]
	v_mfma_f32_16x16x32_bf16 v[146:149], v[214:217], v[74:77], v[50:53]
	v_mfma_f32_16x16x32_bf16 v[50:53], v[90:93], v[86:89], v[118:121]
	v_mfma_f32_16x16x32_bf16 v[114:117], v[210:213], v[234:237], v[54:57]
	v_mfma_f32_16x16x32_bf16 v[54:57], v[182:185], v[230:233], v[98:101]
	v_mfma_f32_16x16x32_bf16 v[50:53], v[210:213], v[218:221], v[50:53]
	v_mfma_f32_16x16x32_bf16 v[130:133], v[214:217], v[234:237], v[54:57]
	s_setprio 0
	v_add_u32_e32 v0, 0x1c000, v190
	s_barrier
	ds_read_b128 v[186:189], v0
	ds_read_b128 v[238:241], v0 offset:256
	ds_read_b128 v[242:245], v0 offset:1024
	ds_read_b128 v[246:249], v0 offset:1280
	s_waitcnt vmcnt(0)
	s_barrier
	s_waitcnt lgkmcnt(0)
	s_setprio 1
	v_mfma_f32_16x16x32_bf16 v[54:57], v[186:189], v[66:69], v[94:97]
	v_mfma_f32_16x16x32_bf16 v[66:69], v[238:241], v[66:69], v[78:81]
	v_mfma_f32_16x16x32_bf16 v[62:65], v[186:189], v[86:89], v[62:65]
	v_mfma_f32_16x16x32_bf16 v[134:137], v[246:249], v[74:77], v[66:69]
	v_mfma_f32_16x16x32_bf16 v[66:69], v[242:245], v[218:221], v[62:65]
	v_mfma_f32_16x16x32_bf16 v[62:65], v[238:241], v[86:89], v[154:157]
	v_mfma_f32_16x16x32_bf16 v[46:49], v[186:189], v[222:225], v[46:49]
	v_mfma_f32_16x16x32_bf16 v[42:45], v[238:241], v[222:225], v[42:45]
	v_mfma_f32_16x16x32_bf16 v[38:41], v[186:189], v[230:233], v[38:41]
	v_mfma_f32_16x16x32_bf16 v[34:37], v[238:241], v[230:233], v[34:37]
	v_mfma_f32_16x16x32_bf16 v[54:57], v[242:245], v[74:77], v[54:57]
	v_mfma_f32_16x16x32_bf16 v[86:89], v[246:249], v[218:221], v[62:65]
	v_mfma_f32_16x16x32_bf16 v[98:101], v[242:245], v[226:229], v[46:49]
	v_mfma_f32_16x16x32_bf16 v[118:121], v[246:249], v[226:229], v[42:45]
	v_mfma_f32_16x16x32_bf16 v[122:125], v[242:245], v[234:237], v[38:41]
	v_mfma_f32_16x16x32_bf16 v[126:129], v[246:249], v[234:237], v[34:37]
	s_setprio 0
	s_barrier
	s_nop 0
	ds_read_b128 v[34:37], v208 offset:49152
	ds_read_b128 v[38:41], v208 offset:50176
	ds_read_b128 v[62:65], v208 offset:51200
	ds_read_b128 v[154:157], v208 offset:52224
	ds_read_b128 v[218:221], v208 offset:53248
	ds_read_b128 v[222:225], v208 offset:54272
	ds_read_b128 v[226:229], v208 offset:55296
	ds_read_b128 v[230:233], v208 offset:56320
	s_barrier
	s_waitcnt lgkmcnt(0)
	s_setprio 1
	v_mfma_f32_16x16x32_bf16 v[30:33], v[90:93], v[34:37], v[30:33]
	v_mfma_f32_16x16x32_bf16 v[26:29], v[182:185], v[34:37], v[26:29]
	v_mfma_f32_16x16x32_bf16 v[22:25], v[90:93], v[62:65], v[22:25]
	v_mfma_f32_16x16x32_bf16 v[18:21], v[182:185], v[62:65], v[18:21]
	v_mfma_f32_16x16x32_bf16 v[14:17], v[90:93], v[218:221], v[14:17]
	v_mfma_f32_16x16x32_bf16 v[10:13], v[182:185], v[218:221], v[10:13]
	v_mfma_f32_16x16x32_bf16 v[6:9], v[90:93], v[226:229], v[6:9]
	v_mfma_f32_16x16x32_bf16 v[2:5], v[182:185], v[226:229], v[2:5]
	v_mfma_f32_16x16x32_bf16 v[106:109], v[210:213], v[38:41], v[30:33]
	v_mfma_f32_16x16x32_bf16 v[110:113], v[214:217], v[38:41], v[26:29]
	v_mfma_f32_16x16x32_bf16 v[74:77], v[210:213], v[154:157], v[22:25]
	v_mfma_f32_16x16x32_bf16 v[78:81], v[214:217], v[154:157], v[18:21]
	v_mfma_f32_16x16x32_bf16 v[42:45], v[210:213], v[222:225], v[14:17]
	v_mfma_f32_16x16x32_bf16 v[46:49], v[214:217], v[222:225], v[10:13]
	v_mfma_f32_16x16x32_bf16 v[10:13], v[210:213], v[230:233], v[6:9]
	v_mfma_f32_16x16x32_bf16 v[14:17], v[214:217], v[230:233], v[2:5]
	s_setprio 0
	s_setprio 1
	v_mfma_f32_16x16x32_bf16 v[2:5], v[186:189], v[34:37], v[142:145]
	v_mfma_f32_16x16x32_bf16 v[90:93], v[242:245], v[38:41], v[2:5]
	v_mfma_f32_16x16x32_bf16 v[2:5], v[238:241], v[34:37], v[58:61]
	v_mfma_f32_16x16x32_bf16 v[94:97], v[246:249], v[38:41], v[2:5]
	v_mfma_f32_16x16x32_bf16 v[2:5], v[186:189], v[62:65], v[158:161]
	v_mfma_f32_16x16x32_bf16 v[58:61], v[242:245], v[154:157], v[2:5]
	v_mfma_f32_16x16x32_bf16 v[2:5], v[238:241], v[62:65], v[162:165]
	v_mfma_f32_16x16x32_bf16 v[62:65], v[246:249], v[154:157], v[2:5]
	v_mfma_f32_16x16x32_bf16 v[2:5], v[186:189], v[218:221], v[166:169]
	v_mfma_f32_16x16x32_bf16 v[34:37], v[242:245], v[222:225], v[2:5]
	v_mfma_f32_16x16x32_bf16 v[2:5], v[238:241], v[218:221], v[170:173]
	v_mfma_f32_16x16x32_bf16 v[38:41], v[246:249], v[222:225], v[2:5]
	v_mfma_f32_16x16x32_bf16 v[2:5], v[186:189], v[226:229], v[174:177]
	v_mfma_f32_16x16x32_bf16 v[6:9], v[238:241], v[226:229], v[178:181]
	v_mfma_f32_16x16x32_bf16 v[2:5], v[242:245], v[230:233], v[2:5]
	v_mfma_f32_16x16x32_bf16 v[6:9], v[246:249], v[230:233], v[6:9]
	s_setprio 0
	s_barrier
	s_and_saveexec_b64 s[20:21], s[4:5]
	s_cbranch_execz .LBB0_1015
	s_barrier

; #define STAGEA(P, br, kt) do { const char* _g = uptr(A + (size_t)(br) * lda + (size_t)(kt) * BK); \
;     _Pragma("unroll") for (int _i = 0; _i < 2; ++_i) { \
;       __builtin_amdgcn_global_load_lds((const unsigned*)(_g + offA[_i]), (unsigned*)((char*)(P) + tidx * 16 + _i * 8192), 16, 0, 0); } } while (0)
; #define STAGEB(P, br, kt) do { const char* _g = uptr(Bt + (size_t)(br) * ldb + (size_t)(kt) * BK); \
;     _Pragma("unroll") for (int _i = 0; _i < 2; ++_i) { \
;       __builtin_amdgcn_global_load_lds((const unsigned*)(_g + offB[_i]), (unsigned*)((char*)(P) + tidx * 16 + _i * 8192), 16, 0, 0); } } while (0)
; #define LDA(dst, b, h) _Pragma("unroll") for (int m = 0; m < 4; ++m) _Pragma("unroll") for (int k = 0; k < 2; ++k) \
;     dst[m][k] = *reinterpret_cast<const bf16x8*>((char*)SA(b, h) + aoff + m * 2048 + k * 1024)
; #define LDB(dst, b, h) _Pragma("unroll") for (int n = 0; n < 2; ++n) _Pragma("unroll") for (int k = 0; k < 2; ++k) \
;     dst[n][k] = *reinterpret_cast<const bf16x8*>((char*)SB(b, h) + boff + n * (SWAP ? 256 : 2048) + k * 1024)
; #define WAIT_V(n) asm volatile("s_waitcnt vmcnt(" #n ")" ::: "memory")
; #define WAIT_L(n) asm volatile("s_waitcnt lgkmcnt(" #n ")" ::: "memory")
; template <int EPI>
; DI void gemm_phase(const u16* __restrict__ A, int lda, const u16* __restrict__ Bt, int ldb,
;                    int M, int N, int K, const Epi& e, unsigned char* shmraw, int wv, int slot) {
;     ...
;     for (int t = 0; t < nt - 2; t += 2) {
;       LDB(B0, 0, 0); SCHED; LDA(At, 0, 0); STAGEA(SA(1, 1), brow + HALF, t + 1);
;       WAIT_L(8); BAR; WAIT_L(0); MMA(0, 0, At, B0); BAR; SCHED;
;       LDB(B1, 0, 1); STAGEB(SB(0, 0), bcol, t + 2);
;       BAR; WAIT_L(0); MMA(0, 1, At, B1); BAR;
;       LDA(At, 0, 1); STAGEA(SA(0, 0), brow, t + 2);
;       BAR; WAIT_L(0); MMA(1, 0, At, B0); BAR; SCHED;
;       STAGEB(SB(0, 1), bcol + HALF, t + 2);
;       WAIT_V(6); BAR; MMA(1, 1, At, B1); BAR;
;       LDB(B0, 1, 0); SCHED; LDA(At, 1, 0); STAGEA(SA(0, 1), brow + HALF, t + 2);
;       WAIT_L(8); BAR; WAIT_L(0); MMA(0, 0, At, B0); BAR; SCHED;
;       LDB(B1, 1, 1); STAGEB(SB(1, 0), bcol, t + 3);
;       BAR; WAIT_L(0); MMA(0, 1, At, B1); BAR;
;       LDA(At, 1, 1); STAGEA(SA(1, 0), brow, t + 3);
;       BAR; WAIT_L(0); MMA(1, 0, At, B0); BAR; SCHED;
;       STAGEB(SB(1, 1), bcol + HALF, t + 3);
;       WAIT_V(6); BAR; MMA(1, 1, At, B1); BAR;
.LBB0_1106:
	v_add_u32_e32 v130, s33, v152
	ds_read_b128 v[132:135], v130
	ds_read_b128 v[136:139], v130 offset:256
	ds_read_b128 v[140:143], v130 offset:1024
	ds_read_b128 v[148:151], v130 offset:1280
	s_add_u32 s11, s41, s14
	s_addc_u32 s37, s1, s15
	s_add_u32 s42, s11, 0x80
	v_add_u32_e32 v130, 0xc000, v155
	s_addc_u32 s43, s37, 0
	v_readfirstlane_b32 s11, v130
	v_add_u32_e32 v131, 0xe000, v155
	v_lshl_add_u64 v[144:145], s[42:43], 0, v[0:1]
	s_mov_b32 m0, s11
	v_readfirstlane_b32 s11, v131
	ds_read_b128 v[168:171], v167
	ds_read_b128 v[172:175], v167 offset:1024
	ds_read_b128 v[176:179], v167 offset:2048
	ds_read_b128 v[180:183], v167 offset:3072
	ds_read_b128 v[184:187], v167 offset:4096
	ds_read_b128 v[188:191], v167 offset:5120
	ds_read_b128 v[192:195], v167 offset:6144
	ds_read_b128 v[196:199], v167 offset:7168
	global_load_lds_dwordx4 v[144:145], off
	v_lshl_add_u64 v[144:145], s[42:43], 0, v[146:147]
	s_mov_b32 m0, s11
	s_nop 0
	global_load_lds_dwordx4 v[144:145], off
	s_waitcnt lgkmcnt(8)
	s_barrier
	s_waitcnt lgkmcnt(0)
	s_setprio 1
	v_mfma_f32_16x16x32_bf16 v[126:129], v[132:135], v[168:171], v[126:129]
	v_mfma_f32_16x16x32_bf16 v[122:125], v[136:139], v[168:171], v[122:125]
	v_mfma_f32_16x16x32_bf16 v[118:121], v[132:135], v[176:179], v[118:121]
	v_mfma_f32_16x16x32_bf16 v[114:117], v[136:139], v[176:179], v[114:117]
	v_mfma_f32_16x16x32_bf16 v[110:113], v[132:135], v[184:187], v[110:113]
	v_mfma_f32_16x16x32_bf16 v[106:109], v[136:139], v[184:187], v[106:109]
	v_mfma_f32_16x16x32_bf16 v[102:105], v[132:135], v[192:195], v[102:105]
	v_mfma_f32_16x16x32_bf16 v[98:101], v[136:139], v[192:195], v[98:101]
	v_mfma_f32_16x16x32_bf16 v[126:129], v[140:143], v[172:175], v[126:129]
	v_mfma_f32_16x16x32_bf16 v[122:125], v[148:151], v[172:175], v[122:125]
	v_mfma_f32_16x16x32_bf16 v[118:121], v[140:143], v[180:183], v[118:121]
	v_mfma_f32_16x16x32_bf16 v[114:117], v[148:151], v[180:183], v[114:117]
	v_mfma_f32_16x16x32_bf16 v[110:113], v[140:143], v[188:191], v[110:113]
	v_mfma_f32_16x16x32_bf16 v[106:109], v[148:151], v[188:191], v[106:109]
	v_mfma_f32_16x16x32_bf16 v[102:105], v[140:143], v[196:199], v[102:105]
	v_mfma_f32_16x16x32_bf16 v[98:101], v[148:151], v[196:199], v[98:101]
	s_setprio 0
	s_barrier
	s_add_u32 s11, s13, s14
	s_addc_u32 s37, s30, s15
	s_add_u32 s42, s11, 0x100
	v_add_u32_e32 v144, s84, v152
	s_addc_u32 s43, s37, 0
	v_readfirstlane_b32 s54, v153
	ds_read_b128 v[200:203], v144
	ds_read_b128 v[204:207], v144 offset:256
	ds_read_b128 v[208:211], v144 offset:1024
	ds_read_b128 v[212:215], v144 offset:1280
	v_lshl_add_u64 v[144:145], s[42:43], 0, v[0:1]
	s_mov_b32 m0, s54
	s_nop 0
	global_load_lds_dwordx4 v[144:145], off
	v_lshl_add_u64 v[144:145], s[42:43], 0, v[146:147]
	v_readfirstlane_b32 s42, v154
	s_mov_b32 m0, s42
	s_nop 0
	global_load_lds_dwordx4 v[144:145], off
	s_barrier
	s_waitcnt lgkmcnt(0)
	s_setprio 1
	v_mfma_f32_16x16x32_bf16 v[94:97], v[200:203], v[168:171], v[94:97]
	v_mfma_f32_16x16x32_bf16 v[78:81], v[204:207], v[168:171], v[78:81]
	v_mfma_f32_16x16x32_bf16 v[62:65], v[200:203], v[176:179], v[62:65]
	v_mfma_f32_16x16x32_bf16 v[50:53], v[204:207], v[176:179], v[50:53]
	v_mfma_f32_16x16x32_bf16 v[46:49], v[200:203], v[184:187], v[46:49]
	v_mfma_f32_16x16x32_bf16 v[42:45], v[204:207], v[184:187], v[42:45]
	v_mfma_f32_16x16x32_bf16 v[38:41], v[200:203], v[192:195], v[38:41]
	v_mfma_f32_16x16x32_bf16 v[34:37], v[204:207], v[192:195], v[34:37]
	v_mfma_f32_16x16x32_bf16 v[94:97], v[208:211], v[172:175], v[94:97]
	v_mfma_f32_16x16x32_bf16 v[78:81], v[212:215], v[172:175], v[78:81]
	v_mfma_f32_16x16x32_bf16 v[62:65], v[208:211], v[180:183], v[62:65]
	v_mfma_f32_16x16x32_bf16 v[50:53], v[212:215], v[180:183], v[50:53]
	v_mfma_f32_16x16x32_bf16 v[46:49], v[208:211], v[188:191], v[46:49]
	v_mfma_f32_16x16x32_bf16 v[42:45], v[212:215], v[188:191], v[42:45]
	v_mfma_f32_16x16x32_bf16 v[38:41], v[208:211], v[196:199], v[38:41]
	v_mfma_f32_16x16x32_bf16 v[34:37], v[212:215], v[196:199], v[34:37]
	s_setprio 0
	s_add_u32 s54, s9, s14
	s_addc_u32 s55, s31, s15
	s_add_u32 s42, s54, 0x100
	s_addc_u32 s43, s55, 0
	v_readfirstlane_b32 s68, v155
	v_lshl_add_u64 v[144:145], s[42:43], 0, v[0:1]
	s_mov_b32 m0, s68
	s_barrier
	ds_read_b128 v[168:171], v167 offset:16384
	ds_read_b128 v[172:175], v167 offset:17408
	ds_read_b128 v[176:179], v167 offset:18432
	ds_read_b128 v[180:183], v167 offset:19456
	ds_read_b128 v[184:187], v167 offset:20480
	ds_read_b128 v[188:191], v167 offset:21504
	ds_read_b128 v[192:195], v167 offset:22528
	ds_read_b128 v[196:199], v167 offset:23552
	global_load_lds_dwordx4 v[144:145], off
	v_lshl_add_u64 v[144:145], s[42:43], 0, v[146:147]
	v_readfirstlane_b32 s42, v156
	s_mov_b32 m0, s42
	s_nop 0
	global_load_lds_dwordx4 v[144:145], off
	s_barrier
	s_waitcnt lgkmcnt(0)
	s_setprio 1
	v_mfma_f32_16x16x32_bf16 v[30:33], v[132:135], v[168:171], v[30:33]
	v_mfma_f32_16x16x32_bf16 v[26:29], v[136:139], v[168:171], v[26:29]
	v_mfma_f32_16x16x32_bf16 v[22:25], v[132:135], v[176:179], v[22:25]
	v_mfma_f32_16x16x32_bf16 v[18:21], v[136:139], v[176:179], v[18:21]
	v_mfma_f32_16x16x32_bf16 v[14:17], v[132:135], v[184:187], v[14:17]
	v_mfma_f32_16x16x32_bf16 v[10:13], v[136:139], v[184:187], v[10:13]
	v_mfma_f32_16x16x32_bf16 v[6:9], v[132:135], v[192:195], v[6:9]
	v_mfma_f32_16x16x32_bf16 v[2:5], v[136:139], v[192:195], v[2:5]
	v_mfma_f32_16x16x32_bf16 v[30:33], v[140:143], v[172:175], v[30:33]
	v_mfma_f32_16x16x32_bf16 v[26:29], v[148:151], v[172:175], v[26:29]
	v_mfma_f32_16x16x32_bf16 v[22:25], v[140:143], v[180:183], v[22:25]
	v_mfma_f32_16x16x32_bf16 v[18:21], v[148:151], v[180:183], v[18:21]
	v_mfma_f32_16x16x32_bf16 v[14:17], v[140:143], v[188:191], v[14:17]
	v_mfma_f32_16x16x32_bf16 v[10:13], v[148:151], v[188:191], v[10:13]
	v_mfma_f32_16x16x32_bf16 v[6:9], v[140:143], v[196:199], v[6:9]
	v_mfma_f32_16x16x32_bf16 v[2:5], v[148:151], v[196:199], v[2:5]
	s_setprio 0
	s_barrier
; #define STAGEA(P, br, kt) do { const char* _g = uptr(A + (size_t)(br) * lda + (size_t)(kt) * BK); \
;     _Pragma("unroll") for (int _i = 0; _i < 2; ++_i) { \
;       __builtin_amdgcn_global_load_lds((const unsigned*)(_g + offA[_i]), (unsigned*)((char*)(P) + tidx * 16 + _i * 8192), 16, 0, 0); } } while (0)
; #define STAGEB(P, br, kt) do { const char* _g = uptr(Bt + (size_t)(br) * ldb + (size_t)(kt) * BK); \
;     _Pragma("unroll") for (int _i = 0; _i < 2; ++_i) { \
;       __builtin_amdgcn_global_load_lds((const unsigned*)(_g + offB[_i]), (unsigned*)((char*)(P) + tidx * 16 + _i * 8192), 16, 0, 0); } } while (0)
; #define LDA(dst, b, h) _Pragma("unroll") for (int m = 0; m < 4; ++m) _Pragma("unroll") for (int k = 0; k < 2; ++k) \
;     dst[m][k] = *reinterpret_cast<const bf16x8*>((char*)SA(b, h) + aoff + m * 2048 + k * 1024)
; #define LDB(dst, b, h) _Pragma("unroll") for (int n = 0; n < 2; ++n) _Pragma("unroll") for (int k = 0; k < 2; ++k) \
;     dst[n][k] = *reinterpret_cast<const bf16x8*>((char*)SB(b, h) + boff + n * (SWAP ? 256 : 2048) + k * 1024)
; #define WAIT_V(n) asm volatile("s_waitcnt vmcnt(" #n ")" ::: "memory")
; #define WAIT_L(n) asm volatile("s_waitcnt lgkmcnt(" #n ")" ::: "memory")
; template <int EPI>
; DI void gemm_phase(const u16* __restrict__ A, int lda, const u16* __restrict__ Bt, int ldb,
;                    int M, int N, int K, const Epi& e, unsigned char* shmraw, int wv, int slot) {
;     ...
;     for (int t = 0; t < nt - 2; t += 2) {
;       LDB(B0, 0, 0); SCHED; LDA(At, 0, 0); STAGEA(SA(1, 1), brow + HALF, t + 1);
;       WAIT_L(8); BAR; WAIT_L(0); MMA(0, 0, At, B0); BAR; SCHED;
;       LDB(B1, 0, 1); STAGEB(SB(0, 0), bcol, t + 2);
;       BAR; WAIT_L(0); MMA(0, 1, At, B1); BAR;
;       LDA(At, 0, 1); STAGEA(SA(0, 0), brow, t + 2);
;       BAR; WAIT_L(0); MMA(1, 0, At, B0); BAR; SCHED;
;       STAGEB(SB(0, 1), bcol + HALF, t + 2);
;       WAIT_V(6); BAR; MMA(1, 1, At, B1); BAR;
;       LDB(B0, 1, 0); SCHED; LDA(At, 1, 0); STAGEA(SA(0, 1), brow + HALF, t + 2);
;       WAIT_L(8); BAR; WAIT_L(0); MMA(0, 0, At, B0); BAR; SCHED;
;       LDB(B1, 1, 1); STAGEB(SB(1, 0), bcol, t + 3);
;       BAR; WAIT_L(0); MMA(0, 1, At, B1); BAR;
;       LDA(At, 1, 1); STAGEA(SA(1, 0), brow, t + 3);
;       BAR; WAIT_L(0); MMA(1, 0, At, B0); BAR; SCHED;
;       STAGEB(SB(1, 1), bcol + HALF, t + 3);
;       WAIT_V(6); BAR; MMA(1, 1, At, B1); BAR;
	s_add_u32 s68, s35, s14
	s_addc_u32 s69, s38, s15
	s_add_u32 s42, s68, 0x100
	s_addc_u32 s43, s69, 0
	v_readfirstlane_b32 s70, v157
	v_lshl_add_u64 v[132:133], s[42:43], 0, v[0:1]
	s_mov_b32 m0, s70
	s_nop 0
	global_load_lds_dwordx4 v[132:133], off
	v_lshl_add_u64 v[132:133], s[42:43], 0, v[146:147]
	v_readfirstlane_b32 s42, v158
	s_mov_b32 m0, s42
	s_nop 0
	global_load_lds_dwordx4 v[132:133], off
	s_waitcnt vmcnt(6)
	s_barrier
	s_setprio 1
	v_mfma_f32_16x16x32_bf16 v[54:57], v[200:203], v[168:171], v[54:57]
	v_mfma_f32_16x16x32_bf16 v[58:61], v[204:207], v[168:171], v[58:61]
	v_mfma_f32_16x16x32_bf16 v[66:69], v[200:203], v[176:179], v[66:69]
	v_mfma_f32_16x16x32_bf16 v[70:73], v[204:207], v[176:179], v[70:73]
	v_mfma_f32_16x16x32_bf16 v[74:77], v[200:203], v[184:187], v[74:77]
	v_mfma_f32_16x16x32_bf16 v[82:85], v[204:207], v[184:187], v[82:85]
	v_mfma_f32_16x16x32_bf16 v[86:89], v[200:203], v[192:195], v[86:89]
	v_mfma_f32_16x16x32_bf16 v[90:93], v[204:207], v[192:195], v[90:93]
	v_mfma_f32_16x16x32_bf16 v[54:57], v[208:211], v[172:175], v[54:57]
	v_mfma_f32_16x16x32_bf16 v[58:61], v[212:215], v[172:175], v[58:61]
	v_mfma_f32_16x16x32_bf16 v[66:69], v[208:211], v[180:183], v[66:69]
	v_mfma_f32_16x16x32_bf16 v[70:73], v[212:215], v[180:183], v[70:73]
	v_mfma_f32_16x16x32_bf16 v[74:77], v[208:211], v[188:191], v[74:77]
	v_mfma_f32_16x16x32_bf16 v[82:85], v[212:215], v[188:191], v[82:85]
	v_mfma_f32_16x16x32_bf16 v[86:89], v[208:211], v[196:199], v[86:89]
	v_mfma_f32_16x16x32_bf16 v[90:93], v[212:215], v[196:199], v[90:93]
	s_setprio 0
	v_add_u32_e32 v144, s85, v152
	s_barrier
	ds_read_b128 v[132:135], v144
	ds_read_b128 v[136:139], v144 offset:256
	ds_read_b128 v[140:143], v144 offset:1024
	ds_read_b128 v[148:151], v144 offset:1280
	s_add_u32 s42, s39, s14
	s_addc_u32 s43, s40, s15
	v_readfirstlane_b32 s70, v159
	v_lshl_add_u64 v[144:145], s[42:43], 0, v[0:1]
	s_mov_b32 m0, s70
	ds_read_b128 v[168:171], v167 offset:32768
	ds_read_b128 v[172:175], v167 offset:33792
	ds_read_b128 v[176:179], v167 offset:34816
	ds_read_b128 v[180:183], v167 offset:35840
	ds_read_b128 v[184:187], v167 offset:36864
	ds_read_b128 v[188:191], v167 offset:37888
	ds_read_b128 v[192:195], v167 offset:38912
	ds_read_b128 v[196:199], v167 offset:39936
	global_load_lds_dwordx4 v[144:145], off
	v_lshl_add_u64 v[144:145], s[42:43], 0, v[146:147]
	v_readfirstlane_b32 s42, v160
	s_mov_b32 m0, s42
	s_nop 0
	global_load_lds_dwordx4 v[144:145], off
	s_waitcnt lgkmcnt(8)
	s_barrier
	s_waitcnt lgkmcnt(0)
	s_setprio 1
	v_mfma_f32_16x16x32_bf16 v[126:129], v[132:135], v[168:171], v[126:129]
	v_mfma_f32_16x16x32_bf16 v[122:125], v[136:139], v[168:171], v[122:125]
	v_mfma_f32_16x16x32_bf16 v[118:121], v[132:135], v[176:179], v[118:121]
	v_mfma_f32_16x16x32_bf16 v[114:117], v[136:139], v[176:179], v[114:117]
	v_mfma_f32_16x16x32_bf16 v[110:113], v[132:135], v[184:187], v[110:113]
	v_mfma_f32_16x16x32_bf16 v[106:109], v[136:139], v[184:187], v[106:109]
	v_mfma_f32_16x16x32_bf16 v[102:105], v[132:135], v[192:195], v[102:105]
	v_mfma_f32_16x16x32_bf16 v[98:101], v[136:139], v[192:195], v[98:101]
	v_mfma_f32_16x16x32_bf16 v[126:129], v[140:143], v[172:175], v[126:129]
	v_mfma_f32_16x16x32_bf16 v[122:125], v[148:151], v[172:175], v[122:125]
	v_mfma_f32_16x16x32_bf16 v[118:121], v[140:143], v[180:183], v[118:121]
	v_mfma_f32_16x16x32_bf16 v[114:117], v[148:151], v[180:183], v[114:117]
	v_mfma_f32_16x16x32_bf16 v[110:113], v[140:143], v[188:191], v[110:113]
	v_mfma_f32_16x16x32_bf16 v[106:109], v[148:151], v[188:191], v[106:109]
	v_mfma_f32_16x16x32_bf16 v[102:105], v[140:143], v[196:199], v[102:105]
	v_mfma_f32_16x16x32_bf16 v[98:101], v[148:151], v[196:199], v[98:101]
	s_setprio 0
	s_barrier
	s_add_u32 s42, s11, 0x180
	v_add_u32_e32 v144, s86, v152
	s_addc_u32 s43, s37, 0
	v_readfirstlane_b32 s11, v161
	ds_read_b128 v[200:203], v144
	ds_read_b128 v[204:207], v144 offset:256
	ds_read_b128 v[208:211], v144 offset:1024
	ds_read_b128 v[212:215], v144 offset:1280
	v_lshl_add_u64 v[144:145], s[42:43], 0, v[0:1]
	s_mov_b32 m0, s11
	v_readfirstlane_b32 s11, v162
	global_load_lds_dwordx4 v[144:145], off
	v_lshl_add_u64 v[144:145], s[42:43], 0, v[146:147]
	s_mov_b32 m0, s11
	s_nop 0
	global_load_lds_dwordx4 v[144:145], off
	s_barrier
	s_waitcnt lgkmcnt(0)
	s_setprio 1
	v_mfma_f32_16x16x32_bf16 v[94:97], v[200:203], v[168:171], v[94:97]
	v_mfma_f32_16x16x32_bf16 v[78:81], v[204:207], v[168:171], v[78:81]
	v_mfma_f32_16x16x32_bf16 v[62:65], v[200:203], v[176:179], v[62:65]
	v_mfma_f32_16x16x32_bf16 v[50:53], v[204:207], v[176:179], v[50:53]
	v_mfma_f32_16x16x32_bf16 v[46:49], v[200:203], v[184:187], v[46:49]
	v_mfma_f32_16x16x32_bf16 v[42:45], v[204:207], v[184:187], v[42:45]
	v_mfma_f32_16x16x32_bf16 v[38:41], v[200:203], v[192:195], v[38:41]
	v_mfma_f32_16x16x32_bf16 v[34:37], v[204:207], v[192:195], v[34:37]
	v_mfma_f32_16x16x32_bf16 v[94:97], v[208:211], v[172:175], v[94:97]
	v_mfma_f32_16x16x32_bf16 v[78:81], v[212:215], v[172:175], v[78:81]
	v_mfma_f32_16x16x32_bf16 v[62:65], v[208:211], v[180:183], v[62:65]
	v_mfma_f32_16x16x32_bf16 v[50:53], v[212:215], v[180:183], v[50:53]
	v_mfma_f32_16x16x32_bf16 v[46:49], v[208:211], v[188:191], v[46:49]
	v_mfma_f32_16x16x32_bf16 v[42:45], v[212:215], v[188:191], v[42:45]
	v_mfma_f32_16x16x32_bf16 v[38:41], v[208:211], v[196:199], v[38:41]
	v_mfma_f32_16x16x32_bf16 v[34:37], v[212:215], v[196:199], v[34:37]
	s_setprio 0
	s_add_u32 s42, s54, 0x180
	s_addc_u32 s43, s55, 0
	v_readfirstlane_b32 s11, v163
	v_lshl_add_u64 v[144:145], s[42:43], 0, v[0:1]
	s_mov_b32 m0, s11
	v_readfirstlane_b32 s11, v164
	s_barrier
; #define STAGEA(P, br, kt) do { const char* _g = uptr(A + (size_t)(br) * lda + (size_t)(kt) * BK); \
;     _Pragma("unroll") for (int _i = 0; _i < 2; ++_i) { \
;       __builtin_amdgcn_global_load_lds((const unsigned*)(_g + offA[_i]), (unsigned*)((char*)(P) + tidx * 16 + _i * 8192), 16, 0, 0); } } while (0)
; #define STAGEB(P, br, kt) do { const char* _g = uptr(Bt + (size_t)(br) * ldb + (size_t)(kt) * BK); \
;     _Pragma("unroll") for (int _i = 0; _i < 2; ++_i) { \
;       __builtin_amdgcn_global_load_lds((const unsigned*)(_g + offB[_i]), (unsigned*)((char*)(P) + tidx * 16 + _i * 8192), 16, 0, 0); } } while (0)
; #define LDA(dst, b, h) _Pragma("unroll") for (int m = 0; m < 4; ++m) _Pragma("unroll") for (int k = 0; k < 2; ++k) \
;     dst[m][k] = *reinterpret_cast<const bf16x8*>((char*)SA(b, h) + aoff + m * 2048 + k * 1024)
; #define LDB(dst, b, h) _Pragma("unroll") for (int n = 0; n < 2; ++n) _Pragma("unroll") for (int k = 0; k < 2; ++k) \
;     dst[n][k] = *reinterpret_cast<const bf16x8*>((char*)SB(b, h) + boff + n * (SWAP ? 256 : 2048) + k * 1024)
; #define WAIT_V(n) asm volatile("s_waitcnt vmcnt(" #n ")" ::: "memory")
; #define WAIT_L(n) asm volatile("s_waitcnt lgkmcnt(" #n ")" ::: "memory")
; #define BAR __builtin_amdgcn_s_barrier()
; #define SCHED __builtin_amdgcn_sched_barrier(0)
; template <int EPI>
; DI void gemm_phase(const u16* __restrict__ A, int lda, const u16* __restrict__ Bt, int ldb,
;                    int M, int N, int K, const Epi& e, unsigned char* shmraw, int wv, int slot) {
;     ...
;       BAR; WAIT_L(0); MMA(1, 0, At, B0); BAR; SCHED;
;       STAGEB(SB(1, 1), bcol + HALF, t + 3);
;       WAIT_V(6); BAR; MMA(1, 1, At, B1); BAR;
;     }
;     { LDB(B0, 0, 0); LDA(At, 0, 0); STAGEA(SA(1, 1), brow + HALF, nt - 1);
;       BAR; WAIT_L(0); MMA(0, 0, At, B0); BAR;
	ds_read_b128 v[168:171], v167 offset:49152
	ds_read_b128 v[172:175], v167 offset:50176
	ds_read_b128 v[176:179], v167 offset:51200
	ds_read_b128 v[180:183], v167 offset:52224
	ds_read_b128 v[184:187], v167 offset:53248
	ds_read_b128 v[188:191], v167 offset:54272
	ds_read_b128 v[192:195], v167 offset:55296
	ds_read_b128 v[196:199], v167 offset:56320
	global_load_lds_dwordx4 v[144:145], off
	v_lshl_add_u64 v[144:145], s[42:43], 0, v[146:147]
	s_mov_b32 m0, s11
	s_nop 0
	global_load_lds_dwordx4 v[144:145], off
	s_barrier
	s_waitcnt lgkmcnt(0)
	s_setprio 1
	v_mfma_f32_16x16x32_bf16 v[30:33], v[132:135], v[168:171], v[30:33]
	v_mfma_f32_16x16x32_bf16 v[26:29], v[136:139], v[168:171], v[26:29]
	v_mfma_f32_16x16x32_bf16 v[22:25], v[132:135], v[176:179], v[22:25]
	v_mfma_f32_16x16x32_bf16 v[18:21], v[136:139], v[176:179], v[18:21]
	v_mfma_f32_16x16x32_bf16 v[14:17], v[132:135], v[184:187], v[14:17]
	v_mfma_f32_16x16x32_bf16 v[10:13], v[136:139], v[184:187], v[10:13]
	v_mfma_f32_16x16x32_bf16 v[6:9], v[132:135], v[192:195], v[6:9]
	v_mfma_f32_16x16x32_bf16 v[2:5], v[136:139], v[192:195], v[2:5]
	v_mfma_f32_16x16x32_bf16 v[30:33], v[140:143], v[172:175], v[30:33]
	v_mfma_f32_16x16x32_bf16 v[26:29], v[148:151], v[172:175], v[26:29]
	v_mfma_f32_16x16x32_bf16 v[22:25], v[140:143], v[180:183], v[22:25]
	v_mfma_f32_16x16x32_bf16 v[18:21], v[148:151], v[180:183], v[18:21]
	v_mfma_f32_16x16x32_bf16 v[14:17], v[140:143], v[188:191], v[14:17]
	v_mfma_f32_16x16x32_bf16 v[10:13], v[148:151], v[188:191], v[10:13]
	v_mfma_f32_16x16x32_bf16 v[6:9], v[140:143], v[196:199], v[6:9]
	v_mfma_f32_16x16x32_bf16 v[2:5], v[148:151], v[196:199], v[2:5]
	s_setprio 0
	s_barrier
	s_add_u32 s42, s68, 0x180
	s_addc_u32 s43, s69, 0
	v_readfirstlane_b32 s11, v165
	v_lshl_add_u64 v[132:133], s[42:43], 0, v[0:1]
	s_mov_b32 m0, s11
	v_readfirstlane_b32 s11, v166
	global_load_lds_dwordx4 v[132:133], off
	v_lshl_add_u64 v[132:133], s[42:43], 0, v[146:147]
	s_mov_b32 m0, s11
	s_nop 0
	global_load_lds_dwordx4 v[132:133], off
	s_waitcnt vmcnt(6)
	s_barrier
	s_setprio 1
	v_mfma_f32_16x16x32_bf16 v[54:57], v[200:203], v[168:171], v[54:57]
	v_mfma_f32_16x16x32_bf16 v[58:61], v[204:207], v[168:171], v[58:61]
	v_mfma_f32_16x16x32_bf16 v[66:69], v[200:203], v[176:179], v[66:69]
	v_mfma_f32_16x16x32_bf16 v[70:73], v[204:207], v[176:179], v[70:73]
	v_mfma_f32_16x16x32_bf16 v[74:77], v[200:203], v[184:187], v[74:77]
	v_mfma_f32_16x16x32_bf16 v[82:85], v[204:207], v[184:187], v[82:85]
	v_mfma_f32_16x16x32_bf16 v[86:89], v[200:203], v[192:195], v[86:89]
	v_mfma_f32_16x16x32_bf16 v[90:93], v[204:207], v[192:195], v[90:93]
	v_mfma_f32_16x16x32_bf16 v[54:57], v[208:211], v[172:175], v[54:57]
	v_mfma_f32_16x16x32_bf16 v[58:61], v[212:215], v[172:175], v[58:61]
	v_mfma_f32_16x16x32_bf16 v[66:69], v[208:211], v[180:183], v[66:69]
	v_mfma_f32_16x16x32_bf16 v[70:73], v[212:215], v[180:183], v[70:73]
	v_mfma_f32_16x16x32_bf16 v[74:77], v[208:211], v[188:191], v[74:77]
	v_mfma_f32_16x16x32_bf16 v[82:85], v[212:215], v[188:191], v[82:85]
	v_mfma_f32_16x16x32_bf16 v[86:89], v[208:211], v[196:199], v[86:89]
	v_mfma_f32_16x16x32_bf16 v[90:93], v[212:215], v[196:199], v[90:93]
	s_setprio 0
	s_add_i32 s36, s36, 2
	s_add_u32 s14, s14, 0x100
	s_addc_u32 s15, s15, 0
	s_cmp_lt_u32 s36, 12
	s_barrier
	s_cbranch_scc1 .LBB0_1106
	v_add_u32_e32 v228, 16, v152
	s_add_u32 s14, s28, 0x780
	v_add_u32_e32 v144, 0x10000, v228
	s_addc_u32 s15, s29, 0
	v_readfirstlane_b32 s1, v130
	ds_read_b128 v[132:135], v144
	ds_read_b128 v[136:139], v144 offset:256
	ds_read_b128 v[140:143], v144 offset:1024
	ds_read_b128 v[148:151], v144 offset:1280
	ds_read_b128 v[168:171], v167
	ds_read_b128 v[172:175], v167 offset:1024
	ds_read_b128 v[176:179], v167 offset:2048
	ds_read_b128 v[180:183], v167 offset:3072
	ds_read_b128 v[184:187], v167 offset:4096
	ds_read_b128 v[188:191], v167 offset:5120
	ds_read_b128 v[192:195], v167 offset:6144
	ds_read_b128 v[196:199], v167 offset:7168
	v_lshl_add_u64 v[144:145], s[14:15], 0, v[0:1]
	s_mov_b32 m0, s1
	v_readfirstlane_b32 s1, v131
	global_load_lds_dwordx4 v[144:145], off
	v_lshl_add_u64 v[144:145], s[14:15], 0, v[146:147]
	s_mov_b32 m0, s1
	s_nop 0
	global_load_lds_dwordx4 v[144:145], off
	s_barrier
	s_waitcnt lgkmcnt(0)
	s_setprio 1
	v_mfma_f32_16x16x32_bf16 v[126:129], v[132:135], v[168:171], v[126:129]
	v_mfma_f32_16x16x32_bf16 v[122:125], v[136:139], v[168:171], v[122:125]
	v_mfma_f32_16x16x32_bf16 v[118:121], v[132:135], v[176:179], v[118:121]
	v_mfma_f32_16x16x32_bf16 v[114:117], v[136:139], v[176:179], v[114:117]
	v_mfma_f32_16x16x32_bf16 v[110:113], v[132:135], v[184:187], v[110:113]
	v_mfma_f32_16x16x32_bf16 v[102:105], v[132:135], v[192:195], v[102:105]
	v_mfma_f32_16x16x32_bf16 v[126:129], v[140:143], v[172:175], v[126:129]
	v_mfma_f32_16x16x32_bf16 v[122:125], v[148:151], v[172:175], v[122:125]
	v_mfma_f32_16x16x32_bf16 v[118:121], v[140:143], v[180:183], v[118:121]
	v_mfma_f32_16x16x32_bf16 v[114:117], v[148:151], v[180:183], v[114:117]
	v_mfma_f32_16x16x32_bf16 v[110:113], v[140:143], v[188:191], v[110:113]
	v_mfma_f32_16x16x32_bf16 v[106:109], v[136:139], v[184:187], v[106:109]
	v_mfma_f32_16x16x32_bf16 v[102:105], v[140:143], v[196:199], v[102:105]
	v_mfma_f32_16x16x32_bf16 v[98:101], v[136:139], v[192:195], v[98:101]
	v_mfma_f32_16x16x32_bf16 v[200:203], v[148:151], v[188:191], v[106:109]
	v_mfma_f32_16x16x32_bf16 v[204:207], v[148:151], v[196:199], v[98:101]
	s_setprio 0
	v_add_u32_e32 v130, 0x14000, v228
	s_barrier
	s_nop 2
	ds_read_b128 v[98:101], v130
	ds_read_b128 v[106:109], v130 offset:256
	ds_read_b128 v[208:211], v130 offset:1024
	ds_read_b128 v[212:215], v130 offset:1280
	s_barrier
; #define LDA(dst, b, h) _Pragma("unroll") for (int m = 0; m < 4; ++m) _Pragma("unroll") for (int k = 0; k < 2; ++k) \
;     dst[m][k] = *reinterpret_cast<const bf16x8*>((char*)SA(b, h) + aoff + m * 2048 + k * 1024)
; #define LDB(dst, b, h) _Pragma("unroll") for (int n = 0; n < 2; ++n) _Pragma("unroll") for (int k = 0; k < 2; ++k) \
;     dst[n][k] = *reinterpret_cast<const bf16x8*>((char*)SB(b, h) + boff + n * (SWAP ? 256 : 2048) + k * 1024)
; #define WAIT_V(n) asm volatile("s_waitcnt vmcnt(" #n ")" ::: "memory")
; #define WAIT_L(n) asm volatile("s_waitcnt lgkmcnt(" #n ")" ::: "memory")
; #define BAR __builtin_amdgcn_s_barrier()
; template <int EPI>
; DI void gemm_phase(const u16* __restrict__ A, int lda, const u16* __restrict__ Bt, int ldb,
;                    int M, int N, int K, const Epi& e, unsigned char* shmraw, int wv, int slot) {
;     ...
;       BAR; WAIT_L(0); MMA(0, 0, At, B0); BAR;
;       LDB(B1, 0, 1); BAR; WAIT_L(0); MMA(0, 1, At, B1); BAR;
;       LDA(At, 0, 1); WAIT_V(4); BAR; WAIT_L(0); MMA(1, 0, At, B0); MMA(1, 1, At, B1); BAR; }
;     { LDB(B0, 1, 0); LDA(At, 1, 0); WAIT_V(2); BAR; WAIT_L(0); MMA(0, 0, At, B0); BAR;
	s_waitcnt lgkmcnt(0)
	s_setprio 1
	v_mfma_f32_16x16x32_bf16 v[94:97], v[98:101], v[168:171], v[94:97]
	v_mfma_f32_16x16x32_bf16 v[78:81], v[106:109], v[168:171], v[78:81]
	v_mfma_f32_16x16x32_bf16 v[62:65], v[98:101], v[176:179], v[62:65]
	v_mfma_f32_16x16x32_bf16 v[50:53], v[106:109], v[176:179], v[50:53]
	v_mfma_f32_16x16x32_bf16 v[46:49], v[98:101], v[184:187], v[46:49]
	v_mfma_f32_16x16x32_bf16 v[42:45], v[106:109], v[184:187], v[42:45]
	v_mfma_f32_16x16x32_bf16 v[38:41], v[98:101], v[192:195], v[38:41]
	v_mfma_f32_16x16x32_bf16 v[34:37], v[106:109], v[192:195], v[34:37]
	v_mfma_f32_16x16x32_bf16 v[94:97], v[208:211], v[172:175], v[94:97]
	v_mfma_f32_16x16x32_bf16 v[78:81], v[212:215], v[172:175], v[78:81]
	v_mfma_f32_16x16x32_bf16 v[62:65], v[208:211], v[180:183], v[62:65]
	v_mfma_f32_16x16x32_bf16 v[50:53], v[212:215], v[180:183], v[50:53]
	v_mfma_f32_16x16x32_bf16 v[46:49], v[208:211], v[188:191], v[46:49]
	v_mfma_f32_16x16x32_bf16 v[42:45], v[212:215], v[188:191], v[42:45]
	v_mfma_f32_16x16x32_bf16 v[38:41], v[208:211], v[196:199], v[38:41]
	v_mfma_f32_16x16x32_bf16 v[34:37], v[212:215], v[196:199], v[34:37]
	s_setprio 0
	s_barrier
	ds_read_b128 v[168:171], v167 offset:16384
	ds_read_b128 v[172:175], v167 offset:17408
	ds_read_b128 v[176:179], v167 offset:18432
	ds_read_b128 v[180:183], v167 offset:19456
	ds_read_b128 v[184:187], v167 offset:20480
	ds_read_b128 v[188:191], v167 offset:21504
	ds_read_b128 v[192:195], v167 offset:22528
	ds_read_b128 v[196:199], v167 offset:23552
	s_waitcnt vmcnt(4)
	s_barrier
	s_waitcnt lgkmcnt(0)
	s_setprio 1
	v_mfma_f32_16x16x32_bf16 v[14:17], v[132:135], v[184:187], v[14:17]
	v_mfma_f32_16x16x32_bf16 v[10:13], v[136:139], v[184:187], v[10:13]
	v_mfma_f32_16x16x32_bf16 v[6:9], v[132:135], v[192:195], v[6:9]
	v_mfma_f32_16x16x32_bf16 v[2:5], v[136:139], v[192:195], v[2:5]
	v_mfma_f32_16x16x32_bf16 v[30:33], v[132:135], v[168:171], v[30:33]
	v_mfma_f32_16x16x32_bf16 v[26:29], v[136:139], v[168:171], v[26:29]
	v_mfma_f32_16x16x32_bf16 v[22:25], v[132:135], v[176:179], v[22:25]
	v_mfma_f32_16x16x32_bf16 v[18:21], v[136:139], v[176:179], v[18:21]
	v_mfma_f32_16x16x32_bf16 v[14:17], v[140:143], v[188:191], v[14:17]
	v_mfma_f32_16x16x32_bf16 v[10:13], v[148:151], v[188:191], v[10:13]
	v_mfma_f32_16x16x32_bf16 v[6:9], v[140:143], v[196:199], v[6:9]
	v_mfma_f32_16x16x32_bf16 v[2:5], v[148:151], v[196:199], v[2:5]
	v_mfma_f32_16x16x32_bf16 v[30:33], v[140:143], v[172:175], v[30:33]
	v_mfma_f32_16x16x32_bf16 v[26:29], v[148:151], v[172:175], v[26:29]
	v_mfma_f32_16x16x32_bf16 v[22:25], v[140:143], v[180:183], v[22:25]
	v_mfma_f32_16x16x32_bf16 v[18:21], v[148:151], v[180:183], v[18:21]
	s_setprio 0
	s_setprio 1
	v_mfma_f32_16x16x32_bf16 v[58:61], v[106:109], v[168:171], v[58:61]
	v_mfma_f32_16x16x32_bf16 v[148:151], v[212:215], v[172:175], v[58:61]
	v_mfma_f32_16x16x32_bf16 v[58:61], v[98:101], v[176:179], v[66:69]
	v_mfma_f32_16x16x32_bf16 v[54:57], v[98:101], v[168:171], v[54:57]
	v_mfma_f32_16x16x32_bf16 v[168:171], v[208:211], v[180:183], v[58:61]
	v_mfma_f32_16x16x32_bf16 v[58:61], v[106:109], v[176:179], v[70:73]
	v_mfma_f32_16x16x32_bf16 v[54:57], v[208:211], v[172:175], v[54:57]
	v_mfma_f32_16x16x32_bf16 v[172:175], v[212:215], v[180:183], v[58:61]
	v_mfma_f32_16x16x32_bf16 v[58:61], v[98:101], v[184:187], v[74:77]
	v_mfma_f32_16x16x32_bf16 v[176:179], v[208:211], v[188:191], v[58:61]
	v_mfma_f32_16x16x32_bf16 v[58:61], v[106:109], v[184:187], v[82:85]
	v_mfma_f32_16x16x32_bf16 v[180:183], v[212:215], v[188:191], v[58:61]
	v_mfma_f32_16x16x32_bf16 v[58:61], v[98:101], v[192:195], v[86:89]
	v_mfma_f32_16x16x32_bf16 v[184:187], v[208:211], v[196:199], v[58:61]
	v_mfma_f32_16x16x32_bf16 v[58:61], v[106:109], v[192:195], v[90:93]
	v_mfma_f32_16x16x32_bf16 v[188:191], v[212:215], v[196:199], v[58:61]
	s_setprio 0
	s_nop 5
	v_add_u32_e32 v58, 0x18000, v228
	s_barrier
	ds_read_b128 v[66:69], v58
	ds_read_b128 v[70:73], v58 offset:256
	ds_read_b128 v[192:195], v58 offset:1024
	ds_read_b128 v[196:199], v58 offset:1280
	ds_read_b128 v[58:61], v167 offset:32768
	ds_read_b128 v[74:77], v167 offset:33792
	ds_read_b128 v[86:89], v167 offset:34816
	ds_read_b128 v[208:211], v167 offset:35840
	ds_read_b128 v[212:215], v167 offset:36864
	ds_read_b128 v[216:219], v167 offset:37888
	ds_read_b128 v[220:223], v167 offset:38912
	ds_read_b128 v[224:227], v167 offset:39936
	s_waitcnt vmcnt(2)
	s_barrier
; #define LDA(dst, b, h) _Pragma("unroll") for (int m = 0; m < 4; ++m) _Pragma("unroll") for (int k = 0; k < 2; ++k) \
;     dst[m][k] = *reinterpret_cast<const bf16x8*>((char*)SA(b, h) + aoff + m * 2048 + k * 1024)
; #define LDB(dst, b, h) _Pragma("unroll") for (int n = 0; n < 2; ++n) _Pragma("unroll") for (int k = 0; k < 2; ++k) \
;     dst[n][k] = *reinterpret_cast<const bf16x8*>((char*)SB(b, h) + boff + n * (SWAP ? 256 : 2048) + k * 1024)
; #define WAIT_V(n) asm volatile("s_waitcnt vmcnt(" #n ")" ::: "memory")
; #define WAIT_L(n) asm volatile("s_waitcnt lgkmcnt(" #n ")" ::: "memory")
; #define BAR __builtin_amdgcn_s_barrier()
; template <int EPI>
; DI void gemm_phase(const u16* __restrict__ A, int lda, const u16* __restrict__ Bt, int ldb,
;                    int M, int N, int K, const Epi& e, unsigned char* shmraw, int wv, int slot) {
;     ...
;     { LDB(B0, 1, 0); LDA(At, 1, 0); WAIT_V(2); BAR; WAIT_L(0); MMA(0, 0, At, B0); BAR;
;       LDB(B1, 1, 1); WAIT_V(0); BAR; WAIT_L(0); MMA(0, 1, At, B1); BAR;
;       LDA(At, 1, 1); BAR; WAIT_L(0); MMA(1, 0, At, B0); MMA(1, 1, At, B1); BAR; }
;     if (wr == 0) BAR;
	s_waitcnt lgkmcnt(0)
	s_setprio 1
	v_mfma_f32_16x16x32_bf16 v[82:85], v[66:69], v[58:61], v[126:129]
	v_mfma_f32_16x16x32_bf16 v[142:145], v[192:195], v[74:77], v[82:85]
	v_mfma_f32_16x16x32_bf16 v[82:85], v[70:73], v[58:61], v[122:125]
	v_mfma_f32_16x16x32_bf16 v[138:141], v[196:199], v[74:77], v[82:85]
	v_mfma_f32_16x16x32_bf16 v[82:85], v[66:69], v[86:89], v[118:121]
	v_mfma_f32_16x16x32_bf16 v[122:125], v[192:195], v[208:211], v[82:85]
	v_mfma_f32_16x16x32_bf16 v[82:85], v[70:73], v[86:89], v[114:117]
	v_mfma_f32_16x16x32_bf16 v[114:117], v[196:199], v[208:211], v[82:85]
	v_mfma_f32_16x16x32_bf16 v[82:85], v[66:69], v[212:215], v[110:113]
	v_mfma_f32_16x16x32_bf16 v[106:109], v[192:195], v[216:219], v[82:85]
	v_mfma_f32_16x16x32_bf16 v[82:85], v[70:73], v[212:215], v[200:203]
	v_mfma_f32_16x16x32_bf16 v[98:101], v[196:199], v[216:219], v[82:85]
	v_mfma_f32_16x16x32_bf16 v[82:85], v[66:69], v[220:223], v[102:105]
	v_mfma_f32_16x16x32_bf16 v[90:93], v[192:195], v[224:227], v[82:85]
	v_mfma_f32_16x16x32_bf16 v[82:85], v[70:73], v[220:223], v[204:207]
	v_mfma_f32_16x16x32_bf16 v[82:85], v[196:199], v[224:227], v[82:85]
	s_setprio 0
	v_add_u32_e32 v102, 0x1c000, v228
	s_barrier
	ds_read_b128 v[200:203], v102
	ds_read_b128 v[204:207], v102 offset:256
	ds_read_b128 v[228:231], v102 offset:1024
	ds_read_b128 v[232:235], v102 offset:1280
	s_waitcnt vmcnt(0)
	s_barrier
	s_waitcnt lgkmcnt(0)
	s_setprio 1
	v_mfma_f32_16x16x32_bf16 v[94:97], v[200:203], v[58:61], v[94:97]
	v_mfma_f32_16x16x32_bf16 v[58:61], v[204:207], v[58:61], v[78:81]
	v_mfma_f32_16x16x32_bf16 v[130:133], v[232:235], v[74:77], v[58:61]
	v_mfma_f32_16x16x32_bf16 v[58:61], v[200:203], v[86:89], v[62:65]
	v_mfma_f32_16x16x32_bf16 v[50:53], v[204:207], v[86:89], v[50:53]
	v_mfma_f32_16x16x32_bf16 v[46:49], v[200:203], v[212:215], v[46:49]
	v_mfma_f32_16x16x32_bf16 v[42:45], v[204:207], v[212:215], v[42:45]
	v_mfma_f32_16x16x32_bf16 v[38:41], v[200:203], v[220:223], v[38:41]
	v_mfma_f32_16x16x32_bf16 v[34:37], v[204:207], v[220:223], v[34:37]
	v_mfma_f32_16x16x32_bf16 v[134:137], v[228:231], v[74:77], v[94:97]
	v_mfma_f32_16x16x32_bf16 v[126:129], v[228:231], v[208:211], v[58:61]
	v_mfma_f32_16x16x32_bf16 v[118:121], v[232:235], v[208:211], v[50:53]
	v_mfma_f32_16x16x32_bf16 v[110:113], v[228:231], v[216:219], v[46:49]
	v_mfma_f32_16x16x32_bf16 v[102:105], v[232:235], v[216:219], v[42:45]
	v_mfma_f32_16x16x32_bf16 v[94:97], v[228:231], v[224:227], v[38:41]
	v_mfma_f32_16x16x32_bf16 v[86:89], v[232:235], v[224:227], v[34:37]
	s_setprio 0
	s_barrier
	s_nop 0
	ds_read_b128 v[34:37], v167 offset:49152
	ds_read_b128 v[38:41], v167 offset:50176
	ds_read_b128 v[50:53], v167 offset:51200
	ds_read_b128 v[208:211], v167 offset:52224
	ds_read_b128 v[212:215], v167 offset:53248
	ds_read_b128 v[216:219], v167 offset:54272
	ds_read_b128 v[220:223], v167 offset:55296
	ds_read_b128 v[224:227], v167 offset:56320
	s_barrier
	s_waitcnt lgkmcnt(0)
	s_setprio 1
	v_mfma_f32_16x16x32_bf16 v[30:33], v[66:69], v[34:37], v[30:33]
	v_mfma_f32_16x16x32_bf16 v[26:29], v[70:73], v[34:37], v[26:29]
	v_mfma_f32_16x16x32_bf16 v[22:25], v[66:69], v[50:53], v[22:25]
	v_mfma_f32_16x16x32_bf16 v[18:21], v[70:73], v[50:53], v[18:21]
	v_mfma_f32_16x16x32_bf16 v[14:17], v[66:69], v[212:215], v[14:17]
	v_mfma_f32_16x16x32_bf16 v[10:13], v[70:73], v[212:215], v[10:13]
	v_mfma_f32_16x16x32_bf16 v[6:9], v[66:69], v[220:223], v[6:9]
	v_mfma_f32_16x16x32_bf16 v[2:5], v[70:73], v[220:223], v[2:5]
	v_mfma_f32_16x16x32_bf16 v[78:81], v[192:195], v[38:41], v[30:33]
	v_mfma_f32_16x16x32_bf16 v[74:77], v[196:199], v[38:41], v[26:29]
	v_mfma_f32_16x16x32_bf16 v[62:65], v[192:195], v[208:211], v[22:25]
	v_mfma_f32_16x16x32_bf16 v[58:61], v[196:199], v[208:211], v[18:21]
	v_mfma_f32_16x16x32_bf16 v[46:49], v[192:195], v[216:219], v[14:17]
	v_mfma_f32_16x16x32_bf16 v[42:45], v[196:199], v[216:219], v[10:13]
	v_mfma_f32_16x16x32_bf16 v[14:17], v[192:195], v[224:227], v[6:9]
	v_mfma_f32_16x16x32_bf16 v[10:13], v[196:199], v[224:227], v[2:5]
	s_setprio 0
	s_setprio 1
	v_mfma_f32_16x16x32_bf16 v[2:5], v[200:203], v[34:37], v[54:57]
	v_mfma_f32_16x16x32_bf16 v[70:73], v[228:231], v[38:41], v[2:5]
	v_mfma_f32_16x16x32_bf16 v[2:5], v[204:207], v[34:37], v[148:151]
	v_mfma_f32_16x16x32_bf16 v[66:69], v[232:235], v[38:41], v[2:5]
	v_mfma_f32_16x16x32_bf16 v[2:5], v[200:203], v[50:53], v[168:171]
	v_mfma_f32_16x16x32_bf16 v[54:57], v[228:231], v[208:211], v[2:5]
	v_mfma_f32_16x16x32_bf16 v[2:5], v[204:207], v[50:53], v[172:175]
	v_mfma_f32_16x16x32_bf16 v[50:53], v[232:235], v[208:211], v[2:5]
	v_mfma_f32_16x16x32_bf16 v[2:5], v[200:203], v[212:215], v[176:179]
	v_mfma_f32_16x16x32_bf16 v[38:41], v[228:231], v[216:219], v[2:5]
	v_mfma_f32_16x16x32_bf16 v[2:5], v[204:207], v[212:215], v[180:183]
	v_mfma_f32_16x16x32_bf16 v[34:37], v[232:235], v[216:219], v[2:5]
	v_mfma_f32_16x16x32_bf16 v[2:5], v[200:203], v[220:223], v[184:187]
	v_mfma_f32_16x16x32_bf16 v[6:9], v[228:231], v[224:227], v[2:5]
	v_mfma_f32_16x16x32_bf16 v[2:5], v[204:207], v[220:223], v[188:191]
	v_mfma_f32_16x16x32_bf16 v[2:5], v[232:235], v[224:227], v[2:5]
	s_setprio 0
	s_barrier
	s_and_saveexec_b64 s[14:15], s[4:5]
	s_cbranch_execz .LBB0_1109
	s_barrier

; #define STAGEA(P, br, kt) do { const char* _g = uptr(A + (size_t)(br) * lda + (size_t)(kt) * BK); \
;     _Pragma("unroll") for (int _i = 0; _i < 2; ++_i) { \
;       __builtin_amdgcn_global_load_lds((const unsigned*)(_g + offA[_i]), (unsigned*)((char*)(P) + tidx * 16 + _i * 8192), 16, 0, 0); } } while (0)
; #define STAGEB(P, br, kt) do { const char* _g = uptr(Bt + (size_t)(br) * ldb + (size_t)(kt) * BK); \
;     _Pragma("unroll") for (int _i = 0; _i < 2; ++_i) { \
;       __builtin_amdgcn_global_load_lds((const unsigned*)(_g + offB[_i]), (unsigned*)((char*)(P) + tidx * 16 + _i * 8192), 16, 0, 0); } } while (0)
; #define LDA(dst, b, h) _Pragma("unroll") for (int m = 0; m < 4; ++m) _Pragma("unroll") for (int k = 0; k < 2; ++k) \
;     dst[m][k] = *reinterpret_cast<const bf16x8*>((char*)SA(b, h) + aoff + m * 2048 + k * 1024)
; #define LDB(dst, b, h) _Pragma("unroll") for (int n = 0; n < 2; ++n) _Pragma("unroll") for (int k = 0; k < 2; ++k) \
;     dst[n][k] = *reinterpret_cast<const bf16x8*>((char*)SB(b, h) + boff + n * (SWAP ? 256 : 2048) + k * 1024)
; #define WAIT_V(n) asm volatile("s_waitcnt vmcnt(" #n ")" ::: "memory")
; #define WAIT_L(n) asm volatile("s_waitcnt lgkmcnt(" #n ")" ::: "memory")
; template <int EPI>
; DI void gemm_phase(const u16* __restrict__ A, int lda, const u16* __restrict__ Bt, int ldb,
;                    int M, int N, int K, const Epi& e, unsigned char* shmraw, int wv, int slot) {
;     ...
;     for (int t = 0; t < nt - 2; t += 2) {
;       LDB(B0, 0, 0); SCHED; LDA(At, 0, 0); STAGEA(SA(1, 1), brow + HALF, t + 1);
;       WAIT_L(8); BAR; WAIT_L(0); MMA(0, 0, At, B0); BAR; SCHED;
;       LDB(B1, 0, 1); STAGEB(SB(0, 0), bcol, t + 2);
;       BAR; WAIT_L(0); MMA(0, 1, At, B1); BAR;
;       LDA(At, 0, 1); STAGEA(SA(0, 0), brow, t + 2);
;       BAR; WAIT_L(0); MMA(1, 0, At, B0); BAR; SCHED;
;       STAGEB(SB(0, 1), bcol + HALF, t + 2);
;       WAIT_V(6); BAR; MMA(1, 1, At, B1); BAR;
;       LDB(B0, 1, 0); SCHED; LDA(At, 1, 0); STAGEA(SA(0, 1), brow + HALF, t + 2);
;       WAIT_L(8); BAR; WAIT_L(0); MMA(0, 0, At, B0); BAR; SCHED;
;       LDB(B1, 1, 1); STAGEB(SB(1, 0), bcol, t + 3);
;       BAR; WAIT_L(0); MMA(0, 1, At, B1); BAR;
;       LDA(At, 1, 1); STAGEA(SA(1, 0), brow, t + 3);
;       BAR; WAIT_L(0); MMA(1, 0, At, B0); BAR; SCHED;
;       STAGEB(SB(1, 1), bcol + HALF, t + 3);
;       WAIT_V(6); BAR; MMA(1, 1, At, B1); BAR;
.LBB0_1185:
	v_add_u32_e32 v0, s33, v176
	ds_read_b128 v[132:135], v0
	ds_read_b128 v[136:139], v0 offset:256
	ds_read_b128 v[140:143], v0 offset:1024
	ds_read_b128 v[144:147], v0 offset:1280
	s_add_u32 s11, s74, vcc_lo
	s_addc_u32 s37, s75, vcc_hi
	s_add_u32 s54, s11, 0x80
	v_add_u32_e32 v0, 0xc000, v179
	s_addc_u32 s55, s37, 0
	v_readfirstlane_b32 s76, v0
	v_lshl_add_u64 v[130:131], s[54:55], 0, v[152:153]
	s_mov_b32 m0, s76
	ds_read_b128 v[154:157], v204
	ds_read_b128 v[158:161], v204 offset:1024
	ds_read_b128 v[162:165], v204 offset:2048
	ds_read_b128 v[166:169], v204 offset:3072
	ds_read_b128 v[170:173], v204 offset:4096
	ds_read_b128 v[180:183], v204 offset:5120
	ds_read_b128 v[184:187], v204 offset:6144
	ds_read_b128 v[188:191], v204 offset:7168
	global_load_lds_dwordx4 v[130:131], off
	v_add_u32_e32 v130, 0xe000, v179
	v_lshl_add_u64 v[148:149], s[54:55], 0, v[150:151]
	v_readfirstlane_b32 s54, v130
	s_mov_b32 m0, s54
	s_nop 0
	global_load_lds_dwordx4 v[148:149], off
	s_waitcnt lgkmcnt(8)
	s_barrier
	s_waitcnt lgkmcnt(0)
	s_setprio 1
	v_mfma_f32_16x16x32_bf16 v[126:129], v[132:135], v[154:157], v[126:129]
	v_mfma_f32_16x16x32_bf16 v[122:125], v[136:139], v[154:157], v[122:125]
	v_mfma_f32_16x16x32_bf16 v[118:121], v[132:135], v[162:165], v[118:121]
	v_mfma_f32_16x16x32_bf16 v[114:117], v[136:139], v[162:165], v[114:117]
	v_mfma_f32_16x16x32_bf16 v[110:113], v[132:135], v[170:173], v[110:113]
	v_mfma_f32_16x16x32_bf16 v[106:109], v[136:139], v[170:173], v[106:109]
	v_mfma_f32_16x16x32_bf16 v[102:105], v[132:135], v[184:187], v[102:105]
	v_mfma_f32_16x16x32_bf16 v[98:101], v[136:139], v[184:187], v[98:101]
	v_mfma_f32_16x16x32_bf16 v[126:129], v[140:143], v[158:161], v[126:129]
	v_mfma_f32_16x16x32_bf16 v[122:125], v[144:147], v[158:161], v[122:125]
	v_mfma_f32_16x16x32_bf16 v[118:121], v[140:143], v[166:169], v[118:121]
	v_mfma_f32_16x16x32_bf16 v[114:117], v[144:147], v[166:169], v[114:117]
	v_mfma_f32_16x16x32_bf16 v[110:113], v[140:143], v[180:183], v[110:113]
	v_mfma_f32_16x16x32_bf16 v[106:109], v[144:147], v[180:183], v[106:109]
	v_mfma_f32_16x16x32_bf16 v[102:105], v[140:143], v[188:191], v[102:105]
	v_mfma_f32_16x16x32_bf16 v[98:101], v[144:147], v[188:191], v[98:101]
	s_setprio 0
	s_barrier
	s_add_u32 s76, s35, vcc_lo
	s_addc_u32 s89, s38, vcc_hi
	s_add_u32 s54, s76, 0x100
	s_addc_u32 s55, s89, 0
	v_readfirstlane_b32 s90, v177
	v_add_u32_e32 v131, s84, v176
	v_lshl_add_u64 v[148:149], s[54:55], 0, v[152:153]
	s_mov_b32 m0, s90
	ds_read_b128 v[206:209], v131
	ds_read_b128 v[210:213], v131 offset:256
	ds_read_b128 v[214:217], v131 offset:1024
	ds_read_b128 v[218:221], v131 offset:1280
	global_load_lds_dwordx4 v[148:149], off
	v_lshl_add_u64 v[148:149], s[54:55], 0, v[150:151]
	v_readfirstlane_b32 s54, v178
	s_mov_b32 m0, s54
	s_nop 0
	global_load_lds_dwordx4 v[148:149], off
	s_barrier
	s_waitcnt lgkmcnt(0)
	s_setprio 1
	v_mfma_f32_16x16x32_bf16 v[94:97], v[206:209], v[154:157], v[94:97]
	v_mfma_f32_16x16x32_bf16 v[78:81], v[210:213], v[154:157], v[78:81]
	v_mfma_f32_16x16x32_bf16 v[62:65], v[206:209], v[162:165], v[62:65]
	v_mfma_f32_16x16x32_bf16 v[50:53], v[210:213], v[162:165], v[50:53]
	v_mfma_f32_16x16x32_bf16 v[46:49], v[206:209], v[170:173], v[46:49]
	v_mfma_f32_16x16x32_bf16 v[42:45], v[210:213], v[170:173], v[42:45]
	v_mfma_f32_16x16x32_bf16 v[38:41], v[206:209], v[184:187], v[38:41]
	v_mfma_f32_16x16x32_bf16 v[34:37], v[210:213], v[184:187], v[34:37]
	v_mfma_f32_16x16x32_bf16 v[94:97], v[214:217], v[158:161], v[94:97]
	v_mfma_f32_16x16x32_bf16 v[78:81], v[218:221], v[158:161], v[78:81]
	v_mfma_f32_16x16x32_bf16 v[62:65], v[214:217], v[166:169], v[62:65]
	v_mfma_f32_16x16x32_bf16 v[50:53], v[218:221], v[166:169], v[50:53]
	v_mfma_f32_16x16x32_bf16 v[46:49], v[214:217], v[180:183], v[46:49]
	v_mfma_f32_16x16x32_bf16 v[42:45], v[218:221], v[180:183], v[42:45]
	v_mfma_f32_16x16x32_bf16 v[38:41], v[214:217], v[188:191], v[38:41]
	v_mfma_f32_16x16x32_bf16 v[34:37], v[218:221], v[188:191], v[34:37]
	s_setprio 0
	s_add_u32 s90, s39, vcc_lo
	s_addc_u32 s77, s40, vcc_hi
	s_add_u32 s54, s90, 0x100
	s_addc_u32 s55, s77, 0
	v_readfirstlane_b32 s16, v179
	v_lshl_add_u64 v[148:149], s[54:55], 0, v[152:153]
	s_mov_b32 m0, s16
	v_readfirstlane_b32 s16, v193
	s_barrier
	ds_read_b128 v[154:157], v204 offset:16384
	ds_read_b128 v[158:161], v204 offset:17408
	ds_read_b128 v[162:165], v204 offset:18432
	ds_read_b128 v[166:169], v204 offset:19456
	ds_read_b128 v[170:173], v204 offset:20480
	ds_read_b128 v[180:183], v204 offset:21504
	ds_read_b128 v[184:187], v204 offset:22528
	ds_read_b128 v[188:191], v204 offset:23552
	global_load_lds_dwordx4 v[148:149], off
	v_lshl_add_u64 v[148:149], s[54:55], 0, v[150:151]
	s_mov_b32 m0, s16
	s_nop 0
	global_load_lds_dwordx4 v[148:149], off
	s_barrier
	s_waitcnt lgkmcnt(0)
	s_setprio 1
	v_mfma_f32_16x16x32_bf16 v[30:33], v[132:135], v[154:157], v[30:33]
	v_mfma_f32_16x16x32_bf16 v[26:29], v[136:139], v[154:157], v[26:29]
	v_mfma_f32_16x16x32_bf16 v[22:25], v[132:135], v[162:165], v[22:25]
	v_mfma_f32_16x16x32_bf16 v[18:21], v[136:139], v[162:165], v[18:21]
	v_mfma_f32_16x16x32_bf16 v[14:17], v[132:135], v[170:173], v[14:17]
	v_mfma_f32_16x16x32_bf16 v[10:13], v[136:139], v[170:173], v[10:13]
	v_mfma_f32_16x16x32_bf16 v[6:9], v[132:135], v[184:187], v[6:9]
	v_mfma_f32_16x16x32_bf16 v[2:5], v[136:139], v[184:187], v[2:5]
	v_mfma_f32_16x16x32_bf16 v[30:33], v[140:143], v[158:161], v[30:33]
	v_mfma_f32_16x16x32_bf16 v[26:29], v[144:147], v[158:161], v[26:29]
	v_mfma_f32_16x16x32_bf16 v[22:25], v[140:143], v[166:169], v[22:25]
	v_mfma_f32_16x16x32_bf16 v[18:21], v[144:147], v[166:169], v[18:21]
	v_mfma_f32_16x16x32_bf16 v[14:17], v[140:143], v[180:183], v[14:17]
	v_mfma_f32_16x16x32_bf16 v[10:13], v[144:147], v[180:183], v[10:13]
	v_mfma_f32_16x16x32_bf16 v[6:9], v[140:143], v[188:191], v[6:9]
	v_mfma_f32_16x16x32_bf16 v[2:5], v[144:147], v[188:191], v[2:5]
	s_setprio 0
	s_barrier
; #define STAGEA(P, br, kt) do { const char* _g = uptr(A + (size_t)(br) * lda + (size_t)(kt) * BK); \
;     _Pragma("unroll") for (int _i = 0; _i < 2; ++_i) { \
;       __builtin_amdgcn_global_load_lds((const unsigned*)(_g + offA[_i]), (unsigned*)((char*)(P) + tidx * 16 + _i * 8192), 16, 0, 0); } } while (0)
; #define STAGEB(P, br, kt) do { const char* _g = uptr(Bt + (size_t)(br) * ldb + (size_t)(kt) * BK); \
;     _Pragma("unroll") for (int _i = 0; _i < 2; ++_i) { \
;       __builtin_amdgcn_global_load_lds((const unsigned*)(_g + offB[_i]), (unsigned*)((char*)(P) + tidx * 16 + _i * 8192), 16, 0, 0); } } while (0)
; #define LDA(dst, b, h) _Pragma("unroll") for (int m = 0; m < 4; ++m) _Pragma("unroll") for (int k = 0; k < 2; ++k) \
;     dst[m][k] = *reinterpret_cast<const bf16x8*>((char*)SA(b, h) + aoff + m * 2048 + k * 1024)
; #define LDB(dst, b, h) _Pragma("unroll") for (int n = 0; n < 2; ++n) _Pragma("unroll") for (int k = 0; k < 2; ++k) \
;     dst[n][k] = *reinterpret_cast<const bf16x8*>((char*)SB(b, h) + boff + n * (SWAP ? 256 : 2048) + k * 1024)
; #define WAIT_V(n) asm volatile("s_waitcnt vmcnt(" #n ")" ::: "memory")
; #define WAIT_L(n) asm volatile("s_waitcnt lgkmcnt(" #n ")" ::: "memory")
; template <int EPI>
; DI void gemm_phase(const u16* __restrict__ A, int lda, const u16* __restrict__ Bt, int ldb,
;                    int M, int N, int K, const Epi& e, unsigned char* shmraw, int wv, int slot) {
;     ...
;     for (int t = 0; t < nt - 2; t += 2) {
;       LDB(B0, 0, 0); SCHED; LDA(At, 0, 0); STAGEA(SA(1, 1), brow + HALF, t + 1);
;       WAIT_L(8); BAR; WAIT_L(0); MMA(0, 0, At, B0); BAR; SCHED;
;       LDB(B1, 0, 1); STAGEB(SB(0, 0), bcol, t + 2);
;       BAR; WAIT_L(0); MMA(0, 1, At, B1); BAR;
;       LDA(At, 0, 1); STAGEA(SA(0, 0), brow, t + 2);
;       BAR; WAIT_L(0); MMA(1, 0, At, B0); BAR; SCHED;
;       STAGEB(SB(0, 1), bcol + HALF, t + 2);
;       WAIT_V(6); BAR; MMA(1, 1, At, B1); BAR;
;       LDB(B0, 1, 0); SCHED; LDA(At, 1, 0); STAGEA(SA(0, 1), brow + HALF, t + 2);
;       WAIT_L(8); BAR; WAIT_L(0); MMA(0, 0, At, B0); BAR; SCHED;
;       LDB(B1, 1, 1); STAGEB(SB(1, 0), bcol, t + 3);
;       BAR; WAIT_L(0); MMA(0, 1, At, B1); BAR;
;       LDA(At, 1, 1); STAGEA(SA(1, 0), brow, t + 3);
;       BAR; WAIT_L(0); MMA(1, 0, At, B0); BAR; SCHED;
;       STAGEB(SB(1, 1), bcol + HALF, t + 3);
;       WAIT_V(6); BAR; MMA(1, 1, At, B1); BAR;
	s_add_u32 s16, s41, vcc_lo
	s_addc_u32 s87, s1, vcc_hi
	s_add_u32 s54, s16, 0x100
	s_addc_u32 s55, s87, 0
	v_readfirstlane_b32 s10, v194
	v_lshl_add_u64 v[132:133], s[54:55], 0, v[152:153]
	s_mov_b32 m0, s10
	v_readfirstlane_b32 s10, v195
	global_load_lds_dwordx4 v[132:133], off
	v_lshl_add_u64 v[132:133], s[54:55], 0, v[150:151]
	s_mov_b32 m0, s10
	s_nop 0
	global_load_lds_dwordx4 v[132:133], off
	s_waitcnt vmcnt(6)
	s_barrier
	s_setprio 1
	v_mfma_f32_16x16x32_bf16 v[54:57], v[206:209], v[154:157], v[54:57]
	v_mfma_f32_16x16x32_bf16 v[58:61], v[210:213], v[154:157], v[58:61]
	v_mfma_f32_16x16x32_bf16 v[66:69], v[206:209], v[162:165], v[66:69]
	v_mfma_f32_16x16x32_bf16 v[70:73], v[210:213], v[162:165], v[70:73]
	v_mfma_f32_16x16x32_bf16 v[74:77], v[206:209], v[170:173], v[74:77]
	v_mfma_f32_16x16x32_bf16 v[82:85], v[210:213], v[170:173], v[82:85]
	v_mfma_f32_16x16x32_bf16 v[86:89], v[206:209], v[184:187], v[86:89]
	v_mfma_f32_16x16x32_bf16 v[90:93], v[210:213], v[184:187], v[90:93]
	v_mfma_f32_16x16x32_bf16 v[54:57], v[214:217], v[158:161], v[54:57]
	v_mfma_f32_16x16x32_bf16 v[58:61], v[218:221], v[158:161], v[58:61]
	v_mfma_f32_16x16x32_bf16 v[66:69], v[214:217], v[166:169], v[66:69]
	v_mfma_f32_16x16x32_bf16 v[70:73], v[218:221], v[166:169], v[70:73]
	v_mfma_f32_16x16x32_bf16 v[74:77], v[214:217], v[180:183], v[74:77]
	v_mfma_f32_16x16x32_bf16 v[82:85], v[218:221], v[180:183], v[82:85]
	v_mfma_f32_16x16x32_bf16 v[86:89], v[214:217], v[188:191], v[86:89]
	v_mfma_f32_16x16x32_bf16 v[90:93], v[218:221], v[188:191], v[90:93]
	s_setprio 0
	v_add_u32_e32 v131, s85, v176
	s_barrier
	ds_read_b128 v[132:135], v131
	ds_read_b128 v[136:139], v131 offset:256
	ds_read_b128 v[140:143], v131 offset:1024
	ds_read_b128 v[144:147], v131 offset:1280
	s_add_u32 s54, s11, 0x100
	s_addc_u32 s55, s37, 0
	v_readfirstlane_b32 s10, v196
	v_lshl_add_u64 v[148:149], s[54:55], 0, v[152:153]
	s_mov_b32 m0, s10
	v_readfirstlane_b32 s10, v197
	ds_read_b128 v[154:157], v204 offset:32768
	ds_read_b128 v[158:161], v204 offset:33792
	ds_read_b128 v[162:165], v204 offset:34816
	ds_read_b128 v[166:169], v204 offset:35840
	ds_read_b128 v[170:173], v204 offset:36864
	ds_read_b128 v[180:183], v204 offset:37888
	ds_read_b128 v[184:187], v204 offset:38912
	ds_read_b128 v[188:191], v204 offset:39936
	global_load_lds_dwordx4 v[148:149], off
	v_lshl_add_u64 v[148:149], s[54:55], 0, v[150:151]
	s_mov_b32 m0, s10
	s_nop 0
	global_load_lds_dwordx4 v[148:149], off
	s_waitcnt lgkmcnt(8)
	s_barrier
	s_waitcnt lgkmcnt(0)
	s_setprio 1
	v_mfma_f32_16x16x32_bf16 v[126:129], v[132:135], v[154:157], v[126:129]
	v_mfma_f32_16x16x32_bf16 v[122:125], v[136:139], v[154:157], v[122:125]
	v_mfma_f32_16x16x32_bf16 v[118:121], v[132:135], v[162:165], v[118:121]
	v_mfma_f32_16x16x32_bf16 v[114:117], v[136:139], v[162:165], v[114:117]
	v_mfma_f32_16x16x32_bf16 v[110:113], v[132:135], v[170:173], v[110:113]
	v_mfma_f32_16x16x32_bf16 v[106:109], v[136:139], v[170:173], v[106:109]
	v_mfma_f32_16x16x32_bf16 v[102:105], v[132:135], v[184:187], v[102:105]
	v_mfma_f32_16x16x32_bf16 v[98:101], v[136:139], v[184:187], v[98:101]
	v_mfma_f32_16x16x32_bf16 v[126:129], v[140:143], v[158:161], v[126:129]
	v_mfma_f32_16x16x32_bf16 v[122:125], v[144:147], v[158:161], v[122:125]
	v_mfma_f32_16x16x32_bf16 v[118:121], v[140:143], v[166:169], v[118:121]
	v_mfma_f32_16x16x32_bf16 v[114:117], v[144:147], v[166:169], v[114:117]
	v_mfma_f32_16x16x32_bf16 v[110:113], v[140:143], v[180:183], v[110:113]
	v_mfma_f32_16x16x32_bf16 v[106:109], v[144:147], v[180:183], v[106:109]
	v_mfma_f32_16x16x32_bf16 v[102:105], v[140:143], v[188:191], v[102:105]
	v_mfma_f32_16x16x32_bf16 v[98:101], v[144:147], v[188:191], v[98:101]
	s_setprio 0
	s_barrier
	s_add_u32 s54, s76, 0x180
	s_addc_u32 s55, s89, 0
	v_readfirstlane_b32 s10, v198
	v_add_u32_e32 v131, s86, v176
	v_lshl_add_u64 v[148:149], s[54:55], 0, v[152:153]
	s_mov_b32 m0, s10
	v_readfirstlane_b32 s10, v199
	ds_read_b128 v[206:209], v131
	ds_read_b128 v[210:213], v131 offset:256
	ds_read_b128 v[214:217], v131 offset:1024
	ds_read_b128 v[218:221], v131 offset:1280
	global_load_lds_dwordx4 v[148:149], off
	v_lshl_add_u64 v[148:149], s[54:55], 0, v[150:151]
	s_mov_b32 m0, s10
	s_nop 0
	global_load_lds_dwordx4 v[148:149], off
	s_barrier
	s_waitcnt lgkmcnt(0)
	s_setprio 1
	v_mfma_f32_16x16x32_bf16 v[94:97], v[206:209], v[154:157], v[94:97]
	v_mfma_f32_16x16x32_bf16 v[78:81], v[210:213], v[154:157], v[78:81]
	v_mfma_f32_16x16x32_bf16 v[62:65], v[206:209], v[162:165], v[62:65]
	v_mfma_f32_16x16x32_bf16 v[50:53], v[210:213], v[162:165], v[50:53]
	v_mfma_f32_16x16x32_bf16 v[46:49], v[206:209], v[170:173], v[46:49]
	v_mfma_f32_16x16x32_bf16 v[42:45], v[210:213], v[170:173], v[42:45]
	v_mfma_f32_16x16x32_bf16 v[38:41], v[206:209], v[184:187], v[38:41]
	v_mfma_f32_16x16x32_bf16 v[34:37], v[210:213], v[184:187], v[34:37]
	v_mfma_f32_16x16x32_bf16 v[94:97], v[214:217], v[158:161], v[94:97]
	v_mfma_f32_16x16x32_bf16 v[78:81], v[218:221], v[158:161], v[78:81]
	v_mfma_f32_16x16x32_bf16 v[62:65], v[214:217], v[166:169], v[62:65]
	v_mfma_f32_16x16x32_bf16 v[50:53], v[218:221], v[166:169], v[50:53]
	v_mfma_f32_16x16x32_bf16 v[46:49], v[214:217], v[180:183], v[46:49]
	v_mfma_f32_16x16x32_bf16 v[42:45], v[218:221], v[180:183], v[42:45]
	v_mfma_f32_16x16x32_bf16 v[38:41], v[214:217], v[188:191], v[38:41]
	v_mfma_f32_16x16x32_bf16 v[34:37], v[218:221], v[188:191], v[34:37]
	s_setprio 0
	s_add_u32 s54, s90, 0x180
	s_addc_u32 s55, s77, 0
	v_readfirstlane_b32 s10, v200
	v_lshl_add_u64 v[148:149], s[54:55], 0, v[152:153]
	s_mov_b32 m0, s10
	v_readfirstlane_b32 s10, v201
	s_barrier
; #define STAGEA(P, br, kt) do { const char* _g = uptr(A + (size_t)(br) * lda + (size_t)(kt) * BK); \
;     _Pragma("unroll") for (int _i = 0; _i < 2; ++_i) { \
;       __builtin_amdgcn_global_load_lds((const unsigned*)(_g + offA[_i]), (unsigned*)((char*)(P) + tidx * 16 + _i * 8192), 16, 0, 0); } } while (0)
; #define STAGEB(P, br, kt) do { const char* _g = uptr(Bt + (size_t)(br) * ldb + (size_t)(kt) * BK); \
;     _Pragma("unroll") for (int _i = 0; _i < 2; ++_i) { \
;       __builtin_amdgcn_global_load_lds((const unsigned*)(_g + offB[_i]), (unsigned*)((char*)(P) + tidx * 16 + _i * 8192), 16, 0, 0); } } while (0)
; #define LDA(dst, b, h) _Pragma("unroll") for (int m = 0; m < 4; ++m) _Pragma("unroll") for (int k = 0; k < 2; ++k) \
;     dst[m][k] = *reinterpret_cast<const bf16x8*>((char*)SA(b, h) + aoff + m * 2048 + k * 1024)
; #define LDB(dst, b, h) _Pragma("unroll") for (int n = 0; n < 2; ++n) _Pragma("unroll") for (int k = 0; k < 2; ++k) \
;     dst[n][k] = *reinterpret_cast<const bf16x8*>((char*)SB(b, h) + boff + n * (SWAP ? 256 : 2048) + k * 1024)
; #define WAIT_V(n) asm volatile("s_waitcnt vmcnt(" #n ")" ::: "memory")
; #define WAIT_L(n) asm volatile("s_waitcnt lgkmcnt(" #n ")" ::: "memory")
; #define BAR __builtin_amdgcn_s_barrier()
; #define SCHED __builtin_amdgcn_sched_barrier(0)
; template <int EPI>
; DI void gemm_phase(const u16* __restrict__ A, int lda, const u16* __restrict__ Bt, int ldb,
;                    int M, int N, int K, const Epi& e, unsigned char* shmraw, int wv, int slot) {
;     ...
;       LDA(At, 1, 1); STAGEA(SA(1, 0), brow, t + 3);
;       BAR; WAIT_L(0); MMA(1, 0, At, B0); BAR; SCHED;
;       STAGEB(SB(1, 1), bcol + HALF, t + 3);
;       WAIT_V(6); BAR; MMA(1, 1, At, B1); BAR;
;     }
;     { LDB(B0, 0, 0); LDA(At, 0, 0); STAGEA(SA(1, 1), brow + HALF, nt - 1);
;       BAR; WAIT_L(0); MMA(0, 0, At, B0); BAR;
	ds_read_b128 v[154:157], v204 offset:49152
	ds_read_b128 v[158:161], v204 offset:50176
	ds_read_b128 v[162:165], v204 offset:51200
	ds_read_b128 v[166:169], v204 offset:52224
	ds_read_b128 v[170:173], v204 offset:53248
	ds_read_b128 v[180:183], v204 offset:54272
	ds_read_b128 v[184:187], v204 offset:55296
	ds_read_b128 v[188:191], v204 offset:56320
	global_load_lds_dwordx4 v[148:149], off
	v_lshl_add_u64 v[148:149], s[54:55], 0, v[150:151]
	s_mov_b32 m0, s10
	s_nop 0
	global_load_lds_dwordx4 v[148:149], off
	s_barrier
	s_waitcnt lgkmcnt(0)
	s_setprio 1
	v_mfma_f32_16x16x32_bf16 v[30:33], v[132:135], v[154:157], v[30:33]
	v_mfma_f32_16x16x32_bf16 v[26:29], v[136:139], v[154:157], v[26:29]
	v_mfma_f32_16x16x32_bf16 v[22:25], v[132:135], v[162:165], v[22:25]
	v_mfma_f32_16x16x32_bf16 v[18:21], v[136:139], v[162:165], v[18:21]
	v_mfma_f32_16x16x32_bf16 v[14:17], v[132:135], v[170:173], v[14:17]
	v_mfma_f32_16x16x32_bf16 v[10:13], v[136:139], v[170:173], v[10:13]
	v_mfma_f32_16x16x32_bf16 v[6:9], v[132:135], v[184:187], v[6:9]
	v_mfma_f32_16x16x32_bf16 v[2:5], v[136:139], v[184:187], v[2:5]
	v_mfma_f32_16x16x32_bf16 v[30:33], v[140:143], v[158:161], v[30:33]
	v_mfma_f32_16x16x32_bf16 v[26:29], v[144:147], v[158:161], v[26:29]
	v_mfma_f32_16x16x32_bf16 v[22:25], v[140:143], v[166:169], v[22:25]
	v_mfma_f32_16x16x32_bf16 v[18:21], v[144:147], v[166:169], v[18:21]
	v_mfma_f32_16x16x32_bf16 v[14:17], v[140:143], v[180:183], v[14:17]
	v_mfma_f32_16x16x32_bf16 v[10:13], v[144:147], v[180:183], v[10:13]
	v_mfma_f32_16x16x32_bf16 v[6:9], v[140:143], v[188:191], v[6:9]
	v_mfma_f32_16x16x32_bf16 v[2:5], v[144:147], v[188:191], v[2:5]
	s_setprio 0
	s_barrier
	s_add_u32 s54, s16, 0x180
	s_addc_u32 s55, s87, 0
	v_readfirstlane_b32 s10, v202
	v_lshl_add_u64 v[132:133], s[54:55], 0, v[152:153]
	s_mov_b32 m0, s10
	v_readfirstlane_b32 s10, v203
	global_load_lds_dwordx4 v[132:133], off
	v_lshl_add_u64 v[132:133], s[54:55], 0, v[150:151]
	s_mov_b32 m0, s10
	s_nop 0
	global_load_lds_dwordx4 v[132:133], off
	s_waitcnt vmcnt(6)
	s_barrier
	s_setprio 1
	v_mfma_f32_16x16x32_bf16 v[54:57], v[206:209], v[154:157], v[54:57]
	v_mfma_f32_16x16x32_bf16 v[58:61], v[210:213], v[154:157], v[58:61]
	v_mfma_f32_16x16x32_bf16 v[66:69], v[206:209], v[162:165], v[66:69]
	v_mfma_f32_16x16x32_bf16 v[70:73], v[210:213], v[162:165], v[70:73]
	v_mfma_f32_16x16x32_bf16 v[74:77], v[206:209], v[170:173], v[74:77]
	v_mfma_f32_16x16x32_bf16 v[82:85], v[210:213], v[170:173], v[82:85]
	v_mfma_f32_16x16x32_bf16 v[86:89], v[206:209], v[184:187], v[86:89]
	v_mfma_f32_16x16x32_bf16 v[90:93], v[210:213], v[184:187], v[90:93]
	v_mfma_f32_16x16x32_bf16 v[54:57], v[214:217], v[158:161], v[54:57]
	v_mfma_f32_16x16x32_bf16 v[58:61], v[218:221], v[158:161], v[58:61]
	v_mfma_f32_16x16x32_bf16 v[66:69], v[214:217], v[166:169], v[66:69]
	v_mfma_f32_16x16x32_bf16 v[70:73], v[218:221], v[166:169], v[70:73]
	v_mfma_f32_16x16x32_bf16 v[74:77], v[214:217], v[180:183], v[74:77]
	v_mfma_f32_16x16x32_bf16 v[82:85], v[218:221], v[180:183], v[82:85]
	v_mfma_f32_16x16x32_bf16 v[86:89], v[214:217], v[188:191], v[86:89]
	v_mfma_f32_16x16x32_bf16 v[90:93], v[218:221], v[188:191], v[90:93]
	s_setprio 0
	s_add_i32 s36, s36, 2
	s_add_u32 vcc_lo, vcc_lo, 0x100
	s_addc_u32 vcc_hi, vcc_hi, 0
	s_cmp_gt_u32 s36, 59
	s_barrier
	s_cbranch_scc0 .LBB0_1185
	s_lshl_b64 s[30:31], s[30:31], 1
	v_readlane_b32 s1, v253, 63
	s_add_u32 s30, s1, s30
	v_readlane_b32 s1, v254, 0
	v_add_u32_e32 v131, 16, v176
	s_addc_u32 s31, s1, s31
	v_readfirstlane_b32 s1, v0
	v_add_u32_e32 v144, 0x10000, v131
	v_lshl_add_u64 v[148:149], s[30:31], 0, v[152:153]
	s_mov_b32 m0, s1
	v_readfirstlane_b32 s1, v130
	ds_read_b128 v[132:135], v144
	ds_read_b128 v[136:139], v144 offset:256
	ds_read_b128 v[140:143], v144 offset:1024
	ds_read_b128 v[144:147], v144 offset:1280
	ds_read_b128 v[154:157], v204
	ds_read_b128 v[158:161], v204 offset:1024
	ds_read_b128 v[162:165], v204 offset:2048
	ds_read_b128 v[166:169], v204 offset:3072
	ds_read_b128 v[170:173], v204 offset:4096
	ds_read_b128 v[180:183], v204 offset:5120
	ds_read_b128 v[184:187], v204 offset:6144
	ds_read_b128 v[188:191], v204 offset:7168
	global_load_lds_dwordx4 v[148:149], off
	v_lshl_add_u64 v[148:149], s[30:31], 0, v[150:151]
	s_mov_b32 m0, s1
	s_nop 0
	global_load_lds_dwordx4 v[148:149], off
	s_barrier
	s_waitcnt lgkmcnt(0)
	s_setprio 1
	v_mfma_f32_16x16x32_bf16 v[126:129], v[132:135], v[154:157], v[126:129]
	v_mfma_f32_16x16x32_bf16 v[122:125], v[136:139], v[154:157], v[122:125]
	v_mfma_f32_16x16x32_bf16 v[118:121], v[132:135], v[162:165], v[118:121]
	v_mfma_f32_16x16x32_bf16 v[114:117], v[136:139], v[162:165], v[114:117]
	v_mfma_f32_16x16x32_bf16 v[110:113], v[132:135], v[170:173], v[110:113]
	v_mfma_f32_16x16x32_bf16 v[102:105], v[132:135], v[184:187], v[102:105]
	v_mfma_f32_16x16x32_bf16 v[98:101], v[136:139], v[184:187], v[98:101]
	v_mfma_f32_16x16x32_bf16 v[126:129], v[140:143], v[158:161], v[126:129]
	v_mfma_f32_16x16x32_bf16 v[122:125], v[144:147], v[158:161], v[122:125]
	v_mfma_f32_16x16x32_bf16 v[118:121], v[140:143], v[166:169], v[118:121]
	v_mfma_f32_16x16x32_bf16 v[114:117], v[144:147], v[166:169], v[114:117]
	v_mfma_f32_16x16x32_bf16 v[110:113], v[140:143], v[180:183], v[110:113]
	v_mfma_f32_16x16x32_bf16 v[106:109], v[136:139], v[170:173], v[106:109]
	v_mfma_f32_16x16x32_bf16 v[102:105], v[140:143], v[188:191], v[102:105]
	v_mfma_f32_16x16x32_bf16 v[98:101], v[144:147], v[188:191], v[98:101]
	v_mfma_f32_16x16x32_bf16 v[206:209], v[144:147], v[180:183], v[106:109]
	s_setprio 0
	v_add_u32_e32 v0, 0x14000, v131
	s_barrier
; #define LDA(dst, b, h) _Pragma("unroll") for (int m = 0; m < 4; ++m) _Pragma("unroll") for (int k = 0; k < 2; ++k) \
;     dst[m][k] = *reinterpret_cast<const bf16x8*>((char*)SA(b, h) + aoff + m * 2048 + k * 1024)
; #define LDB(dst, b, h) _Pragma("unroll") for (int n = 0; n < 2; ++n) _Pragma("unroll") for (int k = 0; k < 2; ++k) \
;     dst[n][k] = *reinterpret_cast<const bf16x8*>((char*)SB(b, h) + boff + n * (SWAP ? 256 : 2048) + k * 1024)
; #define WAIT_V(n) asm volatile("s_waitcnt vmcnt(" #n ")" ::: "memory")
; #define WAIT_L(n) asm volatile("s_waitcnt lgkmcnt(" #n ")" ::: "memory")
; #define BAR __builtin_amdgcn_s_barrier()
; template <int EPI>
; DI void gemm_phase(const u16* __restrict__ A, int lda, const u16* __restrict__ Bt, int ldb,
;                    int M, int N, int K, const Epi& e, unsigned char* shmraw, int wv, int slot) {
;     ...
;       BAR; WAIT_L(0); MMA(0, 0, At, B0); BAR;
;       LDB(B1, 0, 1); BAR; WAIT_L(0); MMA(0, 1, At, B1); BAR;
;       LDA(At, 0, 1); WAIT_V(4); BAR; WAIT_L(0); MMA(1, 0, At, B0); MMA(1, 1, At, B1); BAR; }
;     { LDB(B0, 1, 0); LDA(At, 1, 0); WAIT_V(2); BAR; WAIT_L(0); MMA(0, 0, At, B0); BAR;
	s_nop 1
	ds_read_b128 v[106:109], v0
	ds_read_b128 v[210:213], v0 offset:256
	ds_read_b128 v[214:217], v0 offset:1024
	ds_read_b128 v[218:221], v0 offset:1280
	s_barrier
	s_waitcnt lgkmcnt(0)
	s_setprio 1
	v_mfma_f32_16x16x32_bf16 v[78:81], v[210:213], v[154:157], v[78:81]
	v_mfma_f32_16x16x32_bf16 v[62:65], v[106:109], v[162:165], v[62:65]
	v_mfma_f32_16x16x32_bf16 v[50:53], v[210:213], v[162:165], v[50:53]
	v_mfma_f32_16x16x32_bf16 v[46:49], v[106:109], v[170:173], v[46:49]
	v_mfma_f32_16x16x32_bf16 v[42:45], v[210:213], v[170:173], v[42:45]
	v_mfma_f32_16x16x32_bf16 v[94:97], v[106:109], v[154:157], v[94:97]
	v_mfma_f32_16x16x32_bf16 v[78:81], v[218:221], v[158:161], v[78:81]
	v_mfma_f32_16x16x32_bf16 v[62:65], v[214:217], v[166:169], v[62:65]
	v_mfma_f32_16x16x32_bf16 v[50:53], v[218:221], v[166:169], v[50:53]
	v_mfma_f32_16x16x32_bf16 v[46:49], v[214:217], v[180:183], v[46:49]
	v_mfma_f32_16x16x32_bf16 v[42:45], v[218:221], v[180:183], v[42:45]
	v_mfma_f32_16x16x32_bf16 v[38:41], v[106:109], v[184:187], v[38:41]
	v_mfma_f32_16x16x32_bf16 v[34:37], v[210:213], v[184:187], v[34:37]
	v_mfma_f32_16x16x32_bf16 v[222:225], v[214:217], v[158:161], v[94:97]
	v_mfma_f32_16x16x32_bf16 v[38:41], v[214:217], v[188:191], v[38:41]
	v_mfma_f32_16x16x32_bf16 v[34:37], v[218:221], v[188:191], v[34:37]
	s_setprio 0
	s_barrier
	ds_read_b128 v[94:97], v204 offset:16384
	ds_read_b128 v[154:157], v204 offset:17408
	ds_read_b128 v[158:161], v204 offset:18432
	ds_read_b128 v[162:165], v204 offset:19456
	ds_read_b128 v[166:169], v204 offset:20480
	ds_read_b128 v[170:173], v204 offset:21504
	ds_read_b128 v[180:183], v204 offset:22528
	ds_read_b128 v[184:187], v204 offset:23552
	s_waitcnt vmcnt(4)
	s_barrier
	s_waitcnt lgkmcnt(0)
	s_setprio 1
	v_mfma_f32_16x16x32_bf16 v[30:33], v[132:135], v[94:97], v[30:33]
	v_mfma_f32_16x16x32_bf16 v[26:29], v[136:139], v[94:97], v[26:29]
	v_mfma_f32_16x16x32_bf16 v[14:17], v[132:135], v[166:169], v[14:17]
	v_mfma_f32_16x16x32_bf16 v[10:13], v[136:139], v[166:169], v[10:13]
	v_mfma_f32_16x16x32_bf16 v[6:9], v[132:135], v[180:183], v[6:9]
	v_mfma_f32_16x16x32_bf16 v[2:5], v[136:139], v[180:183], v[2:5]
	v_mfma_f32_16x16x32_bf16 v[30:33], v[140:143], v[154:157], v[30:33]
	v_mfma_f32_16x16x32_bf16 v[26:29], v[144:147], v[154:157], v[26:29]
	v_mfma_f32_16x16x32_bf16 v[22:25], v[132:135], v[158:161], v[22:25]
	v_mfma_f32_16x16x32_bf16 v[18:21], v[136:139], v[158:161], v[18:21]
	v_mfma_f32_16x16x32_bf16 v[14:17], v[140:143], v[170:173], v[14:17]
	v_mfma_f32_16x16x32_bf16 v[10:13], v[144:147], v[170:173], v[10:13]
	v_mfma_f32_16x16x32_bf16 v[6:9], v[140:143], v[184:187], v[6:9]
	v_mfma_f32_16x16x32_bf16 v[2:5], v[144:147], v[184:187], v[2:5]
	v_mfma_f32_16x16x32_bf16 v[22:25], v[140:143], v[162:165], v[22:25]
	v_mfma_f32_16x16x32_bf16 v[18:21], v[144:147], v[162:165], v[18:21]
	s_setprio 0
	s_setprio 1
	v_mfma_f32_16x16x32_bf16 v[58:61], v[210:213], v[94:97], v[58:61]
	v_mfma_f32_16x16x32_bf16 v[54:57], v[106:109], v[94:97], v[54:57]
	v_mfma_f32_16x16x32_bf16 v[146:149], v[218:221], v[154:157], v[58:61]
	v_mfma_f32_16x16x32_bf16 v[58:61], v[106:109], v[158:161], v[66:69]
	v_mfma_f32_16x16x32_bf16 v[54:57], v[214:217], v[154:157], v[54:57]
	v_mfma_f32_16x16x32_bf16 v[154:157], v[214:217], v[162:165], v[58:61]
	v_mfma_f32_16x16x32_bf16 v[58:61], v[210:213], v[158:161], v[70:73]
	v_mfma_f32_16x16x32_bf16 v[158:161], v[218:221], v[162:165], v[58:61]
	v_mfma_f32_16x16x32_bf16 v[58:61], v[106:109], v[166:169], v[74:77]
	v_mfma_f32_16x16x32_bf16 v[162:165], v[214:217], v[170:173], v[58:61]
	v_mfma_f32_16x16x32_bf16 v[58:61], v[210:213], v[166:169], v[82:85]
	v_mfma_f32_16x16x32_bf16 v[166:169], v[218:221], v[170:173], v[58:61]
	v_mfma_f32_16x16x32_bf16 v[58:61], v[106:109], v[180:183], v[86:89]
	v_mfma_f32_16x16x32_bf16 v[170:173], v[214:217], v[184:187], v[58:61]
	v_mfma_f32_16x16x32_bf16 v[58:61], v[210:213], v[180:183], v[90:93]
	v_mfma_f32_16x16x32_bf16 v[180:183], v[218:221], v[184:187], v[58:61]
	s_setprio 0
	v_add_u32_e32 v0, 0x18000, v131
	s_barrier
	ds_read_b128 v[66:69], v0
	ds_read_b128 v[70:73], v0 offset:256
	ds_read_b128 v[184:187], v0 offset:1024
	ds_read_b128 v[188:191], v0 offset:1280
	ds_read_b128 v[58:61], v204 offset:32768
	ds_read_b128 v[74:77], v204 offset:33792
	ds_read_b128 v[82:85], v204 offset:34816
	ds_read_b128 v[86:89], v204 offset:35840
	ds_read_b128 v[210:213], v204 offset:36864
	ds_read_b128 v[214:217], v204 offset:37888
	ds_read_b128 v[218:221], v204 offset:38912
	ds_read_b128 v[226:229], v204 offset:39936
	s_waitcnt vmcnt(2)
	s_barrier
; #define LDA(dst, b, h) _Pragma("unroll") for (int m = 0; m < 4; ++m) _Pragma("unroll") for (int k = 0; k < 2; ++k) \
;     dst[m][k] = *reinterpret_cast<const bf16x8*>((char*)SA(b, h) + aoff + m * 2048 + k * 1024)
; #define LDB(dst, b, h) _Pragma("unroll") for (int n = 0; n < 2; ++n) _Pragma("unroll") for (int k = 0; k < 2; ++k) \
;     dst[n][k] = *reinterpret_cast<const bf16x8*>((char*)SB(b, h) + boff + n * (SWAP ? 256 : 2048) + k * 1024)
; #define WAIT_V(n) asm volatile("s_waitcnt vmcnt(" #n ")" ::: "memory")
; #define WAIT_L(n) asm volatile("s_waitcnt lgkmcnt(" #n ")" ::: "memory")
; #define BAR __builtin_amdgcn_s_barrier()
; template <int EPI>
; DI void gemm_phase(const u16* __restrict__ A, int lda, const u16* __restrict__ Bt, int ldb,
;                    int M, int N, int K, const Epi& e, unsigned char* shmraw, int wv, int slot) {
;     ...
;     { LDB(B0, 1, 0); LDA(At, 1, 0); WAIT_V(2); BAR; WAIT_L(0); MMA(0, 0, At, B0); BAR;
;       LDB(B1, 1, 1); WAIT_V(0); BAR; WAIT_L(0); MMA(0, 1, At, B1); BAR;
;       LDA(At, 1, 1); BAR; WAIT_L(0); MMA(1, 0, At, B0); MMA(1, 1, At, B1); BAR; }
;     if (wr == 0) BAR;
	s_waitcnt lgkmcnt(0)
	s_setprio 1
	v_mfma_f32_16x16x32_bf16 v[90:93], v[66:69], v[58:61], v[126:129]
	v_mfma_f32_16x16x32_bf16 v[138:141], v[184:187], v[74:77], v[90:93]
	v_mfma_f32_16x16x32_bf16 v[90:93], v[70:73], v[58:61], v[122:125]
	v_mfma_f32_16x16x32_bf16 v[142:145], v[188:191], v[74:77], v[90:93]
	v_mfma_f32_16x16x32_bf16 v[90:93], v[66:69], v[82:85], v[118:121]
	v_mfma_f32_16x16x32_bf16 v[122:125], v[184:187], v[86:89], v[90:93]
	v_mfma_f32_16x16x32_bf16 v[90:93], v[70:73], v[82:85], v[114:117]
	v_mfma_f32_16x16x32_bf16 v[126:129], v[188:191], v[86:89], v[90:93]
	v_mfma_f32_16x16x32_bf16 v[90:93], v[66:69], v[210:213], v[110:113]
	v_mfma_f32_16x16x32_bf16 v[106:109], v[184:187], v[214:217], v[90:93]
	v_mfma_f32_16x16x32_bf16 v[90:93], v[70:73], v[210:213], v[206:209]
	v_mfma_f32_16x16x32_bf16 v[110:113], v[188:191], v[214:217], v[90:93]
	v_mfma_f32_16x16x32_bf16 v[90:93], v[66:69], v[218:221], v[102:105]
	v_mfma_f32_16x16x32_bf16 v[94:97], v[70:73], v[218:221], v[98:101]
	v_mfma_f32_16x16x32_bf16 v[90:93], v[184:187], v[226:229], v[90:93]
	v_mfma_f32_16x16x32_bf16 v[94:97], v[188:191], v[226:229], v[94:97]
	s_setprio 0
	v_add_u32_e32 v0, 0x1c000, v131
	s_barrier
	ds_read_b128 v[206:209], v0
	ds_read_b128 v[230:233], v0 offset:256
	ds_read_b128 v[234:237], v0 offset:1024
	ds_read_b128 v[238:241], v0 offset:1280
	s_waitcnt vmcnt(0)
	s_barrier
	s_waitcnt lgkmcnt(0)
	s_setprio 1
	v_mfma_f32_16x16x32_bf16 v[98:101], v[206:209], v[58:61], v[222:225]
	v_mfma_f32_16x16x32_bf16 v[58:61], v[230:233], v[58:61], v[78:81]
	v_mfma_f32_16x16x32_bf16 v[134:137], v[238:241], v[74:77], v[58:61]
	v_mfma_f32_16x16x32_bf16 v[58:61], v[206:209], v[82:85], v[62:65]
	v_mfma_f32_16x16x32_bf16 v[50:53], v[230:233], v[82:85], v[50:53]
	v_mfma_f32_16x16x32_bf16 v[46:49], v[206:209], v[210:213], v[46:49]
	v_mfma_f32_16x16x32_bf16 v[42:45], v[230:233], v[210:213], v[42:45]
	v_mfma_f32_16x16x32_bf16 v[38:41], v[206:209], v[218:221], v[38:41]
	v_mfma_f32_16x16x32_bf16 v[34:37], v[230:233], v[218:221], v[34:37]
	v_mfma_f32_16x16x32_bf16 v[130:133], v[234:237], v[74:77], v[98:101]
	v_mfma_f32_16x16x32_bf16 v[114:117], v[234:237], v[86:89], v[58:61]
	v_mfma_f32_16x16x32_bf16 v[118:121], v[238:241], v[86:89], v[50:53]
	v_mfma_f32_16x16x32_bf16 v[98:101], v[234:237], v[214:217], v[46:49]
	v_mfma_f32_16x16x32_bf16 v[102:105], v[238:241], v[214:217], v[42:45]
	v_mfma_f32_16x16x32_bf16 v[82:85], v[234:237], v[226:229], v[38:41]
	v_mfma_f32_16x16x32_bf16 v[86:89], v[238:241], v[226:229], v[34:37]
	s_setprio 0
	s_barrier
	s_nop 0
	ds_read_b128 v[34:37], v204 offset:49152
	ds_read_b128 v[38:41], v204 offset:50176
	ds_read_b128 v[210:213], v204 offset:51200
	ds_read_b128 v[214:217], v204 offset:52224
	ds_read_b128 v[218:221], v204 offset:53248
	ds_read_b128 v[222:225], v204 offset:54272
	ds_read_b128 v[226:229], v204 offset:55296
	ds_read_b128 v[242:245], v204 offset:56320
	s_barrier
	s_waitcnt lgkmcnt(0)
	s_setprio 1
	v_mfma_f32_16x16x32_bf16 v[30:33], v[66:69], v[34:37], v[30:33]
	v_mfma_f32_16x16x32_bf16 v[26:29], v[70:73], v[34:37], v[26:29]
	v_mfma_f32_16x16x32_bf16 v[22:25], v[66:69], v[210:213], v[22:25]
	v_mfma_f32_16x16x32_bf16 v[18:21], v[70:73], v[210:213], v[18:21]
	v_mfma_f32_16x16x32_bf16 v[14:17], v[66:69], v[218:221], v[14:17]
	v_mfma_f32_16x16x32_bf16 v[10:13], v[70:73], v[218:221], v[10:13]
	v_mfma_f32_16x16x32_bf16 v[6:9], v[66:69], v[226:229], v[6:9]
	v_mfma_f32_16x16x32_bf16 v[2:5], v[70:73], v[226:229], v[2:5]
	v_mfma_f32_16x16x32_bf16 v[74:77], v[184:187], v[38:41], v[30:33]
	v_mfma_f32_16x16x32_bf16 v[78:81], v[188:191], v[38:41], v[26:29]
	v_mfma_f32_16x16x32_bf16 v[58:61], v[184:187], v[214:217], v[22:25]
	v_mfma_f32_16x16x32_bf16 v[62:65], v[188:191], v[214:217], v[18:21]
	v_mfma_f32_16x16x32_bf16 v[42:45], v[184:187], v[222:225], v[14:17]
	v_mfma_f32_16x16x32_bf16 v[46:49], v[188:191], v[222:225], v[10:13]
	v_mfma_f32_16x16x32_bf16 v[10:13], v[184:187], v[242:245], v[6:9]
	v_mfma_f32_16x16x32_bf16 v[14:17], v[188:191], v[242:245], v[2:5]
	s_setprio 0
	s_setprio 1
	v_mfma_f32_16x16x32_bf16 v[2:5], v[206:209], v[34:37], v[54:57]
	v_mfma_f32_16x16x32_bf16 v[66:69], v[234:237], v[38:41], v[2:5]
	v_mfma_f32_16x16x32_bf16 v[2:5], v[230:233], v[34:37], v[146:149]
	v_mfma_f32_16x16x32_bf16 v[70:73], v[238:241], v[38:41], v[2:5]
	v_mfma_f32_16x16x32_bf16 v[2:5], v[206:209], v[210:213], v[154:157]
	v_mfma_f32_16x16x32_bf16 v[50:53], v[234:237], v[214:217], v[2:5]
	v_mfma_f32_16x16x32_bf16 v[2:5], v[230:233], v[210:213], v[158:161]
	v_mfma_f32_16x16x32_bf16 v[54:57], v[238:241], v[214:217], v[2:5]
	v_mfma_f32_16x16x32_bf16 v[2:5], v[206:209], v[218:221], v[162:165]
	v_mfma_f32_16x16x32_bf16 v[26:29], v[234:237], v[222:225], v[2:5]
	v_mfma_f32_16x16x32_bf16 v[2:5], v[230:233], v[218:221], v[166:169]
	v_mfma_f32_16x16x32_bf16 v[30:33], v[238:241], v[222:225], v[2:5]
	v_mfma_f32_16x16x32_bf16 v[2:5], v[206:209], v[226:229], v[170:173]
	v_mfma_f32_16x16x32_bf16 v[6:9], v[230:233], v[226:229], v[180:183]
	v_mfma_f32_16x16x32_bf16 v[2:5], v[234:237], v[242:245], v[2:5]
	v_mfma_f32_16x16x32_bf16 v[6:9], v[238:241], v[242:245], v[6:9]
	s_setprio 0
	s_barrier
	s_and_saveexec_b64 s[30:31], s[4:5]
	s_cbranch_execz .LBB0_1188
	s_barrier
